# GEMM tile prologues: removed xnack-conservative vmcnt store drains before the first LDS-DMA issue (z, wout, ffn_down, glu); ffn_up prologue vmcnt(0)->vmcnt(2) so K-step-0 DMAs are not serialized
# baseline (speedup 1.0000x reference)
; #define MFMA(a, b, c) __builtin_amdgcn_mfma_f32_32x32x16_bf16(a, b, c, 0, 0, 0)
; #define ISSUE(k0, bf) do { char* A_ = lw + (bf) * BUF; \
;     _Pragma("unroll") for (int i_ = 0; i_ < 4; ++i_) { glds16(al.ptr(lrow + 32 * i_, (k0) + cg), A_ + i_ * 4096); glds16(bl.ptr(lrow + 32 * i_, (k0) + cg), A_ + ABYTES + i_ * 4096); } \
;     if (HALO) { if (wid == 0) glds16(gh + (k0), A_ + 16384); } } while (0)
; template <bool HALO, class AL, class BL>
; __device__ __forceinline__ void gemm_core(f32x16 (&acc)[2][2], f32x16& hacc, const AL& al, const BL& bl, int K, char* lds,
;                                           const u16* halo0, const u16* halo1, int brow0, int brow1) {
;     ...
;   const int sa = ((wr * 64 + r32) >> 1) & 7, sb0 = ((brow0 + r32) >> 1) & 7, sb1 = ((brow1 + r32) >> 1) & 7, sh = (r32 >> 1) & 7;
;   const int oa = (wr * 64 + r32) * 128, ob0 = ABYTES + (brow0 + r32) * 128, ob1 = ABYTES + (brow1 + r32) * 128, oh = (128 + r32) * 128;
;   __syncthreads();
;   ISSUE(0, 0);
;   const int nk = K >> 6;
;   for (int kt = 0; kt < nk; ++kt) {
;     asm volatile("s_waitcnt vmcnt(0)" ::: "memory");
;     __syncthreads();
;     if (kt + 1 < nk) ISSUE((kt + 1) * 64, (kt + 1) & 1);
;     const char* T = lds + (kt & 1) * BUF;
; #pragma unroll
;     for (int kk = 0; kk < 4; ++kk) {
;       const int c = kk * 2 + hi;
;       bf16x8 a0 = *(const bf16x8*)(T + oa + ((c ^ sa) << 4));
;       bf16x8 a1 = *(const bf16x8*)(T + oa + 4096 + ((c ^ sa) << 4));
;       bf16x8 b0 = *(const bf16x8*)(T + ob0 + ((c ^ sb0) << 4));
;       bf16x8 b1 = *(const bf16x8*)(T + ob1 + ((c ^ sb1) << 4));
;       acc[0][0] = MFMA(a0, b0, acc[0][0]); acc[0][1] = MFMA(a0, b1, acc[0][1]);
;       acc[1][0] = MFMA(a1, b0, acc[1][0]); acc[1][1] = MFMA(a1, b1, acc[1][1]);
; __device__ __forceinline__ void phase_ffn_down(const P& p, int layer, char* lds) {
;     ...
;   for (int it = 0; tile_at(it, 256, 8, tm, tn); ++it) {
;     f32x16 acc[2][2] = {};
;     { LdBf al{xb + (long)tm * 128 * DM, DM}, bl{wg + (long)tn * 128 * DM, DM}; gemm_plain(acc, al, bl, DM, lds); }
.LBB0_155:
	v_readlane_b32 vcc_lo, v253, 21
	s_or_b32 s3, s80, vcc_lo
	s_lshr_b32 s6, s3, 3
	s_and_b32 s6, s6, 0xf8
	s_lshl_b32 s7, s6, 3
	s_and_b32 s81, s80, 7
	s_sub_i32 s3, s3, s7
	s_or_b32 s85, s6, s81
	s_ashr_i32 s62, s3, 3
	s_lshl_b32 s3, s85, 18
	s_add_u32 s18, s40, s3
	v_mov_b32_e32 v1, v229
	v_mov_b32_e32 v6, v229
	s_addc_u32 s19, s41, 0
	s_ashr_i32 s63, s62, 31
	s_lshl_b64 s[6:7], s[62:63], 18
	v_and_b32_e32 v7, 31, v6
	v_ashrrev_i32_e32 v0, 3, v6
	v_lshrrev_b32_e32 v2, 4, v6
	v_readlane_b32 s3, v255, 19
	v_xor_b32_e32 v4, v2, v6
	v_and_or_b32 v10, v1, 64, v7
	v_ashrrev_i32_e32 v1, 31, v0
	s_add_u32 s64, s3, s6
	v_readlane_b32 s3, v255, 20
	v_lshlrev_b64 v[0:1], 11, v[0:1]
	v_lshlrev_b32_e32 v4, 4, v4
	s_addc_u32 s65, s3, s7
	v_lshl_add_u32 v96, v6, 4, 0
	v_lshl_add_u64 v[2:3], s[18:19], 0, v[0:1]
	v_and_b32_e32 v200, 0x70, v4
	v_add_u32_e32 v101, 0x4000, v96
	v_lshl_add_u64 v[66:67], v[2:3], 0, v[200:201]
	v_readfirstlane_b32 s83, v96
	v_lshl_add_u64 v[2:3], s[64:65], 0, v[0:1]
	s_mov_b64 s[6:7], 0x10000
	s_mov_b32 m0, s83
	v_lshl_add_u64 v[64:65], v[2:3], 0, v[200:201]
	v_readfirstlane_b32 s42, v101
	v_lshl_add_u64 v[2:3], v[0:1], 0, s[6:7]
	v_add_u32_e32 v102, 0x1000, v96
	s_barrier
	global_load_lds_dwordx4 v[66:67], off
	s_mov_b32 m0, s42
	v_lshl_add_u64 v[4:5], s[18:19], 0, v[2:3]
	v_readfirstlane_b32 s43, v102
	v_lshl_add_u64 v[2:3], s[64:65], 0, v[2:3]
	v_add_u32_e32 v103, 0x5000, v96
	s_mov_b64 s[6:7], 0x20000
	global_load_lds_dwordx4 v[64:65], off
	v_lshl_add_u64 v[70:71], v[4:5], 0, v[200:201]
	s_mov_b32 m0, s43
	v_lshl_add_u64 v[68:69], v[2:3], 0, v[200:201]
	v_readfirstlane_b32 s70, v103
	v_lshl_add_u64 v[2:3], v[0:1], 0, s[6:7]
	v_add_u32_e32 v88, 0x2000, v96
	s_mov_b64 s[72:73], 0x30000
	global_load_lds_dwordx4 v[70:71], off
	s_mov_b32 m0, s70
	v_lshl_add_u64 v[4:5], s[18:19], 0, v[2:3]
	v_readfirstlane_b32 s3, v88
	v_lshl_add_u64 v[2:3], s[64:65], 0, v[2:3]
	v_add_u32_e32 v89, 0x6000, v96
	v_lshl_add_u64 v[0:1], v[0:1], 0, s[72:73]
	v_lshrrev_b32_e32 v8, 5, v6
	v_bfe_u32 v11, v6, 1, 3
	global_load_lds_dwordx4 v[68:69], off
	v_lshl_add_u64 v[74:75], v[4:5], 0, v[200:201]
	s_mov_b32 m0, s3
	v_lshl_add_u64 v[72:73], v[2:3], 0, v[200:201]
	v_readfirstlane_b32 s6, v89
	v_lshl_add_u64 v[2:3], s[18:19], 0, v[0:1]
	v_add_u32_e32 v90, 0x3000, v96
	v_lshl_add_u64 v[0:1], s[64:65], 0, v[0:1]
	global_load_lds_dwordx4 v[74:75], off
	s_mov_b32 m0, s6
	v_readfirstlane_b32 s7, v90
	v_lshl_add_u64 v[76:77], v[0:1], 0, v[200:201]
	v_add_u32_e32 v91, 0x7000, v96
	v_bfe_u32 v0, v6, 5, 1
	v_bitop3_b32 v1, v8, v11, 1 bitop3:0x6c
	global_load_lds_dwordx4 v[72:73], off
	v_lshl_add_u64 v[78:79], v[2:3], 0, v[200:201]
	s_mov_b32 m0, s7
	v_readfirstlane_b32 s8, v91
	v_lshlrev_b32_e32 v8, 4, v1
	v_bitop3_b32 v1, v0, v11, 2 bitop3:0x36
	v_add_u32_e32 v93, 0x8000, v96
	global_load_lds_dwordx4 v[78:79], off
	s_mov_b32 m0, s8
	v_lshlrev_b32_e32 v81, 4, v1
	v_bitop3_b32 v1, v0, v11, 4 bitop3:0x36
	v_bitop3_b32 v0, v0, v11, 6 bitop3:0x36
	v_add_u32_e32 v92, 0xc000, v96
	v_readfirstlane_b32 s18, v93
	global_load_lds_dwordx4 v[76:77], off
	v_lshlrev_b32_e32 v84, 4, v1
	v_lshlrev_b32_e32 v120, 4, v0
	v_lshl_add_u64 v[0:1], v[66:67], 0, s[78:79]
	s_mov_b32 m0, s18
	v_readfirstlane_b32 s19, v92
	v_add_u32_e32 v94, 0x9000, v96
	s_waitcnt vmcnt(0)
	s_waitcnt vmcnt(0) lgkmcnt(0)
	s_barrier
	global_load_lds_dwordx4 v[0:1], off
	v_lshl_add_u64 v[0:1], v[64:65], 0, s[78:79]
	s_mov_b32 m0, s19
	v_readfirstlane_b32 s33, v94
	v_add_u32_e32 v95, 0xd000, v96
	global_load_lds_dwordx4 v[0:1], off
	v_lshl_add_u64 v[0:1], v[70:71], 0, s[78:79]
	s_mov_b32 m0, s33
	v_readfirstlane_b32 s72, v95
	v_add_u32_e32 v97, 0xa000, v96
	global_load_lds_dwordx4 v[0:1], off
	v_lshl_add_u64 v[0:1], v[68:69], 0, s[78:79]
	s_mov_b32 m0, s72
	v_readfirstlane_b32 s73, v97
	v_add_u32_e32 v98, 0xe000, v96
	global_load_lds_dwordx4 v[0:1], off
	v_lshl_add_u64 v[0:1], v[74:75], 0, s[78:79]
	s_mov_b32 m0, s73
	v_readfirstlane_b32 s92, v98
	v_add_u32_e32 v99, 0xb000, v96
	v_lshrrev_b32_e32 v9, 1, v6
	s_mov_b32 s52, 0x1ffffc0
	global_load_lds_dwordx4 v[0:1], off
	v_lshl_add_u64 v[0:1], v[72:73], 0, s[78:79]
	s_mov_b32 m0, s92
	v_readfirstlane_b32 s69, v99
	v_add_u32_e32 v100, 0xf000, v96
	v_and_or_b32 v2, v9, s52, v7
	global_load_lds_dwordx4 v[0:1], off
	v_lshl_add_u64 v[0:1], v[78:79], 0, s[78:79]
	s_mov_b32 m0, s69
	v_readfirstlane_b32 s82, v100
	global_load_lds_dwordx4 v[0:1], off
	v_lshl_add_u64 v[0:1], v[76:77], 0, s[78:79]
	s_mov_b32 m0, s82
	v_lshl_add_u32 v87, v2, 7, 0
	v_lshl_add_u32 v121, v10, 7, 0
	global_load_lds_dwordx4 v[0:1], off
	v_add_u32_e32 v80, v87, v8
	v_add_u32_e32 v82, v121, v8
	ds_read_b128 v[0:3], v80
	ds_read_b128 v[4:7], v80 offset:4096
	ds_read_b128 v[8:11], v82 offset:16384
	ds_read_b128 v[12:15], v82 offset:20480
	s_waitcnt lgkmcnt(0)
	v_mfma_f32_32x32x16_bf16 v[48:63], v[0:3], v[8:11], 0
	v_add_u32_e32 v85, v87, v81
	v_add_u32_e32 v83, v121, v81
	ds_read_b128 v[104:107], v85
	ds_read_b128 v[108:111], v85 offset:4096
	ds_read_b128 v[112:115], v83 offset:16384
	ds_read_b128 v[116:119], v83 offset:20480
	v_add_u32_e32 v86, v87, v84
	v_add_u32_e32 v84, v121, v84
	v_add_u32_e32 v87, v87, v120
	v_mfma_f32_32x32x16_bf16 v[32:47], v[0:3], v[12:15], 0
	v_add_u32_e32 v81, v121, v120
	s_mov_b32 m0, s83
	v_readfirstlane_b32 s64, v88
	v_readfirstlane_b32 s65, v89
	v_lshl_add_u64 v[88:89], v[78:79], 0, s[88:89]
	s_mul_i32 s81, s81, 0xb0000
	s_mov_b32 s94, 0x1ffffc0
	v_mfma_f32_32x32x16_bf16 v[16:31], v[4:7], v[8:11], 0
	v_mfma_f32_32x32x16_bf16 v[0:15], v[4:7], v[12:15], 0
	s_waitcnt lgkmcnt(0)
	v_mfma_f32_32x32x16_bf16 v[48:63], v[104:107], v[112:115], v[48:63]
	v_mfma_f32_32x32x16_bf16 v[32:47], v[104:107], v[116:119], v[32:47]
	v_mfma_f32_32x32x16_bf16 v[16:31], v[108:111], v[112:115], v[16:31]
	v_mfma_f32_32x32x16_bf16 v[0:15], v[108:111], v[116:119], v[0:15]
	ds_read_b128 v[104:107], v86
	ds_read_b128 v[108:111], v86 offset:4096
	ds_read_b128 v[112:115], v84 offset:16384
	ds_read_b128 v[116:119], v84 offset:20480
	s_waitcnt lgkmcnt(0)
	v_mfma_f32_32x32x16_bf16 v[48:63], v[104:107], v[112:115], v[48:63]
	v_mfma_f32_32x32x16_bf16 v[32:47], v[104:107], v[116:119], v[32:47]
	v_mfma_f32_32x32x16_bf16 v[16:31], v[108:111], v[112:115], v[16:31]
	v_mfma_f32_32x32x16_bf16 v[0:15], v[108:111], v[116:119], v[0:15]
	ds_read_b128 v[104:107], v87
	ds_read_b128 v[108:111], v87 offset:4096
	ds_read_b128 v[112:115], v81 offset:16384
	ds_read_b128 v[116:119], v81 offset:20480
	s_waitcnt vmcnt(0)
	s_waitcnt vmcnt(0) lgkmcnt(0)
	s_barrier
; #define MFMA(a, b, c) __builtin_amdgcn_mfma_f32_32x32x16_bf16(a, b, c, 0, 0, 0)
; #define ISSUE(k0, bf) do { char* A_ = lw + (bf) * BUF; \
;     _Pragma("unroll") for (int i_ = 0; i_ < 4; ++i_) { glds16(al.ptr(lrow + 32 * i_, (k0) + cg), A_ + i_ * 4096); glds16(bl.ptr(lrow + 32 * i_, (k0) + cg), A_ + ABYTES + i_ * 4096); } \
;     if (HALO) { if (wid == 0) glds16(gh + (k0), A_ + 16384); } } while (0)
; template <bool HALO, class AL, class BL>
; __device__ __forceinline__ void gemm_core(f32x16 (&acc)[2][2], f32x16& hacc, const AL& al, const BL& bl, int K, char* lds,
;                                           const u16* halo0, const u16* halo1, int brow0, int brow1) {
;     ...
;   for (int kt = 0; kt < nk; ++kt) {
;     asm volatile("s_waitcnt vmcnt(0)" ::: "memory");
;     __syncthreads();
;     if (kt + 1 < nk) ISSUE((kt + 1) * 64, (kt + 1) & 1);
;     const char* T = lds + (kt & 1) * BUF;
; #pragma unroll
;     for (int kk = 0; kk < 4; ++kk) {
;       const int c = kk * 2 + hi;
;       bf16x8 a0 = *(const bf16x8*)(T + oa + ((c ^ sa) << 4));
;       bf16x8 a1 = *(const bf16x8*)(T + oa + 4096 + ((c ^ sa) << 4));
;       bf16x8 b0 = *(const bf16x8*)(T + ob0 + ((c ^ sb0) << 4));
;       bf16x8 b1 = *(const bf16x8*)(T + ob1 + ((c ^ sb1) << 4));
;       acc[0][0] = MFMA(a0, b0, acc[0][0]); acc[0][1] = MFMA(a0, b1, acc[0][1]);
;       acc[1][0] = MFMA(a1, b0, acc[1][0]); acc[1][1] = MFMA(a1, b1, acc[1][1]);
	v_mfma_f32_32x32x16_bf16 v[48:63], v[104:107], v[112:115], v[48:63]
	v_mfma_f32_32x32x16_bf16 v[32:47], v[104:107], v[116:119], v[32:47]
	v_lshl_add_u64 v[104:105], v[66:67], 0, s[24:25]
	global_load_lds_dwordx4 v[104:105], off
	v_lshl_add_u64 v[104:105], v[64:65], 0, s[24:25]
	s_mov_b32 m0, s42
	s_nop 0
	global_load_lds_dwordx4 v[104:105], off
	v_lshl_add_u64 v[104:105], v[70:71], 0, s[24:25]
	s_mov_b32 m0, s43
	v_mfma_f32_32x32x16_bf16 v[16:31], v[108:111], v[112:115], v[16:31]
	global_load_lds_dwordx4 v[104:105], off
	v_lshl_add_u64 v[104:105], v[68:69], 0, s[24:25]
	s_mov_b32 m0, s70
	s_nop 0
	global_load_lds_dwordx4 v[104:105], off
	v_lshl_add_u64 v[104:105], v[74:75], 0, s[24:25]
	s_mov_b32 m0, s3
	v_mfma_f32_32x32x16_bf16 v[0:15], v[108:111], v[116:119], v[0:15]
	global_load_lds_dwordx4 v[104:105], off
	v_lshl_add_u64 v[104:105], v[72:73], 0, s[24:25]
	s_mov_b32 m0, s6
	s_nop 0
	global_load_lds_dwordx4 v[104:105], off
	v_lshl_add_u64 v[104:105], v[78:79], 0, s[24:25]
	s_mov_b32 m0, s7
	s_nop 0
	global_load_lds_dwordx4 v[104:105], off
	v_lshl_add_u64 v[104:105], v[76:77], 0, s[24:25]
	s_mov_b32 m0, s8
	s_nop 0
	global_load_lds_dwordx4 v[104:105], off
	ds_read_b128 v[104:107], v80 offset:32768
	ds_read_b128 v[108:111], v80 offset:36864
	ds_read_b128 v[112:115], v82 offset:49152
	ds_read_b128 v[116:119], v82 offset:53248
	s_waitcnt lgkmcnt(0)
	v_mfma_f32_32x32x16_bf16 v[48:63], v[104:107], v[112:115], v[48:63]
	s_mov_b32 m0, s18
	v_mfma_f32_32x32x16_bf16 v[32:47], v[104:107], v[116:119], v[32:47]
	v_mfma_f32_32x32x16_bf16 v[16:31], v[108:111], v[112:115], v[16:31]
	v_mfma_f32_32x32x16_bf16 v[0:15], v[108:111], v[116:119], v[0:15]
	ds_read_b128 v[104:107], v85 offset:32768
	ds_read_b128 v[108:111], v85 offset:36864
	ds_read_b128 v[112:115], v83 offset:49152
	ds_read_b128 v[116:119], v83 offset:53248
	s_waitcnt lgkmcnt(0)
	v_mfma_f32_32x32x16_bf16 v[48:63], v[104:107], v[112:115], v[48:63]
	v_mfma_f32_32x32x16_bf16 v[32:47], v[104:107], v[116:119], v[32:47]
	v_mfma_f32_32x32x16_bf16 v[16:31], v[108:111], v[112:115], v[16:31]
	v_mfma_f32_32x32x16_bf16 v[0:15], v[108:111], v[116:119], v[0:15]
	ds_read_b128 v[104:107], v86 offset:32768
	ds_read_b128 v[108:111], v86 offset:36864
	ds_read_b128 v[112:115], v84 offset:49152
	ds_read_b128 v[116:119], v84 offset:53248
	s_waitcnt lgkmcnt(0)
	v_mfma_f32_32x32x16_bf16 v[48:63], v[104:107], v[112:115], v[48:63]
	v_mfma_f32_32x32x16_bf16 v[32:47], v[104:107], v[116:119], v[32:47]
	v_mfma_f32_32x32x16_bf16 v[16:31], v[108:111], v[112:115], v[16:31]
	v_mfma_f32_32x32x16_bf16 v[0:15], v[108:111], v[116:119], v[0:15]
	ds_read_b128 v[104:107], v87 offset:32768
	ds_read_b128 v[108:111], v87 offset:36864
	ds_read_b128 v[112:115], v81 offset:49152
	ds_read_b128 v[116:119], v81 offset:53248
	s_waitcnt vmcnt(0)
	s_waitcnt vmcnt(0) lgkmcnt(0)
	s_barrier
	v_mfma_f32_32x32x16_bf16 v[48:63], v[104:107], v[112:115], v[48:63]
	v_mfma_f32_32x32x16_bf16 v[32:47], v[104:107], v[116:119], v[32:47]
	v_lshl_add_u64 v[104:105], v[66:67], 0, s[74:75]
	global_load_lds_dwordx4 v[104:105], off
	v_lshl_add_u64 v[104:105], v[64:65], 0, s[74:75]
	s_mov_b32 m0, s19
	s_nop 0
	global_load_lds_dwordx4 v[104:105], off
	v_lshl_add_u64 v[104:105], v[70:71], 0, s[74:75]
	s_mov_b32 m0, s33
	v_mfma_f32_32x32x16_bf16 v[16:31], v[108:111], v[112:115], v[16:31]
	global_load_lds_dwordx4 v[104:105], off
	v_lshl_add_u64 v[104:105], v[68:69], 0, s[74:75]
	s_mov_b32 m0, s72
	s_nop 0
	global_load_lds_dwordx4 v[104:105], off
	v_lshl_add_u64 v[104:105], v[74:75], 0, s[74:75]
	s_mov_b32 m0, s73
	v_mfma_f32_32x32x16_bf16 v[0:15], v[108:111], v[116:119], v[0:15]
	global_load_lds_dwordx4 v[104:105], off
	v_lshl_add_u64 v[104:105], v[72:73], 0, s[74:75]
	s_mov_b32 m0, s92
	s_nop 0
	global_load_lds_dwordx4 v[104:105], off
	v_lshl_add_u64 v[104:105], v[78:79], 0, s[74:75]
	s_mov_b32 m0, s69
	s_nop 0
	global_load_lds_dwordx4 v[104:105], off
	v_lshl_add_u64 v[104:105], v[76:77], 0, s[74:75]
	s_mov_b32 m0, s82
	s_nop 0
	global_load_lds_dwordx4 v[104:105], off
	ds_read_b128 v[104:107], v80
	ds_read_b128 v[108:111], v80 offset:4096
	ds_read_b128 v[112:115], v82 offset:16384
	ds_read_b128 v[116:119], v82 offset:20480
	s_waitcnt lgkmcnt(0)
	v_mfma_f32_32x32x16_bf16 v[48:63], v[104:107], v[112:115], v[48:63]
	s_mov_b32 m0, s83
	v_mfma_f32_32x32x16_bf16 v[32:47], v[104:107], v[116:119], v[32:47]
	v_mfma_f32_32x32x16_bf16 v[16:31], v[108:111], v[112:115], v[16:31]
	v_mfma_f32_32x32x16_bf16 v[0:15], v[108:111], v[116:119], v[0:15]
	ds_read_b128 v[104:107], v85
	ds_read_b128 v[108:111], v85 offset:4096
	ds_read_b128 v[112:115], v83 offset:16384
	ds_read_b128 v[116:119], v83 offset:20480
	s_waitcnt lgkmcnt(0)
	v_mfma_f32_32x32x16_bf16 v[48:63], v[104:107], v[112:115], v[48:63]
	v_mfma_f32_32x32x16_bf16 v[32:47], v[104:107], v[116:119], v[32:47]
	v_mfma_f32_32x32x16_bf16 v[16:31], v[108:111], v[112:115], v[16:31]
	v_mfma_f32_32x32x16_bf16 v[0:15], v[108:111], v[116:119], v[0:15]
	ds_read_b128 v[104:107], v86
	ds_read_b128 v[108:111], v86 offset:4096
	ds_read_b128 v[112:115], v84 offset:16384
	ds_read_b128 v[116:119], v84 offset:20480
	s_waitcnt lgkmcnt(0)
	v_mfma_f32_32x32x16_bf16 v[48:63], v[104:107], v[112:115], v[48:63]
	v_mfma_f32_32x32x16_bf16 v[32:47], v[104:107], v[116:119], v[32:47]
	v_mfma_f32_32x32x16_bf16 v[16:31], v[108:111], v[112:115], v[16:31]
	v_mfma_f32_32x32x16_bf16 v[0:15], v[108:111], v[116:119], v[0:15]
	ds_read_b128 v[104:107], v87
	ds_read_b128 v[108:111], v87 offset:4096
	ds_read_b128 v[112:115], v81 offset:16384
	ds_read_b128 v[116:119], v81 offset:20480
	s_waitcnt vmcnt(0)
	s_waitcnt vmcnt(0) lgkmcnt(0)
	s_barrier
; #define MFMA(a, b, c) __builtin_amdgcn_mfma_f32_32x32x16_bf16(a, b, c, 0, 0, 0)
; #define ISSUE(k0, bf) do { char* A_ = lw + (bf) * BUF; \
;     _Pragma("unroll") for (int i_ = 0; i_ < 4; ++i_) { glds16(al.ptr(lrow + 32 * i_, (k0) + cg), A_ + i_ * 4096); glds16(bl.ptr(lrow + 32 * i_, (k0) + cg), A_ + ABYTES + i_ * 4096); } \
;     if (HALO) { if (wid == 0) glds16(gh + (k0), A_ + 16384); } } while (0)
; template <bool HALO, class AL, class BL>
; __device__ __forceinline__ void gemm_core(f32x16 (&acc)[2][2], f32x16& hacc, const AL& al, const BL& bl, int K, char* lds,
;                                           const u16* halo0, const u16* halo1, int brow0, int brow1) {
;     ...
;   for (int kt = 0; kt < nk; ++kt) {
;     asm volatile("s_waitcnt vmcnt(0)" ::: "memory");
;     __syncthreads();
;     if (kt + 1 < nk) ISSUE((kt + 1) * 64, (kt + 1) & 1);
;     const char* T = lds + (kt & 1) * BUF;
; #pragma unroll
;     for (int kk = 0; kk < 4; ++kk) {
;       const int c = kk * 2 + hi;
;       bf16x8 a0 = *(const bf16x8*)(T + oa + ((c ^ sa) << 4));
;       bf16x8 a1 = *(const bf16x8*)(T + oa + 4096 + ((c ^ sa) << 4));
;       bf16x8 b0 = *(const bf16x8*)(T + ob0 + ((c ^ sb0) << 4));
;       bf16x8 b1 = *(const bf16x8*)(T + ob1 + ((c ^ sb1) << 4));
;       acc[0][0] = MFMA(a0, b0, acc[0][0]); acc[0][1] = MFMA(a0, b1, acc[0][1]);
;       acc[1][0] = MFMA(a1, b0, acc[1][0]); acc[1][1] = MFMA(a1, b1, acc[1][1]);
	v_mfma_f32_32x32x16_bf16 v[48:63], v[104:107], v[112:115], v[48:63]
	v_mfma_f32_32x32x16_bf16 v[32:47], v[104:107], v[116:119], v[32:47]
	v_lshl_add_u64 v[104:105], v[66:67], 0, s[20:21]
	global_load_lds_dwordx4 v[104:105], off
	v_lshl_add_u64 v[104:105], v[64:65], 0, s[20:21]
	s_mov_b32 m0, s42
	s_nop 0
	global_load_lds_dwordx4 v[104:105], off
	v_lshl_add_u64 v[104:105], v[70:71], 0, s[20:21]
	s_mov_b32 m0, s43
	v_mfma_f32_32x32x16_bf16 v[16:31], v[108:111], v[112:115], v[16:31]
	global_load_lds_dwordx4 v[104:105], off
	v_lshl_add_u64 v[104:105], v[68:69], 0, s[20:21]
	s_mov_b32 m0, s70
	s_nop 0
	global_load_lds_dwordx4 v[104:105], off
	v_lshl_add_u64 v[104:105], v[74:75], 0, s[20:21]
	s_mov_b32 m0, s3
	v_mfma_f32_32x32x16_bf16 v[0:15], v[108:111], v[116:119], v[0:15]
	global_load_lds_dwordx4 v[104:105], off
	v_lshl_add_u64 v[104:105], v[72:73], 0, s[20:21]
	s_mov_b32 m0, s6
	s_nop 0
	global_load_lds_dwordx4 v[104:105], off
	v_lshl_add_u64 v[104:105], v[78:79], 0, s[20:21]
	s_mov_b32 m0, s7
	s_nop 0
	global_load_lds_dwordx4 v[104:105], off
	v_lshl_add_u64 v[104:105], v[76:77], 0, s[20:21]
	s_mov_b32 m0, s8
	s_nop 0
	global_load_lds_dwordx4 v[104:105], off
	ds_read_b128 v[104:107], v80 offset:32768
	ds_read_b128 v[108:111], v80 offset:36864
	ds_read_b128 v[112:115], v82 offset:49152
	ds_read_b128 v[116:119], v82 offset:53248
	s_waitcnt lgkmcnt(0)
	v_mfma_f32_32x32x16_bf16 v[48:63], v[104:107], v[112:115], v[48:63]
	s_mov_b32 m0, s18
	v_mfma_f32_32x32x16_bf16 v[32:47], v[104:107], v[116:119], v[32:47]
	v_mfma_f32_32x32x16_bf16 v[16:31], v[108:111], v[112:115], v[16:31]
	v_mfma_f32_32x32x16_bf16 v[0:15], v[108:111], v[116:119], v[0:15]
	ds_read_b128 v[104:107], v85 offset:32768
	ds_read_b128 v[108:111], v85 offset:36864
	ds_read_b128 v[112:115], v83 offset:49152
	ds_read_b128 v[116:119], v83 offset:53248
	s_waitcnt lgkmcnt(0)
	v_mfma_f32_32x32x16_bf16 v[48:63], v[104:107], v[112:115], v[48:63]
	v_mfma_f32_32x32x16_bf16 v[32:47], v[104:107], v[116:119], v[32:47]
	v_mfma_f32_32x32x16_bf16 v[16:31], v[108:111], v[112:115], v[16:31]
	v_mfma_f32_32x32x16_bf16 v[0:15], v[108:111], v[116:119], v[0:15]
	ds_read_b128 v[104:107], v86 offset:32768
	ds_read_b128 v[108:111], v86 offset:36864
	ds_read_b128 v[112:115], v84 offset:49152
	ds_read_b128 v[116:119], v84 offset:53248
	s_waitcnt lgkmcnt(0)
	v_mfma_f32_32x32x16_bf16 v[48:63], v[104:107], v[112:115], v[48:63]
	v_mfma_f32_32x32x16_bf16 v[32:47], v[104:107], v[116:119], v[32:47]
	v_mfma_f32_32x32x16_bf16 v[16:31], v[108:111], v[112:115], v[16:31]
	v_mfma_f32_32x32x16_bf16 v[0:15], v[108:111], v[116:119], v[0:15]
	ds_read_b128 v[104:107], v87 offset:32768
	ds_read_b128 v[108:111], v87 offset:36864
	ds_read_b128 v[112:115], v81 offset:49152
	ds_read_b128 v[116:119], v81 offset:53248
	s_waitcnt vmcnt(0)
	s_waitcnt vmcnt(0) lgkmcnt(0)
	s_barrier
	v_mfma_f32_32x32x16_bf16 v[48:63], v[104:107], v[112:115], v[48:63]
	v_mfma_f32_32x32x16_bf16 v[32:47], v[104:107], v[116:119], v[32:47]
	v_lshl_add_u64 v[104:105], v[66:67], 0, s[86:87]
	global_load_lds_dwordx4 v[104:105], off
	v_lshl_add_u64 v[104:105], v[64:65], 0, s[86:87]
	s_mov_b32 m0, s19
	s_nop 0
	global_load_lds_dwordx4 v[104:105], off
	v_lshl_add_u64 v[104:105], v[70:71], 0, s[86:87]
	s_mov_b32 m0, s33
	v_mfma_f32_32x32x16_bf16 v[16:31], v[108:111], v[112:115], v[16:31]
	global_load_lds_dwordx4 v[104:105], off
	v_lshl_add_u64 v[104:105], v[68:69], 0, s[86:87]
	s_mov_b32 m0, s72
	s_nop 0
	global_load_lds_dwordx4 v[104:105], off
	v_lshl_add_u64 v[104:105], v[74:75], 0, s[86:87]
	s_mov_b32 m0, s73
	v_mfma_f32_32x32x16_bf16 v[0:15], v[108:111], v[116:119], v[0:15]
	global_load_lds_dwordx4 v[104:105], off
	v_lshl_add_u64 v[104:105], v[72:73], 0, s[86:87]
	s_mov_b32 m0, s92
	s_nop 0
	global_load_lds_dwordx4 v[104:105], off
	v_lshl_add_u64 v[104:105], v[78:79], 0, s[86:87]
	s_mov_b32 m0, s69
	s_nop 0
	global_load_lds_dwordx4 v[104:105], off
	v_lshl_add_u64 v[104:105], v[76:77], 0, s[86:87]
	s_mov_b32 m0, s82
	s_nop 0
	global_load_lds_dwordx4 v[104:105], off
	ds_read_b128 v[104:107], v80
	ds_read_b128 v[108:111], v80 offset:4096
	ds_read_b128 v[112:115], v82 offset:16384
	ds_read_b128 v[116:119], v82 offset:20480
	s_waitcnt lgkmcnt(0)
	v_mfma_f32_32x32x16_bf16 v[48:63], v[104:107], v[112:115], v[48:63]
	s_mov_b32 m0, s83
	v_mfma_f32_32x32x16_bf16 v[32:47], v[104:107], v[116:119], v[32:47]
	v_mfma_f32_32x32x16_bf16 v[16:31], v[108:111], v[112:115], v[16:31]
	v_mfma_f32_32x32x16_bf16 v[0:15], v[108:111], v[116:119], v[0:15]
	ds_read_b128 v[104:107], v85
	ds_read_b128 v[108:111], v85 offset:4096
	ds_read_b128 v[112:115], v83 offset:16384
	ds_read_b128 v[116:119], v83 offset:20480
	s_waitcnt lgkmcnt(0)
	v_mfma_f32_32x32x16_bf16 v[48:63], v[104:107], v[112:115], v[48:63]
	v_mfma_f32_32x32x16_bf16 v[32:47], v[104:107], v[116:119], v[32:47]
	v_mfma_f32_32x32x16_bf16 v[16:31], v[108:111], v[112:115], v[16:31]
	v_mfma_f32_32x32x16_bf16 v[0:15], v[108:111], v[116:119], v[0:15]
	ds_read_b128 v[104:107], v86
	ds_read_b128 v[108:111], v86 offset:4096
	ds_read_b128 v[112:115], v84 offset:16384
	ds_read_b128 v[116:119], v84 offset:20480
	s_waitcnt lgkmcnt(0)
	v_mfma_f32_32x32x16_bf16 v[48:63], v[104:107], v[112:115], v[48:63]
	v_mfma_f32_32x32x16_bf16 v[32:47], v[104:107], v[116:119], v[32:47]
	v_mfma_f32_32x32x16_bf16 v[16:31], v[108:111], v[112:115], v[16:31]
	v_mfma_f32_32x32x16_bf16 v[0:15], v[108:111], v[116:119], v[0:15]
	ds_read_b128 v[104:107], v87
	ds_read_b128 v[108:111], v87 offset:4096
	ds_read_b128 v[112:115], v81 offset:16384
	ds_read_b128 v[116:119], v81 offset:20480
	s_waitcnt vmcnt(0)
	s_waitcnt vmcnt(0) lgkmcnt(0)
	s_barrier
; #define MFMA(a, b, c) __builtin_amdgcn_mfma_f32_32x32x16_bf16(a, b, c, 0, 0, 0)
; #define ISSUE(k0, bf) do { char* A_ = lw + (bf) * BUF; \
;     _Pragma("unroll") for (int i_ = 0; i_ < 4; ++i_) { glds16(al.ptr(lrow + 32 * i_, (k0) + cg), A_ + i_ * 4096); glds16(bl.ptr(lrow + 32 * i_, (k0) + cg), A_ + ABYTES + i_ * 4096); } \
;     if (HALO) { if (wid == 0) glds16(gh + (k0), A_ + 16384); } } while (0)
; template <bool HALO, class AL, class BL>
; __device__ __forceinline__ void gemm_core(f32x16 (&acc)[2][2], f32x16& hacc, const AL& al, const BL& bl, int K, char* lds,
;                                           const u16* halo0, const u16* halo1, int brow0, int brow1) {
;     ...
;   for (int kt = 0; kt < nk; ++kt) {
;     asm volatile("s_waitcnt vmcnt(0)" ::: "memory");
;     __syncthreads();
;     if (kt + 1 < nk) ISSUE((kt + 1) * 64, (kt + 1) & 1);
;     const char* T = lds + (kt & 1) * BUF;
; #pragma unroll
;     for (int kk = 0; kk < 4; ++kk) {
;       const int c = kk * 2 + hi;
;       bf16x8 a0 = *(const bf16x8*)(T + oa + ((c ^ sa) << 4));
;       bf16x8 a1 = *(const bf16x8*)(T + oa + 4096 + ((c ^ sa) << 4));
;       bf16x8 b0 = *(const bf16x8*)(T + ob0 + ((c ^ sb0) << 4));
;       bf16x8 b1 = *(const bf16x8*)(T + ob1 + ((c ^ sb1) << 4));
;       acc[0][0] = MFMA(a0, b0, acc[0][0]); acc[0][1] = MFMA(a0, b1, acc[0][1]);
;       acc[1][0] = MFMA(a1, b0, acc[1][0]); acc[1][1] = MFMA(a1, b1, acc[1][1]);
	v_mfma_f32_32x32x16_bf16 v[48:63], v[104:107], v[112:115], v[48:63]
	v_mfma_f32_32x32x16_bf16 v[32:47], v[104:107], v[116:119], v[32:47]
	v_lshl_add_u64 v[104:105], v[66:67], 0, s[30:31]
	global_load_lds_dwordx4 v[104:105], off
	v_lshl_add_u64 v[104:105], v[64:65], 0, s[30:31]
	s_mov_b32 m0, s42
	v_readfirstlane_b32 s42, v90
	global_load_lds_dwordx4 v[104:105], off
	v_lshl_add_u64 v[104:105], v[70:71], 0, s[30:31]
	s_mov_b32 m0, s43
	v_mfma_f32_32x32x16_bf16 v[16:31], v[108:111], v[112:115], v[16:31]
	global_load_lds_dwordx4 v[104:105], off
	v_lshl_add_u64 v[104:105], v[68:69], 0, s[30:31]
	s_mov_b32 m0, s70
	v_readfirstlane_b32 s43, v91
	global_load_lds_dwordx4 v[104:105], off
	v_lshl_add_u64 v[104:105], v[74:75], 0, s[30:31]
	s_mov_b32 m0, s3
	v_mfma_f32_32x32x16_bf16 v[0:15], v[108:111], v[116:119], v[0:15]
	global_load_lds_dwordx4 v[104:105], off
	v_lshl_add_u64 v[104:105], v[72:73], 0, s[30:31]
	s_mov_b32 m0, s6
	s_nop 0
	global_load_lds_dwordx4 v[104:105], off
	v_lshl_add_u64 v[104:105], v[78:79], 0, s[30:31]
	s_mov_b32 m0, s7
	s_nop 0
	global_load_lds_dwordx4 v[104:105], off
	v_lshl_add_u64 v[104:105], v[76:77], 0, s[30:31]
	s_mov_b32 m0, s8
	s_nop 0
	global_load_lds_dwordx4 v[104:105], off
	ds_read_b128 v[104:107], v80 offset:32768
	ds_read_b128 v[108:111], v80 offset:36864
	ds_read_b128 v[112:115], v82 offset:49152
	ds_read_b128 v[116:119], v82 offset:53248
	s_waitcnt lgkmcnt(0)
	v_mfma_f32_32x32x16_bf16 v[48:63], v[104:107], v[112:115], v[48:63]
	s_mov_b32 m0, s18
	v_readfirstlane_b32 s18, v94
	v_mfma_f32_32x32x16_bf16 v[32:47], v[104:107], v[116:119], v[32:47]
	v_mfma_f32_32x32x16_bf16 v[16:31], v[108:111], v[112:115], v[16:31]
	v_mfma_f32_32x32x16_bf16 v[0:15], v[108:111], v[116:119], v[0:15]
	ds_read_b128 v[104:107], v85 offset:32768
	ds_read_b128 v[108:111], v85 offset:36864
	ds_read_b128 v[112:115], v83 offset:49152
	ds_read_b128 v[116:119], v83 offset:53248
	s_waitcnt lgkmcnt(0)
	v_mfma_f32_32x32x16_bf16 v[48:63], v[104:107], v[112:115], v[48:63]
	v_mfma_f32_32x32x16_bf16 v[32:47], v[104:107], v[116:119], v[32:47]
	v_mfma_f32_32x32x16_bf16 v[16:31], v[108:111], v[112:115], v[16:31]
	v_mfma_f32_32x32x16_bf16 v[0:15], v[108:111], v[116:119], v[0:15]
	ds_read_b128 v[104:107], v86 offset:32768
	ds_read_b128 v[108:111], v86 offset:36864
	ds_read_b128 v[112:115], v84 offset:49152
	ds_read_b128 v[116:119], v84 offset:53248
	s_waitcnt lgkmcnt(0)
	v_mfma_f32_32x32x16_bf16 v[48:63], v[104:107], v[112:115], v[48:63]
	v_mfma_f32_32x32x16_bf16 v[32:47], v[104:107], v[116:119], v[32:47]
	v_mfma_f32_32x32x16_bf16 v[16:31], v[108:111], v[112:115], v[16:31]
	v_mfma_f32_32x32x16_bf16 v[0:15], v[108:111], v[116:119], v[0:15]
	ds_read_b128 v[104:107], v87 offset:32768
	ds_read_b128 v[108:111], v87 offset:36864
	ds_read_b128 v[112:115], v81 offset:49152
	ds_read_b128 v[116:119], v81 offset:53248
	s_waitcnt vmcnt(0)
	s_waitcnt vmcnt(0) lgkmcnt(0)
	s_barrier
	v_mfma_f32_32x32x16_bf16 v[48:63], v[104:107], v[112:115], v[48:63]
	v_mfma_f32_32x32x16_bf16 v[32:47], v[104:107], v[116:119], v[32:47]
	v_lshl_add_u64 v[104:105], v[66:67], 0, s[4:5]
	global_load_lds_dwordx4 v[104:105], off
	v_lshl_add_u64 v[104:105], v[64:65], 0, s[4:5]
	s_mov_b32 m0, s19
	v_readfirstlane_b32 s19, v95
	global_load_lds_dwordx4 v[104:105], off
	v_lshl_add_u64 v[104:105], v[70:71], 0, s[4:5]
	s_mov_b32 m0, s33
	v_mfma_f32_32x32x16_bf16 v[16:31], v[108:111], v[112:115], v[16:31]
	global_load_lds_dwordx4 v[104:105], off
	v_lshl_add_u64 v[104:105], v[68:69], 0, s[4:5]
	s_mov_b32 m0, s72
	v_readfirstlane_b32 s33, v93
	global_load_lds_dwordx4 v[104:105], off
	v_lshl_add_u64 v[104:105], v[74:75], 0, s[4:5]
	s_mov_b32 m0, s73
	v_mfma_f32_32x32x16_bf16 v[0:15], v[108:111], v[116:119], v[0:15]
	global_load_lds_dwordx4 v[104:105], off
	v_lshl_add_u64 v[104:105], v[72:73], 0, s[4:5]
	s_mov_b32 m0, s92
	v_readfirstlane_b32 s92, v101
	global_load_lds_dwordx4 v[104:105], off
	v_lshl_add_u64 v[104:105], v[78:79], 0, s[4:5]
	s_mov_b32 m0, s69
	v_readfirstlane_b32 s69, v102
	global_load_lds_dwordx4 v[104:105], off
	v_lshl_add_u64 v[104:105], v[76:77], 0, s[4:5]
	s_mov_b32 m0, s82
	v_readfirstlane_b32 s82, v96
	global_load_lds_dwordx4 v[104:105], off
	ds_read_b128 v[104:107], v80
	ds_read_b128 v[108:111], v80 offset:4096
	ds_read_b128 v[112:115], v82 offset:16384
	ds_read_b128 v[116:119], v82 offset:20480
	s_waitcnt lgkmcnt(0)
	v_mfma_f32_32x32x16_bf16 v[48:63], v[104:107], v[112:115], v[48:63]
	s_mov_b32 m0, s82
	v_readfirstlane_b32 s73, v103
	v_lshl_add_u64 v[102:103], v[74:75], 0, s[66:67]
	v_readfirstlane_b32 s72, v92
	v_lshl_add_u64 v[92:93], v[70:71], 0, s[26:27]
	v_mfma_f32_32x32x16_bf16 v[32:47], v[104:107], v[116:119], v[32:47]
	v_mfma_f32_32x32x16_bf16 v[16:31], v[108:111], v[112:115], v[16:31]
	v_mfma_f32_32x32x16_bf16 v[0:15], v[108:111], v[116:119], v[0:15]
	ds_read_b128 v[104:107], v85
	ds_read_b128 v[108:111], v85 offset:4096
	ds_read_b128 v[112:115], v83 offset:16384
	ds_read_b128 v[116:119], v83 offset:20480
	s_waitcnt lgkmcnt(0)
	v_mfma_f32_32x32x16_bf16 v[48:63], v[104:107], v[112:115], v[48:63]
	v_mfma_f32_32x32x16_bf16 v[32:47], v[104:107], v[116:119], v[32:47]
	v_mfma_f32_32x32x16_bf16 v[16:31], v[108:111], v[112:115], v[16:31]
	v_mfma_f32_32x32x16_bf16 v[0:15], v[108:111], v[116:119], v[0:15]
	ds_read_b128 v[104:107], v86
	ds_read_b128 v[108:111], v86 offset:4096
	ds_read_b128 v[112:115], v84 offset:16384
	ds_read_b128 v[116:119], v84 offset:20480
	s_waitcnt lgkmcnt(0)
	v_mfma_f32_32x32x16_bf16 v[48:63], v[104:107], v[112:115], v[48:63]
	v_mfma_f32_32x32x16_bf16 v[32:47], v[104:107], v[116:119], v[32:47]
	v_mfma_f32_32x32x16_bf16 v[16:31], v[108:111], v[112:115], v[16:31]
	v_mfma_f32_32x32x16_bf16 v[0:15], v[108:111], v[116:119], v[0:15]
	ds_read_b128 v[104:107], v87
	ds_read_b128 v[108:111], v87 offset:4096
	ds_read_b128 v[112:115], v81 offset:16384
	ds_read_b128 v[116:119], v81 offset:20480
	s_waitcnt vmcnt(0)
	s_waitcnt vmcnt(0) lgkmcnt(0)
	s_barrier
; #define MFMA(a, b, c) __builtin_amdgcn_mfma_f32_32x32x16_bf16(a, b, c, 0, 0, 0)
; #define ISSUE(k0, bf) do { char* A_ = lw + (bf) * BUF; \
;     _Pragma("unroll") for (int i_ = 0; i_ < 4; ++i_) { glds16(al.ptr(lrow + 32 * i_, (k0) + cg), A_ + i_ * 4096); glds16(bl.ptr(lrow + 32 * i_, (k0) + cg), A_ + ABYTES + i_ * 4096); } \
;     if (HALO) { if (wid == 0) glds16(gh + (k0), A_ + 16384); } } while (0)
; template <bool HALO, class AL, class BL>
; __device__ __forceinline__ void gemm_core(f32x16 (&acc)[2][2], f32x16& hacc, const AL& al, const BL& bl, int K, char* lds,
;                                           const u16* halo0, const u16* halo1, int brow0, int brow1) {
;     ...
;   for (int kt = 0; kt < nk; ++kt) {
;     asm volatile("s_waitcnt vmcnt(0)" ::: "memory");
;     __syncthreads();
;     if (kt + 1 < nk) ISSUE((kt + 1) * 64, (kt + 1) & 1);
;     const char* T = lds + (kt & 1) * BUF;
; #pragma unroll
;     for (int kk = 0; kk < 4; ++kk) {
;       const int c = kk * 2 + hi;
;       bf16x8 a0 = *(const bf16x8*)(T + oa + ((c ^ sa) << 4));
;       bf16x8 a1 = *(const bf16x8*)(T + oa + 4096 + ((c ^ sa) << 4));
;       bf16x8 b0 = *(const bf16x8*)(T + ob0 + ((c ^ sb0) << 4));
;       bf16x8 b1 = *(const bf16x8*)(T + ob1 + ((c ^ sb1) << 4));
;       acc[0][0] = MFMA(a0, b0, acc[0][0]); acc[0][1] = MFMA(a0, b1, acc[0][1]);
;       acc[1][0] = MFMA(a1, b0, acc[1][0]); acc[1][1] = MFMA(a1, b1, acc[1][1]);
	v_mfma_f32_32x32x16_bf16 v[48:63], v[104:107], v[112:115], v[48:63]
	v_mfma_f32_32x32x16_bf16 v[32:47], v[104:107], v[116:119], v[32:47]
	v_lshl_add_u64 v[104:105], v[66:67], 0, s[66:67]
	global_load_lds_dwordx4 v[104:105], off
	v_lshl_add_u64 v[104:105], v[64:65], 0, s[66:67]
	s_mov_b32 m0, s92
	s_nop 0
	global_load_lds_dwordx4 v[104:105], off
	v_lshl_add_u64 v[104:105], v[70:71], 0, s[66:67]
	s_mov_b32 m0, s69
	v_mfma_f32_32x32x16_bf16 v[16:31], v[108:111], v[112:115], v[16:31]
	global_load_lds_dwordx4 v[104:105], off
	v_lshl_add_u64 v[104:105], v[68:69], 0, s[66:67]
	s_mov_b32 m0, s73
	s_nop 0
	global_load_lds_dwordx4 v[104:105], off
	s_mov_b32 m0, s3
	v_mfma_f32_32x32x16_bf16 v[0:15], v[108:111], v[116:119], v[0:15]
	global_load_lds_dwordx4 v[102:103], off
	v_lshl_add_u64 v[102:103], v[72:73], 0, s[66:67]
	s_mov_b32 m0, s6
	v_readfirstlane_b32 s3, v99
	global_load_lds_dwordx4 v[102:103], off
	v_lshl_add_u64 v[102:103], v[78:79], 0, s[66:67]
	s_mov_b32 m0, s7
	v_readfirstlane_b32 s7, v97
	global_load_lds_dwordx4 v[102:103], off
	v_lshl_add_u64 v[102:103], v[76:77], 0, s[66:67]
	s_mov_b32 m0, s8
	v_readfirstlane_b32 s8, v98
	global_load_lds_dwordx4 v[102:103], off
	ds_read_b128 v[102:105], v80 offset:32768
	ds_read_b128 v[106:109], v80 offset:36864
	ds_read_b128 v[110:113], v82 offset:49152
	ds_read_b128 v[114:117], v82 offset:53248
	s_waitcnt lgkmcnt(0)
	v_mfma_f32_32x32x16_bf16 v[48:63], v[102:105], v[110:113], v[48:63]
	s_mov_b32 m0, s33
	v_readfirstlane_b32 s6, v100
	v_mfma_f32_32x32x16_bf16 v[32:47], v[102:105], v[114:117], v[32:47]
	v_mfma_f32_32x32x16_bf16 v[16:31], v[106:109], v[110:113], v[16:31]
	v_mfma_f32_32x32x16_bf16 v[0:15], v[106:109], v[114:117], v[0:15]
	ds_read_b128 v[102:105], v85 offset:32768
	ds_read_b128 v[106:109], v85 offset:36864
	ds_read_b128 v[110:113], v83 offset:49152
	ds_read_b128 v[114:117], v83 offset:53248
	s_waitcnt lgkmcnt(0)
	v_mfma_f32_32x32x16_bf16 v[48:63], v[102:105], v[110:113], v[48:63]
	v_mfma_f32_32x32x16_bf16 v[32:47], v[102:105], v[114:117], v[32:47]
	v_mfma_f32_32x32x16_bf16 v[16:31], v[106:109], v[110:113], v[16:31]
	v_mfma_f32_32x32x16_bf16 v[0:15], v[106:109], v[114:117], v[0:15]
	ds_read_b128 v[102:105], v86 offset:32768
	ds_read_b128 v[106:109], v86 offset:36864
	ds_read_b128 v[110:113], v84 offset:49152
	ds_read_b128 v[114:117], v84 offset:53248
	s_waitcnt lgkmcnt(0)
	v_mfma_f32_32x32x16_bf16 v[48:63], v[102:105], v[110:113], v[48:63]
	v_mfma_f32_32x32x16_bf16 v[32:47], v[102:105], v[114:117], v[32:47]
	v_mfma_f32_32x32x16_bf16 v[16:31], v[106:109], v[110:113], v[16:31]
	v_mfma_f32_32x32x16_bf16 v[0:15], v[106:109], v[114:117], v[0:15]
	ds_read_b128 v[102:105], v87 offset:32768
	ds_read_b128 v[106:109], v87 offset:36864
	ds_read_b128 v[110:113], v81 offset:49152
	ds_read_b128 v[114:117], v81 offset:53248
	s_waitcnt vmcnt(0)
	s_waitcnt vmcnt(0) lgkmcnt(0)
	s_barrier
	v_mfma_f32_32x32x16_bf16 v[48:63], v[102:105], v[110:113], v[48:63]
	v_mfma_f32_32x32x16_bf16 v[32:47], v[102:105], v[114:117], v[32:47]
	v_lshl_add_u64 v[102:103], v[66:67], 0, s[26:27]
	global_load_lds_dwordx4 v[102:103], off
	v_lshl_add_u64 v[102:103], v[64:65], 0, s[26:27]
	s_mov_b32 m0, s72
	s_nop 0
	global_load_lds_dwordx4 v[102:103], off
	s_mov_b32 m0, s18
	v_mfma_f32_32x32x16_bf16 v[16:31], v[106:109], v[110:113], v[16:31]
	global_load_lds_dwordx4 v[92:93], off
	v_lshl_add_u64 v[92:93], v[68:69], 0, s[26:27]
	s_mov_b32 m0, s19
	s_nop 0
	global_load_lds_dwordx4 v[92:93], off
	v_lshl_add_u64 v[92:93], v[74:75], 0, s[26:27]
	s_mov_b32 m0, s7
	v_mfma_f32_32x32x16_bf16 v[0:15], v[106:109], v[114:117], v[0:15]
	global_load_lds_dwordx4 v[92:93], off
	v_lshl_add_u64 v[92:93], v[72:73], 0, s[26:27]
	s_mov_b32 m0, s8
	s_nop 0
	global_load_lds_dwordx4 v[92:93], off
	v_lshl_add_u64 v[92:93], v[78:79], 0, s[26:27]
	s_mov_b32 m0, s3
	s_nop 0
	global_load_lds_dwordx4 v[92:93], off
	v_lshl_add_u64 v[92:93], v[76:77], 0, s[26:27]
	s_mov_b32 m0, s6
	s_nop 0
	global_load_lds_dwordx4 v[92:93], off
	ds_read_b128 v[92:95], v80
	ds_read_b128 v[96:99], v80 offset:4096
	ds_read_b128 v[100:103], v82 offset:16384
	ds_read_b128 v[104:107], v82 offset:20480
	s_waitcnt lgkmcnt(0)
	v_mfma_f32_32x32x16_bf16 v[48:63], v[92:95], v[100:103], v[48:63]
	s_mov_b32 m0, s82
	v_mfma_f32_32x32x16_bf16 v[32:47], v[92:95], v[104:107], v[32:47]
	v_mfma_f32_32x32x16_bf16 v[16:31], v[96:99], v[100:103], v[16:31]
	v_mfma_f32_32x32x16_bf16 v[0:15], v[96:99], v[104:107], v[0:15]
	ds_read_b128 v[92:95], v85
	ds_read_b128 v[96:99], v85 offset:4096
	ds_read_b128 v[100:103], v83 offset:16384
	ds_read_b128 v[104:107], v83 offset:20480
	s_waitcnt lgkmcnt(0)
	v_mfma_f32_32x32x16_bf16 v[48:63], v[92:95], v[100:103], v[48:63]
	v_mfma_f32_32x32x16_bf16 v[32:47], v[92:95], v[104:107], v[32:47]
	v_mfma_f32_32x32x16_bf16 v[16:31], v[96:99], v[100:103], v[16:31]
	v_mfma_f32_32x32x16_bf16 v[0:15], v[96:99], v[104:107], v[0:15]
	ds_read_b128 v[92:95], v86
	ds_read_b128 v[96:99], v86 offset:4096
	ds_read_b128 v[100:103], v84 offset:16384
	ds_read_b128 v[104:107], v84 offset:20480
	s_waitcnt lgkmcnt(0)
	v_mfma_f32_32x32x16_bf16 v[48:63], v[92:95], v[100:103], v[48:63]
	v_mfma_f32_32x32x16_bf16 v[32:47], v[92:95], v[104:107], v[32:47]
	v_mfma_f32_32x32x16_bf16 v[16:31], v[96:99], v[100:103], v[16:31]
	v_mfma_f32_32x32x16_bf16 v[0:15], v[96:99], v[104:107], v[0:15]
	ds_read_b128 v[92:95], v87
	ds_read_b128 v[96:99], v87 offset:4096
	ds_read_b128 v[100:103], v81 offset:16384
	ds_read_b128 v[104:107], v81 offset:20480
	s_waitcnt vmcnt(0)
	s_waitcnt vmcnt(0) lgkmcnt(0)
	s_barrier
; #define MFMA(a, b, c) __builtin_amdgcn_mfma_f32_32x32x16_bf16(a, b, c, 0, 0, 0)
; #define ISSUE(k0, bf) do { char* A_ = lw + (bf) * BUF; \
;     _Pragma("unroll") for (int i_ = 0; i_ < 4; ++i_) { glds16(al.ptr(lrow + 32 * i_, (k0) + cg), A_ + i_ * 4096); glds16(bl.ptr(lrow + 32 * i_, (k0) + cg), A_ + ABYTES + i_ * 4096); } \
;     if (HALO) { if (wid == 0) glds16(gh + (k0), A_ + 16384); } } while (0)
; template <bool HALO, class AL, class BL>
; __device__ __forceinline__ void gemm_core(f32x16 (&acc)[2][2], f32x16& hacc, const AL& al, const BL& bl, int K, char* lds,
;                                           const u16* halo0, const u16* halo1, int brow0, int brow1) {
;     ...
;   for (int kt = 0; kt < nk; ++kt) {
;     asm volatile("s_waitcnt vmcnt(0)" ::: "memory");
;     __syncthreads();
;     if (kt + 1 < nk) ISSUE((kt + 1) * 64, (kt + 1) & 1);
;     const char* T = lds + (kt & 1) * BUF;
; #pragma unroll
;     for (int kk = 0; kk < 4; ++kk) {
;       const int c = kk * 2 + hi;
;       bf16x8 a0 = *(const bf16x8*)(T + oa + ((c ^ sa) << 4));
;       bf16x8 a1 = *(const bf16x8*)(T + oa + 4096 + ((c ^ sa) << 4));
;       bf16x8 b0 = *(const bf16x8*)(T + ob0 + ((c ^ sb0) << 4));
;       bf16x8 b1 = *(const bf16x8*)(T + ob1 + ((c ^ sb1) << 4));
;       acc[0][0] = MFMA(a0, b0, acc[0][0]); acc[0][1] = MFMA(a0, b1, acc[0][1]);
;       acc[1][0] = MFMA(a1, b0, acc[1][0]); acc[1][1] = MFMA(a1, b1, acc[1][1]);
	v_mfma_f32_32x32x16_bf16 v[48:63], v[92:95], v[100:103], v[48:63]
	v_mfma_f32_32x32x16_bf16 v[32:47], v[92:95], v[104:107], v[32:47]
	v_lshl_add_u64 v[92:93], v[66:67], 0, s[88:89]
	global_load_lds_dwordx4 v[92:93], off
	v_lshl_add_u64 v[92:93], v[64:65], 0, s[88:89]
	s_mov_b32 m0, s92
	s_nop 0
	global_load_lds_dwordx4 v[92:93], off
	v_lshl_add_u64 v[92:93], v[70:71], 0, s[88:89]
	s_mov_b32 m0, s69
	v_mfma_f32_32x32x16_bf16 v[16:31], v[96:99], v[100:103], v[16:31]
	global_load_lds_dwordx4 v[92:93], off
	v_lshl_add_u64 v[92:93], v[68:69], 0, s[88:89]
	s_mov_b32 m0, s73
	s_nop 0
	global_load_lds_dwordx4 v[92:93], off
	v_lshl_add_u64 v[92:93], v[74:75], 0, s[88:89]
	s_mov_b32 m0, s64
	v_mfma_f32_32x32x16_bf16 v[0:15], v[96:99], v[104:107], v[0:15]
	global_load_lds_dwordx4 v[92:93], off
	v_lshl_add_u64 v[92:93], v[72:73], 0, s[88:89]
	s_mov_b32 m0, s65
	s_nop 0
	global_load_lds_dwordx4 v[92:93], off
	s_mov_b32 m0, s42
	s_nop 0
	global_load_lds_dwordx4 v[88:89], off
	v_lshl_add_u64 v[88:89], v[76:77], 0, s[88:89]
	s_mov_b32 m0, s43
	s_nop 0
	global_load_lds_dwordx4 v[88:89], off
	ds_read_b128 v[88:91], v80 offset:32768
	ds_read_b128 v[92:95], v80 offset:36864
	ds_read_b128 v[96:99], v82 offset:49152
	ds_read_b128 v[100:103], v82 offset:53248
	s_waitcnt lgkmcnt(0)
	v_mfma_f32_32x32x16_bf16 v[48:63], v[88:91], v[96:99], v[48:63]
	s_mov_b32 m0, s33
	v_mfma_f32_32x32x16_bf16 v[32:47], v[88:91], v[100:103], v[32:47]
	v_mfma_f32_32x32x16_bf16 v[16:31], v[92:95], v[96:99], v[16:31]
	v_mfma_f32_32x32x16_bf16 v[0:15], v[92:95], v[100:103], v[0:15]
	ds_read_b128 v[88:91], v85 offset:32768
	ds_read_b128 v[92:95], v85 offset:36864
	ds_read_b128 v[96:99], v83 offset:49152
	ds_read_b128 v[100:103], v83 offset:53248
	s_waitcnt lgkmcnt(0)
	v_mfma_f32_32x32x16_bf16 v[48:63], v[88:91], v[96:99], v[48:63]
	v_mfma_f32_32x32x16_bf16 v[32:47], v[88:91], v[100:103], v[32:47]
	v_mfma_f32_32x32x16_bf16 v[16:31], v[92:95], v[96:99], v[16:31]
	v_mfma_f32_32x32x16_bf16 v[0:15], v[92:95], v[100:103], v[0:15]
	ds_read_b128 v[88:91], v86 offset:32768
	ds_read_b128 v[92:95], v86 offset:36864
	ds_read_b128 v[96:99], v84 offset:49152
	ds_read_b128 v[100:103], v84 offset:53248
	s_waitcnt lgkmcnt(0)
	v_mfma_f32_32x32x16_bf16 v[48:63], v[88:91], v[96:99], v[48:63]
	v_mfma_f32_32x32x16_bf16 v[32:47], v[88:91], v[100:103], v[32:47]
	v_mfma_f32_32x32x16_bf16 v[16:31], v[92:95], v[96:99], v[16:31]
	v_mfma_f32_32x32x16_bf16 v[0:15], v[92:95], v[100:103], v[0:15]
	ds_read_b128 v[88:91], v87 offset:32768
	ds_read_b128 v[92:95], v87 offset:36864
	ds_read_b128 v[96:99], v81 offset:49152
	ds_read_b128 v[100:103], v81 offset:53248
	s_waitcnt vmcnt(0)
	s_waitcnt vmcnt(0) lgkmcnt(0)
	s_barrier
	v_mfma_f32_32x32x16_bf16 v[48:63], v[88:91], v[96:99], v[48:63]
	v_mfma_f32_32x32x16_bf16 v[32:47], v[88:91], v[100:103], v[32:47]
	v_lshl_add_u64 v[88:89], v[66:67], 0, s[22:23]
	global_load_lds_dwordx4 v[88:89], off
	v_lshl_add_u64 v[88:89], v[64:65], 0, s[22:23]
	s_mov_b32 m0, s72
	s_nop 0
	global_load_lds_dwordx4 v[88:89], off
	v_lshl_add_u64 v[88:89], v[70:71], 0, s[22:23]
	s_mov_b32 m0, s18
	v_mfma_f32_32x32x16_bf16 v[16:31], v[92:95], v[96:99], v[16:31]
	global_load_lds_dwordx4 v[88:89], off
	v_lshl_add_u64 v[88:89], v[68:69], 0, s[22:23]
	s_mov_b32 m0, s19
	s_nop 0
	global_load_lds_dwordx4 v[88:89], off
	v_lshl_add_u64 v[88:89], v[74:75], 0, s[22:23]
	s_mov_b32 m0, s7
	v_mfma_f32_32x32x16_bf16 v[0:15], v[92:95], v[100:103], v[0:15]
	global_load_lds_dwordx4 v[88:89], off
	v_lshl_add_u64 v[88:89], v[72:73], 0, s[22:23]
	s_mov_b32 m0, s8
	s_nop 0
	global_load_lds_dwordx4 v[88:89], off
	v_lshl_add_u64 v[88:89], v[78:79], 0, s[22:23]
	s_mov_b32 m0, s3
	s_nop 0
	global_load_lds_dwordx4 v[88:89], off
	v_lshl_add_u64 v[88:89], v[76:77], 0, s[22:23]
	s_mov_b32 m0, s6
	s_nop 0
	global_load_lds_dwordx4 v[88:89], off
	ds_read_b128 v[88:91], v80
	ds_read_b128 v[92:95], v80 offset:4096
	ds_read_b128 v[96:99], v82 offset:16384
	ds_read_b128 v[100:103], v82 offset:20480
	s_waitcnt lgkmcnt(0)
	v_mfma_f32_32x32x16_bf16 v[48:63], v[88:91], v[96:99], v[48:63]
	s_mov_b32 m0, s82
	v_mfma_f32_32x32x16_bf16 v[32:47], v[88:91], v[100:103], v[32:47]
	v_mfma_f32_32x32x16_bf16 v[16:31], v[92:95], v[96:99], v[16:31]
	v_mfma_f32_32x32x16_bf16 v[0:15], v[92:95], v[100:103], v[0:15]
	ds_read_b128 v[88:91], v85
	ds_read_b128 v[92:95], v85 offset:4096
	ds_read_b128 v[96:99], v83 offset:16384
	ds_read_b128 v[100:103], v83 offset:20480
	s_waitcnt lgkmcnt(0)
	v_mfma_f32_32x32x16_bf16 v[48:63], v[88:91], v[96:99], v[48:63]
	v_mfma_f32_32x32x16_bf16 v[32:47], v[88:91], v[100:103], v[32:47]
	v_mfma_f32_32x32x16_bf16 v[16:31], v[92:95], v[96:99], v[16:31]
	v_mfma_f32_32x32x16_bf16 v[0:15], v[92:95], v[100:103], v[0:15]
	ds_read_b128 v[88:91], v86
	ds_read_b128 v[92:95], v86 offset:4096
	ds_read_b128 v[96:99], v84 offset:16384
	ds_read_b128 v[100:103], v84 offset:20480
	s_waitcnt lgkmcnt(0)
	v_mfma_f32_32x32x16_bf16 v[48:63], v[88:91], v[96:99], v[48:63]
	v_mfma_f32_32x32x16_bf16 v[32:47], v[88:91], v[100:103], v[32:47]
	v_mfma_f32_32x32x16_bf16 v[16:31], v[92:95], v[96:99], v[16:31]
	v_mfma_f32_32x32x16_bf16 v[0:15], v[92:95], v[100:103], v[0:15]
	ds_read_b128 v[88:91], v87
	ds_read_b128 v[92:95], v87 offset:4096
	ds_read_b128 v[96:99], v81 offset:16384
	ds_read_b128 v[100:103], v81 offset:20480
	s_waitcnt vmcnt(0)
	s_waitcnt vmcnt(0) lgkmcnt(0)
	s_barrier
; #define MFMA(a, b, c) __builtin_amdgcn_mfma_f32_32x32x16_bf16(a, b, c, 0, 0, 0)
; #define ISSUE(k0, bf) do { char* A_ = lw + (bf) * BUF; \
;     _Pragma("unroll") for (int i_ = 0; i_ < 4; ++i_) { glds16(al.ptr(lrow + 32 * i_, (k0) + cg), A_ + i_ * 4096); glds16(bl.ptr(lrow + 32 * i_, (k0) + cg), A_ + ABYTES + i_ * 4096); } \
;     if (HALO) { if (wid == 0) glds16(gh + (k0), A_ + 16384); } } while (0)
; template <bool HALO, class AL, class BL>
; __device__ __forceinline__ void gemm_core(f32x16 (&acc)[2][2], f32x16& hacc, const AL& al, const BL& bl, int K, char* lds,
;                                           const u16* halo0, const u16* halo1, int brow0, int brow1) {
;     ...
;   for (int kt = 0; kt < nk; ++kt) {
;     asm volatile("s_waitcnt vmcnt(0)" ::: "memory");
;     __syncthreads();
;     if (kt + 1 < nk) ISSUE((kt + 1) * 64, (kt + 1) & 1);
;     const char* T = lds + (kt & 1) * BUF;
; #pragma unroll
;     for (int kk = 0; kk < 4; ++kk) {
;       const int c = kk * 2 + hi;
;       bf16x8 a0 = *(const bf16x8*)(T + oa + ((c ^ sa) << 4));
;       bf16x8 a1 = *(const bf16x8*)(T + oa + 4096 + ((c ^ sa) << 4));
;       bf16x8 b0 = *(const bf16x8*)(T + ob0 + ((c ^ sb0) << 4));
;       bf16x8 b1 = *(const bf16x8*)(T + ob1 + ((c ^ sb1) << 4));
;       acc[0][0] = MFMA(a0, b0, acc[0][0]); acc[0][1] = MFMA(a0, b1, acc[0][1]);
;       acc[1][0] = MFMA(a1, b0, acc[1][0]); acc[1][1] = MFMA(a1, b1, acc[1][1]);
	v_mfma_f32_32x32x16_bf16 v[48:63], v[88:91], v[96:99], v[48:63]
	v_mfma_f32_32x32x16_bf16 v[32:47], v[88:91], v[100:103], v[32:47]
	v_lshl_add_u64 v[88:89], v[66:67], 0, s[90:91]
	global_load_lds_dwordx4 v[88:89], off
	v_lshl_add_u64 v[88:89], v[64:65], 0, s[90:91]
	s_mov_b32 m0, s92
	s_nop 0
	global_load_lds_dwordx4 v[88:89], off
	v_lshl_add_u64 v[88:89], v[70:71], 0, s[90:91]
	s_mov_b32 m0, s69
	v_mfma_f32_32x32x16_bf16 v[16:31], v[92:95], v[96:99], v[16:31]
	global_load_lds_dwordx4 v[88:89], off
	v_lshl_add_u64 v[88:89], v[68:69], 0, s[90:91]
	s_mov_b32 m0, s73
	s_nop 0
	global_load_lds_dwordx4 v[88:89], off
	v_lshl_add_u64 v[88:89], v[74:75], 0, s[90:91]
	s_mov_b32 m0, s64
	v_mfma_f32_32x32x16_bf16 v[0:15], v[92:95], v[100:103], v[0:15]
	global_load_lds_dwordx4 v[88:89], off
	v_lshl_add_u64 v[88:89], v[72:73], 0, s[90:91]
	s_mov_b32 m0, s65
	s_nop 0
	global_load_lds_dwordx4 v[88:89], off
	v_lshl_add_u64 v[88:89], v[78:79], 0, s[90:91]
	s_mov_b32 m0, s42
	s_nop 0
	global_load_lds_dwordx4 v[88:89], off
	v_lshl_add_u64 v[88:89], v[76:77], 0, s[90:91]
	s_mov_b32 m0, s43
	s_nop 0
	global_load_lds_dwordx4 v[88:89], off
	ds_read_b128 v[88:91], v80 offset:32768
	ds_read_b128 v[92:95], v80 offset:36864
	ds_read_b128 v[96:99], v82 offset:49152
	ds_read_b128 v[100:103], v82 offset:53248
	s_waitcnt lgkmcnt(0)
	v_mfma_f32_32x32x16_bf16 v[48:63], v[88:91], v[96:99], v[48:63]
	s_mov_b32 m0, s33
	v_mfma_f32_32x32x16_bf16 v[32:47], v[88:91], v[100:103], v[32:47]
	v_mfma_f32_32x32x16_bf16 v[16:31], v[92:95], v[96:99], v[16:31]
	v_mfma_f32_32x32x16_bf16 v[0:15], v[92:95], v[100:103], v[0:15]
	ds_read_b128 v[88:91], v85 offset:32768
	ds_read_b128 v[92:95], v85 offset:36864
	ds_read_b128 v[96:99], v83 offset:49152
	ds_read_b128 v[100:103], v83 offset:53248
	s_waitcnt lgkmcnt(0)
	v_mfma_f32_32x32x16_bf16 v[48:63], v[88:91], v[96:99], v[48:63]
	v_mfma_f32_32x32x16_bf16 v[32:47], v[88:91], v[100:103], v[32:47]
	v_mfma_f32_32x32x16_bf16 v[16:31], v[92:95], v[96:99], v[16:31]
	v_mfma_f32_32x32x16_bf16 v[0:15], v[92:95], v[100:103], v[0:15]
	ds_read_b128 v[88:91], v86 offset:32768
	ds_read_b128 v[92:95], v86 offset:36864
	ds_read_b128 v[96:99], v84 offset:49152
	ds_read_b128 v[100:103], v84 offset:53248
	s_waitcnt lgkmcnt(0)
	v_mfma_f32_32x32x16_bf16 v[48:63], v[88:91], v[96:99], v[48:63]
	v_mfma_f32_32x32x16_bf16 v[32:47], v[88:91], v[100:103], v[32:47]
	v_mfma_f32_32x32x16_bf16 v[16:31], v[92:95], v[96:99], v[16:31]
	v_mfma_f32_32x32x16_bf16 v[0:15], v[92:95], v[100:103], v[0:15]
	ds_read_b128 v[88:91], v87 offset:32768
	ds_read_b128 v[92:95], v87 offset:36864
	ds_read_b128 v[96:99], v81 offset:49152
	ds_read_b128 v[100:103], v81 offset:53248
	s_waitcnt vmcnt(0)
	s_waitcnt vmcnt(0) lgkmcnt(0)
	s_barrier
	v_mfma_f32_32x32x16_bf16 v[48:63], v[88:91], v[96:99], v[48:63]
	v_mfma_f32_32x32x16_bf16 v[32:47], v[88:91], v[100:103], v[32:47]
	v_lshl_add_u64 v[88:89], v[66:67], 0, s[0:1]
	global_load_lds_dwordx4 v[88:89], off
	v_lshl_add_u64 v[88:89], v[64:65], 0, s[0:1]
	s_mov_b32 m0, s72
	s_nop 0
	global_load_lds_dwordx4 v[88:89], off
	v_lshl_add_u64 v[88:89], v[70:71], 0, s[0:1]
	s_mov_b32 m0, s18
	v_mfma_f32_32x32x16_bf16 v[16:31], v[92:95], v[96:99], v[16:31]
	global_load_lds_dwordx4 v[88:89], off
	v_lshl_add_u64 v[88:89], v[68:69], 0, s[0:1]
	s_mov_b32 m0, s19
	s_nop 0
	global_load_lds_dwordx4 v[88:89], off
	v_lshl_add_u64 v[88:89], v[74:75], 0, s[0:1]
	s_mov_b32 m0, s7
	v_mfma_f32_32x32x16_bf16 v[0:15], v[92:95], v[100:103], v[0:15]
	global_load_lds_dwordx4 v[88:89], off
	v_lshl_add_u64 v[88:89], v[72:73], 0, s[0:1]
	s_mov_b32 m0, s8
	s_nop 0
	global_load_lds_dwordx4 v[88:89], off
	v_lshl_add_u64 v[88:89], v[78:79], 0, s[0:1]
	s_mov_b32 m0, s3
	s_nop 0
	global_load_lds_dwordx4 v[88:89], off
	v_lshl_add_u64 v[88:89], v[76:77], 0, s[0:1]
	s_mov_b32 m0, s6
	s_nop 0
	global_load_lds_dwordx4 v[88:89], off
	ds_read_b128 v[88:91], v80
	ds_read_b128 v[92:95], v80 offset:4096
	ds_read_b128 v[96:99], v82 offset:16384
	ds_read_b128 v[100:103], v82 offset:20480
	s_waitcnt lgkmcnt(0)
	v_mfma_f32_32x32x16_bf16 v[48:63], v[88:91], v[96:99], v[48:63]
	s_mov_b32 m0, s82
	v_mfma_f32_32x32x16_bf16 v[32:47], v[88:91], v[100:103], v[32:47]
	v_mfma_f32_32x32x16_bf16 v[16:31], v[92:95], v[96:99], v[16:31]
	v_mfma_f32_32x32x16_bf16 v[0:15], v[92:95], v[100:103], v[0:15]
	ds_read_b128 v[88:91], v85
	ds_read_b128 v[92:95], v85 offset:4096
	ds_read_b128 v[96:99], v83 offset:16384
	ds_read_b128 v[100:103], v83 offset:20480
	s_waitcnt lgkmcnt(0)
	v_mfma_f32_32x32x16_bf16 v[48:63], v[88:91], v[96:99], v[48:63]
	v_mfma_f32_32x32x16_bf16 v[32:47], v[88:91], v[100:103], v[32:47]
	v_mfma_f32_32x32x16_bf16 v[16:31], v[92:95], v[96:99], v[16:31]
	v_mfma_f32_32x32x16_bf16 v[0:15], v[92:95], v[100:103], v[0:15]
	ds_read_b128 v[88:91], v86
	ds_read_b128 v[92:95], v86 offset:4096
	ds_read_b128 v[96:99], v84 offset:16384
	ds_read_b128 v[100:103], v84 offset:20480
	s_waitcnt lgkmcnt(0)
	v_mfma_f32_32x32x16_bf16 v[48:63], v[88:91], v[96:99], v[48:63]
	v_mfma_f32_32x32x16_bf16 v[32:47], v[88:91], v[100:103], v[32:47]
	v_mfma_f32_32x32x16_bf16 v[16:31], v[92:95], v[96:99], v[16:31]
	v_mfma_f32_32x32x16_bf16 v[0:15], v[92:95], v[100:103], v[0:15]
	ds_read_b128 v[88:91], v87
	ds_read_b128 v[92:95], v87 offset:4096
	ds_read_b128 v[96:99], v81 offset:16384
	ds_read_b128 v[100:103], v81 offset:20480
	s_waitcnt vmcnt(0)
	s_waitcnt vmcnt(0) lgkmcnt(0)
	s_barrier
; #define MFMA(a, b, c) __builtin_amdgcn_mfma_f32_32x32x16_bf16(a, b, c, 0, 0, 0)
; #define ISSUE(k0, bf) do { char* A_ = lw + (bf) * BUF; \
;     _Pragma("unroll") for (int i_ = 0; i_ < 4; ++i_) { glds16(al.ptr(lrow + 32 * i_, (k0) + cg), A_ + i_ * 4096); glds16(bl.ptr(lrow + 32 * i_, (k0) + cg), A_ + ABYTES + i_ * 4096); } \
;     if (HALO) { if (wid == 0) glds16(gh + (k0), A_ + 16384); } } while (0)
; template <bool HALO, class AL, class BL>
; __device__ __forceinline__ void gemm_core(f32x16 (&acc)[2][2], f32x16& hacc, const AL& al, const BL& bl, int K, char* lds,
;                                           const u16* halo0, const u16* halo1, int brow0, int brow1) {
;     ...
;   for (int kt = 0; kt < nk; ++kt) {
;     asm volatile("s_waitcnt vmcnt(0)" ::: "memory");
;     __syncthreads();
;     if (kt + 1 < nk) ISSUE((kt + 1) * 64, (kt + 1) & 1);
;     const char* T = lds + (kt & 1) * BUF;
; #pragma unroll
;     for (int kk = 0; kk < 4; ++kk) {
;       const int c = kk * 2 + hi;
;       bf16x8 a0 = *(const bf16x8*)(T + oa + ((c ^ sa) << 4));
;       bf16x8 a1 = *(const bf16x8*)(T + oa + 4096 + ((c ^ sa) << 4));
;       bf16x8 b0 = *(const bf16x8*)(T + ob0 + ((c ^ sb0) << 4));
;       bf16x8 b1 = *(const bf16x8*)(T + ob1 + ((c ^ sb1) << 4));
;       acc[0][0] = MFMA(a0, b0, acc[0][0]); acc[0][1] = MFMA(a0, b1, acc[0][1]);
;       acc[1][0] = MFMA(a1, b0, acc[1][0]); acc[1][1] = MFMA(a1, b1, acc[1][1]);
	v_mfma_f32_32x32x16_bf16 v[48:63], v[88:91], v[96:99], v[48:63]
	v_mfma_f32_32x32x16_bf16 v[32:47], v[88:91], v[100:103], v[32:47]
	v_lshl_add_u64 v[88:89], v[66:67], 0, s[34:35]
	global_load_lds_dwordx4 v[88:89], off
	v_lshl_add_u64 v[88:89], v[64:65], 0, s[34:35]
	s_mov_b32 m0, s92
	v_lshl_add_u64 v[66:67], v[66:67], 0, s[38:39]
	global_load_lds_dwordx4 v[88:89], off
	v_lshl_add_u64 v[88:89], v[70:71], 0, s[34:35]
	s_mov_b32 m0, s69
	v_mfma_f32_32x32x16_bf16 v[0:15], v[92:95], v[100:103], v[0:15]
	global_load_lds_dwordx4 v[88:89], off
	v_lshl_add_u64 v[88:89], v[68:69], 0, s[34:35]
	s_mov_b32 m0, s73
	v_lshl_add_u64 v[64:65], v[64:65], 0, s[38:39]
	global_load_lds_dwordx4 v[88:89], off
	v_lshl_add_u64 v[88:89], v[74:75], 0, s[34:35]
	s_mov_b32 m0, s64
	v_mfma_f32_32x32x16_bf16 v[16:31], v[92:95], v[96:99], v[16:31]
	global_load_lds_dwordx4 v[88:89], off
	v_lshl_add_u64 v[88:89], v[72:73], 0, s[34:35]
	s_mov_b32 m0, s65
	s_nop 0
	global_load_lds_dwordx4 v[88:89], off
	v_lshl_add_u64 v[88:89], v[78:79], 0, s[34:35]
	s_mov_b32 m0, s42
	s_nop 0
	global_load_lds_dwordx4 v[88:89], off
	v_lshl_add_u64 v[88:89], v[76:77], 0, s[34:35]
	s_mov_b32 m0, s43
	s_nop 0
	global_load_lds_dwordx4 v[88:89], off
	ds_read_b128 v[88:91], v80 offset:32768
	ds_read_b128 v[92:95], v80 offset:36864
	ds_read_b128 v[96:99], v82 offset:49152
	ds_read_b128 v[100:103], v82 offset:53248
	s_waitcnt lgkmcnt(0)
	v_mfma_f32_32x32x16_bf16 v[0:15], v[92:95], v[100:103], v[0:15]
	s_mov_b32 m0, s33
	v_mfma_f32_32x32x16_bf16 v[48:63], v[88:91], v[96:99], v[48:63]
	v_mfma_f32_32x32x16_bf16 v[32:47], v[88:91], v[100:103], v[32:47]
	v_mfma_f32_32x32x16_bf16 v[16:31], v[92:95], v[96:99], v[16:31]
	ds_read_b128 v[88:91], v85 offset:32768
	ds_read_b128 v[92:95], v85 offset:36864
	ds_read_b128 v[96:99], v83 offset:49152
	ds_read_b128 v[100:103], v83 offset:53248
	s_waitcnt lgkmcnt(0)
	v_mfma_f32_32x32x16_bf16 v[0:15], v[92:95], v[100:103], v[0:15]
	v_mfma_f32_32x32x16_bf16 v[48:63], v[88:91], v[96:99], v[48:63]
	v_mfma_f32_32x32x16_bf16 v[32:47], v[88:91], v[100:103], v[32:47]
	v_mfma_f32_32x32x16_bf16 v[16:31], v[92:95], v[96:99], v[16:31]
	ds_read_b128 v[88:91], v86 offset:32768
	ds_read_b128 v[92:95], v86 offset:36864
	ds_read_b128 v[96:99], v84 offset:49152
	ds_read_b128 v[100:103], v84 offset:53248
	s_waitcnt lgkmcnt(0)
	v_mfma_f32_32x32x16_bf16 v[0:15], v[92:95], v[100:103], v[0:15]
	v_mfma_f32_32x32x16_bf16 v[48:63], v[88:91], v[96:99], v[48:63]
	v_mfma_f32_32x32x16_bf16 v[32:47], v[88:91], v[100:103], v[32:47]
	v_mfma_f32_32x32x16_bf16 v[16:31], v[92:95], v[96:99], v[16:31]
	ds_read_b128 v[88:91], v87 offset:32768
	ds_read_b128 v[92:95], v87 offset:36864
	ds_read_b128 v[96:99], v81 offset:49152
	ds_read_b128 v[100:103], v81 offset:53248
	s_waitcnt vmcnt(0)
	s_waitcnt vmcnt(0) lgkmcnt(0)
	s_barrier
	global_load_lds_dwordx4 v[66:67], off
	s_mov_b32 m0, s72
	v_mfma_f32_32x32x16_bf16 v[0:15], v[92:95], v[100:103], v[0:15]
	global_load_lds_dwordx4 v[64:65], off
	v_lshl_add_u64 v[64:65], v[70:71], 0, s[38:39]
	s_mov_b32 m0, s18
	s_nop 0
	global_load_lds_dwordx4 v[64:65], off
	v_lshl_add_u64 v[64:65], v[68:69], 0, s[38:39]
	s_mov_b32 m0, s19
	v_mfma_f32_32x32x16_bf16 v[48:63], v[88:91], v[96:99], v[48:63]
	global_load_lds_dwordx4 v[64:65], off
	v_lshl_add_u64 v[64:65], v[74:75], 0, s[38:39]
	s_mov_b32 m0, s7
	s_mov_b64 s[18:19], 0x4000
	global_load_lds_dwordx4 v[64:65], off
	v_lshl_add_u64 v[64:65], v[72:73], 0, s[38:39]
	s_mov_b32 m0, s8
	v_mfma_f32_32x32x16_bf16 v[32:47], v[88:91], v[100:103], v[32:47]
	global_load_lds_dwordx4 v[64:65], off
	v_lshl_add_u64 v[64:65], v[78:79], 0, s[38:39]
	s_mov_b32 m0, s3
	s_lshl_b32 s3, s85, 16
	global_load_lds_dwordx4 v[64:65], off
	v_lshl_add_u64 v[64:65], v[76:77], 0, s[38:39]
	s_mov_b32 m0, s6
	v_mfma_f32_32x32x16_bf16 v[16:31], v[92:95], v[96:99], v[16:31]
	global_load_lds_dwordx4 v[64:65], off
	ds_read_b128 v[64:67], v80
	ds_read_b128 v[68:71], v80 offset:4096
	ds_read_b128 v[72:75], v82 offset:16384
	ds_read_b128 v[76:79], v82 offset:20480
	v_readlane_b32 s6, v255, 23
	s_add_u32 s72, s6, s3
	v_readlane_b32 s3, v255, 24
	s_addc_u32 s73, s3, 0
	s_waitcnt lgkmcnt(0)
	v_mfma_f32_32x32x16_bf16 v[0:15], v[68:71], v[76:79], v[0:15]
	s_lshl_b64 s[6:7], s[62:63], 16
	v_readlane_b32 s3, v255, 21
	s_add_u32 s6, s3, s6
	v_readlane_b32 s3, v255, 22
	s_addc_u32 s7, s3, s7
	v_mfma_f32_32x32x16_bf16 v[48:63], v[64:67], v[72:75], v[48:63]
	v_mfma_f32_32x32x16_bf16 v[32:47], v[64:67], v[76:79], v[32:47]
	v_mfma_f32_32x32x16_bf16 v[16:31], v[68:71], v[72:75], v[16:31]
	ds_read_b128 v[64:67], v85
	ds_read_b128 v[68:71], v85 offset:4096
	ds_read_b128 v[72:75], v83 offset:16384
	ds_read_b128 v[76:79], v83 offset:20480
	s_waitcnt lgkmcnt(0)
	v_mfma_f32_32x32x16_bf16 v[0:15], v[68:71], v[76:79], v[0:15]
	v_mfma_f32_32x32x16_bf16 v[48:63], v[64:67], v[72:75], v[48:63]
	v_mfma_f32_32x32x16_bf16 v[32:47], v[64:67], v[76:79], v[32:47]
	v_mfma_f32_32x32x16_bf16 v[16:31], v[68:71], v[72:75], v[16:31]
	ds_read_b128 v[64:67], v86
	ds_read_b128 v[68:71], v86 offset:4096
	ds_read_b128 v[72:75], v84 offset:16384
	ds_read_b128 v[76:79], v84 offset:20480
	s_waitcnt lgkmcnt(0)
	v_mfma_f32_32x32x16_bf16 v[0:15], v[68:71], v[76:79], v[0:15]
	v_mfma_f32_32x32x16_bf16 v[48:63], v[64:67], v[72:75], v[48:63]
	v_mfma_f32_32x32x16_bf16 v[32:47], v[64:67], v[76:79], v[32:47]
	v_mfma_f32_32x32x16_bf16 v[16:31], v[68:71], v[72:75], v[16:31]
	ds_read_b128 v[64:67], v87
	ds_read_b128 v[68:71], v87 offset:4096
	ds_read_b128 v[72:75], v81 offset:16384
	ds_read_b128 v[76:79], v81 offset:20480
	s_waitcnt vmcnt(0)
	s_waitcnt vmcnt(0) lgkmcnt(0)
	s_barrier
; __device__ __forceinline__ float sigmoidf_(float x) { return __builtin_amdgcn_rcpf(1.f + __expf(-x)); }
; #define MFMA(a, b, c) __builtin_amdgcn_mfma_f32_32x32x16_bf16(a, b, c, 0, 0, 0)
; template <bool HALO, class AL, class BL>
; __device__ __forceinline__ void gemm_core(f32x16 (&acc)[2][2], f32x16& hacc, const AL& al, const BL& bl, int K, char* lds,
;                                           const u16* halo0, const u16* halo1, int brow0, int brow1) {
;     ...
; #pragma unroll
;     for (int kk = 0; kk < 4; ++kk) {
;       const int c = kk * 2 + hi;
;       bf16x8 a0 = *(const bf16x8*)(T + oa + ((c ^ sa) << 4));
;       bf16x8 a1 = *(const bf16x8*)(T + oa + 4096 + ((c ^ sa) << 4));
;       bf16x8 b0 = *(const bf16x8*)(T + ob0 + ((c ^ sb0) << 4));
;       bf16x8 b1 = *(const bf16x8*)(T + ob1 + ((c ^ sb1) << 4));
;       acc[0][0] = MFMA(a0, b0, acc[0][0]); acc[0][1] = MFMA(a0, b1, acc[0][1]);
;       acc[1][0] = MFMA(a1, b0, acc[1][0]); acc[1][1] = MFMA(a1, b1, acc[1][1]);
; __device__ __forceinline__ void phase_ffn_down(const P& p, int layer, char* lds) {
;     ...
; #pragma unroll
;     for (int mi = 0; mi < 2; ++mi)
; #pragma unroll
;       for (int ni = 0; ni < 2; ++ni)
; #pragma unroll
;         for (int r = 0; r < 16; ++r) acc[mi][ni][r] = sigmoidf_(acc[mi][ni][r]);
	v_mfma_f32_32x32x16_bf16 v[0:15], v[68:71], v[76:79], v[0:15]
	v_mfma_f32_32x32x16_bf16 v[48:63], v[64:67], v[72:75], v[48:63]
	v_mfma_f32_32x32x16_bf16 v[32:47], v[64:67], v[76:79], v[32:47]
	v_mfma_f32_32x32x16_bf16 v[16:31], v[68:71], v[72:75], v[16:31]
	ds_read_b128 v[64:67], v80 offset:32768
	ds_read_b128 v[68:71], v80 offset:36864
	ds_read_b128 v[72:75], v82 offset:49152
	ds_read_b128 v[76:79], v82 offset:53248
	s_waitcnt lgkmcnt(0)
	v_mfma_f32_32x32x16_bf16 v[0:15], v[68:71], v[76:79], v[0:15]
	v_mfma_f32_32x32x16_bf16 v[48:63], v[64:67], v[72:75], v[48:63]
	v_mfma_f32_32x32x16_bf16 v[32:47], v[64:67], v[76:79], v[32:47]
	v_mfma_f32_32x32x16_bf16 v[16:31], v[68:71], v[72:75], v[16:31]
	ds_read_b128 v[64:67], v85 offset:32768
	ds_read_b128 v[68:71], v85 offset:36864
	ds_read_b128 v[72:75], v83 offset:49152
	ds_read_b128 v[76:79], v83 offset:53248
	s_waitcnt lgkmcnt(0)
	v_mfma_f32_32x32x16_bf16 v[0:15], v[68:71], v[76:79], v[0:15]
	v_mfma_f32_32x32x16_bf16 v[48:63], v[64:67], v[72:75], v[48:63]
	v_mfma_f32_32x32x16_bf16 v[32:47], v[64:67], v[76:79], v[32:47]
	v_mfma_f32_32x32x16_bf16 v[16:31], v[68:71], v[72:75], v[16:31]
	ds_read_b128 v[64:67], v86 offset:32768
	ds_read_b128 v[68:71], v86 offset:36864
	ds_read_b128 v[72:75], v84 offset:49152
	ds_read_b128 v[76:79], v84 offset:53248
	s_waitcnt lgkmcnt(0)
	v_mfma_f32_32x32x16_bf16 v[0:15], v[68:71], v[76:79], v[0:15]
	v_mfma_f32_32x32x16_bf16 v[48:63], v[64:67], v[72:75], v[48:63]
	v_mfma_f32_32x32x16_bf16 v[32:47], v[64:67], v[76:79], v[32:47]
	v_mfma_f32_32x32x16_bf16 v[16:31], v[68:71], v[72:75], v[16:31]
	ds_read_b128 v[64:67], v87 offset:32768
	ds_read_b128 v[68:71], v87 offset:36864
	ds_read_b128 v[72:75], v81 offset:49152
	ds_read_b128 v[76:79], v81 offset:53248
	s_waitcnt lgkmcnt(0)
	v_mfma_f32_32x32x16_bf16 v[0:15], v[68:71], v[76:79], v[0:15]
	v_mfma_f32_32x32x16_bf16 v[16:31], v[68:71], v[72:75], v[16:31]
	s_nop 10
	v_mul_f32_e32 v0, 0xbfb8aa3b, v0
	v_exp_f32_e32 v0, v0
	s_nop 0
	v_add_f32_e32 v0, 1.0, v0
	v_rcp_f32_e32 v110, v0
	v_mul_f32_e32 v0, 0xbfb8aa3b, v1
	v_exp_f32_e32 v0, v0
	v_mul_f32_e32 v16, 0xbfb8aa3b, v16
	v_exp_f32_e32 v16, v16
	v_mov_b32_e32 v1, v229
	v_add_f32_e32 v0, 1.0, v0
	v_rcp_f32_e32 v111, v0
	v_mul_f32_e32 v0, 0xbfb8aa3b, v2
	v_exp_f32_e32 v0, v0
	v_add_f32_e32 v16, 1.0, v16
	v_rcp_f32_e32 v96, v16
	v_mul_f32_e32 v16, 0xbfb8aa3b, v17
	v_add_f32_e32 v0, 1.0, v0
	v_rcp_f32_e32 v114, v0
	v_mul_f32_e32 v0, 0xbfb8aa3b, v3
	v_exp_f32_e32 v0, v0
	v_exp_f32_e32 v16, v16
	v_mfma_f32_32x32x16_bf16 v[48:63], v[64:67], v[72:75], v[48:63]
	v_add_f32_e32 v0, 1.0, v0
	v_rcp_f32_e32 v115, v0
	v_mul_f32_e32 v0, 0xbfb8aa3b, v4
	v_exp_f32_e32 v0, v0
	v_add_f32_e32 v16, 1.0, v16
	v_rcp_f32_e32 v97, v16
	v_mul_f32_e32 v16, 0xbfb8aa3b, v18
	v_add_f32_e32 v0, 1.0, v0
	v_rcp_f32_e32 v116, v0
	v_mul_f32_e32 v0, 0xbfb8aa3b, v5
	v_exp_f32_e32 v0, v0
	v_exp_f32_e32 v16, v16
	v_mfma_f32_32x32x16_bf16 v[32:47], v[64:67], v[76:79], v[32:47]
	v_mul_f32_e32 v48, 0xbfb8aa3b, v48
	v_add_f32_e32 v0, 1.0, v0
	v_rcp_f32_e32 v117, v0
	v_mul_f32_e32 v0, 0xbfb8aa3b, v6
	v_exp_f32_e32 v0, v0
	v_add_f32_e32 v16, 1.0, v16
	v_rcp_f32_e32 v98, v16
	v_mul_f32_e32 v16, 0xbfb8aa3b, v19
	v_add_f32_e32 v0, 1.0, v0
	v_rcp_f32_e32 v118, v0
	v_mul_f32_e32 v0, 0xbfb8aa3b, v7
	v_exp_f32_e32 v0, v0
	v_exp_f32_e32 v16, v16
	v_mov_b32_e32 v6, v229
	v_add_f32_e32 v0, 1.0, v0
	v_add_f32_e32 v16, 1.0, v16
	v_rcp_f32_e32 v119, v0
	v_mul_f32_e32 v0, 0xbfb8aa3b, v8
	v_rcp_f32_e32 v99, v16
	v_mul_f32_e32 v16, 0xbfb8aa3b, v20
	v_exp_f32_e32 v0, v0
	v_exp_f32_e32 v16, v16
	v_and_b32_e32 v7, 31, v6
	v_lshrrev_b32_e32 v2, 4, v6
	v_add_f32_e32 v0, 1.0, v0
	v_add_f32_e32 v16, 1.0, v16
	v_rcp_f32_e32 v120, v0
	v_mul_f32_e32 v0, 0xbfb8aa3b, v9
	v_rcp_f32_e32 v100, v16
	v_mul_f32_e32 v16, 0xbfb8aa3b, v21
	v_exp_f32_e32 v0, v0
	v_exp_f32_e32 v16, v16
	v_xor_b32_e32 v4, v2, v6
	v_lshlrev_b32_e32 v4, 4, v4
	v_add_f32_e32 v0, 1.0, v0
	v_add_f32_e32 v16, 1.0, v16
	v_rcp_f32_e32 v121, v0
	v_mul_f32_e32 v0, 0xbfb8aa3b, v10
	v_rcp_f32_e32 v101, v16
	v_mul_f32_e32 v16, 0xbfb8aa3b, v22
	v_exp_f32_e32 v0, v0
	v_exp_f32_e32 v16, v16
	v_and_b32_e32 v200, 0x70, v4
	v_lshl_add_u32 v9, v6, 4, 0
	v_add_f32_e32 v0, 1.0, v0
	v_add_f32_e32 v16, 1.0, v16
	v_rcp_f32_e32 v122, v0
	v_mul_f32_e32 v0, 0xbfb8aa3b, v11
	v_rcp_f32_e32 v102, v16
	v_mul_f32_e32 v16, 0xbfb8aa3b, v23
	v_exp_f32_e32 v0, v0
	v_exp_f32_e32 v16, v16
	v_and_or_b32 v11, v1, 64, v7
	v_add_u32_e32 v5, 0x4000, v9
	v_add_f32_e32 v0, 1.0, v0
	v_add_f32_e32 v16, 1.0, v16
	v_rcp_f32_e32 v123, v0
	v_mul_f32_e32 v0, 0xbfb8aa3b, v12
	v_rcp_f32_e32 v103, v16
	v_mul_f32_e32 v16, 0xbfb8aa3b, v24
	v_exp_f32_e32 v0, v0
	v_exp_f32_e32 v16, v16
	v_readfirstlane_b32 s43, v5
	v_readfirstlane_b32 s42, v9
	v_add_f32_e32 v0, 1.0, v0
	v_add_f32_e32 v16, 1.0, v16
	v_rcp_f32_e32 v124, v0
	v_mul_f32_e32 v0, 0xbfb8aa3b, v13
	v_rcp_f32_e32 v104, v16
	v_mul_f32_e32 v16, 0xbfb8aa3b, v25
	v_exp_f32_e32 v0, v0
	v_exp_f32_e32 v16, v16
	s_mov_b32 m0, s42
	v_add_f32_e32 v0, 1.0, v0
	v_add_f32_e32 v16, 1.0, v16
	v_rcp_f32_e32 v125, v0
	v_mul_f32_e32 v0, 0xbfb8aa3b, v14
	v_rcp_f32_e32 v105, v16
	v_mul_f32_e32 v16, 0xbfb8aa3b, v26
	v_exp_f32_e32 v0, v0
	v_exp_f32_e32 v16, v16
	s_barrier
; __device__ __forceinline__ float sigmoidf_(float x) { return __builtin_amdgcn_rcpf(1.f + __expf(-x)); }
; #define MFMA(a, b, c) __builtin_amdgcn_mfma_f32_32x32x16_bf16(a, b, c, 0, 0, 0)
; #define ISSUE(k0, bf) do { char* A_ = lw + (bf) * BUF; \
;     _Pragma("unroll") for (int i_ = 0; i_ < 4; ++i_) { glds16(al.ptr(lrow + 32 * i_, (k0) + cg), A_ + i_ * 4096); glds16(bl.ptr(lrow + 32 * i_, (k0) + cg), A_ + ABYTES + i_ * 4096); } \
;     if (HALO) { if (wid == 0) glds16(gh + (k0), A_ + 16384); } } while (0)
; template <bool HALO, class AL, class BL>
; __device__ __forceinline__ void gemm_core(f32x16 (&acc)[2][2], f32x16& hacc, const AL& al, const BL& bl, int K, char* lds,
;                                           const u16* halo0, const u16* halo1, int brow0, int brow1) {
;     ...
;   const int sa = ((wr * 64 + r32) >> 1) & 7, sb0 = ((brow0 + r32) >> 1) & 7, sb1 = ((brow1 + r32) >> 1) & 7, sh = (r32 >> 1) & 7;
;   const int oa = (wr * 64 + r32) * 128, ob0 = ABYTES + (brow0 + r32) * 128, ob1 = ABYTES + (brow1 + r32) * 128, oh = (128 + r32) * 128;
;   __syncthreads();
;   ISSUE(0, 0);
;   const int nk = K >> 6;
;   for (int kt = 0; kt < nk; ++kt) {
;     asm volatile("s_waitcnt vmcnt(0)" ::: "memory");
;     __syncthreads();
;     if (kt + 1 < nk) ISSUE((kt + 1) * 64, (kt + 1) & 1);
;     const char* T = lds + (kt & 1) * BUF;
; #pragma unroll
;     for (int kk = 0; kk < 4; ++kk) {
;       const int c = kk * 2 + hi;
;       bf16x8 a0 = *(const bf16x8*)(T + oa + ((c ^ sa) << 4));
;       bf16x8 a1 = *(const bf16x8*)(T + oa + 4096 + ((c ^ sa) << 4));
;       bf16x8 b0 = *(const bf16x8*)(T + ob0 + ((c ^ sb0) << 4));
;       bf16x8 b1 = *(const bf16x8*)(T + ob1 + ((c ^ sb1) << 4));
;       acc[0][0] = MFMA(a0, b0, acc[0][0]); acc[0][1] = MFMA(a0, b1, acc[0][1]);
;       acc[1][0] = MFMA(a1, b0, acc[1][0]); acc[1][1] = MFMA(a1, b1, acc[1][1]);
; __device__ __forceinline__ void phase_ffn_down(const P& p, int layer, char* lds) {
;     ...
; #pragma unroll
;     for (int mi = 0; mi < 2; ++mi)
; #pragma unroll
;       for (int ni = 0; ni < 2; ++ni)
; #pragma unroll
;         for (int r = 0; r < 16; ++r) acc[mi][ni][r] = sigmoidf_(acc[mi][ni][r]);
;     f32x16 acc2[2][2] = {};
;     { LdBf al{pb + (long)tm * 128 * 256, 256}; LdBf bl{wp + (long)tn * 128 * 256, 256}; gemm_plain(acc2, al, bl, 256, lds); }
	v_add_f32_e32 v0, 1.0, v0
	v_add_f32_e32 v16, 1.0, v16
	v_rcp_f32_e32 v126, v0
	v_mul_f32_e32 v0, 0xbfb8aa3b, v15
	v_rcp_f32_e32 v106, v16
	v_mul_f32_e32 v16, 0xbfb8aa3b, v27
	v_exp_f32_e32 v0, v0
	v_exp_f32_e32 v16, v16
	v_lshrrev_b32_e32 v8, 5, v6
	v_bfe_u32 v12, v6, 1, 3
	v_add_f32_e32 v0, 1.0, v0
	v_add_f32_e32 v16, 1.0, v16
	v_rcp_f32_e32 v127, v0
	v_ashrrev_i32_e32 v0, 3, v6
	v_rcp_f32_e32 v107, v16
	v_mul_f32_e32 v16, 0xbfb8aa3b, v28
	v_ashrrev_i32_e32 v1, 31, v0
	v_exp_f32_e32 v16, v16
	v_lshlrev_b64 v[0:1], 9, v[0:1]
	v_lshl_add_u64 v[2:3], s[72:73], 0, v[0:1]
	v_lshl_add_u64 v[130:131], v[2:3], 0, v[200:201]
	v_lshl_add_u64 v[2:3], s[6:7], 0, v[0:1]
	v_lshl_add_u64 v[128:129], v[2:3], 0, v[200:201]
	v_lshl_add_u64 v[2:3], v[0:1], 0, s[18:19]
	v_add_f32_e32 v16, 1.0, v16
	v_lshl_add_u64 v[4:5], s[72:73], 0, v[2:3]
	v_lshl_add_u64 v[2:3], s[6:7], 0, v[2:3]
	v_rcp_f32_e32 v108, v16
	v_mul_f32_e32 v16, 0xbfb8aa3b, v29
	v_lshl_add_u64 v[134:135], v[2:3], 0, v[200:201]
	v_add_u32_e32 v2, 0x5000, v9
	v_exp_f32_e32 v16, v16
	v_lshl_add_u64 v[132:133], v[4:5], 0, v[200:201]
	v_add_u32_e32 v4, 0x1000, v9
	v_readfirstlane_b32 s65, v2
	v_lshl_add_u64 v[2:3], v[0:1], 0, s[36:37]
	global_load_lds_dwordx4 v[130:131], off
	s_mov_b32 m0, s43
	v_readfirstlane_b32 s64, v4
	v_lshl_add_u64 v[4:5], s[72:73], 0, v[2:3]
	v_lshl_add_u64 v[2:3], s[6:7], 0, v[2:3]
	s_mov_b64 s[18:19], 0xc000
	global_load_lds_dwordx4 v[128:129], off
	s_mov_b32 m0, s64
	v_lshl_add_u64 v[136:137], v[4:5], 0, v[200:201]
	v_add_u32_e32 v4, 0x2000, v9
	v_lshl_add_u64 v[138:139], v[2:3], 0, v[200:201]
	v_add_u32_e32 v2, 0x6000, v9
	v_lshl_add_u64 v[0:1], v[0:1], 0, s[18:19]
	global_load_lds_dwordx4 v[132:133], off
	s_mov_b32 m0, s65
	v_readfirstlane_b32 s69, v4
	v_readfirstlane_b32 s70, v2
	v_lshl_add_u64 v[2:3], s[72:73], 0, v[0:1]
	v_lshl_add_u64 v[0:1], s[6:7], 0, v[0:1]
	v_add_f32_e32 v16, 1.0, v16
	global_load_lds_dwordx4 v[134:135], off
	s_mov_b32 m0, s69
	v_lshl_add_u64 v[140:141], v[2:3], 0, v[200:201]
	v_add_u32_e32 v2, 0x3000, v9
	v_lshl_add_u64 v[142:143], v[0:1], 0, v[200:201]
	v_add_u32_e32 v0, 0x7000, v9
	v_rcp_f32_e32 v109, v16
	v_mul_f32_e32 v16, 0xbfb8aa3b, v30
	global_load_lds_dwordx4 v[136:137], off
	s_mov_b32 m0, s70
	v_readfirstlane_b32 s71, v2
	v_readfirstlane_b32 s72, v0
	v_bfe_u32 v0, v6, 5, 1
	v_bitop3_b32 v1, v8, v12, 1 bitop3:0x6c
	v_exp_f32_e32 v16, v16
	global_load_lds_dwordx4 v[138:139], off
	s_mov_b32 m0, s71
	v_lshlrev_b32_e32 v3, 4, v1
	v_bitop3_b32 v1, v0, v12, 2 bitop3:0x36
	v_add_u32_e32 v4, 0x8000, v9
	global_load_lds_dwordx4 v[140:141], off
	s_mov_b32 m0, s72
	v_lshlrev_b32_e32 v148, 4, v1
	v_bitop3_b32 v1, v0, v12, 4 bitop3:0x36
	v_bitop3_b32 v0, v0, v12, 6 bitop3:0x36
	v_add_u32_e32 v5, 0xc000, v9
	v_readfirstlane_b32 s3, v4
	global_load_lds_dwordx4 v[142:143], off
	v_lshlrev_b32_e32 v166, 4, v1
	v_lshlrev_b32_e32 v168, 4, v0
	v_lshl_add_u64 v[0:1], v[130:131], 0, s[78:79]
	s_mov_b32 m0, s3
	v_readfirstlane_b32 s6, v5
	v_add_u32_e32 v4, 0x9000, v9
	s_waitcnt vmcnt(0)
	s_waitcnt vmcnt(0) lgkmcnt(0)
	s_barrier
	global_load_lds_dwordx4 v[0:1], off
	v_lshl_add_u64 v[0:1], v[128:129], 0, s[78:79]
	s_mov_b32 m0, s6
	v_readfirstlane_b32 s7, v4
	v_add_u32_e32 v4, 0xd000, v9
	v_add_f32_e32 v16, 1.0, v16
	global_load_lds_dwordx4 v[0:1], off
	v_lshl_add_u64 v[0:1], v[132:133], 0, s[78:79]
	s_mov_b32 m0, s7
	v_readfirstlane_b32 s8, v4
	v_add_u32_e32 v4, 0xa000, v9
	v_rcp_f32_e32 v112, v16
	v_mul_f32_e32 v16, 0xbfb8aa3b, v31
	global_load_lds_dwordx4 v[0:1], off
	v_lshl_add_u64 v[0:1], v[134:135], 0, s[78:79]
	s_mov_b32 m0, s8
	v_readfirstlane_b32 s18, v4
	v_add_u32_e32 v4, 0xe000, v9
	v_exp_f32_e32 v16, v16
	global_load_lds_dwordx4 v[0:1], off
	v_lshl_add_u64 v[0:1], v[136:137], 0, s[78:79]
	s_mov_b32 m0, s18
	v_readfirstlane_b32 s19, v4
	v_add_u32_e32 v4, 0xb000, v9
	v_lshrrev_b32_e32 v10, 1, v6
	global_load_lds_dwordx4 v[0:1], off
	v_lshl_add_u64 v[0:1], v[138:139], 0, s[78:79]
	s_mov_b32 m0, s19
	v_readfirstlane_b32 s33, v4
	v_add_u32_e32 v4, 0xf000, v9
	v_and_or_b32 v2, v10, s52, v7
	global_load_lds_dwordx4 v[0:1], off
	v_lshl_add_u64 v[0:1], v[140:141], 0, s[78:79]
	s_mov_b32 m0, s33
	v_readfirstlane_b32 s63, v4
	global_load_lds_dwordx4 v[0:1], off
	v_lshl_add_u64 v[0:1], v[142:143], 0, s[78:79]
	s_mov_b32 m0, s63
	v_lshl_add_u32 v169, v2, 7, 0
	v_lshl_add_u32 v170, v11, 7, 0
	v_add_f32_e32 v16, 1.0, v16
	global_load_lds_dwordx4 v[0:1], off
	v_add_u32_e32 v147, v169, v3
	v_add_u32_e32 v146, v170, v3
	v_rcp_f32_e32 v113, v16
	ds_read_b128 v[16:19], v147
	ds_read_b128 v[64:67], v147 offset:4096
	ds_read_b128 v[68:71], v146 offset:16384
	ds_read_b128 v[72:75], v146 offset:20480
	s_waitcnt lgkmcnt(0)
	v_mfma_f32_32x32x16_bf16 v[0:15], v[16:19], v[68:71], 0
	v_add_u32_e32 v149, v169, v148
	v_add_u32_e32 v148, v170, v148
	ds_read_b128 v[150:153], v149
	ds_read_b128 v[154:157], v149 offset:4096
	ds_read_b128 v[158:161], v148 offset:16384
	ds_read_b128 v[162:165], v148 offset:20480
	s_mov_b32 m0, s42
	v_mul_f32_e32 v49, 0xbfb8aa3b, v49
	v_mul_f32_e32 v58, 0xbfb8aa3b, v58
	v_mfma_f32_32x32x16_bf16 v[16:31], v[16:19], v[72:75], 0
	v_mul_f32_e32 v59, 0xbfb8aa3b, v59
	v_exp_f32_e32 v48, v48
	v_exp_f32_e32 v49, v49
	v_mul_f32_e32 v56, 0xbfb8aa3b, v56
	v_mul_f32_e32 v57, 0xbfb8aa3b, v57
	v_exp_f32_e32 v58, v58
	v_exp_f32_e32 v59, v59
	v_mfma_f32_32x32x16_bf16 v[80:95], v[64:67], v[68:71], 0
	v_mul_f32_e32 v60, 0xbfb8aa3b, v60
	v_mul_f32_e32 v61, 0xbfb8aa3b, v61
	v_mul_f32_e32 v54, 0xbfb8aa3b, v54
	v_mul_f32_e32 v55, 0xbfb8aa3b, v55
	v_exp_f32_e32 v56, v56
	v_exp_f32_e32 v57, v57
	v_exp_f32_e32 v60, v60
	v_mfma_f32_32x32x16_bf16 v[64:79], v[64:67], v[72:75], 0
	v_exp_f32_e32 v61, v61
	v_mul_f32_e32 v52, 0xbfb8aa3b, v52
	v_mul_f32_e32 v53, 0xbfb8aa3b, v53
	v_exp_f32_e32 v54, v54
	v_exp_f32_e32 v55, v55
	v_mul_f32_e32 v50, 0xbfb8aa3b, v50
	v_mul_f32_e32 v51, 0xbfb8aa3b, v51
	s_waitcnt lgkmcnt(0)
; __device__ __forceinline__ float sigmoidf_(float x) { return __builtin_amdgcn_rcpf(1.f + __expf(-x)); }
; #define MFMA(a, b, c) __builtin_amdgcn_mfma_f32_32x32x16_bf16(a, b, c, 0, 0, 0)
; #define ISSUE(k0, bf) do { char* A_ = lw + (bf) * BUF; \
;     _Pragma("unroll") for (int i_ = 0; i_ < 4; ++i_) { glds16(al.ptr(lrow + 32 * i_, (k0) + cg), A_ + i_ * 4096); glds16(bl.ptr(lrow + 32 * i_, (k0) + cg), A_ + ABYTES + i_ * 4096); } \
;     if (HALO) { if (wid == 0) glds16(gh + (k0), A_ + 16384); } } while (0)
; template <bool HALO, class AL, class BL>
; __device__ __forceinline__ void gemm_core(f32x16 (&acc)[2][2], f32x16& hacc, const AL& al, const BL& bl, int K, char* lds,
;                                           const u16* halo0, const u16* halo1, int brow0, int brow1) {
;     ...
;   for (int kt = 0; kt < nk; ++kt) {
;     asm volatile("s_waitcnt vmcnt(0)" ::: "memory");
;     __syncthreads();
;     if (kt + 1 < nk) ISSUE((kt + 1) * 64, (kt + 1) & 1);
;     const char* T = lds + (kt & 1) * BUF;
; #pragma unroll
;     for (int kk = 0; kk < 4; ++kk) {
;       const int c = kk * 2 + hi;
;       bf16x8 a0 = *(const bf16x8*)(T + oa + ((c ^ sa) << 4));
;       bf16x8 a1 = *(const bf16x8*)(T + oa + 4096 + ((c ^ sa) << 4));
;       bf16x8 b0 = *(const bf16x8*)(T + ob0 + ((c ^ sb0) << 4));
;       bf16x8 b1 = *(const bf16x8*)(T + ob1 + ((c ^ sb1) << 4));
;       acc[0][0] = MFMA(a0, b0, acc[0][0]); acc[0][1] = MFMA(a0, b1, acc[0][1]);
;       acc[1][0] = MFMA(a1, b0, acc[1][0]); acc[1][1] = MFMA(a1, b1, acc[1][1]);
; __device__ __forceinline__ void phase_ffn_down(const P& p, int layer, char* lds) {
;     ...
; #pragma unroll
;     for (int mi = 0; mi < 2; ++mi)
; #pragma unroll
;       for (int ni = 0; ni < 2; ++ni)
; #pragma unroll
;         for (int r = 0; r < 16; ++r) acc[mi][ni][r] = sigmoidf_(acc[mi][ni][r]);
	v_mfma_f32_32x32x16_bf16 v[0:15], v[150:153], v[158:161], v[0:15]
	v_exp_f32_e32 v52, v52
	v_exp_f32_e32 v53, v53
	v_add_f32_e32 v48, 1.0, v48
	v_add_f32_e32 v49, 1.0, v49
	v_exp_f32_e32 v50, v50
	v_exp_f32_e32 v51, v51
	v_add_f32_e32 v58, 1.0, v58
	v_mfma_f32_32x32x16_bf16 v[16:31], v[150:153], v[162:165], v[16:31]
	v_add_u32_e32 v151, v169, v166
	v_add_u32_e32 v150, v170, v166
	v_add_f32_e32 v59, 1.0, v59
	v_rcp_f32_e32 v48, v48
	v_rcp_f32_e32 v49, v49
	v_add_f32_e32 v56, 1.0, v56
	v_add_f32_e32 v57, 1.0, v57
	v_mfma_f32_32x32x16_bf16 v[80:95], v[154:157], v[158:161], v[80:95]
	v_rcp_f32_e32 v58, v58
	v_rcp_f32_e32 v59, v59
	v_add_f32_e32 v60, 1.0, v60
	v_add_f32_e32 v61, 1.0, v61
	v_mul_f32_e32 v62, 0xbfb8aa3b, v62
	v_mul_f32_e32 v63, 0xbfb8aa3b, v63
	v_add_f32_e32 v54, 1.0, v54
	v_mfma_f32_32x32x16_bf16 v[64:79], v[154:157], v[162:165], v[64:79]
	ds_read_b128 v[152:155], v151
	ds_read_b128 v[156:159], v151 offset:4096
	ds_read_b128 v[160:163], v150 offset:16384
	ds_read_b128 v[164:167], v150 offset:20480
	v_add_f32_e32 v55, 1.0, v55
	v_rcp_f32_e32 v56, v56
	v_rcp_f32_e32 v57, v57
	v_rcp_f32_e32 v60, v60
	v_rcp_f32_e32 v61, v61
	s_waitcnt lgkmcnt(0)
	v_mfma_f32_32x32x16_bf16 v[0:15], v[152:155], v[160:163], v[0:15]
	v_exp_f32_e32 v62, v62
	v_exp_f32_e32 v63, v63
	v_add_f32_e32 v52, 1.0, v52
	v_add_f32_e32 v53, 1.0, v53
	v_rcp_f32_e32 v54, v54
	v_rcp_f32_e32 v55, v55
	v_mul_f32_e32 v32, 0xbfb8aa3b, v32
	v_mfma_f32_32x32x16_bf16 v[16:31], v[152:155], v[164:167], v[16:31]
	v_add_u32_e32 v153, v169, v168
	v_add_u32_e32 v152, v170, v168
	v_mul_f32_e32 v33, 0xbfb8aa3b, v33
	v_add_f32_e32 v50, 1.0, v50
	v_add_f32_e32 v51, 1.0, v51
	v_rcp_f32_e32 v52, v52
	v_rcp_f32_e32 v53, v53
	v_mfma_f32_32x32x16_bf16 v[80:95], v[156:159], v[160:163], v[80:95]
	v_exp_f32_e32 v32, v32
	v_exp_f32_e32 v33, v33
	v_rcp_f32_e32 v50, v50
	v_rcp_f32_e32 v51, v51
	v_add_f32_e32 v62, 1.0, v62
	v_add_f32_e32 v63, 1.0, v63
	v_rcp_f32_e32 v62, v62
	v_mfma_f32_32x32x16_bf16 v[64:79], v[156:159], v[164:167], v[64:79]
	ds_read_b128 v[154:157], v153
	ds_read_b128 v[158:161], v153 offset:4096
	ds_read_b128 v[162:165], v152 offset:16384
	ds_read_b128 v[166:169], v152 offset:20480
	s_waitcnt vmcnt(0)
	s_waitcnt vmcnt(0) lgkmcnt(0)
	s_barrier
	v_rcp_f32_e32 v63, v63
	v_mfma_f32_32x32x16_bf16 v[0:15], v[154:157], v[162:165], v[0:15]
	v_add_f32_e32 v32, 1.0, v32
	v_add_f32_e32 v33, 1.0, v33
	v_rcp_f32_e32 v32, v32
	v_rcp_f32_e32 v33, v33
	v_mul_f32_e32 v34, 0xbfb8aa3b, v34
	v_mul_f32_e32 v35, 0xbfb8aa3b, v35
	v_mul_f32_e32 v36, 0xbfb8aa3b, v36
	v_mfma_f32_32x32x16_bf16 v[16:31], v[154:157], v[166:169], v[16:31]
	v_lshl_add_u64 v[154:155], v[130:131], 0, s[24:25]
	global_load_lds_dwordx4 v[154:155], off
	v_lshl_add_u64 v[154:155], v[128:129], 0, s[24:25]
	s_mov_b32 m0, s43
	v_lshl_add_u64 v[130:131], v[130:131], 0, s[74:75]
	global_load_lds_dwordx4 v[154:155], off
	v_lshl_add_u64 v[154:155], v[132:133], 0, s[24:25]
	s_mov_b32 m0, s64
	v_mfma_f32_32x32x16_bf16 v[64:79], v[158:161], v[166:169], v[64:79]
	global_load_lds_dwordx4 v[154:155], off
	v_lshl_add_u64 v[154:155], v[134:135], 0, s[24:25]
	s_mov_b32 m0, s65
	v_lshl_add_u64 v[128:129], v[128:129], 0, s[74:75]
	global_load_lds_dwordx4 v[154:155], off
	v_lshl_add_u64 v[154:155], v[136:137], 0, s[24:25]
	s_mov_b32 m0, s69
	v_mfma_f32_32x32x16_bf16 v[80:95], v[158:161], v[162:165], v[80:95]
	global_load_lds_dwordx4 v[154:155], off
	v_lshl_add_u64 v[154:155], v[138:139], 0, s[24:25]
	s_mov_b32 m0, s70
	v_mul_f32_e32 v37, 0xbfb8aa3b, v37
	global_load_lds_dwordx4 v[154:155], off
	v_lshl_add_u64 v[154:155], v[140:141], 0, s[24:25]
	s_mov_b32 m0, s71
	v_mul_f32_e32 v38, 0xbfb8aa3b, v38
	global_load_lds_dwordx4 v[154:155], off
	v_lshl_add_u64 v[154:155], v[142:143], 0, s[24:25]
	s_mov_b32 m0, s72
	v_mul_f32_e32 v39, 0xbfb8aa3b, v39
	global_load_lds_dwordx4 v[154:155], off
	ds_read_b128 v[154:157], v147 offset:32768
	ds_read_b128 v[158:161], v147 offset:36864
	ds_read_b128 v[162:165], v146 offset:49152
	ds_read_b128 v[166:169], v146 offset:53248
	s_waitcnt lgkmcnt(0)
	v_mfma_f32_32x32x16_bf16 v[0:15], v[154:157], v[162:165], v[0:15]
	s_mov_b32 m0, s3
	s_mul_i32 s3, s85, 0xb0000
	v_mul_f32_e32 v40, 0xbfb8aa3b, v40
	v_mul_f32_e32 v41, 0xbfb8aa3b, v41
	v_mul_f32_e32 v42, 0xbfb8aa3b, v42
	v_mul_f32_e32 v43, 0xbfb8aa3b, v43
	v_mul_f32_e32 v44, 0xbfb8aa3b, v44
	v_mfma_f32_32x32x16_bf16 v[64:79], v[158:161], v[166:169], v[64:79]
	v_mul_f32_e32 v45, 0xbfb8aa3b, v45
	v_mul_f32_e32 v46, 0xbfb8aa3b, v46
	v_mul_f32_e32 v47, 0xbfb8aa3b, v47
	v_exp_f32_e32 v34, v34
	v_exp_f32_e32 v35, v35
	v_exp_f32_e32 v36, v36
	v_exp_f32_e32 v37, v37
	v_mfma_f32_32x32x16_bf16 v[16:31], v[154:157], v[166:169], v[16:31]
	v_exp_f32_e32 v38, v38
	v_exp_f32_e32 v39, v39
	v_exp_f32_e32 v40, v40
	v_exp_f32_e32 v41, v41
	v_exp_f32_e32 v42, v42
	v_exp_f32_e32 v43, v43
	v_exp_f32_e32 v44, v44
	v_mfma_f32_32x32x16_bf16 v[80:95], v[158:161], v[162:165], v[80:95]
	ds_read_b128 v[154:157], v149 offset:32768
	ds_read_b128 v[158:161], v149 offset:36864
	ds_read_b128 v[162:165], v148 offset:49152
	ds_read_b128 v[166:169], v148 offset:53248
	v_exp_f32_e32 v45, v45
	v_exp_f32_e32 v46, v46
	v_exp_f32_e32 v47, v47
	v_add_f32_e32 v34, 1.0, v34
	v_add_f32_e32 v35, 1.0, v35
	v_add_f32_e32 v36, 1.0, v36
	s_waitcnt lgkmcnt(0)
	v_mfma_f32_32x32x16_bf16 v[0:15], v[154:157], v[162:165], v[0:15]
	v_add_f32_e32 v37, 1.0, v37
	v_add_f32_e32 v38, 1.0, v38
	v_add_f32_e32 v39, 1.0, v39
	v_add_f32_e32 v40, 1.0, v40
	v_add_f32_e32 v41, 1.0, v41
	v_add_f32_e32 v42, 1.0, v42
	v_add_f32_e32 v43, 1.0, v43
	v_mfma_f32_32x32x16_bf16 v[64:79], v[158:161], v[166:169], v[64:79]
	v_add_f32_e32 v44, 1.0, v44
	v_add_f32_e32 v45, 1.0, v45
	v_add_f32_e32 v46, 1.0, v46
	v_add_f32_e32 v47, 1.0, v47
	v_rcp_f32_e32 v34, v34
	v_rcp_f32_e32 v35, v35
	v_rcp_f32_e32 v36, v36
	v_mfma_f32_32x32x16_bf16 v[16:31], v[154:157], v[166:169], v[16:31]
	v_rcp_f32_e32 v37, v37
	v_rcp_f32_e32 v38, v38
	v_rcp_f32_e32 v39, v39
	v_rcp_f32_e32 v40, v40
	v_rcp_f32_e32 v41, v41
	v_rcp_f32_e32 v42, v42
	v_rcp_f32_e32 v43, v43
	v_mfma_f32_32x32x16_bf16 v[80:95], v[158:161], v[162:165], v[80:95]
	ds_read_b128 v[154:157], v151 offset:32768
	ds_read_b128 v[158:161], v151 offset:36864
	ds_read_b128 v[162:165], v150 offset:49152
	ds_read_b128 v[166:169], v150 offset:53248
	v_rcp_f32_e32 v44, v44
	v_rcp_f32_e32 v45, v45
	v_rcp_f32_e32 v46, v46
	v_rcp_f32_e32 v47, v47
	s_waitcnt lgkmcnt(0)
	v_mfma_f32_32x32x16_bf16 v[0:15], v[154:157], v[162:165], v[0:15]
	v_mfma_f32_32x32x16_bf16 v[64:79], v[158:161], v[166:169], v[64:79]
	v_mfma_f32_32x32x16_bf16 v[16:31], v[154:157], v[166:169], v[16:31]
	v_mfma_f32_32x32x16_bf16 v[80:95], v[158:161], v[162:165], v[80:95]
	ds_read_b128 v[154:157], v153 offset:32768
	ds_read_b128 v[158:161], v153 offset:36864
	ds_read_b128 v[162:165], v152 offset:49152
	ds_read_b128 v[166:169], v152 offset:53248
	s_waitcnt vmcnt(0)
	s_waitcnt vmcnt(0) lgkmcnt(0)
	s_barrier
; #define MFMA(a, b, c) __builtin_amdgcn_mfma_f32_32x32x16_bf16(a, b, c, 0, 0, 0)
; #define ISSUE(k0, bf) do { char* A_ = lw + (bf) * BUF; \
;     _Pragma("unroll") for (int i_ = 0; i_ < 4; ++i_) { glds16(al.ptr(lrow + 32 * i_, (k0) + cg), A_ + i_ * 4096); glds16(bl.ptr(lrow + 32 * i_, (k0) + cg), A_ + ABYTES + i_ * 4096); } \
;     if (HALO) { if (wid == 0) glds16(gh + (k0), A_ + 16384); } } while (0)
; template <bool HALO, class AL, class BL>
; __device__ __forceinline__ void gemm_core(f32x16 (&acc)[2][2], f32x16& hacc, const AL& al, const BL& bl, int K, char* lds,
;                                           const u16* halo0, const u16* halo1, int brow0, int brow1) {
;     ...
;   for (int kt = 0; kt < nk; ++kt) {
;     asm volatile("s_waitcnt vmcnt(0)" ::: "memory");
;     __syncthreads();
;     if (kt + 1 < nk) ISSUE((kt + 1) * 64, (kt + 1) & 1);
;     const char* T = lds + (kt & 1) * BUF;
; #pragma unroll
;     for (int kk = 0; kk < 4; ++kk) {
;       const int c = kk * 2 + hi;
;       bf16x8 a0 = *(const bf16x8*)(T + oa + ((c ^ sa) << 4));
;       bf16x8 a1 = *(const bf16x8*)(T + oa + 4096 + ((c ^ sa) << 4));
;       bf16x8 b0 = *(const bf16x8*)(T + ob0 + ((c ^ sb0) << 4));
;       bf16x8 b1 = *(const bf16x8*)(T + ob1 + ((c ^ sb1) << 4));
;       acc[0][0] = MFMA(a0, b0, acc[0][0]); acc[0][1] = MFMA(a0, b1, acc[0][1]);
;       acc[1][0] = MFMA(a1, b0, acc[1][0]); acc[1][1] = MFMA(a1, b1, acc[1][1]);
; __device__ __forceinline__ void phase_ffn_down(const P& p, int layer, char* lds) {
;     ...
;     { LdBf al{pb + (long)tm * 128 * 256, 256}; LdBf bl{wp + (long)tn * 128 * 256, 256}; gemm_plain(acc2, al, bl, 256, lds); }
; #pragma unroll
;     for (int mi = 0; mi < 2; ++mi)
; #pragma unroll
;       for (int ni = 0; ni < 2; ++ni) acc[mi][ni] = acc[mi][ni] * acc2[mi][ni];
;     { LdBf al{ab + (long)tm * 128 * DFF, DFF}, bl{wd + (long)tn * 128 * DFF, DFF}; gemm_plain(acc, al, bl, DFF, lds); }
	global_load_lds_dwordx4 v[130:131], off
	s_mov_b32 m0, s6
	v_mfma_f32_32x32x16_bf16 v[0:15], v[154:157], v[162:165], v[0:15]
	global_load_lds_dwordx4 v[128:129], off
	v_lshl_add_u64 v[128:129], v[132:133], 0, s[74:75]
	s_mov_b32 m0, s7
	s_add_u32 s6, s53, s3
	global_load_lds_dwordx4 v[128:129], off
	v_lshl_add_u64 v[128:129], v[134:135], 0, s[74:75]
	s_mov_b32 m0, s8
	v_mfma_f32_32x32x16_bf16 v[64:79], v[158:161], v[166:169], v[64:79]
	global_load_lds_dwordx4 v[128:129], off
	v_lshl_add_u64 v[128:129], v[136:137], 0, s[74:75]
	s_mov_b32 m0, s18
	s_addc_u32 s7, s95, 0
	global_load_lds_dwordx4 v[128:129], off
	v_lshl_add_u64 v[128:129], v[138:139], 0, s[74:75]
	s_mov_b32 m0, s19
	v_mfma_f32_32x32x16_bf16 v[16:31], v[154:157], v[166:169], v[16:31]
	global_load_lds_dwordx4 v[128:129], off
	v_lshl_add_u64 v[128:129], v[140:141], 0, s[74:75]
	s_mov_b32 m0, s33
	s_mul_i32 s8, s62, 0xb0000
	global_load_lds_dwordx4 v[128:129], off
	v_lshl_add_u64 v[128:129], v[142:143], 0, s[74:75]
	s_mov_b32 m0, s63
	v_mfma_f32_32x32x16_bf16 v[80:95], v[158:161], v[162:165], v[80:95]
	global_load_lds_dwordx4 v[128:129], off
	ds_read_b128 v[128:131], v147
	ds_read_b128 v[132:135], v147 offset:4096
	ds_read_b128 v[136:139], v146 offset:16384
	ds_read_b128 v[140:143], v146 offset:20480
	s_mul_hi_i32 s3, s62, 0xb0000
	s_add_u32 s18, vcc_hi, s8
	v_readlane_b32 s8, v255, 15
	s_addc_u32 s19, s8, s3
	s_waitcnt lgkmcnt(0)
	v_mfma_f32_32x32x16_bf16 v[0:15], v[128:131], v[136:139], v[0:15]
	v_mfma_f32_32x32x16_bf16 v[64:79], v[132:135], v[140:143], v[64:79]
	v_mfma_f32_32x32x16_bf16 v[16:31], v[128:131], v[140:143], v[16:31]
	v_mfma_f32_32x32x16_bf16 v[80:95], v[132:135], v[136:139], v[80:95]
	ds_read_b128 v[128:131], v149
	ds_read_b128 v[132:135], v149 offset:4096
	ds_read_b128 v[136:139], v148 offset:16384
	ds_read_b128 v[140:143], v148 offset:20480
	s_waitcnt lgkmcnt(0)
	v_mfma_f32_32x32x16_bf16 v[0:15], v[128:131], v[136:139], v[0:15]
	v_mfma_f32_32x32x16_bf16 v[64:79], v[132:135], v[140:143], v[64:79]
	v_mfma_f32_32x32x16_bf16 v[16:31], v[128:131], v[140:143], v[16:31]
	v_mfma_f32_32x32x16_bf16 v[80:95], v[132:135], v[136:139], v[80:95]
	ds_read_b128 v[128:131], v151
	ds_read_b128 v[132:135], v151 offset:4096
	ds_read_b128 v[136:139], v150 offset:16384
	ds_read_b128 v[140:143], v150 offset:20480
	s_waitcnt lgkmcnt(0)
	v_mfma_f32_32x32x16_bf16 v[0:15], v[128:131], v[136:139], v[0:15]
	v_mfma_f32_32x32x16_bf16 v[64:79], v[132:135], v[140:143], v[64:79]
	v_mfma_f32_32x32x16_bf16 v[16:31], v[128:131], v[140:143], v[16:31]
	v_mfma_f32_32x32x16_bf16 v[80:95], v[132:135], v[136:139], v[80:95]
	ds_read_b128 v[128:131], v153
	ds_read_b128 v[132:135], v153 offset:4096
	ds_read_b128 v[136:139], v152 offset:16384
	ds_read_b128 v[140:143], v152 offset:20480
	s_waitcnt vmcnt(0)
	s_waitcnt vmcnt(0) lgkmcnt(0)
	s_barrier
	v_mfma_f32_32x32x16_bf16 v[0:15], v[128:131], v[136:139], v[0:15]
	v_mfma_f32_32x32x16_bf16 v[64:79], v[132:135], v[140:143], v[64:79]
	v_mfma_f32_32x32x16_bf16 v[16:31], v[128:131], v[140:143], v[16:31]
	v_mfma_f32_32x32x16_bf16 v[80:95], v[132:135], v[136:139], v[80:95]
	ds_read_b128 v[128:131], v147 offset:32768
	ds_read_b128 v[132:135], v147 offset:36864
	ds_read_b128 v[136:139], v146 offset:49152
	ds_read_b128 v[140:143], v146 offset:53248
	s_waitcnt lgkmcnt(1)
	v_mfma_f32_32x32x16_bf16 v[0:15], v[128:131], v[136:139], v[0:15]
	s_waitcnt lgkmcnt(0)
	v_mfma_f32_32x32x16_bf16 v[64:79], v[132:135], v[140:143], v[64:79]
	v_mfma_f32_32x32x16_bf16 v[16:31], v[128:131], v[140:143], v[16:31]
	v_mfma_f32_32x32x16_bf16 v[80:95], v[132:135], v[136:139], v[80:95]
	ds_read_b128 v[128:131], v149 offset:32768
	ds_read_b128 v[132:135], v149 offset:36864
	ds_read_b128 v[136:139], v148 offset:49152
	ds_read_b128 v[140:143], v148 offset:53248
	s_waitcnt lgkmcnt(1)
	v_mfma_f32_32x32x16_bf16 v[0:15], v[128:131], v[136:139], v[0:15]
	s_waitcnt lgkmcnt(0)
	v_mfma_f32_32x32x16_bf16 v[64:79], v[132:135], v[140:143], v[64:79]
	v_mfma_f32_32x32x16_bf16 v[16:31], v[128:131], v[140:143], v[16:31]
	v_mfma_f32_32x32x16_bf16 v[80:95], v[132:135], v[136:139], v[80:95]
	ds_read_b128 v[128:131], v151 offset:32768
	ds_read_b128 v[132:135], v151 offset:36864
	ds_read_b128 v[136:139], v150 offset:49152
	ds_read_b128 v[140:143], v150 offset:53248
	s_waitcnt lgkmcnt(1)
	v_mfma_f32_32x32x16_bf16 v[0:15], v[128:131], v[136:139], v[0:15]
	s_waitcnt lgkmcnt(0)
	v_mfma_f32_32x32x16_bf16 v[64:79], v[132:135], v[140:143], v[64:79]
	v_mfma_f32_32x32x16_bf16 v[16:31], v[128:131], v[140:143], v[16:31]
	v_mfma_f32_32x32x16_bf16 v[80:95], v[132:135], v[136:139], v[80:95]
	ds_read_b128 v[128:131], v153 offset:32768
	ds_read_b128 v[132:135], v153 offset:36864
	ds_read_b128 v[136:139], v152 offset:49152
	ds_read_b128 v[140:143], v152 offset:53248
	s_waitcnt lgkmcnt(1)
	v_mfma_f32_32x32x16_bf16 v[0:15], v[128:131], v[136:139], v[0:15]
	s_waitcnt lgkmcnt(0)
	v_mfma_f32_32x32x16_bf16 v[64:79], v[132:135], v[140:143], v[64:79]
	s_nop 9
	v_mul_f32_e64 v58, v58, v10
	v_mul_f32_e64 v59, v59, v11
	v_mul_f32_e64 v48, v48, v0
	v_mul_f32_e64 v49, v49, v1
	v_mul_f32_e64 v60, v60, v12
	v_mul_f32_e64 v61, v61, v13
	v_pk_mul_f32 v[56:57], v[56:57], v[8:9]
	v_pk_mul_f32 v[54:55], v[54:55], v[6:7]
	v_pk_mul_f32 v[52:53], v[52:53], v[4:5]
	v_pk_mul_f32 v[50:51], v[50:51], v[2:3]
	v_mfma_f32_32x32x16_bf16 v[16:31], v[128:131], v[140:143], v[16:31]
	v_mul_f32_e64 v10, v122, v74
	v_mul_f32_e64 v11, v123, v75
	v_mul_f32_e64 v0, v110, v64
	v_mul_f32_e64 v1, v111, v65
	v_mov_b32_e32 v64, v229
	v_mov_b32_e32 v75, v229
	v_pk_mul_f32 v[12:13], v[124:125], v[76:77]
	v_pk_mul_f32 v[8:9], v[120:121], v[72:73]
	v_mfma_f32_32x32x16_bf16 v[80:95], v[132:135], v[136:139], v[80:95]
	v_mul_f32_e64 v6, v118, v70
	v_mul_f32_e64 v7, v119, v71
	v_and_b32_e32 v72, 31, v75
	v_lshrrev_b32_e32 v77, 4, v75
	v_xor_b32_e32 v70, v77, v75
	v_and_or_b32 v64, v64, 64, v72
	v_pk_mul_f32 v[4:5], v[116:117], v[68:69]
	v_ashrrev_i32_e32 v76, 3, v75
	v_lshl_add_u32 v69, v75, 4, 0
	v_lshlrev_b32_e32 v68, 7, v64
	v_mov_b64_e32 v[64:65], s[6:7]
	v_lshlrev_b32_e32 v70, 4, v70
	v_pk_mul_f32 v[2:3], v[114:115], v[66:67]
	v_mad_i64_i32 v[66:67], s[6:7], v76, s9, v[64:65]
	v_and_b32_e32 v200, 0x70, v70
	v_readfirstlane_b32 s3, v69
	v_lshl_add_u64 v[66:67], v[66:67], 0, v[200:201]
	s_mov_b32 m0, s3
	v_pk_mul_f32 v[62:63], v[62:63], v[14:15]
	v_pk_mul_f32 v[14:15], v[126:127], v[78:79]
	s_barrier
; #define ISSUE(k0, bf) do { char* A_ = lw + (bf) * BUF; \
;     _Pragma("unroll") for (int i_ = 0; i_ < 4; ++i_) { glds16(al.ptr(lrow + 32 * i_, (k0) + cg), A_ + i_ * 4096); glds16(bl.ptr(lrow + 32 * i_, (k0) + cg), A_ + ABYTES + i_ * 4096); } \
;     if (HALO) { if (wid == 0) glds16(gh + (k0), A_ + 16384); } } while (0)
; template <bool HALO, class AL, class BL>
; __device__ __forceinline__ void gemm_core(f32x16 (&acc)[2][2], f32x16& hacc, const AL& al, const BL& bl, int K, char* lds,
;                                           const u16* halo0, const u16* halo1, int brow0, int brow1) {
;     ...
;   const int sa = ((wr * 64 + r32) >> 1) & 7, sb0 = ((brow0 + r32) >> 1) & 7, sb1 = ((brow1 + r32) >> 1) & 7, sh = (r32 >> 1) & 7;
;   const int oa = (wr * 64 + r32) * 128, ob0 = ABYTES + (brow0 + r32) * 128, ob1 = ABYTES + (brow1 + r32) * 128, oh = (128 + r32) * 128;
;   __syncthreads();
;   ISSUE(0, 0);
; __device__ __forceinline__ void phase_ffn_down(const P& p, int layer, char* lds) {
;     ...
;     { LdBf al{pb + (long)tm * 128 * 256, 256}; LdBf bl{wp + (long)tn * 128 * 256, 256}; gemm_plain(acc2, al, bl, 256, lds); }
; #pragma unroll
;     for (int mi = 0; mi < 2; ++mi)
; #pragma unroll
;       for (int ni = 0; ni < 2; ++ni) acc[mi][ni] = acc[mi][ni] * acc2[mi][ni];
;     { LdBf al{ab + (long)tm * 128 * DFF, DFF}, bl{wd + (long)tn * 128 * DFF, DFF}; gemm_plain(acc, al, bl, DFF, lds); }
	v_add_u32_e32 v79, 0x4000, v69
	global_load_lds_dwordx4 v[66:67], off
	v_mov_b64_e32 v[66:67], s[18:19]
	v_mad_i64_i32 v[70:71], s[6:7], v76, s9, v[66:67]
	v_readfirstlane_b32 s3, v79
	v_pk_mul_f32 v[32:33], v[32:33], v[16:17]
	v_pk_mul_f32 v[16:17], v[96:97], v[80:81]
	v_lshl_add_u64 v[70:71], v[70:71], 0, v[200:201]
	s_mov_b32 m0, s3
	v_add_u32_e32 v79, 32, v76
	v_add_u32_e32 v80, 0x1000, v69
	global_load_lds_dwordx4 v[70:71], off
	v_mad_i64_i32 v[70:71], s[6:7], v79, s9, v[64:65]
	v_readfirstlane_b32 s3, v80
	v_lshl_add_u64 v[70:71], v[70:71], 0, v[200:201]
	s_mov_b32 m0, s3
	v_add_u32_e32 v80, 0x2000, v69
	global_load_lds_dwordx4 v[70:71], off
	v_mad_i64_i32 v[70:71], s[6:7], v79, s9, v[66:67]
	v_add_u32_e32 v79, 0x5000, v69
	v_lshl_add_u64 v[70:71], v[70:71], 0, v[200:201]
	v_readfirstlane_b32 s3, v79
	s_mov_b32 m0, s3
	v_add_u32_e32 v79, 64, v76
	global_load_lds_dwordx4 v[70:71], off
	v_mad_i64_i32 v[70:71], s[6:7], v79, s9, v[64:65]
	v_readfirstlane_b32 s3, v80
	v_lshl_add_u64 v[70:71], v[70:71], 0, v[200:201]
	s_mov_b32 m0, s3
	v_lshrrev_b32_e32 v74, 1, v75
	global_load_lds_dwordx4 v[70:71], off
	v_mad_i64_i32 v[70:71], s[6:7], v79, s9, v[66:67]
	v_add_u32_e32 v79, 0x6000, v69
	v_lshl_add_u64 v[70:71], v[70:71], 0, v[200:201]
	v_readfirstlane_b32 s3, v79
	s_mov_b32 m0, s3
	v_lshrrev_b32_e32 v73, 5, v75
	global_load_lds_dwordx4 v[70:71], off
	v_add_u32_e32 v70, 0x60, v76
	v_add_u32_e32 v71, 0x3000, v69
	v_mad_i64_i32 v[64:65], s[6:7], v70, s9, v[64:65]
	v_readfirstlane_b32 s3, v71
	v_lshl_add_u64 v[64:65], v[64:65], 0, v[200:201]
	s_mov_b32 m0, s3
	v_bfe_u32 v78, v75, 1, 3
	global_load_lds_dwordx4 v[64:65], off
	v_mad_i64_i32 v[64:65], s[6:7], v70, s9, v[66:67]
	v_add_u32_e32 v66, 0x7000, v69
	v_lshl_add_u64 v[64:65], v[64:65], 0, v[200:201]
	v_readfirstlane_b32 s3, v66
	s_mov_b32 m0, s3
	s_add_i32 s3, vcc_lo, s80
	global_load_lds_dwordx4 v[64:65], off
	v_and_or_b32 v65, v74, s52, v72
	v_bfe_u32 v64, v75, 5, 1
	v_lshlrev_b32_e32 v74, 7, v65
	v_bitop3_b32 v65, v73, v78, 1 bitop3:0x6c
	v_lshlrev_b32_e32 v73, 4, v65
	v_bitop3_b32 v65, v64, v78, 2 bitop3:0x36
	v_lshlrev_b32_e32 v72, 4, v65
	v_bitop3_b32 v65, v64, v78, 4 bitop3:0x36
	v_bitop3_b32 v64, v64, v78, 6 bitop3:0x36
	s_bfe_u32 s3, s3, 0x50006
	v_lshlrev_b32_e32 v70, 4, v64
	v_mad_i64_i32 v[66:67], s[6:7], v76, s9, 0
	v_mov_b32_e32 v64, 0xb0000
	s_mul_i32 s3, s3, 0x580000
	v_lshlrev_b32_e32 v71, 4, v65
	v_mad_i64_i32 v[64:65], s[6:7], s62, v64, v[66:67]
	v_bitop3_b32 v75, v77, 7, v75 bitop3:0x48
	s_add_i32 s3, s3, s81
	v_lshlrev_b32_e32 v75, 4, v75
	s_add_u32 s6, s50, s3
	v_or_b32_e32 v64, v64, v75
	v_or_b32_e32 v66, v66, v75
	s_addc_u32 s7, s51, 0
	v_pk_mul_f32 v[46:47], v[46:47], v[30:31]
	v_pk_mul_f32 v[44:45], v[44:45], v[28:29]
	v_pk_mul_f32 v[42:43], v[42:43], v[26:27]
	v_pk_mul_f32 v[40:41], v[40:41], v[24:25]
	v_pk_mul_f32 v[38:39], v[38:39], v[22:23]
	v_pk_mul_f32 v[36:37], v[36:37], v[20:21]
	v_pk_mul_f32 v[34:35], v[34:35], v[18:19]
	v_pk_mul_f32 v[30:31], v[112:113], v[94:95]
	v_pk_mul_f32 v[28:29], v[108:109], v[92:93]
	v_pk_mul_f32 v[26:27], v[106:107], v[90:91]
	v_pk_mul_f32 v[24:25], v[104:105], v[88:89]
	v_pk_mul_f32 v[22:23], v[102:103], v[86:87]
	v_pk_mul_f32 v[20:21], v[100:101], v[84:85]
	v_pk_mul_f32 v[18:19], v[98:99], v[82:83]
	v_lshl_add_u64 v[64:65], s[54:55], 0, v[64:65]
	v_lshl_add_u64 v[66:67], s[6:7], 0, v[66:67]
	s_mov_b64 s[80:81], 0
	s_mov_b32 s6, 0

; __device__ __forceinline__ int ltid() { int t = (int)threadIdx.x; asm volatile("" : "+v"(t)); return t; }
; #define ISSUE(k0, bf) do { char* A_ = lw + (bf) * BUF; \
;     _Pragma("unroll") for (int i_ = 0; i_ < 4; ++i_) { glds16(al.ptr(lrow + 32 * i_, (k0) + cg), A_ + i_ * 4096); glds16(bl.ptr(lrow + 32 * i_, (k0) + cg), A_ + ABYTES + i_ * 4096); } \
;     if (HALO) { if (wid == 0) glds16(gh + (k0), A_ + 16384); } } while (0)
; template <bool HALO, class AL, class BL>
; __device__ __forceinline__ void gemm_core(f32x16 (&acc)[2][2], f32x16& hacc, const AL& al, const BL& bl, int K, char* lds,
;                                           const u16* halo0, const u16* halo1, int brow0, int brow1) {
;   constexpr int ABYTES = HALO ? 136 * 128 : 128 * 128, BUF = ABYTES + 16384;
;   const int tid = ltid(), lane = tid & 63, wid = tid >> 6, wr = wid >> 1, r32 = lane & 31, hi = lane >> 5;
;   const int lrow = tid >> 3, cg = ((tid & 7) ^ ((lrow >> 1) & 7)) * 8;
;   const u16* gh = nullptr;
;   if (HALO) { const int c = ((lane & 7) ^ ((lane >> 4) & 7)) * 8; gh = ((lane < 8) ? halo0 : halo1) + c; }
;   char* lw = lds + tid * 16;
;     ...
;   const int sa = ((wr * 64 + r32) >> 1) & 7, sb0 = ((brow0 + r32) >> 1) & 7, sb1 = ((brow1 + r32) >> 1) & 7, sh = (r32 >> 1) & 7;
;   const int oa = (wr * 64 + r32) * 128, ob0 = ABYTES + (brow0 + r32) * 128, ob1 = ABYTES + (brow1 + r32) * 128, oh = (128 + r32) * 128;
;   __syncthreads();
;   ISSUE(0, 0);
; __device__ __forceinline__ void phase_ffn_up(const P& p, int layer, char* lds) {
;     ...
;   for (int it = 0; tile_at(it, 256, 44, tm, tn); ++it) {
;     f32x16 acc[2][2] = {}; f32x16 hacc = {};
;     const long r0 = (long)tm * 128;
;     const bool top0 = (r0 % SEQ) == 0, bot0 = ((r0 + 128) % SEQ) == 0;
;     LdBf al{xb + r0 * DM, DM}; LdBsplit bl{wt, DM, tn * 64};
;     const u16* zr = (const u16*)(p.ws + OFF_ZERO);
;     const u16* h0 = top0 ? zr : xb + (r0 - 1) * DM; const u16* h1 = bot0 ? zr : xb + (r0 + 128) * DM;
;     gemm_core<true>(acc, hacc, al, bl, DM, lds, h0, h1, wc * 32, 64 + wc * 32);
.LBB0_166:
	v_readlane_b32 s7, v254, 55
	s_add_i32 s7, s6, s7
	s_mul_hi_u32 s8, s7, 0xba2e8ba3
	s_lshr_b32 s8, s8, 8
	s_lshl_b32 s42, s8, 3
	s_and_b32 s6, s6, 7
	s_mulk_i32 s8, 0xfea0
	s_or_b32 s92, s42, s6
	s_add_i32 s8, s8, s7
	s_lshl_b64 s[6:7], s[92:93], 7
	s_and_b32 s64, s92, 63
	v_mov_b32_e32 v0, v229
	s_add_u32 s84, s6, 0x80
	s_addc_u32 s85, s7, 0
	v_lshrrev_b32_e32 v1, 4, v0
	s_and_b32 s72, s84, 0x1f80
	s_lshl_b64 s[6:7], s[92:93], 18
	v_xor_b32_e32 v1, v1, v0
	v_lshl_add_u32 v102, v0, 4, 0
	s_add_u32 s6, s69, s6
	v_ashrrev_i32_e32 v2, 3, v0
	v_lshlrev_b32_e32 v1, 4, v1
	v_readfirstlane_b32 s42, v102
	s_addc_u32 s7, s3, s7
	s_lshl_b32 s8, s8, 3
	v_and_b32_e32 v200, 0x70, v1
	v_ashrrev_i32_e32 v3, 31, v2
	s_mov_b32 m0, s42
	v_add_u32_e32 v1, 0xac0, v2
	v_cmp_gt_i32_e64 s[42:43], 64, v2
	s_andn2_b32 s8, s8, 63
	v_lshl_add_u64 v[4:5], s[6:7], 0, v[200:201]
	v_lshlrev_b64 v[6:7], 11, v[2:3]
	v_cndmask_b32_e64 v1, v1, v2, s[42:43]
	v_lshl_add_u64 v[82:83], v[4:5], 0, v[6:7]
	v_add_u32_e32 v6, s8, v1
	v_ashrrev_i32_e32 v7, 31, v6
	v_add_u32_e32 v123, 0x4400, v102
	v_lshlrev_b64 v[6:7], 11, v[6:7]
	v_lshl_add_u64 v[6:7], s[80:81], 0, v[6:7]
	v_readfirstlane_b32 s42, v123
	v_add_u32_e32 v124, 0x1000, v102
	s_waitcnt lgkmcnt(0)
	s_barrier
	global_load_lds_dwordx4 v[82:83], off
	v_lshl_add_u64 v[84:85], v[6:7], 0, v[200:201]
	s_mov_b32 m0, s42
	v_readfirstlane_b32 s42, v124
	global_load_lds_dwordx4 v[84:85], off
	v_add_u32_e32 v6, 32, v2
	s_mov_b32 m0, s42
	v_add_u32_e32 v1, 0xae0, v2
	v_cmp_gt_i32_e64 s[42:43], 32, v2
	v_ashrrev_i32_e32 v7, 31, v6
	s_waitcnt vmcnt(2)
	v_lshlrev_b64 v[8:9], 11, v[6:7]
	v_cndmask_b32_e64 v1, v1, v6, s[42:43]
	v_add_u32_e32 v6, s8, v1
	v_ashrrev_i32_e32 v7, 31, v6
	v_lshlrev_b64 v[6:7], 11, v[6:7]
	v_add_u32_e32 v125, 0x5400, v102
	v_lshl_add_u64 v[86:87], v[4:5], 0, v[8:9]
	v_lshl_add_u64 v[6:7], s[80:81], 0, v[6:7]
	v_readfirstlane_b32 s42, v125
	v_add_u32_e32 v126, 0x2000, v102
	global_load_lds_dwordx4 v[86:87], off
	v_lshl_add_u64 v[88:89], v[6:7], 0, v[200:201]
	s_mov_b32 m0, s42
	v_readfirstlane_b32 s42, v126
	global_load_lds_dwordx4 v[88:89], off
	v_add_u32_e32 v6, 64, v2
	s_mov_b32 m0, s42
	v_add_u32_e32 v1, 0xb00, v2
	v_cmp_gt_i32_e64 s[42:43], 0, v2
	v_ashrrev_i32_e32 v7, 31, v6
	v_lshlrev_b64 v[8:9], 11, v[6:7]
	v_cndmask_b32_e64 v1, v1, v6, s[42:43]
	v_add_u32_e32 v6, s8, v1
	v_ashrrev_i32_e32 v7, 31, v6
	v_lshlrev_b64 v[6:7], 11, v[6:7]
	v_add_u32_e32 v127, 0x6400, v102
	v_lshl_add_u64 v[90:91], v[4:5], 0, v[8:9]
	v_lshl_add_u64 v[6:7], s[80:81], 0, v[6:7]
	v_readfirstlane_b32 s42, v127
	v_add_u32_e32 v128, 0x3000, v102
	global_load_lds_dwordx4 v[90:91], off
	v_lshl_add_u64 v[92:93], v[6:7], 0, v[200:201]
	s_mov_b32 m0, s42
	v_readfirstlane_b32 s42, v128
	global_load_lds_dwordx4 v[92:93], off
	s_mov_b32 m0, s42
	s_movk_i32 s42, 0xffe0
	v_add_u32_e32 v6, 0x60, v2
	v_add_u32_e32 v1, 0xb20, v2
	v_cmp_gt_i32_e64 s[42:43], s42, v2
	v_ashrrev_i32_e32 v7, 31, v6
	v_lshlrev_b64 v[8:9], 11, v[6:7]
	v_cndmask_b32_e64 v1, v1, v6, s[42:43]
	v_add_u32_e32 v2, s8, v1
	v_ashrrev_i32_e32 v3, 31, v2
	v_lshlrev_b64 v[2:3], 11, v[2:3]
	v_add_u32_e32 v129, 0x7400, v102
	v_lshl_add_u64 v[94:95], v[4:5], 0, v[8:9]
	v_lshl_add_u64 v[2:3], s[80:81], 0, v[2:3]
	v_readfirstlane_b32 s42, v129
	global_load_lds_dwordx4 v[94:95], off
	v_lshl_add_u64 v[96:97], v[2:3], 0, v[200:201]
	s_mov_b32 m0, s42
	s_add_u32 s6, s6, 0xfffff800
	global_load_lds_dwordx4 v[96:97], off
	s_addc_u32 s7, s7, -1
	s_cmp_eq_u32 s64, 0
	s_cselect_b32 s64, s40, s6
	s_cselect_b32 s42, s41, s7
	s_lshl_b64 s[6:7], s[84:85], 11
	s_add_u32 s6, s69, s6
	s_mov_b32 s73, s93
	s_addc_u32 s7, s3, s7
	s_cmp_eq_u64 s[72:73], 0
	s_cselect_b32 s7, s41, s7
	v_and_b32_e32 v1, 63, v0
	v_bfe_u32 v2, v0, 4, 2
	s_cselect_b32 s6, s40, s6
	v_bitop3_b32 v4, v2, v0, 7 bitop3:0x78
	v_mov_b32_e32 v2, s7
	v_mov_b32_e32 v3, s42
	v_cmp_gt_u32_e64 s[42:43], 8, v1
	v_mov_b32_e32 v5, s64
	v_lshlrev_b32_e32 v200, 4, v4
	v_cndmask_b32_e64 v3, v2, v3, s[42:43]
	v_mov_b32_e32 v2, s6
	v_cndmask_b32_e64 v2, v2, v5, s[42:43]
	v_lshl_add_u64 v[98:99], v[2:3], 0, v[200:201]
	v_cmp_gt_u32_e64 s[42:43], 64, v0
	s_and_saveexec_b64 s[6:7], s[42:43]
	s_cbranch_execz .LBB0_168
	v_add_u32_e32 v2, 0x4000, v102
	s_nop 0
	v_readfirstlane_b32 s64, v2
	s_mov_b32 m0, s64
	s_nop 0
	global_load_lds_dwordx4 v[98:99], off

; #define MFMA(a, b, c) __builtin_amdgcn_mfma_f32_32x32x16_bf16(a, b, c, 0, 0, 0)
; #define ISSUE(k0, bf) do { char* A_ = lw + (bf) * BUF; \
;     _Pragma("unroll") for (int i_ = 0; i_ < 4; ++i_) { glds16(al.ptr(lrow + 32 * i_, (k0) + cg), A_ + i_ * 4096); glds16(bl.ptr(lrow + 32 * i_, (k0) + cg), A_ + ABYTES + i_ * 4096); } \
;     if (HALO) { if (wid == 0) glds16(gh + (k0), A_ + 16384); } } while (0)
; template <bool HALO, class AL, class BL>
; __device__ __forceinline__ void gemm_core(f32x16 (&acc)[2][2], f32x16& hacc, const AL& al, const BL& bl, int K, char* lds,
;                                           const u16* halo0, const u16* halo1, int brow0, int brow1) {
;     ...
;   const int sa = ((wr * 64 + r32) >> 1) & 7, sb0 = ((brow0 + r32) >> 1) & 7, sb1 = ((brow1 + r32) >> 1) & 7, sh = (r32 >> 1) & 7;
;   const int oa = (wr * 64 + r32) * 128, ob0 = ABYTES + (brow0 + r32) * 128, ob1 = ABYTES + (brow1 + r32) * 128, oh = (128 + r32) * 128;
;   __syncthreads();
;   ISSUE(0, 0);
;   const int nk = K >> 6;
;   for (int kt = 0; kt < nk; ++kt) {
;     asm volatile("s_waitcnt vmcnt(0)" ::: "memory");
;     __syncthreads();
;     if (kt + 1 < nk) ISSUE((kt + 1) * 64, (kt + 1) & 1);
;     const char* T = lds + (kt & 1) * BUF;
; #pragma unroll
;     for (int kk = 0; kk < 4; ++kk) {
;       const int c = kk * 2 + hi;
;       bf16x8 a0 = *(const bf16x8*)(T + oa + ((c ^ sa) << 4));
;       bf16x8 a1 = *(const bf16x8*)(T + oa + 4096 + ((c ^ sa) << 4));
;       bf16x8 b0 = *(const bf16x8*)(T + ob0 + ((c ^ sb0) << 4));
;       bf16x8 b1 = *(const bf16x8*)(T + ob1 + ((c ^ sb1) << 4));
;       acc[0][0] = MFMA(a0, b0, acc[0][0]); acc[0][1] = MFMA(a0, b1, acc[0][1]);
;       acc[1][0] = MFMA(a1, b0, acc[1][0]); acc[1][1] = MFMA(a1, b1, acc[1][1]);
; __device__ __forceinline__ void phase_wout(const P& p, int layer, char* lds) {
;     ...
;   for (int it = 0; tile_at(it, 256, 8, tm, tn); ++it) {
;     f32x16 acc[2][2] = {};
;     LdBf al{ym + (long)tm * 128 * 1024, 1024}, bl{wt + (long)tn * 128 * 1024, 1024};
;     gemm_plain(acc, al, bl, 1024, lds);
.LBB0_240:
	v_readlane_b32 s40, v253, 21
	s_or_b32 s40, s8, s40
	s_lshr_b32 s41, s40, 3
	s_and_b32 s41, s41, 0xf8
	s_lshl_b32 s60, s41, 3
	s_and_b32 s8, s8, 7
	s_sub_i32 s40, s40, s60
	s_or_b32 s8, s41, s8
	s_ashr_i32 s40, s40, 3
	s_lshl_b32 s41, s8, 18
	s_add_u32 s64, s3, s41
	v_mov_b32_e32 v1, v229
	v_mov_b32_e32 v6, v229
	s_addc_u32 s65, s6, 0
	s_ashr_i32 s41, s40, 31
	s_lshl_b64 s[60:61], s[40:41], 18
	v_and_b32_e32 v7, 31, v6
	v_ashrrev_i32_e32 v0, 3, v6
	v_lshrrev_b32_e32 v2, 4, v6
	v_xor_b32_e32 v4, v2, v6
	v_and_or_b32 v10, v1, 64, v7
	v_ashrrev_i32_e32 v1, 31, v0
	s_add_u32 s72, s7, s60
	v_lshlrev_b64 v[0:1], 11, v[0:1]
	v_lshlrev_b32_e32 v4, 4, v4
	s_addc_u32 s73, s18, s61
	v_lshl_add_u64 v[2:3], s[64:65], 0, v[0:1]
	v_and_b32_e32 v200, 0x70, v4
	v_lshl_add_u64 v[64:65], v[2:3], 0, v[200:201]
	v_lshl_add_u64 v[2:3], s[72:73], 0, v[0:1]
	s_mov_b64 s[60:61], 0x10000
	v_lshl_add_u32 v95, v6, 4, 0
	v_lshl_add_u64 v[66:67], v[2:3], 0, v[200:201]
	v_lshl_add_u64 v[2:3], v[0:1], 0, s[60:61]
	v_add_u32_e32 v99, 0x4000, v95
	v_readfirstlane_b32 s85, v95
	v_lshl_add_u64 v[4:5], s[64:65], 0, v[2:3]
	v_lshl_add_u64 v[2:3], s[72:73], 0, v[2:3]
	s_mov_b64 s[60:61], 0x20000
	s_mov_b32 m0, s85
	v_readfirstlane_b32 s92, v99
	v_add_u32_e32 v100, 0x1000, v95
	v_lshl_add_u64 v[70:71], v[2:3], 0, v[200:201]
	v_lshl_add_u64 v[2:3], v[0:1], 0, s[60:61]
	s_barrier
	global_load_lds_dwordx4 v[64:65], off
	s_mov_b32 m0, s92
	v_lshl_add_u64 v[68:69], v[4:5], 0, v[200:201]
	v_readfirstlane_b32 s70, v100
	v_add_u32_e32 v101, 0x5000, v95
	v_lshl_add_u64 v[4:5], s[64:65], 0, v[2:3]
	global_load_lds_dwordx4 v[66:67], off
	s_mov_b32 m0, s70
	v_readfirstlane_b32 s71, v101
	v_lshl_add_u64 v[72:73], v[4:5], 0, v[200:201]
	v_add_u32_e32 v4, 0x2000, v95
	v_lshl_add_u64 v[2:3], s[72:73], 0, v[2:3]
	s_mov_b64 s[80:81], 0x30000
	global_load_lds_dwordx4 v[68:69], off
	s_mov_b32 m0, s71
	v_readfirstlane_b32 s41, v4
	v_lshl_add_u64 v[74:75], v[2:3], 0, v[200:201]
	v_add_u32_e32 v2, 0x6000, v95
	v_lshl_add_u64 v[0:1], v[0:1], 0, s[80:81]
	v_lshrrev_b32_e32 v8, 5, v6
	v_bfe_u32 v11, v6, 1, 3
	global_load_lds_dwordx4 v[70:71], off
	s_mov_b32 m0, s41
	v_readfirstlane_b32 s60, v2
	v_lshl_add_u64 v[2:3], s[64:65], 0, v[0:1]
	v_add_u32_e32 v88, 0x3000, v95
	v_lshl_add_u64 v[0:1], s[72:73], 0, v[0:1]
	global_load_lds_dwordx4 v[72:73], off
	s_mov_b32 m0, s60
	v_readfirstlane_b32 s61, v88
	v_lshl_add_u64 v[78:79], v[0:1], 0, v[200:201]
	v_add_u32_e32 v89, 0x7000, v95
	v_bfe_u32 v0, v6, 5, 1
	v_bitop3_b32 v1, v8, v11, 1 bitop3:0x6c
	global_load_lds_dwordx4 v[74:75], off
	v_lshl_add_u64 v[76:77], v[2:3], 0, v[200:201]
	s_mov_b32 m0, s61
	v_readfirstlane_b32 s63, v89
	v_lshlrev_b32_e32 v8, 4, v1
	v_bitop3_b32 v1, v0, v11, 2 bitop3:0x36
	v_add_u32_e32 v91, 0x8000, v95
	global_load_lds_dwordx4 v[76:77], off
	s_mov_b32 m0, s63
	v_lshlrev_b32_e32 v82, 4, v1
	v_bitop3_b32 v1, v0, v11, 4 bitop3:0x36
	v_bitop3_b32 v0, v0, v11, 6 bitop3:0x36
	v_add_u32_e32 v90, 0xc000, v95
	v_readfirstlane_b32 s69, v91
	global_load_lds_dwordx4 v[78:79], off
	v_lshlrev_b32_e32 v114, 4, v1
	v_lshlrev_b32_e32 v118, 4, v0
	v_lshl_add_u64 v[0:1], v[64:65], 0, s[78:79]
	s_mov_b32 m0, s69
	v_readfirstlane_b32 s72, v90
	v_add_u32_e32 v92, 0x9000, v95
	s_waitcnt vmcnt(0)
	s_waitcnt vmcnt(0) lgkmcnt(0)
	s_barrier
	global_load_lds_dwordx4 v[0:1], off
	v_lshl_add_u64 v[0:1], v[66:67], 0, s[78:79]
	s_mov_b32 m0, s72
	v_readfirstlane_b32 s73, v92
	v_add_u32_e32 v93, 0xd000, v95
	global_load_lds_dwordx4 v[0:1], off
	v_lshl_add_u64 v[0:1], v[68:69], 0, s[78:79]
	s_mov_b32 m0, s73
	v_readfirstlane_b32 s80, v93
	v_add_u32_e32 v94, 0xa000, v95
	global_load_lds_dwordx4 v[0:1], off
	v_lshl_add_u64 v[0:1], v[70:71], 0, s[78:79]
	s_mov_b32 m0, s80
	v_readfirstlane_b32 s81, v94
	v_add_u32_e32 v96, 0xe000, v95
	global_load_lds_dwordx4 v[0:1], off
	v_lshl_add_u64 v[0:1], v[72:73], 0, s[78:79]
	s_mov_b32 m0, s81
	v_readfirstlane_b32 s82, v96
	v_add_u32_e32 v97, 0xb000, v95
	v_lshrrev_b32_e32 v9, 1, v6
	global_load_lds_dwordx4 v[0:1], off
	v_lshl_add_u64 v[0:1], v[74:75], 0, s[78:79]
	s_mov_b32 m0, s82
	v_readfirstlane_b32 s83, v97
	v_add_u32_e32 v98, 0xf000, v95
	v_and_or_b32 v2, v9, s52, v7
	global_load_lds_dwordx4 v[0:1], off
	v_lshl_add_u64 v[0:1], v[76:77], 0, s[78:79]
	s_mov_b32 m0, s83
	v_readfirstlane_b32 s84, v98
	global_load_lds_dwordx4 v[0:1], off
	v_lshl_add_u64 v[0:1], v[78:79], 0, s[78:79]
	s_mov_b32 m0, s84
	v_lshl_add_u32 v119, v2, 7, 0
	v_lshl_add_u32 v120, v10, 7, 0
	global_load_lds_dwordx4 v[0:1], off
	v_add_u32_e32 v80, v119, v8
	v_add_u32_e32 v81, v120, v8
	ds_read_b128 v[0:3], v80
	ds_read_b128 v[4:7], v80 offset:4096
	ds_read_b128 v[8:11], v81 offset:16384
	ds_read_b128 v[12:15], v81 offset:20480
	s_waitcnt lgkmcnt(0)
	v_mfma_f32_32x32x16_bf16 v[48:63], v[0:3], v[8:11], 0
	v_add_u32_e32 v83, v119, v82
	v_add_u32_e32 v82, v120, v82
	ds_read_b128 v[84:87], v83
	ds_read_b128 v[102:105], v83 offset:4096
	ds_read_b128 v[106:109], v82 offset:16384
	ds_read_b128 v[110:113], v82 offset:20480
	s_mov_b32 m0, s85
	v_readfirstlane_b32 s64, v88
	v_readfirstlane_b32 s65, v89
	v_mfma_f32_32x32x16_bf16 v[32:47], v[0:3], v[12:15], 0
	v_lshl_or_b32 v128, s40, 7, v127
	s_andn2_b64 vcc, exec, s[76:77]
	v_or_b32_e32 v136, 32, v128
	v_mfma_f32_32x32x16_bf16 v[16:31], v[4:7], v[8:11], 0
	v_mfma_f32_32x32x16_bf16 v[0:15], v[4:7], v[12:15], 0
	s_waitcnt lgkmcnt(0)
	v_mfma_f32_32x32x16_bf16 v[48:63], v[84:87], v[106:109], v[48:63]
	v_mfma_f32_32x32x16_bf16 v[32:47], v[84:87], v[110:113], v[32:47]
	v_add_u32_e32 v87, v119, v114
	v_add_u32_e32 v85, v120, v114
	v_add_u32_e32 v84, v119, v118
	v_add_u32_e32 v86, v120, v118
	v_mfma_f32_32x32x16_bf16 v[16:31], v[102:105], v[106:109], v[16:31]
	v_mfma_f32_32x32x16_bf16 v[0:15], v[102:105], v[110:113], v[0:15]
	ds_read_b128 v[102:105], v87
	ds_read_b128 v[106:109], v87 offset:4096
	ds_read_b128 v[110:113], v85 offset:16384
	ds_read_b128 v[114:117], v85 offset:20480
	s_waitcnt lgkmcnt(0)
	v_mfma_f32_32x32x16_bf16 v[48:63], v[102:105], v[110:113], v[48:63]
	v_mfma_f32_32x32x16_bf16 v[32:47], v[102:105], v[114:117], v[32:47]
	v_mfma_f32_32x32x16_bf16 v[16:31], v[106:109], v[110:113], v[16:31]
	v_mfma_f32_32x32x16_bf16 v[0:15], v[106:109], v[114:117], v[0:15]
	ds_read_b128 v[102:105], v84
	ds_read_b128 v[106:109], v84 offset:4096
	ds_read_b128 v[110:113], v86 offset:16384
	ds_read_b128 v[114:117], v86 offset:20480
	s_waitcnt vmcnt(0)
	s_waitcnt vmcnt(0) lgkmcnt(0)
	s_barrier
; #define MFMA(a, b, c) __builtin_amdgcn_mfma_f32_32x32x16_bf16(a, b, c, 0, 0, 0)
; #define ISSUE(k0, bf) do { char* A_ = lw + (bf) * BUF; \
;     _Pragma("unroll") for (int i_ = 0; i_ < 4; ++i_) { glds16(al.ptr(lrow + 32 * i_, (k0) + cg), A_ + i_ * 4096); glds16(bl.ptr(lrow + 32 * i_, (k0) + cg), A_ + ABYTES + i_ * 4096); } \
;     if (HALO) { if (wid == 0) glds16(gh + (k0), A_ + 16384); } } while (0)
; template <bool HALO, class AL, class BL>
; __device__ __forceinline__ void gemm_core(f32x16 (&acc)[2][2], f32x16& hacc, const AL& al, const BL& bl, int K, char* lds,
;                                           const u16* halo0, const u16* halo1, int brow0, int brow1) {
;     ...
;   for (int kt = 0; kt < nk; ++kt) {
;     asm volatile("s_waitcnt vmcnt(0)" ::: "memory");
;     __syncthreads();
;     if (kt + 1 < nk) ISSUE((kt + 1) * 64, (kt + 1) & 1);
;     const char* T = lds + (kt & 1) * BUF;
; #pragma unroll
;     for (int kk = 0; kk < 4; ++kk) {
;       const int c = kk * 2 + hi;
;       bf16x8 a0 = *(const bf16x8*)(T + oa + ((c ^ sa) << 4));
;       bf16x8 a1 = *(const bf16x8*)(T + oa + 4096 + ((c ^ sa) << 4));
;       bf16x8 b0 = *(const bf16x8*)(T + ob0 + ((c ^ sb0) << 4));
;       bf16x8 b1 = *(const bf16x8*)(T + ob1 + ((c ^ sb1) << 4));
;       acc[0][0] = MFMA(a0, b0, acc[0][0]); acc[0][1] = MFMA(a0, b1, acc[0][1]);
;       acc[1][0] = MFMA(a1, b0, acc[1][0]); acc[1][1] = MFMA(a1, b1, acc[1][1]);
	v_mfma_f32_32x32x16_bf16 v[48:63], v[102:105], v[110:113], v[48:63]
	v_mfma_f32_32x32x16_bf16 v[32:47], v[102:105], v[114:117], v[32:47]
	v_lshl_add_u64 v[102:103], v[64:65], 0, s[24:25]
	global_load_lds_dwordx4 v[102:103], off
	v_lshl_add_u64 v[102:103], v[66:67], 0, s[24:25]
	s_mov_b32 m0, s92
	s_nop 0
	global_load_lds_dwordx4 v[102:103], off
	v_lshl_add_u64 v[102:103], v[68:69], 0, s[24:25]
	s_mov_b32 m0, s70
	v_mfma_f32_32x32x16_bf16 v[16:31], v[106:109], v[110:113], v[16:31]
	global_load_lds_dwordx4 v[102:103], off
	v_lshl_add_u64 v[102:103], v[70:71], 0, s[24:25]
	s_mov_b32 m0, s71
	s_nop 0
	global_load_lds_dwordx4 v[102:103], off
	v_lshl_add_u64 v[102:103], v[72:73], 0, s[24:25]
	s_mov_b32 m0, s41
	v_mfma_f32_32x32x16_bf16 v[0:15], v[106:109], v[114:117], v[0:15]
	global_load_lds_dwordx4 v[102:103], off
	v_lshl_add_u64 v[102:103], v[74:75], 0, s[24:25]
	s_mov_b32 m0, s60
	s_nop 0
	global_load_lds_dwordx4 v[102:103], off
	v_lshl_add_u64 v[102:103], v[76:77], 0, s[24:25]
	s_mov_b32 m0, s61
	s_nop 0
	global_load_lds_dwordx4 v[102:103], off
	v_lshl_add_u64 v[102:103], v[78:79], 0, s[24:25]
	s_mov_b32 m0, s63
	s_nop 0
	global_load_lds_dwordx4 v[102:103], off
	ds_read_b128 v[102:105], v80 offset:32768
	ds_read_b128 v[106:109], v80 offset:36864
	ds_read_b128 v[110:113], v81 offset:49152
	ds_read_b128 v[114:117], v81 offset:53248
	s_waitcnt lgkmcnt(0)
	v_mfma_f32_32x32x16_bf16 v[48:63], v[102:105], v[110:113], v[48:63]
	s_mov_b32 m0, s69
	v_mfma_f32_32x32x16_bf16 v[32:47], v[102:105], v[114:117], v[32:47]
	v_mfma_f32_32x32x16_bf16 v[16:31], v[106:109], v[110:113], v[16:31]
	v_mfma_f32_32x32x16_bf16 v[0:15], v[106:109], v[114:117], v[0:15]
	ds_read_b128 v[102:105], v83 offset:32768
	ds_read_b128 v[106:109], v83 offset:36864
	ds_read_b128 v[110:113], v82 offset:49152
	ds_read_b128 v[114:117], v82 offset:53248
	s_waitcnt lgkmcnt(0)
	v_mfma_f32_32x32x16_bf16 v[48:63], v[102:105], v[110:113], v[48:63]
	v_mfma_f32_32x32x16_bf16 v[32:47], v[102:105], v[114:117], v[32:47]
	v_mfma_f32_32x32x16_bf16 v[16:31], v[106:109], v[110:113], v[16:31]
	v_mfma_f32_32x32x16_bf16 v[0:15], v[106:109], v[114:117], v[0:15]
	ds_read_b128 v[102:105], v87 offset:32768
	ds_read_b128 v[106:109], v87 offset:36864
	ds_read_b128 v[110:113], v85 offset:49152
	ds_read_b128 v[114:117], v85 offset:53248
	s_waitcnt lgkmcnt(0)
	v_mfma_f32_32x32x16_bf16 v[48:63], v[102:105], v[110:113], v[48:63]
	v_mfma_f32_32x32x16_bf16 v[32:47], v[102:105], v[114:117], v[32:47]
	v_mfma_f32_32x32x16_bf16 v[16:31], v[106:109], v[110:113], v[16:31]
	v_mfma_f32_32x32x16_bf16 v[0:15], v[106:109], v[114:117], v[0:15]
	ds_read_b128 v[102:105], v84 offset:32768
	ds_read_b128 v[106:109], v84 offset:36864
	ds_read_b128 v[110:113], v86 offset:49152
	ds_read_b128 v[114:117], v86 offset:53248
	s_waitcnt vmcnt(0)
	s_waitcnt vmcnt(0) lgkmcnt(0)
	s_barrier
	v_mfma_f32_32x32x16_bf16 v[48:63], v[102:105], v[110:113], v[48:63]
	v_mfma_f32_32x32x16_bf16 v[32:47], v[102:105], v[114:117], v[32:47]
	v_lshl_add_u64 v[102:103], v[64:65], 0, s[74:75]
	global_load_lds_dwordx4 v[102:103], off
	v_lshl_add_u64 v[102:103], v[66:67], 0, s[74:75]
	s_mov_b32 m0, s72
	s_nop 0
	global_load_lds_dwordx4 v[102:103], off
	v_lshl_add_u64 v[102:103], v[68:69], 0, s[74:75]
	s_mov_b32 m0, s73
	v_mfma_f32_32x32x16_bf16 v[16:31], v[106:109], v[110:113], v[16:31]
	global_load_lds_dwordx4 v[102:103], off
	v_lshl_add_u64 v[102:103], v[70:71], 0, s[74:75]
	s_mov_b32 m0, s80
	s_nop 0
	global_load_lds_dwordx4 v[102:103], off
	v_lshl_add_u64 v[102:103], v[72:73], 0, s[74:75]
	s_mov_b32 m0, s81
	v_mfma_f32_32x32x16_bf16 v[0:15], v[106:109], v[114:117], v[0:15]
	global_load_lds_dwordx4 v[102:103], off
	v_lshl_add_u64 v[102:103], v[74:75], 0, s[74:75]
	s_mov_b32 m0, s82
	s_nop 0
	global_load_lds_dwordx4 v[102:103], off
	v_lshl_add_u64 v[102:103], v[76:77], 0, s[74:75]
	s_mov_b32 m0, s83
	s_nop 0
	global_load_lds_dwordx4 v[102:103], off
	v_lshl_add_u64 v[102:103], v[78:79], 0, s[74:75]
	s_mov_b32 m0, s84
	s_nop 0
	global_load_lds_dwordx4 v[102:103], off
	ds_read_b128 v[102:105], v80
	ds_read_b128 v[106:109], v80 offset:4096
	ds_read_b128 v[110:113], v81 offset:16384
	ds_read_b128 v[114:117], v81 offset:20480
	s_waitcnt lgkmcnt(0)
	v_mfma_f32_32x32x16_bf16 v[48:63], v[102:105], v[110:113], v[48:63]
	s_mov_b32 m0, s85
	v_mfma_f32_32x32x16_bf16 v[32:47], v[102:105], v[114:117], v[32:47]
	v_mfma_f32_32x32x16_bf16 v[16:31], v[106:109], v[110:113], v[16:31]
	v_mfma_f32_32x32x16_bf16 v[0:15], v[106:109], v[114:117], v[0:15]
	ds_read_b128 v[102:105], v83
	ds_read_b128 v[106:109], v83 offset:4096
	ds_read_b128 v[110:113], v82 offset:16384
	ds_read_b128 v[114:117], v82 offset:20480
	s_waitcnt lgkmcnt(0)
	v_mfma_f32_32x32x16_bf16 v[48:63], v[102:105], v[110:113], v[48:63]
	v_mfma_f32_32x32x16_bf16 v[32:47], v[102:105], v[114:117], v[32:47]
	v_mfma_f32_32x32x16_bf16 v[16:31], v[106:109], v[110:113], v[16:31]
	v_mfma_f32_32x32x16_bf16 v[0:15], v[106:109], v[114:117], v[0:15]
	ds_read_b128 v[102:105], v87
	ds_read_b128 v[106:109], v87 offset:4096
	ds_read_b128 v[110:113], v85 offset:16384
	ds_read_b128 v[114:117], v85 offset:20480
	s_waitcnt lgkmcnt(0)
	v_mfma_f32_32x32x16_bf16 v[48:63], v[102:105], v[110:113], v[48:63]
	v_mfma_f32_32x32x16_bf16 v[32:47], v[102:105], v[114:117], v[32:47]
	v_mfma_f32_32x32x16_bf16 v[16:31], v[106:109], v[110:113], v[16:31]
	v_mfma_f32_32x32x16_bf16 v[0:15], v[106:109], v[114:117], v[0:15]
	ds_read_b128 v[102:105], v84
	ds_read_b128 v[106:109], v84 offset:4096
	ds_read_b128 v[110:113], v86 offset:16384
	ds_read_b128 v[114:117], v86 offset:20480
	s_waitcnt vmcnt(0)
	s_waitcnt vmcnt(0) lgkmcnt(0)
	s_barrier
; #define MFMA(a, b, c) __builtin_amdgcn_mfma_f32_32x32x16_bf16(a, b, c, 0, 0, 0)
; #define ISSUE(k0, bf) do { char* A_ = lw + (bf) * BUF; \
;     _Pragma("unroll") for (int i_ = 0; i_ < 4; ++i_) { glds16(al.ptr(lrow + 32 * i_, (k0) + cg), A_ + i_ * 4096); glds16(bl.ptr(lrow + 32 * i_, (k0) + cg), A_ + ABYTES + i_ * 4096); } \
;     if (HALO) { if (wid == 0) glds16(gh + (k0), A_ + 16384); } } while (0)
; template <bool HALO, class AL, class BL>
; __device__ __forceinline__ void gemm_core(f32x16 (&acc)[2][2], f32x16& hacc, const AL& al, const BL& bl, int K, char* lds,
;                                           const u16* halo0, const u16* halo1, int brow0, int brow1) {
;     ...
;   for (int kt = 0; kt < nk; ++kt) {
;     asm volatile("s_waitcnt vmcnt(0)" ::: "memory");
;     __syncthreads();
;     if (kt + 1 < nk) ISSUE((kt + 1) * 64, (kt + 1) & 1);
;     const char* T = lds + (kt & 1) * BUF;
; #pragma unroll
;     for (int kk = 0; kk < 4; ++kk) {
;       const int c = kk * 2 + hi;
;       bf16x8 a0 = *(const bf16x8*)(T + oa + ((c ^ sa) << 4));
;       bf16x8 a1 = *(const bf16x8*)(T + oa + 4096 + ((c ^ sa) << 4));
;       bf16x8 b0 = *(const bf16x8*)(T + ob0 + ((c ^ sb0) << 4));
;       bf16x8 b1 = *(const bf16x8*)(T + ob1 + ((c ^ sb1) << 4));
;       acc[0][0] = MFMA(a0, b0, acc[0][0]); acc[0][1] = MFMA(a0, b1, acc[0][1]);
;       acc[1][0] = MFMA(a1, b0, acc[1][0]); acc[1][1] = MFMA(a1, b1, acc[1][1]);
	v_mfma_f32_32x32x16_bf16 v[48:63], v[102:105], v[110:113], v[48:63]
	v_mfma_f32_32x32x16_bf16 v[32:47], v[102:105], v[114:117], v[32:47]
	v_lshl_add_u64 v[102:103], v[64:65], 0, s[20:21]
	global_load_lds_dwordx4 v[102:103], off
	v_lshl_add_u64 v[102:103], v[66:67], 0, s[20:21]
	s_mov_b32 m0, s92
	s_nop 0
	global_load_lds_dwordx4 v[102:103], off
	v_lshl_add_u64 v[102:103], v[68:69], 0, s[20:21]
	s_mov_b32 m0, s70
	v_mfma_f32_32x32x16_bf16 v[16:31], v[106:109], v[110:113], v[16:31]
	global_load_lds_dwordx4 v[102:103], off
	v_lshl_add_u64 v[102:103], v[70:71], 0, s[20:21]
	s_mov_b32 m0, s71
	s_nop 0
	global_load_lds_dwordx4 v[102:103], off
	v_lshl_add_u64 v[102:103], v[72:73], 0, s[20:21]
	s_mov_b32 m0, s41
	v_mfma_f32_32x32x16_bf16 v[0:15], v[106:109], v[114:117], v[0:15]
	global_load_lds_dwordx4 v[102:103], off
	v_lshl_add_u64 v[102:103], v[74:75], 0, s[20:21]
	s_mov_b32 m0, s60
	s_nop 0
	global_load_lds_dwordx4 v[102:103], off
	v_lshl_add_u64 v[102:103], v[76:77], 0, s[20:21]
	s_mov_b32 m0, s61
	s_nop 0
	global_load_lds_dwordx4 v[102:103], off
	v_lshl_add_u64 v[102:103], v[78:79], 0, s[20:21]
	s_mov_b32 m0, s63
	s_nop 0
	global_load_lds_dwordx4 v[102:103], off
	ds_read_b128 v[102:105], v80 offset:32768
	ds_read_b128 v[106:109], v80 offset:36864
	ds_read_b128 v[110:113], v81 offset:49152
	ds_read_b128 v[114:117], v81 offset:53248
	s_waitcnt lgkmcnt(0)
	v_mfma_f32_32x32x16_bf16 v[48:63], v[102:105], v[110:113], v[48:63]
	s_mov_b32 m0, s69
	v_mfma_f32_32x32x16_bf16 v[32:47], v[102:105], v[114:117], v[32:47]
	v_mfma_f32_32x32x16_bf16 v[16:31], v[106:109], v[110:113], v[16:31]
	v_mfma_f32_32x32x16_bf16 v[0:15], v[106:109], v[114:117], v[0:15]
	ds_read_b128 v[102:105], v83 offset:32768
	ds_read_b128 v[106:109], v83 offset:36864
	ds_read_b128 v[110:113], v82 offset:49152
	ds_read_b128 v[114:117], v82 offset:53248
	s_waitcnt lgkmcnt(0)
	v_mfma_f32_32x32x16_bf16 v[48:63], v[102:105], v[110:113], v[48:63]
	v_mfma_f32_32x32x16_bf16 v[32:47], v[102:105], v[114:117], v[32:47]
	v_mfma_f32_32x32x16_bf16 v[16:31], v[106:109], v[110:113], v[16:31]
	v_mfma_f32_32x32x16_bf16 v[0:15], v[106:109], v[114:117], v[0:15]
	ds_read_b128 v[102:105], v87 offset:32768
	ds_read_b128 v[106:109], v87 offset:36864
	ds_read_b128 v[110:113], v85 offset:49152
	ds_read_b128 v[114:117], v85 offset:53248
	s_waitcnt lgkmcnt(0)
	v_mfma_f32_32x32x16_bf16 v[48:63], v[102:105], v[110:113], v[48:63]
	v_mfma_f32_32x32x16_bf16 v[32:47], v[102:105], v[114:117], v[32:47]
	v_mfma_f32_32x32x16_bf16 v[16:31], v[106:109], v[110:113], v[16:31]
	v_mfma_f32_32x32x16_bf16 v[0:15], v[106:109], v[114:117], v[0:15]
	ds_read_b128 v[102:105], v84 offset:32768
	ds_read_b128 v[106:109], v84 offset:36864
	ds_read_b128 v[110:113], v86 offset:49152
	ds_read_b128 v[114:117], v86 offset:53248
	s_waitcnt vmcnt(0)
	s_waitcnt vmcnt(0) lgkmcnt(0)
	s_barrier
	v_mfma_f32_32x32x16_bf16 v[48:63], v[102:105], v[110:113], v[48:63]
	v_mfma_f32_32x32x16_bf16 v[32:47], v[102:105], v[114:117], v[32:47]
	v_lshl_add_u64 v[102:103], v[64:65], 0, s[86:87]
	global_load_lds_dwordx4 v[102:103], off
	v_lshl_add_u64 v[102:103], v[66:67], 0, s[86:87]
	s_mov_b32 m0, s72
	s_nop 0
	global_load_lds_dwordx4 v[102:103], off
	v_lshl_add_u64 v[102:103], v[68:69], 0, s[86:87]
	s_mov_b32 m0, s73
	v_mfma_f32_32x32x16_bf16 v[16:31], v[106:109], v[110:113], v[16:31]
	global_load_lds_dwordx4 v[102:103], off
	v_lshl_add_u64 v[102:103], v[70:71], 0, s[86:87]
	s_mov_b32 m0, s80
	s_nop 0
	global_load_lds_dwordx4 v[102:103], off
	v_lshl_add_u64 v[102:103], v[72:73], 0, s[86:87]
	s_mov_b32 m0, s81
	v_mfma_f32_32x32x16_bf16 v[0:15], v[106:109], v[114:117], v[0:15]
	global_load_lds_dwordx4 v[102:103], off
	v_lshl_add_u64 v[102:103], v[74:75], 0, s[86:87]
	s_mov_b32 m0, s82
	s_nop 0
	global_load_lds_dwordx4 v[102:103], off
	v_lshl_add_u64 v[102:103], v[76:77], 0, s[86:87]
	s_mov_b32 m0, s83
	s_nop 0
	global_load_lds_dwordx4 v[102:103], off
	v_lshl_add_u64 v[102:103], v[78:79], 0, s[86:87]
	s_mov_b32 m0, s84
	s_nop 0
	global_load_lds_dwordx4 v[102:103], off
	ds_read_b128 v[102:105], v80
	ds_read_b128 v[106:109], v80 offset:4096
	ds_read_b128 v[110:113], v81 offset:16384
	ds_read_b128 v[114:117], v81 offset:20480
	s_waitcnt lgkmcnt(0)
	v_mfma_f32_32x32x16_bf16 v[48:63], v[102:105], v[110:113], v[48:63]
	s_mov_b32 m0, s85
	v_mfma_f32_32x32x16_bf16 v[32:47], v[102:105], v[114:117], v[32:47]
	v_mfma_f32_32x32x16_bf16 v[16:31], v[106:109], v[110:113], v[16:31]
	v_mfma_f32_32x32x16_bf16 v[0:15], v[106:109], v[114:117], v[0:15]
	ds_read_b128 v[102:105], v83
	ds_read_b128 v[106:109], v83 offset:4096
	ds_read_b128 v[110:113], v82 offset:16384
	ds_read_b128 v[114:117], v82 offset:20480
	s_waitcnt lgkmcnt(0)
	v_mfma_f32_32x32x16_bf16 v[48:63], v[102:105], v[110:113], v[48:63]
	v_mfma_f32_32x32x16_bf16 v[32:47], v[102:105], v[114:117], v[32:47]
	v_mfma_f32_32x32x16_bf16 v[16:31], v[106:109], v[110:113], v[16:31]
	v_mfma_f32_32x32x16_bf16 v[0:15], v[106:109], v[114:117], v[0:15]
	ds_read_b128 v[102:105], v87
	ds_read_b128 v[106:109], v87 offset:4096
	ds_read_b128 v[110:113], v85 offset:16384
	ds_read_b128 v[114:117], v85 offset:20480
	s_waitcnt lgkmcnt(0)
	v_mfma_f32_32x32x16_bf16 v[48:63], v[102:105], v[110:113], v[48:63]
	v_mfma_f32_32x32x16_bf16 v[32:47], v[102:105], v[114:117], v[32:47]
	v_mfma_f32_32x32x16_bf16 v[16:31], v[106:109], v[110:113], v[16:31]
	v_mfma_f32_32x32x16_bf16 v[0:15], v[106:109], v[114:117], v[0:15]
	ds_read_b128 v[102:105], v84
	ds_read_b128 v[106:109], v84 offset:4096
	ds_read_b128 v[110:113], v86 offset:16384
	ds_read_b128 v[114:117], v86 offset:20480
	s_waitcnt vmcnt(0)
	s_waitcnt vmcnt(0) lgkmcnt(0)
	s_barrier
; #define MFMA(a, b, c) __builtin_amdgcn_mfma_f32_32x32x16_bf16(a, b, c, 0, 0, 0)
; #define ISSUE(k0, bf) do { char* A_ = lw + (bf) * BUF; \
;     _Pragma("unroll") for (int i_ = 0; i_ < 4; ++i_) { glds16(al.ptr(lrow + 32 * i_, (k0) + cg), A_ + i_ * 4096); glds16(bl.ptr(lrow + 32 * i_, (k0) + cg), A_ + ABYTES + i_ * 4096); } \
;     if (HALO) { if (wid == 0) glds16(gh + (k0), A_ + 16384); } } while (0)
; template <bool HALO, class AL, class BL>
; __device__ __forceinline__ void gemm_core(f32x16 (&acc)[2][2], f32x16& hacc, const AL& al, const BL& bl, int K, char* lds,
;                                           const u16* halo0, const u16* halo1, int brow0, int brow1) {
;     ...
;   for (int kt = 0; kt < nk; ++kt) {
;     asm volatile("s_waitcnt vmcnt(0)" ::: "memory");
;     __syncthreads();
;     if (kt + 1 < nk) ISSUE((kt + 1) * 64, (kt + 1) & 1);
;     const char* T = lds + (kt & 1) * BUF;
; #pragma unroll
;     for (int kk = 0; kk < 4; ++kk) {
;       const int c = kk * 2 + hi;
;       bf16x8 a0 = *(const bf16x8*)(T + oa + ((c ^ sa) << 4));
;       bf16x8 a1 = *(const bf16x8*)(T + oa + 4096 + ((c ^ sa) << 4));
;       bf16x8 b0 = *(const bf16x8*)(T + ob0 + ((c ^ sb0) << 4));
;       bf16x8 b1 = *(const bf16x8*)(T + ob1 + ((c ^ sb1) << 4));
;       acc[0][0] = MFMA(a0, b0, acc[0][0]); acc[0][1] = MFMA(a0, b1, acc[0][1]);
;       acc[1][0] = MFMA(a1, b0, acc[1][0]); acc[1][1] = MFMA(a1, b1, acc[1][1]);
	v_mfma_f32_32x32x16_bf16 v[48:63], v[102:105], v[110:113], v[48:63]
	v_mfma_f32_32x32x16_bf16 v[32:47], v[102:105], v[114:117], v[32:47]
	v_lshl_add_u64 v[102:103], v[64:65], 0, s[30:31]
	global_load_lds_dwordx4 v[102:103], off
	v_lshl_add_u64 v[102:103], v[66:67], 0, s[30:31]
	s_mov_b32 m0, s92
	s_nop 0
	global_load_lds_dwordx4 v[102:103], off
	v_lshl_add_u64 v[102:103], v[68:69], 0, s[30:31]
	s_mov_b32 m0, s70
	v_mfma_f32_32x32x16_bf16 v[16:31], v[106:109], v[110:113], v[16:31]
	global_load_lds_dwordx4 v[102:103], off
	v_lshl_add_u64 v[102:103], v[70:71], 0, s[30:31]
	s_mov_b32 m0, s71
	v_readfirstlane_b32 s70, v99
	global_load_lds_dwordx4 v[102:103], off
	v_lshl_add_u64 v[102:103], v[72:73], 0, s[30:31]
	s_mov_b32 m0, s41
	v_mfma_f32_32x32x16_bf16 v[0:15], v[106:109], v[114:117], v[0:15]
	global_load_lds_dwordx4 v[102:103], off
	v_lshl_add_u64 v[102:103], v[74:75], 0, s[30:31]
	s_mov_b32 m0, s60
	v_readfirstlane_b32 s71, v100
	global_load_lds_dwordx4 v[102:103], off
	v_lshl_add_u64 v[102:103], v[76:77], 0, s[30:31]
	s_mov_b32 m0, s61
	s_nop 0
	global_load_lds_dwordx4 v[102:103], off
	v_lshl_add_u64 v[102:103], v[78:79], 0, s[30:31]
	s_mov_b32 m0, s63
	s_nop 0
	global_load_lds_dwordx4 v[102:103], off
	ds_read_b128 v[102:105], v80 offset:32768
	ds_read_b128 v[106:109], v80 offset:36864
	ds_read_b128 v[110:113], v81 offset:49152
	ds_read_b128 v[114:117], v81 offset:53248
	s_waitcnt lgkmcnt(0)
	v_mfma_f32_32x32x16_bf16 v[48:63], v[102:105], v[110:113], v[48:63]
	s_mov_b32 m0, s69
	v_readfirstlane_b32 s69, v95
	v_mfma_f32_32x32x16_bf16 v[32:47], v[102:105], v[114:117], v[32:47]
	v_mfma_f32_32x32x16_bf16 v[16:31], v[106:109], v[110:113], v[16:31]
	v_mfma_f32_32x32x16_bf16 v[0:15], v[106:109], v[114:117], v[0:15]
	ds_read_b128 v[102:105], v83 offset:32768
	ds_read_b128 v[106:109], v83 offset:36864
	ds_read_b128 v[110:113], v82 offset:49152
	ds_read_b128 v[114:117], v82 offset:53248
	s_waitcnt lgkmcnt(0)
	v_mfma_f32_32x32x16_bf16 v[48:63], v[102:105], v[110:113], v[48:63]
	v_mfma_f32_32x32x16_bf16 v[32:47], v[102:105], v[114:117], v[32:47]
	v_mfma_f32_32x32x16_bf16 v[16:31], v[106:109], v[110:113], v[16:31]
	v_mfma_f32_32x32x16_bf16 v[0:15], v[106:109], v[114:117], v[0:15]
	ds_read_b128 v[102:105], v87 offset:32768
	ds_read_b128 v[106:109], v87 offset:36864
	ds_read_b128 v[110:113], v85 offset:49152
	ds_read_b128 v[114:117], v85 offset:53248
	s_waitcnt lgkmcnt(0)
	v_mfma_f32_32x32x16_bf16 v[48:63], v[102:105], v[110:113], v[48:63]
	v_mfma_f32_32x32x16_bf16 v[32:47], v[102:105], v[114:117], v[32:47]
	v_mfma_f32_32x32x16_bf16 v[16:31], v[106:109], v[110:113], v[16:31]
	v_mfma_f32_32x32x16_bf16 v[0:15], v[106:109], v[114:117], v[0:15]
	ds_read_b128 v[102:105], v84 offset:32768
	ds_read_b128 v[106:109], v84 offset:36864
	ds_read_b128 v[110:113], v86 offset:49152
	ds_read_b128 v[114:117], v86 offset:53248
	s_waitcnt vmcnt(0)
	s_waitcnt vmcnt(0) lgkmcnt(0)
	s_barrier
	v_mfma_f32_32x32x16_bf16 v[48:63], v[102:105], v[110:113], v[48:63]
	v_mfma_f32_32x32x16_bf16 v[32:47], v[102:105], v[114:117], v[32:47]
	v_lshl_add_u64 v[102:103], v[64:65], 0, s[4:5]
	global_load_lds_dwordx4 v[102:103], off
	v_lshl_add_u64 v[102:103], v[66:67], 0, s[4:5]
	s_mov_b32 m0, s72
	v_readfirstlane_b32 s72, v101
	global_load_lds_dwordx4 v[102:103], off
	v_lshl_add_u64 v[102:103], v[68:69], 0, s[4:5]
	s_mov_b32 m0, s73
	v_mfma_f32_32x32x16_bf16 v[16:31], v[106:109], v[110:113], v[16:31]
	global_load_lds_dwordx4 v[102:103], off
	v_lshl_add_u64 v[102:103], v[70:71], 0, s[4:5]
	s_mov_b32 m0, s80
	v_lshl_add_u64 v[100:101], v[72:73], 0, s[66:67]
	global_load_lds_dwordx4 v[102:103], off
	v_lshl_add_u64 v[102:103], v[72:73], 0, s[4:5]
	s_mov_b32 m0, s81
	v_mfma_f32_32x32x16_bf16 v[0:15], v[106:109], v[114:117], v[0:15]
	global_load_lds_dwordx4 v[102:103], off
	v_lshl_add_u64 v[102:103], v[74:75], 0, s[4:5]
	s_mov_b32 m0, s82
	v_readfirstlane_b32 s73, v92
	global_load_lds_dwordx4 v[102:103], off
	v_lshl_add_u64 v[102:103], v[76:77], 0, s[4:5]
	s_mov_b32 m0, s83
	v_readfirstlane_b32 s80, v93
	global_load_lds_dwordx4 v[102:103], off
	v_lshl_add_u64 v[102:103], v[78:79], 0, s[4:5]
	s_mov_b32 m0, s84
	v_readfirstlane_b32 s81, v94
	global_load_lds_dwordx4 v[102:103], off
	ds_read_b128 v[102:105], v80
	ds_read_b128 v[106:109], v80 offset:4096
	ds_read_b128 v[110:113], v81 offset:16384
	ds_read_b128 v[114:117], v81 offset:20480
	s_waitcnt lgkmcnt(0)
	v_mfma_f32_32x32x16_bf16 v[48:63], v[102:105], v[110:113], v[48:63]
	s_mov_b32 m0, s69
	v_readfirstlane_b32 s82, v96
	v_readfirstlane_b32 s83, v97
	v_readfirstlane_b32 s84, v98
	v_mfma_f32_32x32x16_bf16 v[32:47], v[102:105], v[114:117], v[32:47]
	v_mfma_f32_32x32x16_bf16 v[16:31], v[106:109], v[110:113], v[16:31]
	v_mfma_f32_32x32x16_bf16 v[0:15], v[106:109], v[114:117], v[0:15]
	ds_read_b128 v[102:105], v83
	ds_read_b128 v[106:109], v83 offset:4096
	ds_read_b128 v[110:113], v82 offset:16384
	ds_read_b128 v[114:117], v82 offset:20480
	s_waitcnt lgkmcnt(0)
	v_mfma_f32_32x32x16_bf16 v[48:63], v[102:105], v[110:113], v[48:63]
	v_mfma_f32_32x32x16_bf16 v[32:47], v[102:105], v[114:117], v[32:47]
	v_mfma_f32_32x32x16_bf16 v[16:31], v[106:109], v[110:113], v[16:31]
	v_mfma_f32_32x32x16_bf16 v[0:15], v[106:109], v[114:117], v[0:15]
	ds_read_b128 v[102:105], v87
	ds_read_b128 v[106:109], v87 offset:4096
	ds_read_b128 v[110:113], v85 offset:16384
	ds_read_b128 v[114:117], v85 offset:20480
	s_waitcnt lgkmcnt(0)
	v_mfma_f32_32x32x16_bf16 v[48:63], v[102:105], v[110:113], v[48:63]
	v_mfma_f32_32x32x16_bf16 v[32:47], v[102:105], v[114:117], v[32:47]
	v_mfma_f32_32x32x16_bf16 v[16:31], v[106:109], v[110:113], v[16:31]
	v_mfma_f32_32x32x16_bf16 v[0:15], v[106:109], v[114:117], v[0:15]
	ds_read_b128 v[102:105], v84
	ds_read_b128 v[106:109], v84 offset:4096
	ds_read_b128 v[110:113], v86 offset:16384
	ds_read_b128 v[114:117], v86 offset:20480
	s_waitcnt vmcnt(0)
	s_waitcnt vmcnt(0) lgkmcnt(0)
	s_barrier
; #define MFMA(a, b, c) __builtin_amdgcn_mfma_f32_32x32x16_bf16(a, b, c, 0, 0, 0)
; #define ISSUE(k0, bf) do { char* A_ = lw + (bf) * BUF; \
;     _Pragma("unroll") for (int i_ = 0; i_ < 4; ++i_) { glds16(al.ptr(lrow + 32 * i_, (k0) + cg), A_ + i_ * 4096); glds16(bl.ptr(lrow + 32 * i_, (k0) + cg), A_ + ABYTES + i_ * 4096); } \
;     if (HALO) { if (wid == 0) glds16(gh + (k0), A_ + 16384); } } while (0)
; template <bool HALO, class AL, class BL>
; __device__ __forceinline__ void gemm_core(f32x16 (&acc)[2][2], f32x16& hacc, const AL& al, const BL& bl, int K, char* lds,
;                                           const u16* halo0, const u16* halo1, int brow0, int brow1) {
;     ...
;   for (int kt = 0; kt < nk; ++kt) {
;     asm volatile("s_waitcnt vmcnt(0)" ::: "memory");
;     __syncthreads();
;     if (kt + 1 < nk) ISSUE((kt + 1) * 64, (kt + 1) & 1);
;     const char* T = lds + (kt & 1) * BUF;
; #pragma unroll
;     for (int kk = 0; kk < 4; ++kk) {
;       const int c = kk * 2 + hi;
;       bf16x8 a0 = *(const bf16x8*)(T + oa + ((c ^ sa) << 4));
;       bf16x8 a1 = *(const bf16x8*)(T + oa + 4096 + ((c ^ sa) << 4));
;       bf16x8 b0 = *(const bf16x8*)(T + ob0 + ((c ^ sb0) << 4));
;       bf16x8 b1 = *(const bf16x8*)(T + ob1 + ((c ^ sb1) << 4));
;       acc[0][0] = MFMA(a0, b0, acc[0][0]); acc[0][1] = MFMA(a0, b1, acc[0][1]);
;       acc[1][0] = MFMA(a1, b0, acc[1][0]); acc[1][1] = MFMA(a1, b1, acc[1][1]);
	v_mfma_f32_32x32x16_bf16 v[48:63], v[102:105], v[110:113], v[48:63]
	v_mfma_f32_32x32x16_bf16 v[32:47], v[102:105], v[114:117], v[32:47]
	v_lshl_add_u64 v[102:103], v[64:65], 0, s[66:67]
	global_load_lds_dwordx4 v[102:103], off
	v_lshl_add_u64 v[102:103], v[66:67], 0, s[66:67]
	s_mov_b32 m0, s70
	s_nop 0
	global_load_lds_dwordx4 v[102:103], off
	v_lshl_add_u64 v[102:103], v[68:69], 0, s[66:67]
	s_mov_b32 m0, s71
	v_mfma_f32_32x32x16_bf16 v[16:31], v[106:109], v[110:113], v[16:31]
	global_load_lds_dwordx4 v[102:103], off
	v_lshl_add_u64 v[102:103], v[70:71], 0, s[66:67]
	s_mov_b32 m0, s72
	s_nop 0
	global_load_lds_dwordx4 v[102:103], off
	s_mov_b32 m0, s41
	v_mfma_f32_32x32x16_bf16 v[0:15], v[106:109], v[114:117], v[0:15]
	global_load_lds_dwordx4 v[100:101], off
	v_lshl_add_u64 v[100:101], v[74:75], 0, s[66:67]
	s_mov_b32 m0, s60
	s_nop 0
	global_load_lds_dwordx4 v[100:101], off
	v_lshl_add_u64 v[100:101], v[76:77], 0, s[66:67]
	s_mov_b32 m0, s61
	v_readfirstlane_b32 s61, v91
	global_load_lds_dwordx4 v[100:101], off
	v_lshl_add_u64 v[100:101], v[78:79], 0, s[66:67]
	s_mov_b32 m0, s63
	v_readfirstlane_b32 s63, v90
	global_load_lds_dwordx4 v[100:101], off
	ds_read_b128 v[100:103], v80 offset:32768
	ds_read_b128 v[104:107], v80 offset:36864
	ds_read_b128 v[108:111], v81 offset:49152
	ds_read_b128 v[112:115], v81 offset:53248
	s_waitcnt lgkmcnt(0)
	v_mfma_f32_32x32x16_bf16 v[48:63], v[100:103], v[108:111], v[48:63]
	s_mov_b32 m0, s61
	v_lshl_add_u64 v[90:91], v[68:69], 0, s[26:27]
	v_mfma_f32_32x32x16_bf16 v[32:47], v[100:103], v[112:115], v[32:47]
	v_mfma_f32_32x32x16_bf16 v[16:31], v[104:107], v[108:111], v[16:31]
	v_mfma_f32_32x32x16_bf16 v[0:15], v[104:107], v[112:115], v[0:15]
	ds_read_b128 v[100:103], v83 offset:32768
	ds_read_b128 v[104:107], v83 offset:36864
	ds_read_b128 v[108:111], v82 offset:49152
	ds_read_b128 v[112:115], v82 offset:53248
	s_waitcnt lgkmcnt(0)
	v_mfma_f32_32x32x16_bf16 v[48:63], v[100:103], v[108:111], v[48:63]
	v_mfma_f32_32x32x16_bf16 v[32:47], v[100:103], v[112:115], v[32:47]
	v_mfma_f32_32x32x16_bf16 v[16:31], v[104:107], v[108:111], v[16:31]
	v_mfma_f32_32x32x16_bf16 v[0:15], v[104:107], v[112:115], v[0:15]
	ds_read_b128 v[100:103], v87 offset:32768
	ds_read_b128 v[104:107], v87 offset:36864
	ds_read_b128 v[108:111], v85 offset:49152
	ds_read_b128 v[112:115], v85 offset:53248
	s_waitcnt lgkmcnt(0)
	v_mfma_f32_32x32x16_bf16 v[48:63], v[100:103], v[108:111], v[48:63]
	v_mfma_f32_32x32x16_bf16 v[32:47], v[100:103], v[112:115], v[32:47]
	v_mfma_f32_32x32x16_bf16 v[16:31], v[104:107], v[108:111], v[16:31]
	v_mfma_f32_32x32x16_bf16 v[0:15], v[104:107], v[112:115], v[0:15]
	ds_read_b128 v[100:103], v84 offset:32768
	ds_read_b128 v[104:107], v84 offset:36864
	ds_read_b128 v[108:111], v86 offset:49152
	ds_read_b128 v[112:115], v86 offset:53248
	s_waitcnt vmcnt(0)
	s_waitcnt vmcnt(0) lgkmcnt(0)
	s_barrier
	v_mfma_f32_32x32x16_bf16 v[48:63], v[100:103], v[108:111], v[48:63]
	v_mfma_f32_32x32x16_bf16 v[32:47], v[100:103], v[112:115], v[32:47]
	v_lshl_add_u64 v[100:101], v[64:65], 0, s[26:27]
	global_load_lds_dwordx4 v[100:101], off
	v_lshl_add_u64 v[100:101], v[66:67], 0, s[26:27]
	s_mov_b32 m0, s63
	s_nop 0
	global_load_lds_dwordx4 v[100:101], off
	s_mov_b32 m0, s73
	v_mfma_f32_32x32x16_bf16 v[16:31], v[104:107], v[108:111], v[16:31]
	global_load_lds_dwordx4 v[90:91], off
	v_lshl_add_u64 v[90:91], v[70:71], 0, s[26:27]
	s_mov_b32 m0, s80
	s_nop 0
	global_load_lds_dwordx4 v[90:91], off
	v_lshl_add_u64 v[90:91], v[72:73], 0, s[26:27]
	s_mov_b32 m0, s81
	v_mfma_f32_32x32x16_bf16 v[0:15], v[104:107], v[112:115], v[0:15]
	global_load_lds_dwordx4 v[90:91], off
	v_lshl_add_u64 v[90:91], v[74:75], 0, s[26:27]
	s_mov_b32 m0, s82
	s_nop 0
	global_load_lds_dwordx4 v[90:91], off
	v_lshl_add_u64 v[90:91], v[76:77], 0, s[26:27]
	s_mov_b32 m0, s83
	s_nop 0
	global_load_lds_dwordx4 v[90:91], off
	v_lshl_add_u64 v[90:91], v[78:79], 0, s[26:27]
	s_mov_b32 m0, s84
	s_nop 0
	global_load_lds_dwordx4 v[90:91], off
	ds_read_b128 v[90:93], v80
	ds_read_b128 v[94:97], v80 offset:4096
	ds_read_b128 v[98:101], v81 offset:16384
	ds_read_b128 v[102:105], v81 offset:20480
	s_waitcnt lgkmcnt(0)
	v_mfma_f32_32x32x16_bf16 v[48:63], v[90:93], v[98:101], v[48:63]
	s_mov_b32 m0, s69
	v_mfma_f32_32x32x16_bf16 v[32:47], v[90:93], v[102:105], v[32:47]
	v_mfma_f32_32x32x16_bf16 v[16:31], v[94:97], v[98:101], v[16:31]
	v_mfma_f32_32x32x16_bf16 v[0:15], v[94:97], v[102:105], v[0:15]
	ds_read_b128 v[90:93], v83
	ds_read_b128 v[94:97], v83 offset:4096
	ds_read_b128 v[98:101], v82 offset:16384
	ds_read_b128 v[102:105], v82 offset:20480
	s_waitcnt lgkmcnt(0)
	v_mfma_f32_32x32x16_bf16 v[48:63], v[90:93], v[98:101], v[48:63]
	v_mfma_f32_32x32x16_bf16 v[32:47], v[90:93], v[102:105], v[32:47]
	v_mfma_f32_32x32x16_bf16 v[16:31], v[94:97], v[98:101], v[16:31]
	v_mfma_f32_32x32x16_bf16 v[0:15], v[94:97], v[102:105], v[0:15]
	ds_read_b128 v[90:93], v87
	ds_read_b128 v[94:97], v87 offset:4096
	ds_read_b128 v[98:101], v85 offset:16384
	ds_read_b128 v[102:105], v85 offset:20480
	s_waitcnt lgkmcnt(0)
	v_mfma_f32_32x32x16_bf16 v[48:63], v[90:93], v[98:101], v[48:63]
	v_mfma_f32_32x32x16_bf16 v[32:47], v[90:93], v[102:105], v[32:47]
	v_mfma_f32_32x32x16_bf16 v[16:31], v[94:97], v[98:101], v[16:31]
	v_mfma_f32_32x32x16_bf16 v[0:15], v[94:97], v[102:105], v[0:15]
	ds_read_b128 v[90:93], v84
	ds_read_b128 v[94:97], v84 offset:4096
	ds_read_b128 v[98:101], v86 offset:16384
	ds_read_b128 v[102:105], v86 offset:20480
	s_waitcnt vmcnt(0)
	s_waitcnt vmcnt(0) lgkmcnt(0)
	s_barrier
; #define MFMA(a, b, c) __builtin_amdgcn_mfma_f32_32x32x16_bf16(a, b, c, 0, 0, 0)
; #define ISSUE(k0, bf) do { char* A_ = lw + (bf) * BUF; \
;     _Pragma("unroll") for (int i_ = 0; i_ < 4; ++i_) { glds16(al.ptr(lrow + 32 * i_, (k0) + cg), A_ + i_ * 4096); glds16(bl.ptr(lrow + 32 * i_, (k0) + cg), A_ + ABYTES + i_ * 4096); } \
;     if (HALO) { if (wid == 0) glds16(gh + (k0), A_ + 16384); } } while (0)
; template <bool HALO, class AL, class BL>
; __device__ __forceinline__ void gemm_core(f32x16 (&acc)[2][2], f32x16& hacc, const AL& al, const BL& bl, int K, char* lds,
;                                           const u16* halo0, const u16* halo1, int brow0, int brow1) {
;     ...
;   for (int kt = 0; kt < nk; ++kt) {
;     asm volatile("s_waitcnt vmcnt(0)" ::: "memory");
;     __syncthreads();
;     if (kt + 1 < nk) ISSUE((kt + 1) * 64, (kt + 1) & 1);
;     const char* T = lds + (kt & 1) * BUF;
; #pragma unroll
;     for (int kk = 0; kk < 4; ++kk) {
;       const int c = kk * 2 + hi;
;       bf16x8 a0 = *(const bf16x8*)(T + oa + ((c ^ sa) << 4));
;       bf16x8 a1 = *(const bf16x8*)(T + oa + 4096 + ((c ^ sa) << 4));
;       bf16x8 b0 = *(const bf16x8*)(T + ob0 + ((c ^ sb0) << 4));
;       bf16x8 b1 = *(const bf16x8*)(T + ob1 + ((c ^ sb1) << 4));
;       acc[0][0] = MFMA(a0, b0, acc[0][0]); acc[0][1] = MFMA(a0, b1, acc[0][1]);
;       acc[1][0] = MFMA(a1, b0, acc[1][0]); acc[1][1] = MFMA(a1, b1, acc[1][1]);
	v_mfma_f32_32x32x16_bf16 v[48:63], v[90:93], v[98:101], v[48:63]
	v_mfma_f32_32x32x16_bf16 v[32:47], v[90:93], v[102:105], v[32:47]
	v_lshl_add_u64 v[90:91], v[64:65], 0, s[88:89]
	global_load_lds_dwordx4 v[90:91], off
	v_lshl_add_u64 v[90:91], v[66:67], 0, s[88:89]
	s_mov_b32 m0, s70
	s_nop 0
	global_load_lds_dwordx4 v[90:91], off
	v_lshl_add_u64 v[90:91], v[68:69], 0, s[88:89]
	s_mov_b32 m0, s71
	v_mfma_f32_32x32x16_bf16 v[16:31], v[94:97], v[98:101], v[16:31]
	global_load_lds_dwordx4 v[90:91], off
	v_lshl_add_u64 v[90:91], v[70:71], 0, s[88:89]
	s_mov_b32 m0, s72
	s_nop 0
	global_load_lds_dwordx4 v[90:91], off
	v_lshl_add_u64 v[90:91], v[72:73], 0, s[88:89]
	s_mov_b32 m0, s41
	v_mfma_f32_32x32x16_bf16 v[0:15], v[94:97], v[102:105], v[0:15]
	global_load_lds_dwordx4 v[90:91], off
	v_lshl_add_u64 v[90:91], v[74:75], 0, s[88:89]
	s_mov_b32 m0, s60
	s_nop 0
	global_load_lds_dwordx4 v[90:91], off
	v_lshl_add_u64 v[90:91], v[76:77], 0, s[88:89]
	s_mov_b32 m0, s64
	s_nop 0
	global_load_lds_dwordx4 v[90:91], off
	v_lshl_add_u64 v[90:91], v[78:79], 0, s[88:89]
	s_mov_b32 m0, s65
	s_nop 0
	global_load_lds_dwordx4 v[90:91], off
	ds_read_b128 v[88:91], v80 offset:32768
	ds_read_b128 v[92:95], v80 offset:36864
	ds_read_b128 v[96:99], v81 offset:49152
	ds_read_b128 v[100:103], v81 offset:53248
	s_waitcnt lgkmcnt(0)
	v_mfma_f32_32x32x16_bf16 v[48:63], v[88:91], v[96:99], v[48:63]
	s_mov_b32 m0, s61
	v_mfma_f32_32x32x16_bf16 v[32:47], v[88:91], v[100:103], v[32:47]
	v_mfma_f32_32x32x16_bf16 v[16:31], v[92:95], v[96:99], v[16:31]
	v_mfma_f32_32x32x16_bf16 v[0:15], v[92:95], v[100:103], v[0:15]
	ds_read_b128 v[88:91], v83 offset:32768
	ds_read_b128 v[92:95], v83 offset:36864
	ds_read_b128 v[96:99], v82 offset:49152
	ds_read_b128 v[100:103], v82 offset:53248
	s_waitcnt lgkmcnt(0)
	v_mfma_f32_32x32x16_bf16 v[48:63], v[88:91], v[96:99], v[48:63]
	v_mfma_f32_32x32x16_bf16 v[32:47], v[88:91], v[100:103], v[32:47]
	v_mfma_f32_32x32x16_bf16 v[16:31], v[92:95], v[96:99], v[16:31]
	v_mfma_f32_32x32x16_bf16 v[0:15], v[92:95], v[100:103], v[0:15]
	ds_read_b128 v[88:91], v87 offset:32768
	ds_read_b128 v[92:95], v87 offset:36864
	ds_read_b128 v[96:99], v85 offset:49152
	ds_read_b128 v[100:103], v85 offset:53248
	s_waitcnt lgkmcnt(0)
	v_mfma_f32_32x32x16_bf16 v[48:63], v[88:91], v[96:99], v[48:63]
	v_mfma_f32_32x32x16_bf16 v[32:47], v[88:91], v[100:103], v[32:47]
	v_mfma_f32_32x32x16_bf16 v[16:31], v[92:95], v[96:99], v[16:31]
	v_mfma_f32_32x32x16_bf16 v[0:15], v[92:95], v[100:103], v[0:15]
	ds_read_b128 v[88:91], v84 offset:32768
	ds_read_b128 v[92:95], v84 offset:36864
	ds_read_b128 v[96:99], v86 offset:49152
	ds_read_b128 v[100:103], v86 offset:53248
	s_waitcnt vmcnt(0)
	s_waitcnt vmcnt(0) lgkmcnt(0)
	s_barrier
	v_mfma_f32_32x32x16_bf16 v[48:63], v[88:91], v[96:99], v[48:63]
	v_mfma_f32_32x32x16_bf16 v[32:47], v[88:91], v[100:103], v[32:47]
	v_lshl_add_u64 v[88:89], v[64:65], 0, s[22:23]
	global_load_lds_dwordx4 v[88:89], off
	v_lshl_add_u64 v[88:89], v[66:67], 0, s[22:23]
	s_mov_b32 m0, s63
	s_nop 0
	global_load_lds_dwordx4 v[88:89], off
	v_lshl_add_u64 v[88:89], v[68:69], 0, s[22:23]
	s_mov_b32 m0, s73
	v_mfma_f32_32x32x16_bf16 v[16:31], v[92:95], v[96:99], v[16:31]
	global_load_lds_dwordx4 v[88:89], off
	v_lshl_add_u64 v[88:89], v[70:71], 0, s[22:23]
	s_mov_b32 m0, s80
	s_nop 0
	global_load_lds_dwordx4 v[88:89], off
	v_lshl_add_u64 v[88:89], v[72:73], 0, s[22:23]
	s_mov_b32 m0, s81
	v_mfma_f32_32x32x16_bf16 v[0:15], v[92:95], v[100:103], v[0:15]
	global_load_lds_dwordx4 v[88:89], off
	v_lshl_add_u64 v[88:89], v[74:75], 0, s[22:23]
	s_mov_b32 m0, s82
	s_nop 0
	global_load_lds_dwordx4 v[88:89], off
	v_lshl_add_u64 v[88:89], v[76:77], 0, s[22:23]
	s_mov_b32 m0, s83
	s_nop 0
	global_load_lds_dwordx4 v[88:89], off
	v_lshl_add_u64 v[88:89], v[78:79], 0, s[22:23]
	s_mov_b32 m0, s84
	s_nop 0
	global_load_lds_dwordx4 v[88:89], off
	ds_read_b128 v[88:91], v80
	ds_read_b128 v[92:95], v80 offset:4096
	ds_read_b128 v[96:99], v81 offset:16384
	ds_read_b128 v[100:103], v81 offset:20480
	s_waitcnt lgkmcnt(0)
	v_mfma_f32_32x32x16_bf16 v[48:63], v[88:91], v[96:99], v[48:63]
	s_mov_b32 m0, s69
	v_mfma_f32_32x32x16_bf16 v[32:47], v[88:91], v[100:103], v[32:47]
	v_mfma_f32_32x32x16_bf16 v[16:31], v[92:95], v[96:99], v[16:31]
	v_mfma_f32_32x32x16_bf16 v[0:15], v[92:95], v[100:103], v[0:15]
	ds_read_b128 v[88:91], v83
	ds_read_b128 v[92:95], v83 offset:4096
	ds_read_b128 v[96:99], v82 offset:16384
	ds_read_b128 v[100:103], v82 offset:20480
	s_waitcnt lgkmcnt(0)
	v_mfma_f32_32x32x16_bf16 v[48:63], v[88:91], v[96:99], v[48:63]
	v_mfma_f32_32x32x16_bf16 v[32:47], v[88:91], v[100:103], v[32:47]
	v_mfma_f32_32x32x16_bf16 v[16:31], v[92:95], v[96:99], v[16:31]
	v_mfma_f32_32x32x16_bf16 v[0:15], v[92:95], v[100:103], v[0:15]
	ds_read_b128 v[88:91], v87
	ds_read_b128 v[92:95], v87 offset:4096
	ds_read_b128 v[96:99], v85 offset:16384
	ds_read_b128 v[100:103], v85 offset:20480
	s_waitcnt lgkmcnt(0)
	v_mfma_f32_32x32x16_bf16 v[48:63], v[88:91], v[96:99], v[48:63]
	v_mfma_f32_32x32x16_bf16 v[32:47], v[88:91], v[100:103], v[32:47]
	v_mfma_f32_32x32x16_bf16 v[16:31], v[92:95], v[96:99], v[16:31]
	v_mfma_f32_32x32x16_bf16 v[0:15], v[92:95], v[100:103], v[0:15]
	ds_read_b128 v[88:91], v84
	ds_read_b128 v[92:95], v84 offset:4096
	ds_read_b128 v[96:99], v86 offset:16384
	ds_read_b128 v[100:103], v86 offset:20480
	s_waitcnt vmcnt(0)
	s_waitcnt vmcnt(0) lgkmcnt(0)
	s_barrier
; #define MFMA(a, b, c) __builtin_amdgcn_mfma_f32_32x32x16_bf16(a, b, c, 0, 0, 0)
; #define ISSUE(k0, bf) do { char* A_ = lw + (bf) * BUF; \
;     _Pragma("unroll") for (int i_ = 0; i_ < 4; ++i_) { glds16(al.ptr(lrow + 32 * i_, (k0) + cg), A_ + i_ * 4096); glds16(bl.ptr(lrow + 32 * i_, (k0) + cg), A_ + ABYTES + i_ * 4096); } \
;     if (HALO) { if (wid == 0) glds16(gh + (k0), A_ + 16384); } } while (0)
; template <bool HALO, class AL, class BL>
; __device__ __forceinline__ void gemm_core(f32x16 (&acc)[2][2], f32x16& hacc, const AL& al, const BL& bl, int K, char* lds,
;                                           const u16* halo0, const u16* halo1, int brow0, int brow1) {
;     ...
;   for (int kt = 0; kt < nk; ++kt) {
;     asm volatile("s_waitcnt vmcnt(0)" ::: "memory");
;     __syncthreads();
;     if (kt + 1 < nk) ISSUE((kt + 1) * 64, (kt + 1) & 1);
;     const char* T = lds + (kt & 1) * BUF;
; #pragma unroll
;     for (int kk = 0; kk < 4; ++kk) {
;       const int c = kk * 2 + hi;
;       bf16x8 a0 = *(const bf16x8*)(T + oa + ((c ^ sa) << 4));
;       bf16x8 a1 = *(const bf16x8*)(T + oa + 4096 + ((c ^ sa) << 4));
;       bf16x8 b0 = *(const bf16x8*)(T + ob0 + ((c ^ sb0) << 4));
;       bf16x8 b1 = *(const bf16x8*)(T + ob1 + ((c ^ sb1) << 4));
;       acc[0][0] = MFMA(a0, b0, acc[0][0]); acc[0][1] = MFMA(a0, b1, acc[0][1]);
;       acc[1][0] = MFMA(a1, b0, acc[1][0]); acc[1][1] = MFMA(a1, b1, acc[1][1]);
;       if (HALO) { bf16x8 ah = *(const bf16x8*)(T + oh + ((c ^ sh) << 4)); hacc = MFMA(ah, b0, hacc); }
;     }
;   }
	v_mfma_f32_32x32x16_bf16 v[48:63], v[88:91], v[96:99], v[48:63]
	v_mfma_f32_32x32x16_bf16 v[32:47], v[88:91], v[100:103], v[32:47]
	v_lshl_add_u64 v[88:89], v[64:65], 0, s[90:91]
	global_load_lds_dwordx4 v[88:89], off
	v_lshl_add_u64 v[88:89], v[66:67], 0, s[90:91]
	s_mov_b32 m0, s70
	s_nop 0
	global_load_lds_dwordx4 v[88:89], off
	v_lshl_add_u64 v[88:89], v[68:69], 0, s[90:91]
	s_mov_b32 m0, s71
	v_mfma_f32_32x32x16_bf16 v[16:31], v[92:95], v[96:99], v[16:31]
	global_load_lds_dwordx4 v[88:89], off
	v_lshl_add_u64 v[88:89], v[70:71], 0, s[90:91]
	s_mov_b32 m0, s72
	s_nop 0
	global_load_lds_dwordx4 v[88:89], off
	v_lshl_add_u64 v[88:89], v[72:73], 0, s[90:91]
	s_mov_b32 m0, s41
	v_mfma_f32_32x32x16_bf16 v[0:15], v[92:95], v[100:103], v[0:15]
	global_load_lds_dwordx4 v[88:89], off
	v_lshl_add_u64 v[88:89], v[74:75], 0, s[90:91]
	s_mov_b32 m0, s60
	s_nop 0
	global_load_lds_dwordx4 v[88:89], off
	v_lshl_add_u64 v[88:89], v[76:77], 0, s[90:91]
	s_mov_b32 m0, s64
	s_nop 0
	global_load_lds_dwordx4 v[88:89], off
	v_lshl_add_u64 v[88:89], v[78:79], 0, s[90:91]
	s_mov_b32 m0, s65
	s_nop 0
	global_load_lds_dwordx4 v[88:89], off
	ds_read_b128 v[88:91], v80 offset:32768
	ds_read_b128 v[92:95], v80 offset:36864
	ds_read_b128 v[96:99], v81 offset:49152
	ds_read_b128 v[100:103], v81 offset:53248
	s_waitcnt lgkmcnt(0)
	v_mfma_f32_32x32x16_bf16 v[48:63], v[88:91], v[96:99], v[48:63]
	s_mov_b32 m0, s61
	v_mfma_f32_32x32x16_bf16 v[32:47], v[88:91], v[100:103], v[32:47]
	v_mfma_f32_32x32x16_bf16 v[16:31], v[92:95], v[96:99], v[16:31]
	v_mfma_f32_32x32x16_bf16 v[0:15], v[92:95], v[100:103], v[0:15]
	ds_read_b128 v[88:91], v83 offset:32768
	ds_read_b128 v[92:95], v83 offset:36864
	ds_read_b128 v[96:99], v82 offset:49152
	ds_read_b128 v[100:103], v82 offset:53248
	s_waitcnt lgkmcnt(0)
	v_mfma_f32_32x32x16_bf16 v[48:63], v[88:91], v[96:99], v[48:63]
	v_mfma_f32_32x32x16_bf16 v[32:47], v[88:91], v[100:103], v[32:47]
	v_mfma_f32_32x32x16_bf16 v[16:31], v[92:95], v[96:99], v[16:31]
	v_mfma_f32_32x32x16_bf16 v[0:15], v[92:95], v[100:103], v[0:15]
	ds_read_b128 v[88:91], v87 offset:32768
	ds_read_b128 v[92:95], v87 offset:36864
	ds_read_b128 v[96:99], v85 offset:49152
	ds_read_b128 v[100:103], v85 offset:53248
	s_waitcnt lgkmcnt(0)
	v_mfma_f32_32x32x16_bf16 v[48:63], v[88:91], v[96:99], v[48:63]
	v_mfma_f32_32x32x16_bf16 v[32:47], v[88:91], v[100:103], v[32:47]
	v_mfma_f32_32x32x16_bf16 v[16:31], v[92:95], v[96:99], v[16:31]
	v_mfma_f32_32x32x16_bf16 v[0:15], v[92:95], v[100:103], v[0:15]
	ds_read_b128 v[88:91], v84 offset:32768
	ds_read_b128 v[92:95], v84 offset:36864
	ds_read_b128 v[96:99], v86 offset:49152
	ds_read_b128 v[100:103], v86 offset:53248
	s_waitcnt vmcnt(0)
	s_waitcnt vmcnt(0) lgkmcnt(0)
	s_barrier
	v_mfma_f32_32x32x16_bf16 v[48:63], v[88:91], v[96:99], v[48:63]
	v_mfma_f32_32x32x16_bf16 v[32:47], v[88:91], v[100:103], v[32:47]
	v_lshl_add_u64 v[88:89], v[64:65], 0, s[0:1]
	global_load_lds_dwordx4 v[88:89], off
	v_lshl_add_u64 v[88:89], v[66:67], 0, s[0:1]
	s_mov_b32 m0, s63
	s_nop 0
	global_load_lds_dwordx4 v[88:89], off
	v_lshl_add_u64 v[88:89], v[68:69], 0, s[0:1]
	s_mov_b32 m0, s73
	v_mfma_f32_32x32x16_bf16 v[16:31], v[92:95], v[96:99], v[16:31]
	global_load_lds_dwordx4 v[88:89], off
	v_lshl_add_u64 v[88:89], v[70:71], 0, s[0:1]
	s_mov_b32 m0, s80
	s_nop 0
	global_load_lds_dwordx4 v[88:89], off
	v_lshl_add_u64 v[88:89], v[72:73], 0, s[0:1]
	s_mov_b32 m0, s81
	v_mfma_f32_32x32x16_bf16 v[0:15], v[92:95], v[100:103], v[0:15]
	global_load_lds_dwordx4 v[88:89], off
	v_lshl_add_u64 v[88:89], v[74:75], 0, s[0:1]
	s_mov_b32 m0, s82
	s_nop 0
	global_load_lds_dwordx4 v[88:89], off
	v_lshl_add_u64 v[88:89], v[76:77], 0, s[0:1]
	s_mov_b32 m0, s83
	s_nop 0
	global_load_lds_dwordx4 v[88:89], off
	v_lshl_add_u64 v[88:89], v[78:79], 0, s[0:1]
	s_mov_b32 m0, s84
	s_nop 0
	global_load_lds_dwordx4 v[88:89], off
	ds_read_b128 v[88:91], v80
	ds_read_b128 v[92:95], v80 offset:4096
	ds_read_b128 v[96:99], v81 offset:16384
	ds_read_b128 v[100:103], v81 offset:20480
	s_waitcnt lgkmcnt(0)
	v_mfma_f32_32x32x16_bf16 v[48:63], v[88:91], v[96:99], v[48:63]
	s_mov_b32 m0, s69
	v_mfma_f32_32x32x16_bf16 v[32:47], v[88:91], v[100:103], v[32:47]
	v_mfma_f32_32x32x16_bf16 v[16:31], v[92:95], v[96:99], v[16:31]
	v_mfma_f32_32x32x16_bf16 v[0:15], v[92:95], v[100:103], v[0:15]
	ds_read_b128 v[88:91], v83
	ds_read_b128 v[92:95], v83 offset:4096
	ds_read_b128 v[96:99], v82 offset:16384
	ds_read_b128 v[100:103], v82 offset:20480
	s_waitcnt lgkmcnt(0)
	v_mfma_f32_32x32x16_bf16 v[48:63], v[88:91], v[96:99], v[48:63]
	v_mfma_f32_32x32x16_bf16 v[32:47], v[88:91], v[100:103], v[32:47]
	v_mfma_f32_32x32x16_bf16 v[16:31], v[92:95], v[96:99], v[16:31]
	v_mfma_f32_32x32x16_bf16 v[0:15], v[92:95], v[100:103], v[0:15]
	ds_read_b128 v[88:91], v87
	ds_read_b128 v[92:95], v87 offset:4096
	ds_read_b128 v[96:99], v85 offset:16384
	ds_read_b128 v[100:103], v85 offset:20480
	s_waitcnt lgkmcnt(0)
	v_mfma_f32_32x32x16_bf16 v[48:63], v[88:91], v[96:99], v[48:63]
	v_mfma_f32_32x32x16_bf16 v[32:47], v[88:91], v[100:103], v[32:47]
	v_mfma_f32_32x32x16_bf16 v[16:31], v[92:95], v[96:99], v[16:31]
	v_mfma_f32_32x32x16_bf16 v[0:15], v[92:95], v[100:103], v[0:15]
	ds_read_b128 v[88:91], v84
	ds_read_b128 v[92:95], v84 offset:4096
	ds_read_b128 v[96:99], v86 offset:16384
	ds_read_b128 v[100:103], v86 offset:20480
	s_waitcnt vmcnt(0)
	s_waitcnt vmcnt(0) lgkmcnt(0)
	s_barrier
; #define MFMA(a, b, c) __builtin_amdgcn_mfma_f32_32x32x16_bf16(a, b, c, 0, 0, 0)
; #define ISSUE(k0, bf) do { char* A_ = lw + (bf) * BUF; \
;     _Pragma("unroll") for (int i_ = 0; i_ < 4; ++i_) { glds16(al.ptr(lrow + 32 * i_, (k0) + cg), A_ + i_ * 4096); glds16(bl.ptr(lrow + 32 * i_, (k0) + cg), A_ + ABYTES + i_ * 4096); } \
;     if (HALO) { if (wid == 0) glds16(gh + (k0), A_ + 16384); } } while (0)
; template <bool HALO, class AL, class BL>
; __device__ __forceinline__ void gemm_core(f32x16 (&acc)[2][2], f32x16& hacc, const AL& al, const BL& bl, int K, char* lds,
;                                           const u16* halo0, const u16* halo1, int brow0, int brow1) {
;     ...
;   for (int kt = 0; kt < nk; ++kt) {
;     asm volatile("s_waitcnt vmcnt(0)" ::: "memory");
;     __syncthreads();
;     if (kt + 1 < nk) ISSUE((kt + 1) * 64, (kt + 1) & 1);
;     const char* T = lds + (kt & 1) * BUF;
; #pragma unroll
;     for (int kk = 0; kk < 4; ++kk) {
;       const int c = kk * 2 + hi;
;       bf16x8 a0 = *(const bf16x8*)(T + oa + ((c ^ sa) << 4));
;       bf16x8 a1 = *(const bf16x8*)(T + oa + 4096 + ((c ^ sa) << 4));
;       bf16x8 b0 = *(const bf16x8*)(T + ob0 + ((c ^ sb0) << 4));
;       bf16x8 b1 = *(const bf16x8*)(T + ob1 + ((c ^ sb1) << 4));
;       acc[0][0] = MFMA(a0, b0, acc[0][0]); acc[0][1] = MFMA(a0, b1, acc[0][1]);
;       acc[1][0] = MFMA(a1, b0, acc[1][0]); acc[1][1] = MFMA(a1, b1, acc[1][1]);
;       if (HALO) { bf16x8 ah = *(const bf16x8*)(T + oh + ((c ^ sh) << 4)); hacc = MFMA(ah, b0, hacc); }
;     }
;   }
	v_mfma_f32_32x32x16_bf16 v[48:63], v[88:91], v[96:99], v[48:63]
	v_mfma_f32_32x32x16_bf16 v[32:47], v[88:91], v[100:103], v[32:47]
	v_lshl_add_u64 v[88:89], v[64:65], 0, s[34:35]
	global_load_lds_dwordx4 v[88:89], off
	v_lshl_add_u64 v[88:89], v[66:67], 0, s[34:35]
	s_mov_b32 m0, s70
	v_lshl_add_u64 v[64:65], v[64:65], 0, s[38:39]
	global_load_lds_dwordx4 v[88:89], off
	v_lshl_add_u64 v[88:89], v[68:69], 0, s[34:35]
	s_mov_b32 m0, s71
	v_mfma_f32_32x32x16_bf16 v[16:31], v[92:95], v[96:99], v[16:31]
	global_load_lds_dwordx4 v[88:89], off
	v_lshl_add_u64 v[88:89], v[70:71], 0, s[34:35]
	s_mov_b32 m0, s72
	s_nop 0
	global_load_lds_dwordx4 v[88:89], off
	v_lshl_add_u64 v[88:89], v[72:73], 0, s[34:35]
	s_mov_b32 m0, s41
	v_mfma_f32_32x32x16_bf16 v[0:15], v[92:95], v[100:103], v[0:15]
	global_load_lds_dwordx4 v[88:89], off
	v_lshl_add_u64 v[88:89], v[74:75], 0, s[34:35]
	s_mov_b32 m0, s60
	s_nop 0
	global_load_lds_dwordx4 v[88:89], off
	v_lshl_add_u64 v[88:89], v[76:77], 0, s[34:35]
	s_mov_b32 m0, s64
	s_nop 0
	global_load_lds_dwordx4 v[88:89], off
	v_lshl_add_u64 v[88:89], v[78:79], 0, s[34:35]
	s_mov_b32 m0, s65
	s_nop 0
	global_load_lds_dwordx4 v[88:89], off
	ds_read_b128 v[88:91], v80 offset:32768
	ds_read_b128 v[92:95], v80 offset:36864
	ds_read_b128 v[96:99], v81 offset:49152
	ds_read_b128 v[100:103], v81 offset:53248
	s_waitcnt lgkmcnt(0)
	v_mfma_f32_32x32x16_bf16 v[48:63], v[88:91], v[96:99], v[48:63]
	s_mov_b32 m0, s61
	s_mov_b64 s[60:61], -1
	v_mfma_f32_32x32x16_bf16 v[32:47], v[88:91], v[100:103], v[32:47]
	v_mfma_f32_32x32x16_bf16 v[16:31], v[92:95], v[96:99], v[16:31]
	v_mfma_f32_32x32x16_bf16 v[0:15], v[92:95], v[100:103], v[0:15]
	ds_read_b128 v[88:91], v83 offset:32768
	ds_read_b128 v[92:95], v83 offset:36864
	ds_read_b128 v[96:99], v82 offset:49152
	ds_read_b128 v[100:103], v82 offset:53248
	s_waitcnt lgkmcnt(0)
	v_mfma_f32_32x32x16_bf16 v[48:63], v[88:91], v[96:99], v[48:63]
	v_mfma_f32_32x32x16_bf16 v[32:47], v[88:91], v[100:103], v[32:47]
	v_mfma_f32_32x32x16_bf16 v[16:31], v[92:95], v[96:99], v[16:31]
	v_mfma_f32_32x32x16_bf16 v[0:15], v[92:95], v[100:103], v[0:15]
	ds_read_b128 v[88:91], v87 offset:32768
	ds_read_b128 v[92:95], v87 offset:36864
	ds_read_b128 v[96:99], v85 offset:49152
	ds_read_b128 v[100:103], v85 offset:53248
	s_waitcnt lgkmcnt(0)
	v_mfma_f32_32x32x16_bf16 v[48:63], v[88:91], v[96:99], v[48:63]
	v_mfma_f32_32x32x16_bf16 v[32:47], v[88:91], v[100:103], v[32:47]
	v_mfma_f32_32x32x16_bf16 v[16:31], v[92:95], v[96:99], v[16:31]
	v_mfma_f32_32x32x16_bf16 v[0:15], v[92:95], v[100:103], v[0:15]
	ds_read_b128 v[88:91], v84 offset:32768
	ds_read_b128 v[92:95], v84 offset:36864
	ds_read_b128 v[96:99], v86 offset:49152
	ds_read_b128 v[100:103], v86 offset:53248
	s_waitcnt vmcnt(0)
	s_waitcnt vmcnt(0) lgkmcnt(0)
	s_barrier
	global_load_lds_dwordx4 v[64:65], off
	v_lshl_add_u64 v[64:65], v[66:67], 0, s[38:39]
	s_mov_b32 m0, s63
	v_mfma_f32_32x32x16_bf16 v[48:63], v[88:91], v[96:99], v[48:63]
	global_load_lds_dwordx4 v[64:65], off
	v_lshl_add_u64 v[64:65], v[68:69], 0, s[38:39]
	s_mov_b32 m0, s73
	s_nop 0
	global_load_lds_dwordx4 v[64:65], off
	v_lshl_add_u64 v[64:65], v[70:71], 0, s[38:39]
	s_mov_b32 m0, s80
	v_mfma_f32_32x32x16_bf16 v[32:47], v[88:91], v[100:103], v[32:47]
	global_load_lds_dwordx4 v[64:65], off
	v_lshl_add_u64 v[64:65], v[72:73], 0, s[38:39]
	s_mov_b32 m0, s81
	s_nop 0
	global_load_lds_dwordx4 v[64:65], off
	v_lshl_add_u64 v[64:65], v[74:75], 0, s[38:39]
	s_mov_b32 m0, s82
	v_mfma_f32_32x32x16_bf16 v[16:31], v[92:95], v[96:99], v[16:31]
	global_load_lds_dwordx4 v[64:65], off
	v_lshl_add_u64 v[64:65], v[76:77], 0, s[38:39]
	s_mov_b32 m0, s83
	s_nop 0
	global_load_lds_dwordx4 v[64:65], off
	v_lshl_add_u64 v[64:65], v[78:79], 0, s[38:39]
	s_mov_b32 m0, s84
	v_mfma_f32_32x32x16_bf16 v[0:15], v[92:95], v[100:103], v[0:15]
	global_load_lds_dwordx4 v[64:65], off
	ds_read_b128 v[64:67], v80
	ds_read_b128 v[68:71], v80 offset:4096
	ds_read_b128 v[72:75], v81 offset:16384
	ds_read_b128 v[76:79], v81 offset:20480
	s_waitcnt lgkmcnt(0)
	v_mfma_f32_32x32x16_bf16 v[48:63], v[64:67], v[72:75], v[48:63]
	v_mfma_f32_32x32x16_bf16 v[32:47], v[64:67], v[76:79], v[32:47]
	v_mfma_f32_32x32x16_bf16 v[16:31], v[68:71], v[72:75], v[16:31]
	v_mfma_f32_32x32x16_bf16 v[0:15], v[68:71], v[76:79], v[0:15]
	ds_read_b128 v[64:67], v83
	ds_read_b128 v[68:71], v83 offset:4096
	ds_read_b128 v[72:75], v82 offset:16384
	ds_read_b128 v[76:79], v82 offset:20480
	s_waitcnt lgkmcnt(0)
	v_mfma_f32_32x32x16_bf16 v[48:63], v[64:67], v[72:75], v[48:63]
	v_mfma_f32_32x32x16_bf16 v[32:47], v[64:67], v[76:79], v[32:47]
	v_mfma_f32_32x32x16_bf16 v[16:31], v[68:71], v[72:75], v[16:31]
	v_mfma_f32_32x32x16_bf16 v[0:15], v[68:71], v[76:79], v[0:15]
	ds_read_b128 v[64:67], v87
	ds_read_b128 v[68:71], v87 offset:4096
	ds_read_b128 v[72:75], v85 offset:16384
	ds_read_b128 v[76:79], v85 offset:20480
	s_waitcnt lgkmcnt(0)
	v_mfma_f32_32x32x16_bf16 v[48:63], v[64:67], v[72:75], v[48:63]
	v_mfma_f32_32x32x16_bf16 v[32:47], v[64:67], v[76:79], v[32:47]
	v_mfma_f32_32x32x16_bf16 v[16:31], v[68:71], v[72:75], v[16:31]
	v_mfma_f32_32x32x16_bf16 v[0:15], v[68:71], v[76:79], v[0:15]
	ds_read_b128 v[64:67], v84
	ds_read_b128 v[68:71], v84 offset:4096
	ds_read_b128 v[72:75], v86 offset:16384
	ds_read_b128 v[76:79], v86 offset:20480
	s_waitcnt vmcnt(0)
	s_waitcnt vmcnt(0) lgkmcnt(0)
	s_barrier
; __device__ __forceinline__ float bf2f(u16 v) { return __uint_as_float(((unsigned)v) << 16); }
; __device__ __forceinline__ int opq() { int z = 0; asm volatile("" : "+v"(z)); return z; }
; #define MFMA(a, b, c) __builtin_amdgcn_mfma_f32_32x32x16_bf16(a, b, c, 0, 0, 0)
; template <bool HALO, class AL, class BL>
; __device__ __forceinline__ void gemm_core(f32x16 (&acc)[2][2], f32x16& hacc, const AL& al, const BL& bl, int K, char* lds,
;                                           const u16* halo0, const u16* halo1, int brow0, int brow1) {
;     ...
;       bf16x8 a0 = *(const bf16x8*)(T + oa + ((c ^ sa) << 4));
;       bf16x8 a1 = *(const bf16x8*)(T + oa + 4096 + ((c ^ sa) << 4));
;       bf16x8 b0 = *(const bf16x8*)(T + ob0 + ((c ^ sb0) << 4));
;       bf16x8 b1 = *(const bf16x8*)(T + ob1 + ((c ^ sb1) << 4));
;       acc[0][0] = MFMA(a0, b0, acc[0][0]); acc[0][1] = MFMA(a0, b1, acc[0][1]);
;       acc[1][0] = MFMA(a1, b0, acc[1][0]); acc[1][1] = MFMA(a1, b1, acc[1][1]);
; __device__ __forceinline__ void phase_wout(const P& p, int layer, char* lds) {
;     ...
;     const unsigned rb = (unsigned)(tm * 128 + wr * 64 + 4 * hi + opq());
;     _Float16* pre1 = (_Float16*)(p.ws + OFF_PRE1);
; #pragma unroll
;     for (int mi = 0; mi < 2; ++mi) {
;       float xr[2][16];
;       if (layer == 0) {
; #pragma unroll
;         for (int ni = 0; ni < 2; ++ni)
; #pragma unroll
;           for (int r = 0; r < 16; ++r) xr[ni][r] = p.x[(rb + mi * 32 + (r & 3) + 8 * (r >> 2)) * DM + tn * 128 + wc * 64 + ni * 32 + r32];
;       } else {
; #pragma unroll
;         for (int ni = 0; ni < 2; ++ni)
; #pragma unroll
;           for (int r = 0; r < 16; ++r) xr[ni][r] = bf2f(xbr[(rb + mi * 32 + (r & 3) + 8 * (r >> 2)) * DM + tn * 128 + wc * 64 + ni * 32 + r32]);
	v_mfma_f32_32x32x16_bf16 v[48:63], v[64:67], v[72:75], v[48:63]
	v_mfma_f32_32x32x16_bf16 v[32:47], v[64:67], v[76:79], v[32:47]
	v_mfma_f32_32x32x16_bf16 v[16:31], v[68:71], v[72:75], v[16:31]
	v_mfma_f32_32x32x16_bf16 v[0:15], v[68:71], v[76:79], v[0:15]
	ds_read_b128 v[64:67], v80 offset:32768
	ds_read_b128 v[68:71], v80 offset:36864
	ds_read_b128 v[72:75], v81 offset:49152
	ds_read_b128 v[76:79], v81 offset:53248
	s_waitcnt lgkmcnt(1)
	v_mfma_f32_32x32x16_bf16 v[48:63], v[64:67], v[72:75], v[48:63]
	s_waitcnt lgkmcnt(0)
	v_mfma_f32_32x32x16_bf16 v[32:47], v[64:67], v[76:79], v[32:47]
	v_mfma_f32_32x32x16_bf16 v[16:31], v[68:71], v[72:75], v[16:31]
	v_mfma_f32_32x32x16_bf16 v[0:15], v[68:71], v[76:79], v[0:15]
	ds_read_b128 v[64:67], v83 offset:32768
	ds_read_b128 v[68:71], v83 offset:36864
	ds_read_b128 v[72:75], v82 offset:49152
	ds_read_b128 v[76:79], v82 offset:53248
	s_waitcnt lgkmcnt(1)
	v_mfma_f32_32x32x16_bf16 v[48:63], v[64:67], v[72:75], v[48:63]
	s_waitcnt lgkmcnt(0)
	v_mfma_f32_32x32x16_bf16 v[32:47], v[64:67], v[76:79], v[32:47]
	v_mfma_f32_32x32x16_bf16 v[16:31], v[68:71], v[72:75], v[16:31]
	v_mfma_f32_32x32x16_bf16 v[0:15], v[68:71], v[76:79], v[0:15]
	ds_read_b128 v[64:67], v87 offset:32768
	ds_read_b128 v[68:71], v87 offset:36864
	ds_read_b128 v[72:75], v85 offset:49152
	ds_read_b128 v[76:79], v85 offset:53248
	s_waitcnt lgkmcnt(1)
	v_mfma_f32_32x32x16_bf16 v[48:63], v[64:67], v[72:75], v[48:63]
	s_waitcnt lgkmcnt(0)
	v_mfma_f32_32x32x16_bf16 v[32:47], v[64:67], v[76:79], v[32:47]
	v_mfma_f32_32x32x16_bf16 v[16:31], v[68:71], v[72:75], v[16:31]
	v_mfma_f32_32x32x16_bf16 v[0:15], v[68:71], v[76:79], v[0:15]
	ds_read_b128 v[64:67], v84 offset:32768
	ds_read_b128 v[68:71], v84 offset:36864
	ds_read_b128 v[72:75], v86 offset:49152
	ds_read_b128 v[76:79], v86 offset:53248
	s_waitcnt lgkmcnt(1)
	v_mfma_f32_32x32x16_bf16 v[48:63], v[64:67], v[72:75], v[48:63]
	s_waitcnt lgkmcnt(0)
	v_mfma_f32_32x32x16_bf16 v[32:47], v[64:67], v[76:79], v[32:47]
	v_mov_b32_e32 v64, v201
	v_lshl_add_u32 v65, s8, 7, v126
	s_nop 0
	v_add_lshl_u32 v129, v65, v64, 10
	v_cndmask_b32_e64 v64, 0, 1, s[76:77]
	v_add_u32_e32 v157, 0x400, v129
	v_mfma_f32_32x32x16_bf16 v[16:31], v[68:71], v[72:75], v[16:31]
	v_add_u32_e32 v156, 0x800, v129
	v_add_u32_e32 v155, 0xc00, v129
	v_add_u32_e32 v153, 0x2000, v129
	v_add_u32_e32 v151, 0x2400, v129
	v_add_u32_e32 v150, 0x2800, v129
	v_add_u32_e32 v149, 0x2c00, v129
	v_add_u32_e32 v146, 0x4000, v129
	v_mfma_f32_32x32x16_bf16 v[0:15], v[68:71], v[76:79], v[0:15]
	v_add_u32_e32 v145, 0x4400, v129
	v_add_u32_e32 v144, 0x4800, v129
	v_add_u32_e32 v142, 0x4c00, v129
	v_add_u32_e32 v141, 0x6000, v129
	v_add_u32_e32 v140, 0x6400, v129
	v_add_u32_e32 v138, 0x6800, v129
	v_add_u32_e32 v137, 0x6c00, v129
	v_add_u32_e32 v200, v129, v128
	v_cmp_ne_u32_e64 s[40:41], 1, v64
	v_add_u32_e32 v90, v157, v128
	v_add_u32_e32 v92, v156, v128
	v_add_u32_e32 v88, v155, v128
	v_add_u32_e32 v86, v153, v128
	v_add_u32_e32 v84, v151, v128
	v_add_u32_e32 v82, v150, v128
	v_add_u32_e32 v80, v149, v128
	v_add_u32_e32 v76, v146, v128
	v_add_u32_e32 v78, v145, v128
	v_add_u32_e32 v74, v144, v128
	v_add_u32_e32 v72, v142, v128
	v_add_u32_e32 v70, v141, v128
	v_add_u32_e32 v68, v140, v128
	v_add_u32_e32 v66, v138, v128
	v_add_u32_e32 v64, v137, v128
	s_cbranch_vccnz .LBB0_242
; __device__ __forceinline__ float bf2f(u16 v) { return __uint_as_float(((unsigned)v) << 16); }
; __device__ __forceinline__ void phase_wout(const P& p, int layer, char* lds) {
;     ...
; #pragma unroll
;         for (int ni = 0; ni < 2; ++ni)
; #pragma unroll
;           for (int r = 0; r < 16; ++r) xr[ni][r] = bf2f(xbr[(rb + mi * 32 + (r & 3) + 8 * (r >> 2)) * DM + tn * 128 + wc * 64 + ni * 32 + r32]);
;       }
	v_lshl_add_u64 v[94:95], v[200:201], 1, s[42:43]
	v_mov_b32_e32 v91, v201
	v_lshl_add_u64 v[96:97], v[90:91], 1, s[42:43]
	global_load_ushort v65, v[94:95], off
	global_load_ushort v67, v[96:97], off
	v_mov_b32_e32 v93, v201
	v_lshl_add_u64 v[94:95], v[92:93], 1, s[42:43]
	v_mov_b32_e32 v89, v201
	v_lshl_add_u64 v[96:97], v[88:89], 1, s[42:43]
	v_mov_b32_e32 v87, v201
	v_mov_b32_e32 v85, v201
	v_mov_b32_e32 v83, v201
	v_mov_b32_e32 v81, v201
	v_mov_b32_e32 v77, v201
	v_mov_b32_e32 v79, v201
	v_mov_b32_e32 v75, v201
	v_mov_b32_e32 v73, v201
	v_mov_b32_e32 v71, v201
	v_mov_b32_e32 v69, v201
	v_or_b32_e32 v168, 32, v128
	v_mov_b32_e32 v205, v179
	v_mov_b32_e32 v217, v181
	s_mov_b64 s[60:61], 0
	s_waitcnt vmcnt(1)
	v_lshlrev_b32_e32 v130, 16, v65
	s_waitcnt vmcnt(0)
	v_lshlrev_b32_e32 v131, 16, v67
	global_load_ushort v65, v[94:95], off
	global_load_ushort v67, v[96:97], off
	v_lshl_add_u64 v[94:95], v[86:87], 1, s[42:43]
	v_lshl_add_u64 v[96:97], v[84:85], 1, s[42:43]
	s_waitcnt vmcnt(1)
	v_lshlrev_b32_e32 v132, 16, v65
	s_waitcnt vmcnt(0)
	v_lshlrev_b32_e32 v133, 16, v67
	global_load_ushort v65, v[94:95], off
	global_load_ushort v67, v[96:97], off
	v_lshl_add_u64 v[94:95], v[82:83], 1, s[42:43]
	v_lshl_add_u64 v[96:97], v[80:81], 1, s[42:43]
	s_waitcnt vmcnt(1)
	v_lshlrev_b32_e32 v134, 16, v65
	s_waitcnt vmcnt(0)
	v_lshlrev_b32_e32 v135, 16, v67
	global_load_ushort v65, v[94:95], off
	global_load_ushort v67, v[96:97], off
	v_lshl_add_u64 v[94:95], v[76:77], 1, s[42:43]
	v_lshl_add_u64 v[96:97], v[78:79], 1, s[42:43]
	s_waitcnt vmcnt(1)
	v_lshlrev_b32_e32 v139, 16, v65
	s_waitcnt vmcnt(0)
	v_lshlrev_b32_e32 v143, 16, v67
	global_load_ushort v65, v[94:95], off
	global_load_ushort v67, v[96:97], off
	v_lshl_add_u64 v[94:95], v[74:75], 1, s[42:43]
	v_lshl_add_u64 v[96:97], v[72:73], 1, s[42:43]
	s_waitcnt vmcnt(1)
	v_lshlrev_b32_e32 v147, 16, v65
	s_waitcnt vmcnt(0)
	v_lshlrev_b32_e32 v148, 16, v67
	global_load_ushort v65, v[94:95], off
	global_load_ushort v67, v[96:97], off
	v_lshl_add_u64 v[94:95], v[70:71], 1, s[42:43]
	v_lshl_add_u64 v[96:97], v[68:69], 1, s[42:43]
	s_waitcnt vmcnt(1)
	v_lshlrev_b32_e32 v152, 16, v65
	s_waitcnt vmcnt(0)
	v_lshlrev_b32_e32 v154, 16, v67
	global_load_ushort v65, v[94:95], off
	global_load_ushort v67, v[96:97], off
	s_waitcnt vmcnt(1)
	v_lshlrev_b32_e32 v158, 16, v65
	s_waitcnt vmcnt(0)
	v_lshlrev_b32_e32 v159, 16, v67
	v_mov_b32_e32 v67, v201
	v_lshl_add_u64 v[94:95], v[66:67], 1, s[42:43]
	v_mov_b32_e32 v65, v201
	v_lshl_add_u64 v[96:97], v[64:65], 1, s[42:43]
	global_load_ushort v94, v[94:95], off
	s_nop 0
	global_load_ushort v95, v[96:97], off
	v_add_u32_e32 v96, v157, v168
	v_mov_b32_e32 v97, v201
	v_lshl_add_u64 v[100:101], v[96:97], 1, s[42:43]
	s_waitcnt vmcnt(1)
	v_lshlrev_b32_e32 v160, 16, v94
	s_waitcnt vmcnt(0)
	v_lshlrev_b32_e32 v161, 16, v95
	v_add_u32_e32 v94, v129, v168
	v_mov_b32_e32 v95, v201
	v_lshl_add_u64 v[98:99], v[94:95], 1, s[42:43]
	global_load_ushort v100, v[100:101], off
	s_nop 0
	global_load_ushort v98, v[98:99], off
	v_mov_b32_e32 v99, v201
	v_mov_b32_e32 v101, v201
	s_waitcnt vmcnt(1)
	v_lshlrev_b32_e32 v163, 16, v100
	s_waitcnt vmcnt(0)
	v_lshlrev_b32_e32 v162, 16, v98
	v_add_u32_e32 v98, v156, v168
	v_lshl_add_u64 v[102:103], v[98:99], 1, s[42:43]
	v_add_u32_e32 v100, v155, v168
	v_lshl_add_u64 v[104:105], v[100:101], 1, s[42:43]
	global_load_ushort v102, v[102:103], off
	s_nop 0
	global_load_ushort v103, v[104:105], off
	v_add_u32_e32 v104, v151, v168
	v_mov_b32_e32 v105, v201
	v_lshl_add_u64 v[108:109], v[104:105], 1, s[42:43]
	s_waitcnt vmcnt(1)
	v_lshlrev_b32_e32 v164, 16, v102
	s_waitcnt vmcnt(0)
	v_lshlrev_b32_e32 v165, 16, v103
	v_add_u32_e32 v102, v153, v168
	v_mov_b32_e32 v103, v201
	v_lshl_add_u64 v[106:107], v[102:103], 1, s[42:43]
	global_load_ushort v106, v[106:107], off
	s_nop 0
	global_load_ushort v107, v[108:109], off
	v_add_u32_e32 v108, v149, v168
	v_mov_b32_e32 v109, v201
	v_lshl_add_u64 v[112:113], v[108:109], 1, s[42:43]
	s_waitcnt vmcnt(1)
	v_lshlrev_b32_e32 v166, 16, v106
	s_waitcnt vmcnt(0)
	v_lshlrev_b32_e32 v167, 16, v107
	v_add_u32_e32 v106, v150, v168
	v_mov_b32_e32 v107, v201
	v_lshl_add_u64 v[110:111], v[106:107], 1, s[42:43]
	global_load_ushort v110, v[110:111], off
	s_nop 0
	global_load_ushort v111, v[112:113], off
	v_add_u32_e32 v112, v145, v168
	v_mov_b32_e32 v113, v201
	v_lshl_add_u64 v[116:117], v[112:113], 1, s[42:43]
	s_waitcnt vmcnt(1)
	v_lshlrev_b32_e32 v169, 16, v110
	s_waitcnt vmcnt(0)
	v_lshlrev_b32_e32 v170, 16, v111
	v_add_u32_e32 v110, v146, v168
	v_mov_b32_e32 v111, v201
	v_lshl_add_u64 v[114:115], v[110:111], 1, s[42:43]
	global_load_ushort v114, v[114:115], off
	s_nop 0
	global_load_ushort v115, v[116:117], off
	v_add_u32_e32 v116, v142, v168
	v_mov_b32_e32 v117, v201
	v_lshl_add_u64 v[120:121], v[116:117], 1, s[42:43]
	s_waitcnt vmcnt(1)
	v_lshlrev_b32_e32 v171, 16, v114
	s_waitcnt vmcnt(0)
	v_lshlrev_b32_e32 v172, 16, v115
	v_add_u32_e32 v114, v144, v168
	v_mov_b32_e32 v115, v201
	v_lshl_add_u64 v[118:119], v[114:115], 1, s[42:43]
	global_load_ushort v118, v[118:119], off
	s_nop 0
	global_load_ushort v119, v[120:121], off
	v_add_u32_e32 v120, v140, v168
	v_mov_b32_e32 v121, v201
	v_lshl_add_u64 v[124:125], v[120:121], 1, s[42:43]
	s_waitcnt vmcnt(1)
	v_lshlrev_b32_e32 v173, 16, v118
	s_waitcnt vmcnt(0)
	v_lshlrev_b32_e32 v174, 16, v119
	v_add_u32_e32 v118, v141, v168
	v_mov_b32_e32 v119, v201
	v_lshl_add_u64 v[122:123], v[118:119], 1, s[42:43]
	global_load_ushort v122, v[122:123], off
	s_nop 0
	global_load_ushort v123, v[124:125], off
	v_add_u32_e32 v124, v137, v168
	v_mov_b32_e32 v125, v201
	v_lshl_add_u64 v[180:181], v[124:125], 1, s[42:43]
	s_waitcnt vmcnt(1)
	v_lshlrev_b32_e32 v175, 16, v122
	s_waitcnt vmcnt(0)
	v_lshlrev_b32_e32 v176, 16, v123
	v_add_u32_e32 v122, v138, v168
	v_mov_b32_e32 v123, v201
	v_lshl_add_u64 v[178:179], v[122:123], 1, s[42:43]
	global_load_ushort v177, v[178:179], off
	v_mov_b32_e32 v179, v205
	global_load_ushort v178, v[180:181], off
	v_mov_b32_e32 v181, v217
	s_waitcnt vmcnt(1)
	v_lshlrev_b32_e32 v177, 16, v177
	s_waitcnt vmcnt(0)
	v_lshlrev_b32_e32 v178, 16, v178

; __device__ __forceinline__ int ltid() { int t = (int)threadIdx.x; asm volatile("" : "+v"(t)); return t; }
; #define MFMA(a, b, c) __builtin_amdgcn_mfma_f32_32x32x16_bf16(a, b, c, 0, 0, 0)
; template <bool HALO, class AL, class BL>
; __device__ __forceinline__ void gemm_core(f32x16 (&acc)[2][2], f32x16& hacc, const AL& al, const BL& bl, int K, char* lds,
;                                           const u16* halo0, const u16* halo1, int brow0, int brow1) {
;     ...
;   const int tid = ltid(), lane = tid & 63, wid = tid >> 6, wr = wid >> 1, r32 = lane & 31, hi = lane >> 5;
;   const int lrow = tid >> 3, cg = ((tid & 7) ^ ((lrow >> 1) & 7)) * 8;
;   const u16* gh = nullptr;
;   if (HALO) { const int c = ((lane & 7) ^ ((lane >> 4) & 7)) * 8; gh = ((lane < 8) ? halo0 : halo1) + c; }
;   char* lw = lds + tid * 16;
;     ...
;   const int sa = ((wr * 64 + r32) >> 1) & 7, sb0 = ((brow0 + r32) >> 1) & 7, sb1 = ((brow1 + r32) >> 1) & 7, sh = (r32 >> 1) & 7;
;   const int oa = (wr * 64 + r32) * 128, ob0 = ABYTES + (brow0 + r32) * 128, ob1 = ABYTES + (brow1 + r32) * 128, oh = (128 + r32) * 128;
;   __syncthreads();
;   ISSUE(0, 0);
;   const int nk = K >> 6;
;   for (int kt = 0; kt < nk; ++kt) {
;     asm volatile("s_waitcnt vmcnt(0)" ::: "memory");
;     __syncthreads();
;     if (kt + 1 < nk) ISSUE((kt + 1) * 64, (kt + 1) & 1);
;     const char* T = lds + (kt & 1) * BUF;
; #pragma unroll
;     for (int kk = 0; kk < 4; ++kk) {
;       const int c = kk * 2 + hi;
;       bf16x8 a0 = *(const bf16x8*)(T + oa + ((c ^ sa) << 4));
;       bf16x8 a1 = *(const bf16x8*)(T + oa + 4096 + ((c ^ sa) << 4));
;       bf16x8 b0 = *(const bf16x8*)(T + ob0 + ((c ^ sb0) << 4));
;       bf16x8 b1 = *(const bf16x8*)(T + ob1 + ((c ^ sb1) << 4));
;       acc[0][0] = MFMA(a0, b0, acc[0][0]); acc[0][1] = MFMA(a0, b1, acc[0][1]);
;       acc[1][0] = MFMA(a1, b0, acc[1][0]); acc[1][1] = MFMA(a1, b1, acc[1][1]);
;       if (HALO) { bf16x8 ah = *(const bf16x8*)(T + oh + ((c ^ sh) << 4)); hacc = MFMA(ah, b0, hacc); }
;     }
;   }
; __device__ __forceinline__ void phase_glu(const P& p, int layer, char* lds) {
;     ...
;   for (int it = 0; tile_at(it, 256, 2, tm, tn); ++it) {
;     f32x16 acc[2][2] = {};
;     LdBf al{yg + (long)tm * 128 * 256, 256}, bl{wt + (long)tn * 128 * 256, 256};
;     gemm_plain(acc, al, bl, 256, lds);
.LBB0_252:
	s_or_b32 s58, s8, s82
	s_lshr_b32 s59, s58, 1
	s_and_b32 s59, s59, 0xf8
	s_lshl_b32 s60, s59, 1
	s_and_b32 s8, s8, 7
	s_sub_i32 s58, s58, s60
	s_or_b32 s8, s59, s8
	s_ashr_i32 s58, s58, 3
	s_lshl_b32 s59, s8, 16
	s_add_u32 s60, s42, s59
	v_mov_b32_e32 v1, v229
	v_mov_b32_e32 v6, v229
	s_addc_u32 s61, s43, 0
	s_ashr_i32 s59, s58, 31
	s_lshl_b64 s[62:63], s[58:59], 16
	v_and_b32_e32 v7, 31, v6
	v_ashrrev_i32_e32 v0, 3, v6
	v_lshrrev_b32_e32 v2, 4, v6
	v_xor_b32_e32 v4, v2, v6
	v_and_or_b32 v11, v1, 64, v7
	v_ashrrev_i32_e32 v1, 31, v0
	s_add_u32 s62, s3, s62
	v_lshlrev_b64 v[0:1], 9, v[0:1]
	v_lshlrev_b32_e32 v4, 4, v4
	s_addc_u32 s63, s6, s63
	v_lshl_add_u64 v[2:3], s[60:61], 0, v[0:1]
	v_and_b32_e32 v200, 0x70, v4
	v_lshl_add_u32 v9, v6, 4, 0
	v_lshl_add_u64 v[64:65], v[2:3], 0, v[200:201]
	v_lshl_add_u64 v[2:3], s[62:63], 0, v[0:1]
	v_add_u32_e32 v5, 0x4000, v9
	v_lshl_add_u64 v[66:67], v[2:3], 0, v[200:201]
	v_lshl_add_u64 v[2:3], v[0:1], 0, s[84:85]
	v_readfirstlane_b32 s71, v5
	v_lshl_add_u64 v[4:5], s[60:61], 0, v[2:3]
	v_lshl_add_u64 v[2:3], s[62:63], 0, v[2:3]
	v_readfirstlane_b32 s70, v9
	v_lshl_add_u64 v[70:71], v[2:3], 0, v[200:201]
	v_add_u32_e32 v2, 0x5000, v9
	s_mov_b32 m0, s70
	v_lshl_add_u64 v[68:69], v[4:5], 0, v[200:201]
	v_add_u32_e32 v4, 0x1000, v9
	v_readfirstlane_b32 s73, v2
	v_lshl_add_u64 v[2:3], v[0:1], 0, s[36:37]
	s_waitcnt lgkmcnt(0)
	s_barrier
	global_load_lds_dwordx4 v[64:65], off
	s_mov_b32 m0, s71
	v_readfirstlane_b32 s72, v4
	v_lshl_add_u64 v[4:5], s[60:61], 0, v[2:3]
	v_lshl_add_u64 v[2:3], s[62:63], 0, v[2:3]
	global_load_lds_dwordx4 v[66:67], off
	s_mov_b32 m0, s72
	v_lshl_add_u64 v[72:73], v[4:5], 0, v[200:201]
	v_add_u32_e32 v4, 0x2000, v9
	v_lshl_add_u64 v[74:75], v[2:3], 0, v[200:201]
	v_add_u32_e32 v2, 0x6000, v9
	v_lshl_add_u64 v[0:1], v[0:1], 0, s[54:55]
	global_load_lds_dwordx4 v[68:69], off
	s_mov_b32 m0, s73
	v_readfirstlane_b32 s76, v4
	v_readfirstlane_b32 s77, v2
	v_lshl_add_u64 v[2:3], s[60:61], 0, v[0:1]
	v_lshl_add_u64 v[0:1], s[62:63], 0, v[0:1]
	v_lshrrev_b32_e32 v8, 5, v6
	v_bfe_u32 v12, v6, 1, 3
	global_load_lds_dwordx4 v[70:71], off
	s_mov_b32 m0, s76
	v_lshl_add_u64 v[76:77], v[2:3], 0, v[200:201]
	v_add_u32_e32 v2, 0x3000, v9
	v_lshl_add_u64 v[78:79], v[0:1], 0, v[200:201]
	v_add_u32_e32 v0, 0x7000, v9
	global_load_lds_dwordx4 v[72:73], off
	s_mov_b32 m0, s77
	v_readfirstlane_b32 s80, v2
	v_readfirstlane_b32 s81, v0
	v_bfe_u32 v0, v6, 5, 1
	v_bitop3_b32 v1, v8, v12, 1 bitop3:0x6c
	global_load_lds_dwordx4 v[74:75], off
	s_mov_b32 m0, s80
	v_lshlrev_b32_e32 v8, 4, v1
	v_bitop3_b32 v1, v0, v12, 2 bitop3:0x36
	v_add_u32_e32 v3, 0x8000, v9
	global_load_lds_dwordx4 v[76:77], off
	s_mov_b32 m0, s81
	v_lshlrev_b32_e32 v88, 4, v1
	v_bitop3_b32 v1, v0, v12, 4 bitop3:0x36
	v_bitop3_b32 v0, v0, v12, 6 bitop3:0x36
	v_add_u32_e32 v4, 0xc000, v9
	v_readfirstlane_b32 s59, v3
	global_load_lds_dwordx4 v[78:79], off
	v_lshlrev_b32_e32 v96, 4, v1
	v_lshlrev_b32_e32 v97, 4, v0
	v_lshl_add_u64 v[0:1], v[64:65], 0, s[78:79]
	s_mov_b32 m0, s59
	v_readfirstlane_b32 s60, v4
	v_add_u32_e32 v3, 0x9000, v9
	s_waitcnt vmcnt(0)
	s_waitcnt vmcnt(0) lgkmcnt(0)
	s_barrier
	global_load_lds_dwordx4 v[0:1], off
	v_lshl_add_u64 v[0:1], v[66:67], 0, s[78:79]
	s_mov_b32 m0, s60
	v_readfirstlane_b32 s61, v3
	v_add_u32_e32 v3, 0xd000, v9
	global_load_lds_dwordx4 v[0:1], off
	v_lshl_add_u64 v[0:1], v[68:69], 0, s[78:79]
	s_mov_b32 m0, s61
	v_readfirstlane_b32 s62, v3
	v_add_u32_e32 v3, 0xa000, v9
	global_load_lds_dwordx4 v[0:1], off
	v_lshl_add_u64 v[0:1], v[70:71], 0, s[78:79]
	s_mov_b32 m0, s62
	v_readfirstlane_b32 s63, v3
	v_add_u32_e32 v3, 0xe000, v9
	global_load_lds_dwordx4 v[0:1], off
	v_lshl_add_u64 v[0:1], v[72:73], 0, s[78:79]
	s_mov_b32 m0, s63
	v_readfirstlane_b32 s64, v3
	v_add_u32_e32 v3, 0xb000, v9
	v_lshrrev_b32_e32 v10, 1, v6
	global_load_lds_dwordx4 v[0:1], off
	v_lshl_add_u64 v[0:1], v[74:75], 0, s[78:79]
	s_mov_b32 m0, s64
	v_readfirstlane_b32 s65, v3
	v_add_u32_e32 v3, 0xf000, v9
	v_and_or_b32 v2, v10, s52, v7
	global_load_lds_dwordx4 v[0:1], off
	v_lshl_add_u64 v[0:1], v[76:77], 0, s[78:79]
	s_mov_b32 m0, s65
	v_readfirstlane_b32 s69, v3
	global_load_lds_dwordx4 v[0:1], off
	v_lshl_add_u64 v[0:1], v[78:79], 0, s[78:79]
	s_mov_b32 m0, s69
	v_lshl_add_u32 v100, v2, 7, 0
	v_lshl_add_u32 v101, v11, 7, 0
	global_load_lds_dwordx4 v[0:1], off
	v_add_u32_e32 v102, v100, v8
	v_add_u32_e32 v103, v101, v8
	ds_read_b128 v[0:3], v102
	ds_read_b128 v[4:7], v102 offset:4096
	ds_read_b128 v[8:11], v103 offset:16384
	ds_read_b128 v[12:15], v103 offset:20480
	s_waitcnt lgkmcnt(0)
	v_mfma_f32_32x32x16_bf16 v[48:63], v[0:3], v[8:11], 0
	v_add_u32_e32 v104, v100, v88
	v_add_u32_e32 v105, v101, v88
	ds_read_b128 v[80:83], v104
	ds_read_b128 v[84:87], v104 offset:4096
	ds_read_b128 v[88:91], v105 offset:16384
	ds_read_b128 v[92:95], v105 offset:20480
	v_add_u32_e32 v106, v100, v96
	v_add_u32_e32 v96, v101, v96
	v_add_u32_e32 v100, v100, v97
	v_mfma_f32_32x32x16_bf16 v[32:47], v[0:3], v[12:15], 0
	v_add_u32_e32 v97, v101, v97
	s_mov_b32 m0, s70
	v_lshl_or_b32 v101, s58, 7, v98
	s_lshl_b32 s8, s8, 7
	v_add_u32_e32 v200, s18, v101
	v_mfma_f32_32x32x16_bf16 v[16:31], v[4:7], v[8:11], 0
	v_mfma_f32_32x32x16_bf16 v[0:15], v[4:7], v[12:15], 0
	s_waitcnt lgkmcnt(0)
	v_mfma_f32_32x32x16_bf16 v[48:63], v[80:83], v[88:91], v[48:63]
	v_mfma_f32_32x32x16_bf16 v[32:47], v[80:83], v[92:95], v[32:47]
	v_mfma_f32_32x32x16_bf16 v[16:31], v[84:87], v[88:91], v[16:31]
	v_mfma_f32_32x32x16_bf16 v[0:15], v[84:87], v[92:95], v[0:15]
	ds_read_b128 v[80:83], v106
	ds_read_b128 v[84:87], v106 offset:4096
	ds_read_b128 v[88:91], v96 offset:16384
	ds_read_b128 v[92:95], v96 offset:20480
	s_waitcnt lgkmcnt(0)
	v_mfma_f32_32x32x16_bf16 v[48:63], v[80:83], v[88:91], v[48:63]
	v_mfma_f32_32x32x16_bf16 v[32:47], v[80:83], v[92:95], v[32:47]
	v_mfma_f32_32x32x16_bf16 v[16:31], v[84:87], v[88:91], v[16:31]
	v_mfma_f32_32x32x16_bf16 v[0:15], v[84:87], v[92:95], v[0:15]
	ds_read_b128 v[80:83], v100
	ds_read_b128 v[84:87], v100 offset:4096
	ds_read_b128 v[88:91], v97 offset:16384
	ds_read_b128 v[92:95], v97 offset:20480
	s_waitcnt vmcnt(0)
	s_waitcnt vmcnt(0) lgkmcnt(0)
	s_barrier
; #define MFMA(a, b, c) __builtin_amdgcn_mfma_f32_32x32x16_bf16(a, b, c, 0, 0, 0)
; #define ISSUE(k0, bf) do { char* A_ = lw + (bf) * BUF; \
;     _Pragma("unroll") for (int i_ = 0; i_ < 4; ++i_) { glds16(al.ptr(lrow + 32 * i_, (k0) + cg), A_ + i_ * 4096); glds16(bl.ptr(lrow + 32 * i_, (k0) + cg), A_ + ABYTES + i_ * 4096); } \
;     if (HALO) { if (wid == 0) glds16(gh + (k0), A_ + 16384); } } while (0)
; template <bool HALO, class AL, class BL>
; __device__ __forceinline__ void gemm_core(f32x16 (&acc)[2][2], f32x16& hacc, const AL& al, const BL& bl, int K, char* lds,
;                                           const u16* halo0, const u16* halo1, int brow0, int brow1) {
;     ...
;   for (int kt = 0; kt < nk; ++kt) {
;     asm volatile("s_waitcnt vmcnt(0)" ::: "memory");
;     __syncthreads();
;     if (kt + 1 < nk) ISSUE((kt + 1) * 64, (kt + 1) & 1);
;     const char* T = lds + (kt & 1) * BUF;
; #pragma unroll
;     for (int kk = 0; kk < 4; ++kk) {
;       const int c = kk * 2 + hi;
;       bf16x8 a0 = *(const bf16x8*)(T + oa + ((c ^ sa) << 4));
;       bf16x8 a1 = *(const bf16x8*)(T + oa + 4096 + ((c ^ sa) << 4));
;       bf16x8 b0 = *(const bf16x8*)(T + ob0 + ((c ^ sb0) << 4));
;       bf16x8 b1 = *(const bf16x8*)(T + ob1 + ((c ^ sb1) << 4));
;       acc[0][0] = MFMA(a0, b0, acc[0][0]); acc[0][1] = MFMA(a0, b1, acc[0][1]);
;       acc[1][0] = MFMA(a1, b0, acc[1][0]); acc[1][1] = MFMA(a1, b1, acc[1][1]);
;       if (HALO) { bf16x8 ah = *(const bf16x8*)(T + oh + ((c ^ sh) << 4)); hacc = MFMA(ah, b0, hacc); }
;     }
;   }
	v_mfma_f32_32x32x16_bf16 v[48:63], v[80:83], v[88:91], v[48:63]
	v_mfma_f32_32x32x16_bf16 v[32:47], v[80:83], v[92:95], v[32:47]
	v_lshl_add_u64 v[80:81], v[64:65], 0, s[24:25]
	global_load_lds_dwordx4 v[80:81], off
	v_lshl_add_u64 v[80:81], v[66:67], 0, s[24:25]
	s_mov_b32 m0, s71
	v_lshl_add_u64 v[64:65], v[64:65], 0, s[74:75]
	global_load_lds_dwordx4 v[80:81], off
	v_lshl_add_u64 v[80:81], v[68:69], 0, s[24:25]
	s_mov_b32 m0, s72
	v_mfma_f32_32x32x16_bf16 v[16:31], v[84:87], v[88:91], v[16:31]
	global_load_lds_dwordx4 v[80:81], off
	v_lshl_add_u64 v[80:81], v[70:71], 0, s[24:25]
	s_mov_b32 m0, s73
	s_nop 0
	global_load_lds_dwordx4 v[80:81], off
	v_lshl_add_u64 v[80:81], v[72:73], 0, s[24:25]
	s_mov_b32 m0, s76
	v_mfma_f32_32x32x16_bf16 v[0:15], v[84:87], v[92:95], v[0:15]
	global_load_lds_dwordx4 v[80:81], off
	v_lshl_add_u64 v[80:81], v[74:75], 0, s[24:25]
	s_mov_b32 m0, s77
	s_nop 0
	global_load_lds_dwordx4 v[80:81], off
	v_lshl_add_u64 v[80:81], v[76:77], 0, s[24:25]
	s_mov_b32 m0, s80
	s_nop 0
	global_load_lds_dwordx4 v[80:81], off
	v_lshl_add_u64 v[80:81], v[78:79], 0, s[24:25]
	s_mov_b32 m0, s81
	s_nop 0
	global_load_lds_dwordx4 v[80:81], off
	ds_read_b128 v[80:83], v102 offset:32768
	ds_read_b128 v[84:87], v102 offset:36864
	ds_read_b128 v[88:91], v103 offset:49152
	ds_read_b128 v[92:95], v103 offset:53248
	s_waitcnt lgkmcnt(0)
	v_mfma_f32_32x32x16_bf16 v[48:63], v[80:83], v[88:91], v[48:63]
	s_mov_b32 m0, s59
	v_mfma_f32_32x32x16_bf16 v[32:47], v[80:83], v[92:95], v[32:47]
	v_mfma_f32_32x32x16_bf16 v[16:31], v[84:87], v[88:91], v[16:31]
	v_mfma_f32_32x32x16_bf16 v[0:15], v[84:87], v[92:95], v[0:15]
	ds_read_b128 v[80:83], v104 offset:32768
	ds_read_b128 v[84:87], v104 offset:36864
	ds_read_b128 v[88:91], v105 offset:49152
	ds_read_b128 v[92:95], v105 offset:53248
	s_waitcnt lgkmcnt(0)
	v_mfma_f32_32x32x16_bf16 v[48:63], v[80:83], v[88:91], v[48:63]
	v_mfma_f32_32x32x16_bf16 v[32:47], v[80:83], v[92:95], v[32:47]
	v_mfma_f32_32x32x16_bf16 v[16:31], v[84:87], v[88:91], v[16:31]
	v_mfma_f32_32x32x16_bf16 v[0:15], v[84:87], v[92:95], v[0:15]
	ds_read_b128 v[80:83], v106 offset:32768
	ds_read_b128 v[84:87], v106 offset:36864
	ds_read_b128 v[88:91], v96 offset:49152
	ds_read_b128 v[92:95], v96 offset:53248
	s_waitcnt lgkmcnt(0)
	v_mfma_f32_32x32x16_bf16 v[48:63], v[80:83], v[88:91], v[48:63]
	v_mfma_f32_32x32x16_bf16 v[32:47], v[80:83], v[92:95], v[32:47]
	v_mfma_f32_32x32x16_bf16 v[16:31], v[84:87], v[88:91], v[16:31]
	v_mfma_f32_32x32x16_bf16 v[0:15], v[84:87], v[92:95], v[0:15]
	ds_read_b128 v[80:83], v100 offset:32768
	ds_read_b128 v[84:87], v100 offset:36864
	ds_read_b128 v[88:91], v97 offset:49152
	ds_read_b128 v[92:95], v97 offset:53248
	s_waitcnt vmcnt(0)
	s_waitcnt vmcnt(0) lgkmcnt(0)
	s_barrier
	global_load_lds_dwordx4 v[64:65], off
	v_lshl_add_u64 v[64:65], v[66:67], 0, s[74:75]
	s_mov_b32 m0, s60
	v_mfma_f32_32x32x16_bf16 v[48:63], v[80:83], v[88:91], v[48:63]
	global_load_lds_dwordx4 v[64:65], off
	v_lshl_add_u64 v[64:65], v[68:69], 0, s[74:75]
	s_mov_b32 m0, s61
	s_nop 0
	global_load_lds_dwordx4 v[64:65], off
	v_lshl_add_u64 v[64:65], v[70:71], 0, s[74:75]
	s_mov_b32 m0, s62
	v_mfma_f32_32x32x16_bf16 v[32:47], v[80:83], v[92:95], v[32:47]
	global_load_lds_dwordx4 v[64:65], off
	v_lshl_add_u64 v[64:65], v[72:73], 0, s[74:75]
	s_mov_b32 m0, s63
	s_nop 0
	global_load_lds_dwordx4 v[64:65], off
	v_lshl_add_u64 v[64:65], v[74:75], 0, s[74:75]
	s_mov_b32 m0, s64
	v_mfma_f32_32x32x16_bf16 v[16:31], v[84:87], v[88:91], v[16:31]
	global_load_lds_dwordx4 v[64:65], off
	v_lshl_add_u64 v[64:65], v[76:77], 0, s[74:75]
	s_mov_b32 m0, s65
	s_nop 0
	global_load_lds_dwordx4 v[64:65], off
	v_lshl_add_u64 v[64:65], v[78:79], 0, s[74:75]
	s_mov_b32 m0, s69
	v_mfma_f32_32x32x16_bf16 v[0:15], v[84:87], v[92:95], v[0:15]
	global_load_lds_dwordx4 v[64:65], off
	ds_read_b128 v[64:67], v102
	ds_read_b128 v[68:71], v102 offset:4096
	ds_read_b128 v[72:75], v103 offset:16384
	ds_read_b128 v[76:79], v103 offset:20480
	s_waitcnt lgkmcnt(0)
	v_mfma_f32_32x32x16_bf16 v[48:63], v[64:67], v[72:75], v[48:63]
	v_mfma_f32_32x32x16_bf16 v[32:47], v[64:67], v[76:79], v[32:47]
	v_mfma_f32_32x32x16_bf16 v[16:31], v[68:71], v[72:75], v[16:31]
	v_mfma_f32_32x32x16_bf16 v[0:15], v[68:71], v[76:79], v[0:15]
	ds_read_b128 v[64:67], v104
	ds_read_b128 v[68:71], v104 offset:4096
	ds_read_b128 v[72:75], v105 offset:16384
	ds_read_b128 v[76:79], v105 offset:20480
	s_waitcnt lgkmcnt(0)
	v_mfma_f32_32x32x16_bf16 v[48:63], v[64:67], v[72:75], v[48:63]
	v_mfma_f32_32x32x16_bf16 v[32:47], v[64:67], v[76:79], v[32:47]
	v_mfma_f32_32x32x16_bf16 v[16:31], v[68:71], v[72:75], v[16:31]
	v_mfma_f32_32x32x16_bf16 v[0:15], v[68:71], v[76:79], v[0:15]
	ds_read_b128 v[64:67], v106
	ds_read_b128 v[68:71], v106 offset:4096
	ds_read_b128 v[72:75], v96 offset:16384
	ds_read_b128 v[76:79], v96 offset:20480
	s_waitcnt lgkmcnt(0)
	v_mfma_f32_32x32x16_bf16 v[48:63], v[64:67], v[72:75], v[48:63]
	v_mfma_f32_32x32x16_bf16 v[32:47], v[64:67], v[76:79], v[32:47]
	v_mfma_f32_32x32x16_bf16 v[16:31], v[68:71], v[72:75], v[16:31]
	v_mfma_f32_32x32x16_bf16 v[0:15], v[68:71], v[76:79], v[0:15]
	ds_read_b128 v[64:67], v100
	ds_read_b128 v[68:71], v100 offset:4096
	ds_read_b128 v[72:75], v97 offset:16384
	ds_read_b128 v[76:79], v97 offset:20480
	s_waitcnt vmcnt(0)
	s_waitcnt vmcnt(0) lgkmcnt(0)
	s_barrier
; __device__ __forceinline__ u16 f2bf(float x) { return (u16)(cvtpk(x, 0.f) & 0xffffu); }
; __device__ __forceinline__ float bf2f(u16 v) { return __uint_as_float(((unsigned)v) << 16); }
; __device__ __forceinline__ float sigmoidf_(float x) { return __builtin_amdgcn_rcpf(1.f + __expf(-x)); }
; #define MFMA(a, b, c) __builtin_amdgcn_mfma_f32_32x32x16_bf16(a, b, c, 0, 0, 0)
; template <bool HALO, class AL, class BL>
; __device__ __forceinline__ void gemm_core(f32x16 (&acc)[2][2], f32x16& hacc, const AL& al, const BL& bl, int K, char* lds,
;                                           const u16* halo0, const u16* halo1, int brow0, int brow1) {
;     ...
;       bf16x8 a0 = *(const bf16x8*)(T + oa + ((c ^ sa) << 4));
;       bf16x8 a1 = *(const bf16x8*)(T + oa + 4096 + ((c ^ sa) << 4));
;       bf16x8 b0 = *(const bf16x8*)(T + ob0 + ((c ^ sb0) << 4));
;       bf16x8 b1 = *(const bf16x8*)(T + ob1 + ((c ^ sb1) << 4));
;       acc[0][0] = MFMA(a0, b0, acc[0][0]); acc[0][1] = MFMA(a0, b1, acc[0][1]);
;       acc[1][0] = MFMA(a1, b0, acc[1][0]); acc[1][1] = MFMA(a1, b1, acc[1][1]);
; __device__ __forceinline__ void phase_glu(const P& p, int layer, char* lds) {
;     ...
;     for (int mi = 0; mi < 2; ++mi) {
; #pragma unroll
;       for (int ni = 0; ni < 2; ++ni) {
;         const unsigned col = tn * 128 + wc * 64 + ni * 32 + r32;
;         const float gb = p.glu_b[layer * 256 + col];
;         u16 yv[16];
; #pragma unroll
;         for (int r = 0; r < 16; ++r) yv[r] = yg[(rb + mi * 32 + (r & 3) + 8 * (r >> 2)) * 256 + col];
; #pragma unroll
;         for (int r = 0; r < 16; ++r) {
;           const unsigned row = rb + mi * 32 + (r & 3) + 8 * (r >> 2);
;           ymix[row * 1024 + 768 + col] = f2bf(bf2f(yv[r]) * sigmoidf_(acc[mi][ni][r] + gb));
	v_mfma_f32_32x32x16_bf16 v[48:63], v[64:67], v[72:75], v[48:63]
	v_mfma_f32_32x32x16_bf16 v[32:47], v[64:67], v[76:79], v[32:47]
	v_mfma_f32_32x32x16_bf16 v[16:31], v[68:71], v[72:75], v[16:31]
	v_mfma_f32_32x32x16_bf16 v[0:15], v[68:71], v[76:79], v[0:15]
	ds_read_b128 v[64:67], v102 offset:32768
	ds_read_b128 v[68:71], v102 offset:36864
	ds_read_b128 v[72:75], v103 offset:49152
	ds_read_b128 v[76:79], v103 offset:53248
	s_waitcnt lgkmcnt(1)
	v_mfma_f32_32x32x16_bf16 v[48:63], v[64:67], v[72:75], v[48:63]
	s_waitcnt lgkmcnt(0)
	v_mfma_f32_32x32x16_bf16 v[32:47], v[64:67], v[76:79], v[32:47]
	v_mfma_f32_32x32x16_bf16 v[16:31], v[68:71], v[72:75], v[16:31]
	v_mfma_f32_32x32x16_bf16 v[0:15], v[68:71], v[76:79], v[0:15]
	ds_read_b128 v[64:67], v104 offset:32768
	ds_read_b128 v[68:71], v104 offset:36864
	ds_read_b128 v[72:75], v105 offset:49152
	ds_read_b128 v[76:79], v105 offset:53248
	s_waitcnt lgkmcnt(1)
	v_mfma_f32_32x32x16_bf16 v[48:63], v[64:67], v[72:75], v[48:63]
	s_waitcnt lgkmcnt(0)
	v_mfma_f32_32x32x16_bf16 v[32:47], v[64:67], v[76:79], v[32:47]
	v_mfma_f32_32x32x16_bf16 v[16:31], v[68:71], v[72:75], v[16:31]
	v_mfma_f32_32x32x16_bf16 v[0:15], v[68:71], v[76:79], v[0:15]
	ds_read_b128 v[64:67], v106 offset:32768
	ds_read_b128 v[68:71], v106 offset:36864
	ds_read_b128 v[72:75], v96 offset:49152
	ds_read_b128 v[76:79], v96 offset:53248
	s_waitcnt lgkmcnt(1)
	v_mfma_f32_32x32x16_bf16 v[48:63], v[64:67], v[72:75], v[48:63]
	s_waitcnt lgkmcnt(0)
	v_mfma_f32_32x32x16_bf16 v[32:47], v[64:67], v[76:79], v[32:47]
	v_mfma_f32_32x32x16_bf16 v[16:31], v[68:71], v[72:75], v[16:31]
	v_mfma_f32_32x32x16_bf16 v[0:15], v[68:71], v[76:79], v[0:15]
	ds_read_b128 v[64:67], v100 offset:32768
	ds_read_b128 v[68:71], v100 offset:36864
	ds_read_b128 v[72:75], v97 offset:49152
	ds_read_b128 v[76:79], v97 offset:53248
	v_add_u32_e32 v100, 0x300, v101
	s_waitcnt lgkmcnt(1)
	v_mfma_f32_32x32x16_bf16 v[48:63], v[64:67], v[72:75], v[48:63]
	s_waitcnt lgkmcnt(0)
	v_mfma_f32_32x32x16_bf16 v[32:47], v[64:67], v[76:79], v[32:47]
	v_mov_b32_e32 v64, v201
	s_nop 0
	v_add3_u32 v102, v99, s8, v64
	v_lshl_add_u64 v[64:65], v[200:201], 2, s[40:41]
	global_load_dword v119, v[64:65], off
	v_lshlrev_b32_e32 v103, 8, v102
	v_add_u32_e32 v200, v103, v101
	v_lshl_add_u64 v[96:97], v[200:201], 1, s[42:43]
	global_load_ushort v96, v[96:97], off
	v_add_u32_e32 v134, 1, v102
	v_lshlrev_b32_e32 v104, 8, v134
	v_add_u32_e32 v133, 2, v102
	v_add_u32_e32 v200, v104, v101
	v_lshlrev_b32_e32 v105, 8, v133
	v_add_u32_e32 v132, 3, v102
	v_lshl_add_u64 v[94:95], v[200:201], 1, s[42:43]
	v_add_u32_e32 v200, v105, v101
	v_lshlrev_b32_e32 v106, 8, v132
	v_add_u32_e32 v131, 8, v102
	v_lshl_add_u64 v[92:93], v[200:201], 1, s[42:43]
	v_add_u32_e32 v200, v106, v101
	v_lshlrev_b32_e32 v107, 8, v131
	v_add_u32_e32 v130, 9, v102
	v_lshl_add_u64 v[90:91], v[200:201], 1, s[42:43]
	v_add_u32_e32 v200, v107, v101
	v_lshlrev_b32_e32 v108, 8, v130
	v_add_u32_e32 v129, 10, v102
	v_lshl_add_u64 v[88:89], v[200:201], 1, s[42:43]
	v_add_u32_e32 v200, v108, v101
	v_lshlrev_b32_e32 v109, 8, v129
	v_add_u32_e32 v128, 11, v102
	v_lshl_add_u64 v[86:87], v[200:201], 1, s[42:43]
	v_add_u32_e32 v200, v109, v101
	v_lshlrev_b32_e32 v110, 8, v128
	v_add_u32_e32 v127, 16, v102
	v_mfma_f32_32x32x16_bf16 v[16:31], v[68:71], v[72:75], v[16:31]
	v_lshlrev_b32_e32 v111, 8, v127
	v_add_u32_e32 v126, 17, v102
	v_lshlrev_b32_e32 v112, 8, v126
	v_add_u32_e32 v125, 18, v102
	v_lshlrev_b32_e32 v113, 8, v125
	v_add_u32_e32 v124, 19, v102
	v_lshlrev_b32_e32 v114, 8, v124
	v_mfma_f32_32x32x16_bf16 v[0:15], v[68:71], v[76:79], v[0:15]
	v_lshl_add_u64 v[70:71], v[200:201], 1, s[42:43]
	v_add_u32_e32 v200, v110, v101
	v_lshl_add_u64 v[72:73], v[200:201], 1, s[42:43]
	v_add_u32_e32 v200, v111, v101
	v_lshl_add_u64 v[66:67], v[200:201], 1, s[42:43]
	v_add_u32_e32 v200, v112, v101
	v_lshl_add_u64 v[68:69], v[200:201], 1, s[42:43]
	v_add_u32_e32 v200, v113, v101
	v_add_u32_e32 v123, 24, v102
	v_lshl_add_u64 v[74:75], v[200:201], 1, s[42:43]
	v_add_u32_e32 v200, v114, v101
	v_lshlrev_b32_e32 v115, 8, v123
	v_add_u32_e32 v122, 25, v102
	v_lshl_add_u64 v[76:77], v[200:201], 1, s[42:43]
	v_add_u32_e32 v200, v115, v101
	v_lshlrev_b32_e32 v116, 8, v122
	v_add_u32_e32 v121, 26, v102
	v_lshl_add_u64 v[78:79], v[200:201], 1, s[42:43]
	v_add_u32_e32 v200, v116, v101
	v_lshlrev_b32_e32 v117, 8, v121
	v_add_u32_e32 v120, 27, v102
	v_lshl_add_u64 v[80:81], v[200:201], 1, s[42:43]
	v_add_u32_e32 v200, v117, v101
	v_lshlrev_b32_e32 v118, 8, v120
	v_lshl_add_u64 v[82:83], v[200:201], 1, s[42:43]
	v_add_u32_e32 v200, v118, v101
	v_lshl_add_u64 v[84:85], v[200:201], 1, s[42:43]
	s_waitcnt vmcnt(1)
	v_add_f32_e32 v48, v48, v119
	v_mul_f32_e32 v48, 0xbfb8aa3b, v48
	v_exp_f32_e32 v48, v48
	v_add_f32_e32 v49, v49, v119
	s_waitcnt vmcnt(0)
	v_lshlrev_b32_e32 v96, 16, v96
	v_mul_f32_e32 v49, 0xbfb8aa3b, v49
	v_add_f32_e32 v48, 1.0, v48
	v_rcp_f32_e32 v48, v48
	v_exp_f32_e32 v49, v49
	v_add_f32_e32 v50, v50, v119
	v_mul_f32_e32 v50, 0xbfb8aa3b, v50
	v_mul_f32_e32 v96, v48, v96
	global_load_ushort v94, v[94:95], off
	s_nop 0
	global_load_ushort v92, v[92:93], off
	s_nop 0
	global_load_ushort v90, v[90:91], off
	s_nop 0
	global_load_ushort v88, v[88:89], off
	s_nop 0
	global_load_ushort v86, v[86:87], off
	s_nop 0
	global_load_ushort v87, v[70:71], off
	global_load_ushort v89, v[72:73], off
	global_load_ushort v91, v[66:67], off
	s_nop 0
	global_load_ushort v71, v[68:69], off
	global_load_ushort v70, v[74:75], off
	s_nop 0
	global_load_ushort v69, v[76:77], off
	global_load_ushort v68, v[78:79], off
	global_load_ushort v67, v[80:81], off
	global_load_ushort v66, v[82:83], off
	global_load_ushort v48, v[84:85], off
	v_exp_f32_e32 v50, v50
	v_add_f32_e32 v49, 1.0, v49
	v_lshlrev_b32_e32 v81, 10, v102
	v_rcp_f32_e32 v49, v49
	v_add_u32_e32 v200, v81, v100
	v_lshl_add_u64 v[72:73], v[200:201], 1, s[56:57]
	v_add_f32_e32 v50, 1.0, v50
	v_cvt_pk_bf16_f32 v74, v96, v201
	global_store_short v[72:73], v74, off
	v_lshlrev_b32_e32 v78, 10, v134
	v_rcp_f32_e32 v50, v50
	v_add_u32_e32 v200, v78, v100
	v_lshlrev_b32_e32 v79, 10, v133
	v_lshlrev_b32_e32 v80, 10, v132
	v_lshlrev_b32_e32 v82, 10, v131
	v_lshlrev_b32_e32 v83, 10, v130
	v_lshlrev_b32_e32 v84, 10, v129
	v_lshlrev_b32_e32 v85, 10, v128
	v_lshlrev_b32_e32 v93, 10, v120
	v_or_b32_e32 v77, 32, v101
	v_add_u32_e32 v76, 0x320, v101
	s_waitcnt vmcnt(15)
; __device__ __forceinline__ u16 f2bf(float x) { return (u16)(cvtpk(x, 0.f) & 0xffffu); }
; __device__ __forceinline__ float bf2f(u16 v) { return __uint_as_float(((unsigned)v) << 16); }
; __device__ __forceinline__ float sigmoidf_(float x) { return __builtin_amdgcn_rcpf(1.f + __expf(-x)); }
; __device__ __forceinline__ void phase_glu(const P& p, int layer, char* lds) {
;     ...
;     for (int mi = 0; mi < 2; ++mi) {
; #pragma unroll
;       for (int ni = 0; ni < 2; ++ni) {
;         const unsigned col = tn * 128 + wc * 64 + ni * 32 + r32;
;         const float gb = p.glu_b[layer * 256 + col];
;         u16 yv[16];
; #pragma unroll
;         for (int r = 0; r < 16; ++r) yv[r] = yg[(rb + mi * 32 + (r & 3) + 8 * (r >> 2)) * 256 + col];
; #pragma unroll
;         for (int r = 0; r < 16; ++r) {
;           const unsigned row = rb + mi * 32 + (r & 3) + 8 * (r >> 2);
;           ymix[row * 1024 + 768 + col] = f2bf(bf2f(yv[r]) * sigmoidf_(acc[mi][ni][r] + gb));
	v_lshlrev_b32_e32 v72, 16, v94
	v_mul_f32_e32 v49, v49, v72
	v_cvt_pk_bf16_f32 v49, v49, v201
	v_lshl_add_u64 v[72:73], v[200:201], 1, s[56:57]
	global_store_short v[72:73], v49, off
	s_waitcnt vmcnt(15)
	v_lshlrev_b32_e32 v49, 16, v92
	v_mul_f32_e32 v49, v50, v49
	v_add_f32_e32 v50, v51, v119
	v_mul_f32_e32 v50, 0xbfb8aa3b, v50
	v_exp_f32_e32 v50, v50
	v_add_u32_e32 v200, v79, v100
	v_cvt_pk_bf16_f32 v49, v49, v201
	v_lshl_add_u64 v[72:73], v[200:201], 1, s[56:57]
	v_add_f32_e32 v50, 1.0, v50
	v_rcp_f32_e32 v50, v50
	global_store_short v[72:73], v49, off
	s_waitcnt vmcnt(15)
	v_lshlrev_b32_e32 v49, 16, v90
	v_add_u32_e32 v200, v80, v100
	v_mul_f32_e32 v49, v50, v49
	v_lshl_add_u64 v[50:51], v[200:201], 1, s[56:57]
	v_cvt_pk_bf16_f32 v49, v49, v201
	global_store_short v[50:51], v49, off
	v_add_f32_e32 v50, v52, v119
	v_mul_f32_e32 v50, 0xbfb8aa3b, v50
	v_exp_f32_e32 v50, v50
	s_waitcnt vmcnt(15)
	v_lshlrev_b32_e32 v49, 16, v88
	v_add_u32_e32 v200, v82, v100
	v_lshlrev_b32_e32 v88, 10, v125
	v_add_f32_e32 v50, 1.0, v50
	v_rcp_f32_e32 v50, v50
	v_lshlrev_b32_e32 v90, 10, v123
	v_lshlrev_b32_e32 v92, 10, v121
	s_waitcnt vmcnt(4)
	v_lshlrev_b32_e32 v48, 16, v48
	v_mul_f32_e32 v49, v50, v49
	v_lshl_add_u64 v[50:51], v[200:201], 1, s[56:57]
	v_cvt_pk_bf16_f32 v49, v49, v201
	global_store_short v[50:51], v49, off
	v_add_f32_e32 v50, v53, v119
	v_mul_f32_e32 v50, 0xbfb8aa3b, v50
	v_exp_f32_e32 v50, v50
	v_lshlrev_b32_e32 v49, 16, v86
	v_add_u32_e32 v200, v83, v100
	v_lshlrev_b32_e32 v86, 10, v127
	v_add_f32_e32 v50, 1.0, v50
	v_rcp_f32_e32 v50, v50
	s_nop 0
	v_mul_f32_e32 v49, v50, v49
	v_lshl_add_u64 v[50:51], v[200:201], 1, s[56:57]
	v_cvt_pk_bf16_f32 v49, v49, v201
	global_store_short v[50:51], v49, off
	v_add_f32_e32 v50, v54, v119
	v_mul_f32_e32 v50, 0xbfb8aa3b, v50
	v_exp_f32_e32 v50, v50
	v_lshlrev_b32_e32 v49, 16, v87
	v_add_u32_e32 v200, v84, v100
	v_lshlrev_b32_e32 v87, 10, v126
	v_add_f32_e32 v50, 1.0, v50
	v_rcp_f32_e32 v50, v50
	s_nop 0
	v_mul_f32_e32 v49, v50, v49
	v_lshl_add_u64 v[50:51], v[200:201], 1, s[56:57]
	v_cvt_pk_bf16_f32 v49, v49, v201
	global_store_short v[50:51], v49, off
	v_add_f32_e32 v50, v55, v119
	v_mul_f32_e32 v50, 0xbfb8aa3b, v50
	v_exp_f32_e32 v50, v50
	v_lshlrev_b32_e32 v49, 16, v89
	v_add_u32_e32 v200, v85, v100
	v_lshlrev_b32_e32 v89, 10, v124
	v_add_f32_e32 v50, 1.0, v50
	v_rcp_f32_e32 v50, v50
	s_nop 0
	v_mul_f32_e32 v49, v50, v49
	v_lshl_add_u64 v[50:51], v[200:201], 1, s[56:57]
	v_cvt_pk_bf16_f32 v49, v49, v201
	global_store_short v[50:51], v49, off
	v_add_f32_e32 v50, v56, v119
	v_mul_f32_e32 v50, 0xbfb8aa3b, v50
	v_exp_f32_e32 v50, v50
	v_lshlrev_b32_e32 v49, 16, v91
	v_add_u32_e32 v200, v86, v100
	v_lshlrev_b32_e32 v91, 10, v122
	v_add_f32_e32 v50, 1.0, v50
	v_rcp_f32_e32 v50, v50
	s_nop 0
	v_mul_f32_e32 v49, v50, v49
	v_lshl_add_u64 v[50:51], v[200:201], 1, s[56:57]
	v_cvt_pk_bf16_f32 v49, v49, v201
	global_store_short v[50:51], v49, off
	v_add_f32_e32 v50, v57, v119
	v_mul_f32_e32 v50, 0xbfb8aa3b, v50
	v_exp_f32_e32 v50, v50
	v_lshlrev_b32_e32 v49, 16, v71
	v_add_u32_e32 v200, v87, v100
	v_add_f32_e32 v50, 1.0, v50
	v_rcp_f32_e32 v50, v50
	s_nop 0
	v_mul_f32_e32 v49, v50, v49
	v_lshl_add_u64 v[50:51], v[200:201], 1, s[56:57]
	v_cvt_pk_bf16_f32 v49, v49, v201
	global_store_short v[50:51], v49, off
	v_add_f32_e32 v50, v58, v119
	v_mul_f32_e32 v50, 0xbfb8aa3b, v50
	v_exp_f32_e32 v50, v50
	v_lshlrev_b32_e32 v49, 16, v70
	v_add_u32_e32 v200, v88, v100
	v_add_f32_e32 v50, 1.0, v50
	v_rcp_f32_e32 v50, v50
	s_nop 0
	v_mul_f32_e32 v49, v50, v49
	v_lshl_add_u64 v[50:51], v[200:201], 1, s[56:57]
	v_cvt_pk_bf16_f32 v49, v49, v201
	global_store_short v[50:51], v49, off
	v_add_f32_e32 v50, v59, v119
	v_mul_f32_e32 v50, 0xbfb8aa3b, v50
	v_exp_f32_e32 v50, v50
	v_lshlrev_b32_e32 v49, 16, v69
	v_add_u32_e32 v200, v89, v100
	v_add_f32_e32 v50, 1.0, v50
	v_rcp_f32_e32 v50, v50
	s_nop 0
	v_mul_f32_e32 v49, v50, v49
	v_lshl_add_u64 v[50:51], v[200:201], 1, s[56:57]
	v_cvt_pk_bf16_f32 v49, v49, v201
	global_store_short v[50:51], v49, off
	v_add_f32_e32 v50, v60, v119
	v_mul_f32_e32 v50, 0xbfb8aa3b, v50
	v_exp_f32_e32 v50, v50
	v_lshlrev_b32_e32 v49, 16, v68
	v_add_u32_e32 v200, v90, v100
	v_add_f32_e32 v50, 1.0, v50
	v_rcp_f32_e32 v50, v50
	s_nop 0
	v_mul_f32_e32 v49, v50, v49
	v_lshl_add_u64 v[50:51], v[200:201], 1, s[56:57]
	v_cvt_pk_bf16_f32 v49, v49, v201
	global_store_short v[50:51], v49, off
	v_add_f32_e32 v50, v61, v119
	v_mul_f32_e32 v50, 0xbfb8aa3b, v50
	v_exp_f32_e32 v50, v50
	v_lshlrev_b32_e32 v49, 16, v67
	v_add_u32_e32 v200, v91, v100
	v_add_f32_e32 v50, 1.0, v50
	v_rcp_f32_e32 v50, v50
	s_nop 0
	v_mul_f32_e32 v49, v50, v49
	v_lshl_add_u64 v[50:51], v[200:201], 1, s[56:57]
	v_cvt_pk_bf16_f32 v49, v49, v201
	global_store_short v[50:51], v49, off
	v_add_f32_e32 v50, v62, v119
	v_mul_f32_e32 v50, 0xbfb8aa3b, v50
	v_exp_f32_e32 v50, v50
	v_lshlrev_b32_e32 v49, 16, v66
	v_add_u32_e32 v200, v92, v100
	v_add_f32_e32 v50, 1.0, v50
	v_rcp_f32_e32 v50, v50
	s_nop 0
	v_mul_f32_e32 v49, v50, v49
	v_cvt_pk_bf16_f32 v49, v49, v201
	v_lshl_add_u64 v[50:51], v[200:201], 1, s[56:57]
	global_store_short v[50:51], v49, off
	v_add_f32_e32 v49, v63, v119
	v_mul_f32_e32 v49, 0xbfb8aa3b, v49
	v_exp_f32_e32 v49, v49
	v_add_u32_e32 v200, v93, v100
	v_add_f32_e32 v49, 1.0, v49
	v_rcp_f32_e32 v49, v49
	s_nop 0
	v_mul_f32_e32 v48, v49, v48
	v_cvt_pk_bf16_f32 v50, v48, v201
	v_lshl_add_u64 v[48:49], v[200:201], 1, s[56:57]
	v_add_u32_e32 v200, s18, v77
	global_store_short v[48:49], v50, off
	v_lshl_add_u64 v[48:49], v[200:201], 2, s[40:41]
	global_load_dword v94, v[48:49], off
	v_add_u32_e32 v200, v103, v77
	v_lshl_add_u64 v[96:97], v[200:201], 1, s[42:43]
	global_load_ushort v95, v[96:97], off
	v_add_u32_e32 v200, v104, v77
	v_lshl_add_u64 v[120:121], v[200:201], 1, s[42:43]
	v_add_u32_e32 v200, v105, v77
	v_lshl_add_u64 v[104:105], v[200:201], 1, s[42:43]
	v_add_u32_e32 v200, v106, v77
	v_lshl_add_u64 v[122:123], v[200:201], 1, s[42:43]
	v_add_u32_e32 v200, v107, v77
	v_lshl_add_u64 v[74:75], v[200:201], 1, s[42:43]
	v_add_u32_e32 v200, v108, v77
	v_lshl_add_u64 v[72:73], v[200:201], 1, s[42:43]
	v_add_u32_e32 v200, v109, v77
	v_lshl_add_u64 v[70:71], v[200:201], 1, s[42:43]
	v_add_u32_e32 v200, v110, v77
	v_lshl_add_u64 v[50:51], v[200:201], 1, s[42:43]
	v_add_u32_e32 v200, v111, v77
	v_lshl_add_u64 v[52:53], v[200:201], 1, s[42:43]
	v_add_u32_e32 v200, v112, v77
	v_lshl_add_u64 v[54:55], v[200:201], 1, s[42:43]
	v_add_u32_e32 v200, v113, v77
	v_lshl_add_u64 v[56:57], v[200:201], 1, s[42:43]
	v_add_u32_e32 v200, v114, v77
	v_lshl_add_u64 v[58:59], v[200:201], 1, s[42:43]
	v_add_u32_e32 v200, v115, v77
	v_lshl_add_u64 v[60:61], v[200:201], 1, s[42:43]
	v_add_u32_e32 v200, v116, v77
	v_lshl_add_u64 v[62:63], v[200:201], 1, s[42:43]
	v_add_u32_e32 v200, v117, v77
	v_lshl_add_u64 v[66:67], v[200:201], 1, s[42:43]
	v_add_u32_e32 v200, v118, v77
	v_lshl_add_u64 v[68:69], v[200:201], 1, s[42:43]
	v_add_u32_e32 v200, v81, v76
	s_waitcnt vmcnt(1)
; __device__ __forceinline__ u16 f2bf(float x) { return (u16)(cvtpk(x, 0.f) & 0xffffu); }
; __device__ __forceinline__ float bf2f(u16 v) { return __uint_as_float(((unsigned)v) << 16); }
; __device__ __forceinline__ float sigmoidf_(float x) { return __builtin_amdgcn_rcpf(1.f + __expf(-x)); }
; __device__ __forceinline__ void phase_glu(const P& p, int layer, char* lds) {
;     ...
;     for (int mi = 0; mi < 2; ++mi) {
; #pragma unroll
;       for (int ni = 0; ni < 2; ++ni) {
;         const unsigned col = tn * 128 + wc * 64 + ni * 32 + r32;
;         const float gb = p.glu_b[layer * 256 + col];
;         u16 yv[16];
; #pragma unroll
;         for (int r = 0; r < 16; ++r) yv[r] = yg[(rb + mi * 32 + (r & 3) + 8 * (r >> 2)) * 256 + col];
; #pragma unroll
;         for (int r = 0; r < 16; ++r) {
;           const unsigned row = rb + mi * 32 + (r & 3) + 8 * (r >> 2);
;           ymix[row * 1024 + 768 + col] = f2bf(bf2f(yv[r]) * sigmoidf_(acc[mi][ni][r] + gb));
	v_add_f32_e32 v32, v32, v94
	v_mul_f32_e32 v32, 0xbfb8aa3b, v32
	v_exp_f32_e32 v32, v32
	s_waitcnt vmcnt(0)
	v_lshlrev_b32_e32 v95, 16, v95
	v_add_f32_e32 v33, v33, v94
	v_mul_f32_e32 v33, 0xbfb8aa3b, v33
	v_add_f32_e32 v32, 1.0, v32
	v_rcp_f32_e32 v32, v32
	v_exp_f32_e32 v33, v33
	v_add_f32_e32 v34, v34, v94
	v_mul_f32_e32 v34, 0xbfb8aa3b, v34
	v_mul_f32_e32 v95, v32, v95
	global_load_ushort v96, v[120:121], off
	global_load_ushort v97, v[104:105], off
	global_load_ushort v103, v[122:123], off
	s_nop 0
	global_load_ushort v74, v[74:75], off
	s_nop 0
	global_load_ushort v72, v[72:73], off
	s_nop 0
	global_load_ushort v70, v[70:71], off
	s_nop 0
	global_load_ushort v71, v[50:51], off
	global_load_ushort v73, v[52:53], off
	s_nop 0
	global_load_ushort v55, v[54:55], off
	s_nop 0
	global_load_ushort v54, v[56:57], off
	global_load_ushort v53, v[58:59], off
	global_load_ushort v52, v[60:61], off
	global_load_ushort v51, v[62:63], off
	global_load_ushort v50, v[66:67], off
	global_load_ushort v32, v[68:69], off
	v_exp_f32_e32 v34, v34
	v_add_f32_e32 v33, 1.0, v33
	v_rcp_f32_e32 v33, v33
	v_lshl_add_u64 v[56:57], v[200:201], 1, s[56:57]
	v_add_f32_e32 v34, 1.0, v34
	v_cvt_pk_bf16_f32 v58, v95, v201
	global_store_short v[56:57], v58, off
	v_rcp_f32_e32 v34, v34
	v_add_u32_e32 v200, v78, v76
	s_waitcnt vmcnt(15)
	v_lshlrev_b32_e32 v56, 16, v96
	v_mul_f32_e32 v33, v33, v56
	v_cvt_pk_bf16_f32 v33, v33, v201
	v_lshl_add_u64 v[56:57], v[200:201], 1, s[56:57]
	global_store_short v[56:57], v33, off
	s_waitcnt vmcnt(15)
	v_lshlrev_b32_e32 v33, 16, v97
	v_mul_f32_e32 v33, v34, v33
	v_add_f32_e32 v34, v35, v94
	v_mul_f32_e32 v34, 0xbfb8aa3b, v34
	v_exp_f32_e32 v34, v34
	v_add_u32_e32 v200, v79, v76
	v_cvt_pk_bf16_f32 v33, v33, v201
	v_lshl_add_u64 v[56:57], v[200:201], 1, s[56:57]
	v_add_f32_e32 v34, 1.0, v34
	v_rcp_f32_e32 v34, v34
	global_store_short v[56:57], v33, off
	s_waitcnt vmcnt(15)
	v_lshlrev_b32_e32 v33, 16, v103
	v_add_u32_e32 v200, v80, v76
	v_mul_f32_e32 v33, v34, v33
	v_lshl_add_u64 v[34:35], v[200:201], 1, s[56:57]
	v_cvt_pk_bf16_f32 v33, v33, v201
	global_store_short v[34:35], v33, off
	v_add_f32_e32 v34, v36, v94
	v_mul_f32_e32 v34, 0xbfb8aa3b, v34
	v_exp_f32_e32 v34, v34
	s_waitcnt vmcnt(15)
	v_lshlrev_b32_e32 v33, 16, v74
	v_add_u32_e32 v200, v82, v76
	s_waitcnt vmcnt(4)
	v_lshlrev_b32_e32 v32, 16, v32
	v_add_f32_e32 v34, 1.0, v34
	v_rcp_f32_e32 v34, v34
	s_nop 0
	v_mul_f32_e32 v33, v34, v33
	v_lshl_add_u64 v[34:35], v[200:201], 1, s[56:57]
	v_cvt_pk_bf16_f32 v33, v33, v201
	global_store_short v[34:35], v33, off
	v_add_f32_e32 v34, v37, v94
	v_mul_f32_e32 v34, 0xbfb8aa3b, v34
	v_exp_f32_e32 v34, v34
	v_lshlrev_b32_e32 v33, 16, v72
	v_add_u32_e32 v200, v83, v76
	v_add_f32_e32 v34, 1.0, v34
	v_rcp_f32_e32 v34, v34
	s_nop 0
	v_mul_f32_e32 v33, v34, v33
	v_lshl_add_u64 v[34:35], v[200:201], 1, s[56:57]
	v_cvt_pk_bf16_f32 v33, v33, v201
	global_store_short v[34:35], v33, off
	v_add_f32_e32 v34, v38, v94
	v_mul_f32_e32 v34, 0xbfb8aa3b, v34
	v_exp_f32_e32 v34, v34
	v_lshlrev_b32_e32 v33, 16, v70
	v_add_u32_e32 v200, v84, v76
	v_add_f32_e32 v34, 1.0, v34
	v_rcp_f32_e32 v34, v34
	s_nop 0
	v_mul_f32_e32 v33, v34, v33
	v_lshl_add_u64 v[34:35], v[200:201], 1, s[56:57]
	v_cvt_pk_bf16_f32 v33, v33, v201
	global_store_short v[34:35], v33, off
	v_add_f32_e32 v34, v39, v94
	v_mul_f32_e32 v34, 0xbfb8aa3b, v34
	v_exp_f32_e32 v34, v34
	v_lshlrev_b32_e32 v33, 16, v71
	v_add_u32_e32 v200, v85, v76
	v_add_f32_e32 v34, 1.0, v34
	v_rcp_f32_e32 v34, v34
	s_nop 0
	v_mul_f32_e32 v33, v34, v33
	v_lshl_add_u64 v[34:35], v[200:201], 1, s[56:57]
	v_cvt_pk_bf16_f32 v33, v33, v201
	global_store_short v[34:35], v33, off
	v_add_f32_e32 v34, v40, v94
	v_mul_f32_e32 v34, 0xbfb8aa3b, v34
	v_exp_f32_e32 v34, v34
	v_lshlrev_b32_e32 v33, 16, v73
	v_add_u32_e32 v200, v86, v76
	v_add_f32_e32 v34, 1.0, v34
	v_rcp_f32_e32 v34, v34
	s_nop 0
	v_mul_f32_e32 v33, v34, v33
	v_lshl_add_u64 v[34:35], v[200:201], 1, s[56:57]
	v_cvt_pk_bf16_f32 v33, v33, v201
	global_store_short v[34:35], v33, off
	v_add_f32_e32 v34, v41, v94
	v_mul_f32_e32 v34, 0xbfb8aa3b, v34
	v_exp_f32_e32 v34, v34
	v_lshlrev_b32_e32 v33, 16, v55
	v_add_u32_e32 v200, v87, v76
	v_add_f32_e32 v34, 1.0, v34
	v_rcp_f32_e32 v34, v34
	s_nop 0
	v_mul_f32_e32 v33, v34, v33
	v_lshl_add_u64 v[34:35], v[200:201], 1, s[56:57]
	v_cvt_pk_bf16_f32 v33, v33, v201
	global_store_short v[34:35], v33, off
	v_add_f32_e32 v34, v42, v94
	v_mul_f32_e32 v34, 0xbfb8aa3b, v34
	v_exp_f32_e32 v34, v34
	v_lshlrev_b32_e32 v33, 16, v54
	v_add_u32_e32 v200, v88, v76
	v_add_f32_e32 v34, 1.0, v34
	v_rcp_f32_e32 v34, v34
	s_nop 0
	v_mul_f32_e32 v33, v34, v33
	v_lshl_add_u64 v[34:35], v[200:201], 1, s[56:57]
	v_cvt_pk_bf16_f32 v33, v33, v201
	global_store_short v[34:35], v33, off
	v_add_f32_e32 v34, v43, v94
	v_mul_f32_e32 v34, 0xbfb8aa3b, v34
	v_exp_f32_e32 v34, v34
	v_lshlrev_b32_e32 v33, 16, v53
	v_add_u32_e32 v200, v89, v76
	v_add_f32_e32 v34, 1.0, v34
	v_rcp_f32_e32 v34, v34
	s_nop 0
	v_mul_f32_e32 v33, v34, v33
	v_lshl_add_u64 v[34:35], v[200:201], 1, s[56:57]
	v_cvt_pk_bf16_f32 v33, v33, v201
	global_store_short v[34:35], v33, off
	v_add_f32_e32 v34, v44, v94
	v_mul_f32_e32 v34, 0xbfb8aa3b, v34
	v_exp_f32_e32 v34, v34
	v_lshlrev_b32_e32 v33, 16, v52
	v_add_u32_e32 v200, v90, v76
	v_add_f32_e32 v34, 1.0, v34
	v_rcp_f32_e32 v34, v34
	s_nop 0
	v_mul_f32_e32 v33, v34, v33
	v_lshl_add_u64 v[34:35], v[200:201], 1, s[56:57]
	v_cvt_pk_bf16_f32 v33, v33, v201
	global_store_short v[34:35], v33, off
	v_add_f32_e32 v34, v45, v94
	v_mul_f32_e32 v34, 0xbfb8aa3b, v34
	v_exp_f32_e32 v34, v34
	v_lshlrev_b32_e32 v33, 16, v51
	v_add_u32_e32 v200, v91, v76
; __device__ __forceinline__ u16 f2bf(float x) { return (u16)(cvtpk(x, 0.f) & 0xffffu); }
; __device__ __forceinline__ float bf2f(u16 v) { return __uint_as_float(((unsigned)v) << 16); }
; __device__ __forceinline__ float sigmoidf_(float x) { return __builtin_amdgcn_rcpf(1.f + __expf(-x)); }
; __device__ __forceinline__ void phase_glu(const P& p, int layer, char* lds) {
;     ...
;     for (int mi = 0; mi < 2; ++mi) {
; #pragma unroll
;       for (int ni = 0; ni < 2; ++ni) {
;         const unsigned col = tn * 128 + wc * 64 + ni * 32 + r32;
;         const float gb = p.glu_b[layer * 256 + col];
;         u16 yv[16];
; #pragma unroll
;         for (int r = 0; r < 16; ++r) yv[r] = yg[(rb + mi * 32 + (r & 3) + 8 * (r >> 2)) * 256 + col];
; #pragma unroll
;         for (int r = 0; r < 16; ++r) {
;           const unsigned row = rb + mi * 32 + (r & 3) + 8 * (r >> 2);
;           ymix[row * 1024 + 768 + col] = f2bf(bf2f(yv[r]) * sigmoidf_(acc[mi][ni][r] + gb));
	v_add_f32_e32 v34, 1.0, v34
	v_rcp_f32_e32 v34, v34
	s_nop 0
	v_mul_f32_e32 v33, v34, v33
	v_lshl_add_u64 v[34:35], v[200:201], 1, s[56:57]
	v_cvt_pk_bf16_f32 v33, v33, v201
	global_store_short v[34:35], v33, off
	v_add_f32_e32 v34, v46, v94
	v_mul_f32_e32 v34, 0xbfb8aa3b, v34
	v_exp_f32_e32 v34, v34
	v_lshlrev_b32_e32 v33, 16, v50
	v_add_u32_e32 v200, v92, v76
	v_add_f32_e32 v34, 1.0, v34
	v_rcp_f32_e32 v34, v34
	s_nop 0
	v_mul_f32_e32 v33, v34, v33
	v_cvt_pk_bf16_f32 v33, v33, v201
	v_lshl_add_u64 v[34:35], v[200:201], 1, s[56:57]
	global_store_short v[34:35], v33, off
	v_add_f32_e32 v33, v47, v94
	v_mul_f32_e32 v33, 0xbfb8aa3b, v33
	v_exp_f32_e32 v33, v33
	v_add_u32_e32 v200, v93, v76
	v_add_f32_e32 v33, 1.0, v33
	v_rcp_f32_e32 v33, v33
	s_nop 0
	v_mul_f32_e32 v32, v33, v32
	v_cvt_pk_bf16_f32 v34, v32, v201
	v_lshl_add_u64 v[32:33], v[200:201], 1, s[56:57]
	global_store_short v[32:33], v34, off
	global_load_dword v33, v[64:65], off
	v_add_u32_e32 v32, 32, v102
	v_lshlrev_b32_e32 v34, 8, v32
	v_add_u32_e32 v200, v34, v101
	v_lshl_add_u64 v[36:37], v[200:201], 1, s[42:43]
	global_load_ushort v61, v[36:37], off
	v_add_u32_e32 v56, 33, v102
	v_lshlrev_b32_e32 v41, 8, v56
	v_add_u32_e32 v200, v41, v101
	v_lshl_add_u64 v[36:37], v[200:201], 1, s[42:43]
	global_load_ushort v66, v[36:37], off
	v_add_u32_e32 v57, 34, v102
	v_lshlrev_b32_e32 v51, 8, v57
	v_add_u32_e32 v200, v51, v101
	v_lshl_add_u64 v[36:37], v[200:201], 1, s[42:43]
	global_load_ushort v73, v[36:37], off
	v_add_u32_e32 v58, 35, v102
	v_lshlrev_b32_e32 v47, 8, v58
	v_add_u32_e32 v200, v47, v101
	v_lshl_add_u64 v[52:53], v[200:201], 1, s[42:43]
	global_load_ushort v74, v[52:53], off
	v_add_u32_e32 v59, 40, v102
	v_lshlrev_b32_e32 v45, 8, v59
	v_add_u32_e32 v200, v45, v101
	v_lshl_add_u64 v[52:53], v[200:201], 1, s[42:43]
	global_load_ushort v75, v[52:53], off
	v_add_u32_e32 v60, 41, v102
	v_lshlrev_b32_e32 v50, 8, v60
	v_add_u32_e32 v200, v50, v101
	v_lshl_add_u64 v[54:55], v[200:201], 1, s[42:43]
	global_load_ushort v78, v[54:55], off
	v_add_u32_e32 v62, 42, v102
	v_lshlrev_b32_e32 v46, 8, v62
	v_add_u32_e32 v200, v46, v101
	v_lshl_add_u64 v[52:53], v[200:201], 1, s[42:43]
	global_load_ushort v79, v[52:53], off
	v_add_u32_e32 v63, 43, v102
	v_lshlrev_b32_e32 v44, 8, v63
	v_add_u32_e32 v200, v44, v101
	v_lshl_add_u64 v[54:55], v[200:201], 1, s[42:43]
	global_load_ushort v80, v[54:55], off
	v_add_u32_e32 v64, 48, v102
	v_lshlrev_b32_e32 v43, 8, v64
	v_add_u32_e32 v200, v43, v101
	v_lshl_add_u64 v[52:53], v[200:201], 1, s[42:43]
	global_load_ushort v81, v[52:53], off
	v_add_u32_e32 v65, 49, v102
	v_lshlrev_b32_e32 v42, 8, v65
	v_add_u32_e32 v200, v42, v101
	v_add_u32_e32 v67, 50, v102
	v_lshl_add_u64 v[54:55], v[200:201], 1, s[42:43]
	v_add_u32_e32 v68, 51, v102
	v_lshlrev_b32_e32 v40, 8, v67
	global_load_ushort v82, v[54:55], off
	v_add_u32_e32 v69, 56, v102
	v_lshlrev_b32_e32 v39, 8, v68
	v_add_u32_e32 v200, v40, v101
	v_add_u32_e32 v70, 57, v102
	v_lshlrev_b32_e32 v38, 8, v69
	v_lshl_add_u64 v[52:53], v[200:201], 1, s[42:43]
	v_add_u32_e32 v200, v39, v101
	v_add_u32_e32 v71, 58, v102
	v_lshlrev_b32_e32 v37, 8, v70
	v_lshl_add_u64 v[54:55], v[200:201], 1, s[42:43]
	v_add_u32_e32 v200, v38, v101
	v_add_u32_e32 v72, 59, v102
	v_lshlrev_b32_e32 v36, 8, v71
	global_load_ushort v83, v[52:53], off
	global_load_ushort v84, v[54:55], off
	v_lshl_add_u64 v[52:53], v[200:201], 1, s[42:43]
	v_add_u32_e32 v200, v37, v101
	v_lshlrev_b32_e32 v35, 8, v72
	v_lshl_add_u64 v[54:55], v[200:201], 1, s[42:43]
	v_add_u32_e32 v200, v36, v101
	global_load_ushort v85, v[52:53], off
	global_load_ushort v86, v[54:55], off
	v_lshl_add_u64 v[52:53], v[200:201], 1, s[42:43]
	v_add_u32_e32 v200, v35, v101
	v_lshl_add_u64 v[54:55], v[200:201], 1, s[42:43]
	global_load_ushort v52, v[52:53], off
	s_nop 0
	global_load_ushort v53, v[54:55], off
	s_waitcnt vmcnt(16)
	v_add_f32_e32 v16, v16, v33
	v_mul_f32_e32 v16, 0xbfb8aa3b, v16
	v_exp_f32_e32 v16, v16
	v_add_f32_e32 v17, v17, v33
	v_mul_f32_e32 v17, 0xbfb8aa3b, v17
	v_exp_f32_e32 v17, v17
	v_add_f32_e32 v16, 1.0, v16
	v_rcp_f32_e32 v16, v16
	s_waitcnt vmcnt(15)
	v_lshlrev_b32_e32 v54, 16, v61
	v_lshlrev_b32_e32 v32, 10, v32
	v_add_u32_e32 v200, v32, v100
	v_mul_f32_e32 v16, v16, v54
	v_cvt_pk_bf16_f32 v54, v16, v201
	v_add_f32_e32 v16, 1.0, v17
	v_rcp_f32_e32 v55, v16
	v_lshl_add_u64 v[16:17], v[200:201], 1, s[56:57]
	global_store_short v[16:17], v54, off
	v_add_f32_e32 v17, v18, v33
	v_mul_f32_e32 v17, 0xbfb8aa3b, v17
	v_exp_f32_e32 v17, v17
	s_waitcnt vmcnt(15)
	v_lshlrev_b32_e32 v16, 16, v66
	v_mul_f32_e32 v16, v55, v16
	v_lshlrev_b32_e32 v54, 10, v56
	v_cvt_pk_bf16_f32 v18, v16, v201
	v_add_u32_e32 v200, v54, v100
	v_add_f32_e32 v16, 1.0, v17
	v_rcp_f32_e32 v55, v16
	v_lshl_add_u64 v[16:17], v[200:201], 1, s[56:57]
	global_store_short v[16:17], v18, off
	v_add_f32_e32 v17, v19, v33
	v_mul_f32_e32 v17, 0xbfb8aa3b, v17
	v_exp_f32_e32 v17, v17
	s_waitcnt vmcnt(15)
	v_lshlrev_b32_e32 v16, 16, v73
	v_mul_f32_e32 v16, v55, v16
	v_lshlrev_b32_e32 v55, 10, v57
	v_cvt_pk_bf16_f32 v18, v16, v201
	v_add_u32_e32 v200, v55, v100
	v_add_f32_e32 v16, 1.0, v17
	v_rcp_f32_e32 v19, v16
	v_lshl_add_u64 v[16:17], v[200:201], 1, s[56:57]
	global_store_short v[16:17], v18, off
	v_add_f32_e32 v17, v20, v33
	v_mul_f32_e32 v17, 0xbfb8aa3b, v17
	v_exp_f32_e32 v17, v17
	s_waitcnt vmcnt(15)
	v_lshlrev_b32_e32 v16, 16, v74
	v_mul_f32_e32 v16, v19, v16
	v_lshlrev_b32_e32 v56, 10, v58
	v_cvt_pk_bf16_f32 v18, v16, v201
	v_add_u32_e32 v200, v56, v100
	v_add_f32_e32 v16, 1.0, v17
	v_rcp_f32_e32 v19, v16
	v_lshl_add_u64 v[16:17], v[200:201], 1, s[56:57]
	global_store_short v[16:17], v18, off
	v_add_f32_e32 v17, v21, v33
	v_mul_f32_e32 v17, 0xbfb8aa3b, v17
	v_exp_f32_e32 v17, v17
	s_waitcnt vmcnt(15)
; __device__ __forceinline__ u16 f2bf(float x) { return (u16)(cvtpk(x, 0.f) & 0xffffu); }
; __device__ __forceinline__ float bf2f(u16 v) { return __uint_as_float(((unsigned)v) << 16); }
; __device__ __forceinline__ float sigmoidf_(float x) { return __builtin_amdgcn_rcpf(1.f + __expf(-x)); }
; __device__ __forceinline__ void phase_glu(const P& p, int layer, char* lds) {
;     ...
;     for (int mi = 0; mi < 2; ++mi) {
; #pragma unroll
;       for (int ni = 0; ni < 2; ++ni) {
;         const unsigned col = tn * 128 + wc * 64 + ni * 32 + r32;
;         const float gb = p.glu_b[layer * 256 + col];
;         u16 yv[16];
; #pragma unroll
;         for (int r = 0; r < 16; ++r) yv[r] = yg[(rb + mi * 32 + (r & 3) + 8 * (r >> 2)) * 256 + col];
; #pragma unroll
;         for (int r = 0; r < 16; ++r) {
;           const unsigned row = rb + mi * 32 + (r & 3) + 8 * (r >> 2);
;           ymix[row * 1024 + 768 + col] = f2bf(bf2f(yv[r]) * sigmoidf_(acc[mi][ni][r] + gb));
	v_lshlrev_b32_e32 v16, 16, v75
	v_mul_f32_e32 v16, v19, v16
	v_lshlrev_b32_e32 v57, 10, v59
	v_cvt_pk_bf16_f32 v18, v16, v201
	v_add_u32_e32 v200, v57, v100
	v_add_f32_e32 v16, 1.0, v17
	v_rcp_f32_e32 v19, v16
	v_lshl_add_u64 v[16:17], v[200:201], 1, s[56:57]
	global_store_short v[16:17], v18, off
	v_add_f32_e32 v17, v22, v33
	v_mul_f32_e32 v17, 0xbfb8aa3b, v17
	v_exp_f32_e32 v17, v17
	s_waitcnt vmcnt(15)
	v_lshlrev_b32_e32 v16, 16, v78
	v_mul_f32_e32 v16, v19, v16
	v_lshlrev_b32_e32 v58, 10, v60
	v_cvt_pk_bf16_f32 v18, v16, v201
	v_add_u32_e32 v200, v58, v100
	v_add_f32_e32 v16, 1.0, v17
	v_rcp_f32_e32 v19, v16
	v_lshl_add_u64 v[16:17], v[200:201], 1, s[56:57]
	global_store_short v[16:17], v18, off
	v_add_f32_e32 v17, v23, v33
	v_mul_f32_e32 v17, 0xbfb8aa3b, v17
	v_exp_f32_e32 v17, v17
	s_waitcnt vmcnt(15)
	v_lshlrev_b32_e32 v16, 16, v79
	v_mul_f32_e32 v16, v19, v16
	v_lshlrev_b32_e32 v59, 10, v62
	v_cvt_pk_bf16_f32 v18, v16, v201
	v_add_u32_e32 v200, v59, v100
	v_add_f32_e32 v16, 1.0, v17
	v_rcp_f32_e32 v19, v16
	v_lshl_add_u64 v[16:17], v[200:201], 1, s[56:57]
	global_store_short v[16:17], v18, off
	v_add_f32_e32 v17, v24, v33
	v_mul_f32_e32 v17, 0xbfb8aa3b, v17
	v_exp_f32_e32 v17, v17
	s_waitcnt vmcnt(15)
	v_lshlrev_b32_e32 v16, 16, v80
	v_mul_f32_e32 v16, v19, v16
	v_lshlrev_b32_e32 v60, 10, v63
	v_cvt_pk_bf16_f32 v18, v16, v201
	v_add_u32_e32 v200, v60, v100
	v_add_f32_e32 v16, 1.0, v17
	v_rcp_f32_e32 v19, v16
	v_lshl_add_u64 v[16:17], v[200:201], 1, s[56:57]
	global_store_short v[16:17], v18, off
	v_add_f32_e32 v17, v25, v33
	v_mul_f32_e32 v17, 0xbfb8aa3b, v17
	v_exp_f32_e32 v17, v17
	s_waitcnt vmcnt(15)
	v_lshlrev_b32_e32 v16, 16, v81
	v_mul_f32_e32 v16, v19, v16
	v_lshlrev_b32_e32 v61, 10, v64
	v_cvt_pk_bf16_f32 v18, v16, v201
	v_add_u32_e32 v200, v61, v100
	v_add_f32_e32 v16, 1.0, v17
	v_rcp_f32_e32 v19, v16
	v_lshl_add_u64 v[16:17], v[200:201], 1, s[56:57]
	global_store_short v[16:17], v18, off
	v_add_f32_e32 v17, v26, v33
	v_mul_f32_e32 v17, 0xbfb8aa3b, v17
	v_exp_f32_e32 v17, v17
	s_waitcnt vmcnt(15)
	v_lshlrev_b32_e32 v16, 16, v82
	v_mul_f32_e32 v16, v19, v16
	v_lshlrev_b32_e32 v62, 10, v65
	v_cvt_pk_bf16_f32 v18, v16, v201
	v_add_u32_e32 v200, v62, v100
	v_add_f32_e32 v16, 1.0, v17
	v_rcp_f32_e32 v19, v16
	v_lshl_add_u64 v[16:17], v[200:201], 1, s[56:57]
	global_store_short v[16:17], v18, off
	v_add_f32_e32 v17, v27, v33
	v_mul_f32_e32 v17, 0xbfb8aa3b, v17
	v_exp_f32_e32 v17, v17
	s_waitcnt vmcnt(15)
	v_lshlrev_b32_e32 v16, 16, v83
	v_mul_f32_e32 v16, v19, v16
	v_lshlrev_b32_e32 v63, 10, v67
	v_cvt_pk_bf16_f32 v18, v16, v201
	v_add_u32_e32 v200, v63, v100
	v_add_f32_e32 v16, 1.0, v17
	v_rcp_f32_e32 v19, v16
	v_lshl_add_u64 v[16:17], v[200:201], 1, s[56:57]
	global_store_short v[16:17], v18, off
	v_add_f32_e32 v17, v28, v33
	v_mul_f32_e32 v17, 0xbfb8aa3b, v17
	v_exp_f32_e32 v17, v17
	s_waitcnt vmcnt(15)
	v_lshlrev_b32_e32 v16, 16, v84
	v_mul_f32_e32 v16, v19, v16
	v_lshlrev_b32_e32 v64, 10, v68
	v_cvt_pk_bf16_f32 v18, v16, v201
	v_add_u32_e32 v200, v64, v100
	v_add_f32_e32 v16, 1.0, v17
	v_rcp_f32_e32 v19, v16
	v_lshl_add_u64 v[16:17], v[200:201], 1, s[56:57]
	global_store_short v[16:17], v18, off
	v_add_f32_e32 v17, v29, v33
	v_mul_f32_e32 v17, 0xbfb8aa3b, v17
	v_exp_f32_e32 v17, v17
	s_waitcnt vmcnt(15)
	v_lshlrev_b32_e32 v16, 16, v85
	v_mul_f32_e32 v16, v19, v16
	v_lshlrev_b32_e32 v65, 10, v69
	v_cvt_pk_bf16_f32 v18, v16, v201
	v_add_u32_e32 v200, v65, v100
	v_add_f32_e32 v16, 1.0, v17
	v_rcp_f32_e32 v19, v16
	v_lshl_add_u64 v[16:17], v[200:201], 1, s[56:57]
	global_store_short v[16:17], v18, off
	v_add_f32_e32 v17, v30, v33
	v_mul_f32_e32 v17, 0xbfb8aa3b, v17
	v_exp_f32_e32 v17, v17
	s_waitcnt vmcnt(15)
	v_lshlrev_b32_e32 v16, 16, v86
	v_mul_f32_e32 v16, v19, v16
	v_lshlrev_b32_e32 v66, 10, v70
	v_cvt_pk_bf16_f32 v18, v16, v201
	v_add_u32_e32 v200, v66, v100
	v_add_f32_e32 v16, 1.0, v17
	v_rcp_f32_e32 v19, v16
	v_lshl_add_u64 v[16:17], v[200:201], 1, s[56:57]
	global_store_short v[16:17], v18, off
	v_add_f32_e32 v17, v31, v33
	v_mul_f32_e32 v17, 0xbfb8aa3b, v17
	v_exp_f32_e32 v17, v17
	s_waitcnt vmcnt(15)
	v_lshlrev_b32_e32 v16, 16, v52
	v_mul_f32_e32 v16, v19, v16
	v_cvt_pk_bf16_f32 v18, v16, v201
	v_add_f32_e32 v16, 1.0, v17
	v_lshlrev_b32_e32 v33, 10, v71
	v_rcp_f32_e32 v19, v16
	v_add_u32_e32 v200, v33, v100
	v_lshl_add_u64 v[16:17], v[200:201], 1, s[56:57]
	global_store_short v[16:17], v18, off
	s_waitcnt vmcnt(15)
	v_lshlrev_b32_e32 v16, 16, v53
	v_mul_f32_e32 v16, v19, v16
	v_cvt_pk_bf16_f32 v18, v16, v201
	global_load_dword v48, v[48:49], off
	v_lshlrev_b32_e32 v49, 10, v72
	v_add_u32_e32 v200, v49, v100
	v_lshl_add_u64 v[16:17], v[200:201], 1, s[56:57]
	v_add_u32_e32 v200, v34, v77
	global_store_short v[16:17], v18, off
	v_lshl_add_u64 v[16:17], v[200:201], 1, s[42:43]
	global_load_ushort v52, v[16:17], off
	v_add_u32_e32 v200, v41, v77
	v_lshl_add_u64 v[16:17], v[200:201], 1, s[42:43]
	global_load_ushort v41, v[16:17], off
	v_add_u32_e32 v200, v51, v77
	v_lshl_add_u64 v[16:17], v[200:201], 1, s[42:43]
	global_load_ushort v51, v[16:17], off
	v_add_u32_e32 v200, v47, v77
	v_lshl_add_u64 v[16:17], v[200:201], 1, s[42:43]
	global_load_ushort v47, v[16:17], off
	v_add_u32_e32 v200, v45, v77
	v_lshl_add_u64 v[16:17], v[200:201], 1, s[42:43]
	v_add_u32_e32 v200, v50, v77
	global_load_ushort v45, v[16:17], off
	v_lshl_add_u64 v[16:17], v[200:201], 1, s[42:43]
	v_add_u32_e32 v200, v46, v77
	v_lshl_add_u64 v[18:19], v[200:201], 1, s[42:43]
	v_add_u32_e32 v200, v44, v77
	v_lshl_add_u64 v[20:21], v[200:201], 1, s[42:43]
	v_add_u32_e32 v200, v43, v77
	v_lshl_add_u64 v[22:23], v[200:201], 1, s[42:43]
	v_add_u32_e32 v200, v42, v77
	v_lshl_add_u64 v[24:25], v[200:201], 1, s[42:43]
	v_add_u32_e32 v200, v40, v77
	v_lshl_add_u64 v[26:27], v[200:201], 1, s[42:43]
	v_add_u32_e32 v200, v39, v77
	global_load_ushort v39, v[16:17], off
	s_waitcnt vmcnt(7)
; __device__ __forceinline__ u16 f2bf(float x) { return (u16)(cvtpk(x, 0.f) & 0xffffu); }
; __device__ __forceinline__ float bf2f(u16 v) { return __uint_as_float(((unsigned)v) << 16); }
; __device__ __forceinline__ float sigmoidf_(float x) { return __builtin_amdgcn_rcpf(1.f + __expf(-x)); }
; #define SBAR() __builtin_amdgcn_sched_barrier(0)
; __device__ __forceinline__ void phase_glu(const P& p, int layer, char* lds) {
;     ...
;     for (int mi = 0; mi < 2; ++mi) {
; #pragma unroll
;       for (int ni = 0; ni < 2; ++ni) {
;         const unsigned col = tn * 128 + wc * 64 + ni * 32 + r32;
;         const float gb = p.glu_b[layer * 256 + col];
;         u16 yv[16];
; #pragma unroll
;         for (int r = 0; r < 16; ++r) yv[r] = yg[(rb + mi * 32 + (r & 3) + 8 * (r >> 2)) * 256 + col];
; #pragma unroll
;         for (int r = 0; r < 16; ++r) {
;           const unsigned row = rb + mi * 32 + (r & 3) + 8 * (r >> 2);
;           ymix[row * 1024 + 768 + col] = f2bf(bf2f(yv[r]) * sigmoidf_(acc[mi][ni][r] + gb));
;         }
;       }
;       SBAR();
;     }
;   }
	v_add_f32_e32 v0, v0, v48
	global_load_ushort v20, v[20:21], off
	v_lshl_add_u64 v[16:17], v[200:201], 1, s[42:43]
	v_add_u32_e32 v200, v38, v77
	v_lshl_add_u64 v[28:29], v[200:201], 1, s[42:43]
	v_add_u32_e32 v200, v37, v77
	global_load_ushort v37, v[18:19], off
	v_mul_f32_e32 v0, 0xbfb8aa3b, v0
	v_exp_f32_e32 v0, v0
	v_add_f32_e32 v1, v1, v48
	v_lshl_add_u64 v[30:31], v[200:201], 1, s[42:43]
	v_add_u32_e32 v200, v36, v77
	v_add_f32_e32 v0, 1.0, v0
	v_rcp_f32_e32 v0, v0
	v_mul_f32_e32 v1, 0xbfb8aa3b, v1
	v_lshl_add_u64 v[18:19], v[200:201], 1, s[42:43]
	v_add_u32_e32 v200, v35, v77
	s_waitcnt vmcnt(7)
	v_lshlrev_b32_e32 v21, 16, v52
	v_exp_f32_e32 v1, v1
	v_lshl_add_u64 v[34:35], v[200:201], 1, s[42:43]
	v_mul_f32_e32 v0, v0, v21
	global_load_ushort v21, v[22:23], off
	s_nop 0
	global_load_ushort v22, v[24:25], off
	global_load_ushort v23, v[26:27], off
	s_nop 0
	global_load_ushort v16, v[16:17], off
	s_nop 0
	global_load_ushort v17, v[28:29], off
	global_load_ushort v24, v[30:31], off
	s_nop 0
	global_load_ushort v18, v[18:19], off
	s_nop 0
	global_load_ushort v19, v[34:35], off
	v_cvt_pk_bf16_f32 v25, v0, v201
	v_add_f32_e32 v0, 1.0, v1
	v_rcp_f32_e32 v26, v0
	v_add_u32_e32 v200, v32, v76
	v_lshl_add_u64 v[0:1], v[200:201], 1, s[56:57]
	global_store_short v[0:1], v25, off
	s_waitcnt vmcnt(15)
	v_lshlrev_b32_e32 v0, 16, v41
	v_mul_f32_e32 v0, v26, v0
	v_cvt_pk_bf16_f32 v25, v0, v201
	v_add_f32_e32 v0, v2, v48
	v_mul_f32_e32 v0, 0xbfb8aa3b, v0
	v_exp_f32_e32 v2, v0
	v_add_u32_e32 v200, v54, v76
	v_lshl_add_u64 v[0:1], v[200:201], 1, s[56:57]
	global_store_short v[0:1], v25, off
	v_add_f32_e32 v1, 1.0, v2
	v_add_f32_e32 v2, v3, v48
	v_rcp_f32_e32 v1, v1
	v_mul_f32_e32 v2, 0xbfb8aa3b, v2
	v_exp_f32_e32 v2, v2
	s_waitcnt vmcnt(15)
	v_lshlrev_b32_e32 v0, 16, v51
	v_mul_f32_e32 v0, v1, v0
	v_cvt_pk_bf16_f32 v3, v0, v201
	v_add_f32_e32 v0, 1.0, v2
	v_rcp_f32_e32 v2, v0
	v_add_u32_e32 v200, v55, v76
	v_lshl_add_u64 v[0:1], v[200:201], 1, s[56:57]
	global_store_short v[0:1], v3, off
	s_waitcnt vmcnt(15)
	v_lshlrev_b32_e32 v0, 16, v47
	v_mul_f32_e32 v0, v2, v0
	v_cvt_pk_bf16_f32 v2, v0, v201
	v_add_f32_e32 v0, v4, v48
	v_mul_f32_e32 v0, 0xbfb8aa3b, v0
	v_exp_f32_e32 v3, v0
	v_add_u32_e32 v200, v56, v76
	v_lshl_add_u64 v[0:1], v[200:201], 1, s[56:57]
	global_store_short v[0:1], v2, off
	v_add_f32_e32 v1, 1.0, v3
	v_add_f32_e32 v2, v5, v48
	v_rcp_f32_e32 v1, v1
	v_mul_f32_e32 v2, 0xbfb8aa3b, v2
	v_exp_f32_e32 v2, v2
	s_waitcnt vmcnt(15)
	v_lshlrev_b32_e32 v0, 16, v45
	v_mul_f32_e32 v0, v1, v0
	v_cvt_pk_bf16_f32 v3, v0, v201
	v_add_f32_e32 v0, 1.0, v2
	v_rcp_f32_e32 v2, v0
	v_add_u32_e32 v200, v57, v76
	v_lshl_add_u64 v[0:1], v[200:201], 1, s[56:57]
	global_store_short v[0:1], v3, off
	s_waitcnt vmcnt(15)
	v_lshlrev_b32_e32 v0, 16, v39
	v_mul_f32_e32 v0, v2, v0
	v_cvt_pk_bf16_f32 v2, v0, v201
	v_add_f32_e32 v0, v6, v48
	v_mul_f32_e32 v0, 0xbfb8aa3b, v0
	v_exp_f32_e32 v3, v0
	v_add_u32_e32 v200, v58, v76
	v_lshl_add_u64 v[0:1], v[200:201], 1, s[56:57]
	global_store_short v[0:1], v2, off
	v_add_f32_e32 v1, 1.0, v3
	v_add_f32_e32 v2, v7, v48
	v_rcp_f32_e32 v1, v1
	v_mul_f32_e32 v2, 0xbfb8aa3b, v2
	v_exp_f32_e32 v2, v2
	s_waitcnt vmcnt(14)
	v_lshlrev_b32_e32 v0, 16, v37
	v_mul_f32_e32 v0, v1, v0
	v_cvt_pk_bf16_f32 v3, v0, v201
	v_add_f32_e32 v0, 1.0, v2
	v_rcp_f32_e32 v2, v0
	v_add_u32_e32 v200, v59, v76
	v_lshl_add_u64 v[0:1], v[200:201], 1, s[56:57]
	global_store_short v[0:1], v3, off
	v_lshlrev_b32_e32 v0, 16, v20
	v_mul_f32_e32 v0, v2, v0
	v_cvt_pk_bf16_f32 v2, v0, v201
	v_add_f32_e32 v0, v8, v48
	v_mul_f32_e32 v0, 0xbfb8aa3b, v0
	v_exp_f32_e32 v3, v0
	v_add_u32_e32 v200, v60, v76
	v_lshl_add_u64 v[0:1], v[200:201], 1, s[56:57]
	global_store_short v[0:1], v2, off
	v_add_f32_e32 v1, 1.0, v3
	v_add_f32_e32 v2, v9, v48
	v_rcp_f32_e32 v1, v1
	v_mul_f32_e32 v2, 0xbfb8aa3b, v2
	v_exp_f32_e32 v2, v2
	s_waitcnt vmcnt(15)
	v_lshlrev_b32_e32 v0, 16, v21
	v_mul_f32_e32 v0, v1, v0
	v_cvt_pk_bf16_f32 v3, v0, v201
	v_add_f32_e32 v0, 1.0, v2
	v_rcp_f32_e32 v2, v0
	v_add_u32_e32 v200, v61, v76
	v_lshl_add_u64 v[0:1], v[200:201], 1, s[56:57]
	global_store_short v[0:1], v3, off
	s_waitcnt vmcnt(15)
	v_lshlrev_b32_e32 v0, 16, v22
	v_mul_f32_e32 v0, v2, v0
	v_cvt_pk_bf16_f32 v2, v0, v201
	v_add_f32_e32 v0, v10, v48
	v_mul_f32_e32 v0, 0xbfb8aa3b, v0
	v_exp_f32_e32 v3, v0
	v_add_u32_e32 v200, v62, v76
	v_lshl_add_u64 v[0:1], v[200:201], 1, s[56:57]
	global_store_short v[0:1], v2, off
	v_add_f32_e32 v1, 1.0, v3
	v_add_f32_e32 v2, v11, v48
	v_rcp_f32_e32 v1, v1
	v_mul_f32_e32 v2, 0xbfb8aa3b, v2
	v_exp_f32_e32 v2, v2
	s_waitcnt vmcnt(15)
	v_lshlrev_b32_e32 v0, 16, v23
	v_mul_f32_e32 v0, v1, v0
	v_cvt_pk_bf16_f32 v3, v0, v201
	v_add_f32_e32 v0, 1.0, v2
	v_rcp_f32_e32 v2, v0
	v_add_u32_e32 v200, v63, v76
	v_lshl_add_u64 v[0:1], v[200:201], 1, s[56:57]
	global_store_short v[0:1], v3, off
	s_waitcnt vmcnt(15)
	v_lshlrev_b32_e32 v0, 16, v16
	v_mul_f32_e32 v0, v2, v0
	v_cvt_pk_bf16_f32 v2, v0, v201
	v_add_f32_e32 v0, v12, v48
	v_mul_f32_e32 v0, 0xbfb8aa3b, v0
	v_exp_f32_e32 v3, v0
	v_add_u32_e32 v200, v64, v76
	v_lshl_add_u64 v[0:1], v[200:201], 1, s[56:57]
	global_store_short v[0:1], v2, off
	v_add_f32_e32 v1, 1.0, v3
	v_add_f32_e32 v2, v13, v48
	v_rcp_f32_e32 v1, v1
	v_mul_f32_e32 v2, 0xbfb8aa3b, v2
	v_exp_f32_e32 v2, v2
	s_waitcnt vmcnt(15)
	v_lshlrev_b32_e32 v0, 16, v17
	v_mul_f32_e32 v0, v1, v0
	v_cvt_pk_bf16_f32 v3, v0, v201
	v_add_f32_e32 v0, 1.0, v2
	v_rcp_f32_e32 v2, v0
	v_add_u32_e32 v200, v65, v76
	v_lshl_add_u64 v[0:1], v[200:201], 1, s[56:57]
	global_store_short v[0:1], v3, off
	s_waitcnt vmcnt(15)
	v_lshlrev_b32_e32 v0, 16, v24
	v_mul_f32_e32 v0, v2, v0
	v_cvt_pk_bf16_f32 v2, v0, v201
	v_add_f32_e32 v0, v14, v48
	v_mul_f32_e32 v0, 0xbfb8aa3b, v0
	v_exp_f32_e32 v3, v0
	v_add_u32_e32 v200, v66, v76
	v_lshl_add_u64 v[0:1], v[200:201], 1, s[56:57]
	global_store_short v[0:1], v2, off
	v_add_f32_e32 v1, 1.0, v3
	v_add_f32_e32 v2, v15, v48
	v_rcp_f32_e32 v1, v1
	v_mul_f32_e32 v2, 0xbfb8aa3b, v2
	v_exp_f32_e32 v2, v2
	s_waitcnt vmcnt(15)
	v_lshlrev_b32_e32 v0, 16, v18
	v_mul_f32_e32 v0, v1, v0
	v_cvt_pk_bf16_f32 v3, v0, v201
	v_add_f32_e32 v0, 1.0, v2
	v_rcp_f32_e32 v2, v0
	v_add_u32_e32 v200, v33, v76
	v_lshl_add_u64 v[0:1], v[200:201], 1, s[56:57]
	global_store_short v[0:1], v3, off
	s_waitcnt vmcnt(15)
	v_lshlrev_b32_e32 v0, 16, v19
	v_mul_f32_e32 v0, v2, v0
	v_add_u32_e32 v200, v49, v76
	v_cvt_pk_bf16_f32 v2, v0, v201
	v_lshl_add_u64 v[0:1], v[200:201], 1, s[56:57]
	global_store_short v[0:1], v2, off
	s_add_i32 s19, s19, 1
	s_mul_i32 s8, s19, s7
	s_add_i32 s8, s8, s13
	s_add_i32 s33, s33, s7
	s_cmp_gt_u32 s33, 63
	s_cbranch_scc0 .LBB0_252

; __device__ __forceinline__ int ltid() { int t = (int)threadIdx.x; asm volatile("" : "+v"(t)); return t; }
; #define MFMA(a, b, c) __builtin_amdgcn_mfma_f32_32x32x16_bf16(a, b, c, 0, 0, 0)
; template <bool HALO, class AL, class BL>
; __device__ __forceinline__ void gemm_core(f32x16 (&acc)[2][2], f32x16& hacc, const AL& al, const BL& bl, int K, char* lds,
;                                           const u16* halo0, const u16* halo1, int brow0, int brow1) {
;     ...
;   const int tid = ltid(), lane = tid & 63, wid = tid >> 6, wr = wid >> 1, r32 = lane & 31, hi = lane >> 5;
;   const int lrow = tid >> 3, cg = ((tid & 7) ^ ((lrow >> 1) & 7)) * 8;
;   const u16* gh = nullptr;
;   if (HALO) { const int c = ((lane & 7) ^ ((lane >> 4) & 7)) * 8; gh = ((lane < 8) ? halo0 : halo1) + c; }
;   char* lw = lds + tid * 16;
;     ...
;   const int sa = ((wr * 64 + r32) >> 1) & 7, sb0 = ((brow0 + r32) >> 1) & 7, sb1 = ((brow1 + r32) >> 1) & 7, sh = (r32 >> 1) & 7;
;   const int oa = (wr * 64 + r32) * 128, ob0 = ABYTES + (brow0 + r32) * 128, ob1 = ABYTES + (brow1 + r32) * 128, oh = (128 + r32) * 128;
;   __syncthreads();
;   ISSUE(0, 0);
;   const int nk = K >> 6;
;   for (int kt = 0; kt < nk; ++kt) {
;     asm volatile("s_waitcnt vmcnt(0)" ::: "memory");
;     __syncthreads();
;     if (kt + 1 < nk) ISSUE((kt + 1) * 64, (kt + 1) & 1);
;     const char* T = lds + (kt & 1) * BUF;
; #pragma unroll
;     for (int kk = 0; kk < 4; ++kk) {
;       const int c = kk * 2 + hi;
;       bf16x8 a0 = *(const bf16x8*)(T + oa + ((c ^ sa) << 4));
;       bf16x8 a1 = *(const bf16x8*)(T + oa + 4096 + ((c ^ sa) << 4));
;       bf16x8 b0 = *(const bf16x8*)(T + ob0 + ((c ^ sb0) << 4));
;       bf16x8 b1 = *(const bf16x8*)(T + ob1 + ((c ^ sb1) << 4));
;       acc[0][0] = MFMA(a0, b0, acc[0][0]); acc[0][1] = MFMA(a0, b1, acc[0][1]);
;       acc[1][0] = MFMA(a1, b0, acc[1][0]); acc[1][1] = MFMA(a1, b1, acc[1][1]);
;       if (HALO) { bf16x8 ah = *(const bf16x8*)(T + oh + ((c ^ sh) << 4)); hacc = MFMA(ah, b0, hacc); }
;     }
;   }
; __device__ __forceinline__ void phase_z(const P& p, int layer, char* lds) {
;     ...
;   for (int it = 0; tile_at(it, 256, 22, tm, tn); ++it) {
;     f32x16 acc[2][2] = {};
;     LdBf al{xb + (long)tm * 128 * DM, DM}, bl{wt + (long)tn * 128 * DM, DM};
;     gemm_plain(acc, al, bl, DM, lds);
.LBB0_345:
	v_readlane_b32 s47, v253, 6
	s_add_i32 s47, s46, s47
	s_mul_hi_u32 s48, s47, 0xba2e8ba3
	s_lshr_b32 s48, s48, 7
	s_lshl_b32 s49, s48, 3
	s_mulk_i32 s48, 0xff50
	s_and_b32 s46, s46, 7
	s_add_i32 s47, s48, s47
	s_or_b32 s48, s49, s46
	s_ashr_i32 s46, s47, 3
	s_lshl_b32 s47, s48, 18
	s_add_u32 s56, s3, s47
	v_mov_b32_e32 v6, v229
	v_mov_b32_e32 v24, v229
	s_addc_u32 s57, s6, 0
	s_ashr_i32 s47, s46, 31
	s_lshl_b64 s[58:59], s[46:47], 18
	v_ashrrev_i32_e32 v0, 3, v24
	v_lshrrev_b32_e32 v1, 4, v24
	v_xor_b32_e32 v4, v1, v24
	v_ashrrev_i32_e32 v1, 31, v0
	s_add_u32 s58, s7, s58
	v_lshlrev_b64 v[0:1], 11, v[0:1]
	v_lshlrev_b32_e32 v4, 4, v4
	s_addc_u32 s59, s8, s59
	v_lshl_add_u64 v[2:3], s[56:57], 0, v[0:1]
	v_and_b32_e32 v200, 0x70, v4
	v_lshl_add_u64 v[64:65], v[2:3], 0, v[200:201]
	v_lshl_add_u64 v[2:3], s[58:59], 0, v[0:1]
	s_mov_b64 s[60:61], 0x10000
	v_lshl_add_u32 v101, v24, 4, 0
	v_lshl_add_u64 v[66:67], v[2:3], 0, v[200:201]
	v_lshl_add_u64 v[2:3], v[0:1], 0, s[60:61]
	v_add_u32_e32 v102, 0x4000, v101
	v_readfirstlane_b32 s71, v101
	v_lshl_add_u64 v[4:5], s[56:57], 0, v[2:3]
	v_lshl_add_u64 v[2:3], s[58:59], 0, v[2:3]
	s_mov_b64 s[60:61], 0x20000
	s_mov_b32 m0, s71
	v_readfirstlane_b32 s72, v102
	v_add_u32_e32 v103, 0x1000, v101
	v_lshl_add_u64 v[70:71], v[2:3], 0, v[200:201]
	v_lshl_add_u64 v[2:3], v[0:1], 0, s[60:61]
	s_barrier
	global_load_lds_dwordx4 v[64:65], off
	s_mov_b32 m0, s72
	v_lshl_add_u64 v[68:69], v[4:5], 0, v[200:201]
	v_readfirstlane_b32 s73, v103
	v_add_u32_e32 v104, 0x5000, v101
	v_lshl_add_u64 v[4:5], s[56:57], 0, v[2:3]
	global_load_lds_dwordx4 v[66:67], off
	s_mov_b32 m0, s73
	v_readfirstlane_b32 s76, v104
	v_lshl_add_u64 v[72:73], v[4:5], 0, v[200:201]
	v_add_u32_e32 v4, 0x2000, v101
	v_lshl_add_u64 v[2:3], s[58:59], 0, v[2:3]
	global_load_lds_dwordx4 v[68:69], off
	s_mov_b32 m0, s76
	v_readfirstlane_b32 s47, v4
	v_lshl_add_u64 v[74:75], v[2:3], 0, v[200:201]
	v_add_u32_e32 v2, 0x6000, v101
	s_mov_b64 s[60:61], 0x30000
	global_load_lds_dwordx4 v[70:71], off
	s_mov_b32 m0, s47
	v_readfirstlane_b32 s49, v2
	v_lshl_add_u64 v[0:1], v[0:1], 0, s[60:61]
	v_add_u32_e32 v91, 0x3000, v101
	global_load_lds_dwordx4 v[72:73], off
	s_mov_b32 m0, s49
	v_lshl_add_u64 v[2:3], s[56:57], 0, v[0:1]
	v_readfirstlane_b32 s56, v91
	v_add_u32_e32 v92, 0x7000, v101
	v_lshrrev_b32_e32 v8, 5, v24
	v_bfe_u32 v89, v24, 1, 3
	global_load_lds_dwordx4 v[74:75], off
	v_lshl_add_u64 v[76:77], v[2:3], 0, v[200:201]
	s_mov_b32 m0, s56
	v_lshl_add_u64 v[0:1], s[58:59], 0, v[0:1]
	v_readfirstlane_b32 s57, v92
	v_add_u32_e32 v94, 0x8000, v101
	global_load_lds_dwordx4 v[76:77], off
	v_lshl_add_u64 v[78:79], v[0:1], 0, v[200:201]
	s_mov_b32 m0, s57
	v_bitop3_b32 v0, v8, v89, 1 bitop3:0x6c
	v_add_u32_e32 v93, 0xc000, v101
	v_readfirstlane_b32 s58, v94
	global_load_lds_dwordx4 v[78:79], off
	v_lshlrev_b32_e32 v4, 4, v0
	v_lshl_add_u64 v[0:1], v[64:65], 0, s[78:79]
	s_mov_b32 m0, s58
	v_readfirstlane_b32 s59, v93
	v_add_u32_e32 v95, 0x9000, v101
	s_waitcnt vmcnt(0)
	s_waitcnt vmcnt(0) lgkmcnt(0)
	s_barrier
	global_load_lds_dwordx4 v[0:1], off
	v_lshl_add_u64 v[0:1], v[66:67], 0, s[78:79]
	s_mov_b32 m0, s59
	v_readfirstlane_b32 s60, v95
	v_add_u32_e32 v96, 0xd000, v101
	global_load_lds_dwordx4 v[0:1], off
	v_lshl_add_u64 v[0:1], v[68:69], 0, s[78:79]
	s_mov_b32 m0, s60
	v_readfirstlane_b32 s61, v96
	v_add_u32_e32 v97, 0xa000, v101
	global_load_lds_dwordx4 v[0:1], off
	v_lshl_add_u64 v[0:1], v[70:71], 0, s[78:79]
	s_mov_b32 m0, s61
	v_readfirstlane_b32 s62, v97
	v_add_u32_e32 v98, 0xe000, v101
	global_load_lds_dwordx4 v[0:1], off
	v_lshl_add_u64 v[0:1], v[72:73], 0, s[78:79]
	s_mov_b32 m0, s62
	v_readfirstlane_b32 s63, v98
	v_add_u32_e32 v99, 0xb000, v101
	v_and_b32_e32 v7, 31, v24
	v_lshrrev_b32_e32 v9, 1, v24
	global_load_lds_dwordx4 v[0:1], off
	v_lshl_add_u64 v[0:1], v[74:75], 0, s[78:79]
	s_mov_b32 m0, s63
	v_readfirstlane_b32 s69, v99
	v_add_u32_e32 v100, 0xf000, v101
	v_and_or_b32 v2, v9, s94, v7
	global_load_lds_dwordx4 v[0:1], off
	v_lshl_add_u64 v[0:1], v[76:77], 0, s[78:79]
	s_mov_b32 m0, s69
	v_readfirstlane_b32 s70, v100
	global_load_lds_dwordx4 v[0:1], off
	v_lshl_add_u64 v[0:1], v[78:79], 0, s[78:79]
	s_mov_b32 m0, s70
	v_lshl_add_u32 v90, v2, 7, 0
	global_load_lds_dwordx4 v[0:1], off
	v_add_u32_e32 v83, v90, v4
	ds_read_b128 v[0:3], v83
	ds_read_b128 v[20:23], v83 offset:4096
	v_and_or_b32 v5, v6, 64, v7
	v_lshl_add_u32 v105, v5, 7, 0
	v_add_u32_e32 v85, v105, v4
	ds_read_b128 v[4:7], v85 offset:16384
	ds_read_b128 v[16:19], v85 offset:20480
	v_bfe_u32 v118, v24, 5, 1
	v_bitop3_b32 v24, v118, v89, 2 bitop3:0x36
	v_lshlrev_b32_e32 v86, 4, v24
	v_add_u32_e32 v84, v90, v86
	ds_read_b128 v[106:109], v84
	v_add_u32_e32 v87, v105, v86
	s_waitcnt lgkmcnt(0)
	v_mfma_f32_32x32x16_bf16 v[32:47], v[0:3], v[4:7], 0
	ds_read_b128 v[110:113], v87 offset:16384
	ds_read_b128 v[114:117], v87 offset:20480
	v_bitop3_b32 v86, v118, v89, 4 bitop3:0x36
	v_lshlrev_b32_e32 v88, 4, v86
	v_add_u32_e32 v86, v90, v88
	v_add_u32_e32 v88, v105, v88
	v_bitop3_b32 v89, v118, v89, 6 bitop3:0x36
	v_mfma_f32_32x32x16_bf16 v[48:63], v[0:3], v[16:19], 0
	s_mov_b32 m0, s71
	v_readfirstlane_b32 s64, v91
	v_readfirstlane_b32 s65, v92
	s_waitcnt lgkmcnt(0)
	v_mfma_f32_32x32x16_bf16 v[32:47], v[106:109], v[110:113], v[32:47]
	v_mfma_f32_32x32x16_bf16 v[48:63], v[106:109], v[114:117], v[48:63]
	ds_read_b128 v[106:109], v84 offset:4096
	v_mfma_f32_32x32x16_bf16 v[0:15], v[20:23], v[4:7], 0
	v_mfma_f32_32x32x16_bf16 v[16:31], v[20:23], v[16:19], 0
	s_waitcnt lgkmcnt(0)
	v_mfma_f32_32x32x16_bf16 v[0:15], v[106:109], v[110:113], v[0:15]
	ds_read_b128 v[110:113], v88 offset:16384
	v_mfma_f32_32x32x16_bf16 v[16:31], v[106:109], v[114:117], v[16:31]
	ds_read_b128 v[106:109], v86
	ds_read_b128 v[114:117], v88 offset:20480
	s_waitcnt lgkmcnt(0)
	v_mfma_f32_32x32x16_bf16 v[32:47], v[106:109], v[110:113], v[32:47]
	v_mfma_f32_32x32x16_bf16 v[48:63], v[106:109], v[114:117], v[48:63]
	ds_read_b128 v[106:109], v86 offset:4096
	s_waitcnt lgkmcnt(0)
	v_mfma_f32_32x32x16_bf16 v[0:15], v[106:109], v[110:113], v[0:15]
	v_lshlrev_b32_e32 v110, 4, v89
	v_add_u32_e32 v89, v90, v110
	v_add_u32_e32 v90, v105, v110
	ds_read_b128 v[110:113], v90 offset:16384
	v_mfma_f32_32x32x16_bf16 v[16:31], v[106:109], v[114:117], v[16:31]
	ds_read_b128 v[106:109], v89
	ds_read_b128 v[114:117], v90 offset:20480
	s_waitcnt lgkmcnt(0)
	v_mfma_f32_32x32x16_bf16 v[32:47], v[106:109], v[110:113], v[32:47]
	v_mfma_f32_32x32x16_bf16 v[48:63], v[106:109], v[114:117], v[48:63]
	ds_read_b128 v[106:109], v89 offset:4096
	s_waitcnt vmcnt(0)
	s_waitcnt vmcnt(0) lgkmcnt(0)
	s_barrier
; #define MFMA(a, b, c) __builtin_amdgcn_mfma_f32_32x32x16_bf16(a, b, c, 0, 0, 0)
; #define ISSUE(k0, bf) do { char* A_ = lw + (bf) * BUF; \
;     _Pragma("unroll") for (int i_ = 0; i_ < 4; ++i_) { glds16(al.ptr(lrow + 32 * i_, (k0) + cg), A_ + i_ * 4096); glds16(bl.ptr(lrow + 32 * i_, (k0) + cg), A_ + ABYTES + i_ * 4096); } \
;     if (HALO) { if (wid == 0) glds16(gh + (k0), A_ + 16384); } } while (0)
; template <bool HALO, class AL, class BL>
; __device__ __forceinline__ void gemm_core(f32x16 (&acc)[2][2], f32x16& hacc, const AL& al, const BL& bl, int K, char* lds,
;                                           const u16* halo0, const u16* halo1, int brow0, int brow1) {
;     ...
;   for (int kt = 0; kt < nk; ++kt) {
;     asm volatile("s_waitcnt vmcnt(0)" ::: "memory");
;     __syncthreads();
;     if (kt + 1 < nk) ISSUE((kt + 1) * 64, (kt + 1) & 1);
;     const char* T = lds + (kt & 1) * BUF;
; #pragma unroll
;     for (int kk = 0; kk < 4; ++kk) {
;       const int c = kk * 2 + hi;
;       bf16x8 a0 = *(const bf16x8*)(T + oa + ((c ^ sa) << 4));
;       bf16x8 a1 = *(const bf16x8*)(T + oa + 4096 + ((c ^ sa) << 4));
;       bf16x8 b0 = *(const bf16x8*)(T + ob0 + ((c ^ sb0) << 4));
;       bf16x8 b1 = *(const bf16x8*)(T + ob1 + ((c ^ sb1) << 4));
;       acc[0][0] = MFMA(a0, b0, acc[0][0]); acc[0][1] = MFMA(a0, b1, acc[0][1]);
;       acc[1][0] = MFMA(a1, b0, acc[1][0]); acc[1][1] = MFMA(a1, b1, acc[1][1]);
;       if (HALO) { bf16x8 ah = *(const bf16x8*)(T + oh + ((c ^ sh) << 4)); hacc = MFMA(ah, b0, hacc); }
;     }
;   }
	v_mfma_f32_32x32x16_bf16 v[0:15], v[106:109], v[110:113], v[0:15]
	v_mfma_f32_32x32x16_bf16 v[16:31], v[106:109], v[114:117], v[16:31]
	v_lshl_add_u64 v[106:107], v[64:65], 0, s[24:25]
	global_load_lds_dwordx4 v[106:107], off
	v_lshl_add_u64 v[106:107], v[66:67], 0, s[24:25]
	s_mov_b32 m0, s72
	s_nop 0
	global_load_lds_dwordx4 v[106:107], off
	v_lshl_add_u64 v[106:107], v[68:69], 0, s[24:25]
	s_mov_b32 m0, s73
	s_nop 0
	global_load_lds_dwordx4 v[106:107], off
	v_lshl_add_u64 v[106:107], v[70:71], 0, s[24:25]
	s_mov_b32 m0, s76
	s_nop 0
	global_load_lds_dwordx4 v[106:107], off
	v_lshl_add_u64 v[106:107], v[72:73], 0, s[24:25]
	s_mov_b32 m0, s47
	s_nop 0
	global_load_lds_dwordx4 v[106:107], off
	v_lshl_add_u64 v[106:107], v[74:75], 0, s[24:25]
	s_mov_b32 m0, s49
	s_nop 0
	global_load_lds_dwordx4 v[106:107], off
	v_lshl_add_u64 v[106:107], v[76:77], 0, s[24:25]
	s_mov_b32 m0, s56
	s_nop 0
	global_load_lds_dwordx4 v[106:107], off
	v_lshl_add_u64 v[106:107], v[78:79], 0, s[24:25]
	s_mov_b32 m0, s57
	s_nop 0
	global_load_lds_dwordx4 v[106:107], off
	ds_read_b128 v[106:109], v83 offset:32768
	ds_read_b128 v[110:113], v85 offset:49152
	ds_read_b128 v[114:117], v85 offset:53248
	s_waitcnt lgkmcnt(0)
	v_mfma_f32_32x32x16_bf16 v[32:47], v[106:109], v[110:113], v[32:47]
	s_mov_b32 m0, s58
	v_mfma_f32_32x32x16_bf16 v[48:63], v[106:109], v[114:117], v[48:63]
	ds_read_b128 v[106:109], v83 offset:36864
	s_waitcnt lgkmcnt(0)
	v_mfma_f32_32x32x16_bf16 v[0:15], v[106:109], v[110:113], v[0:15]
	v_mfma_f32_32x32x16_bf16 v[16:31], v[106:109], v[114:117], v[16:31]
	ds_read_b128 v[106:109], v84 offset:32768
	ds_read_b128 v[110:113], v87 offset:49152
	ds_read_b128 v[114:117], v87 offset:53248
	s_waitcnt lgkmcnt(0)
	v_mfma_f32_32x32x16_bf16 v[32:47], v[106:109], v[110:113], v[32:47]
	v_mfma_f32_32x32x16_bf16 v[48:63], v[106:109], v[114:117], v[48:63]
	ds_read_b128 v[106:109], v84 offset:36864
	s_waitcnt lgkmcnt(0)
	v_mfma_f32_32x32x16_bf16 v[0:15], v[106:109], v[110:113], v[0:15]
	v_mfma_f32_32x32x16_bf16 v[16:31], v[106:109], v[114:117], v[16:31]
	ds_read_b128 v[106:109], v86 offset:32768
	ds_read_b128 v[110:113], v88 offset:49152
	ds_read_b128 v[114:117], v88 offset:53248
	s_waitcnt lgkmcnt(0)
	v_mfma_f32_32x32x16_bf16 v[32:47], v[106:109], v[110:113], v[32:47]
	v_mfma_f32_32x32x16_bf16 v[48:63], v[106:109], v[114:117], v[48:63]
	ds_read_b128 v[106:109], v86 offset:36864
	s_waitcnt lgkmcnt(0)
	v_mfma_f32_32x32x16_bf16 v[0:15], v[106:109], v[110:113], v[0:15]
	v_mfma_f32_32x32x16_bf16 v[16:31], v[106:109], v[114:117], v[16:31]
	ds_read_b128 v[106:109], v89 offset:32768
	ds_read_b128 v[110:113], v90 offset:49152
	ds_read_b128 v[114:117], v90 offset:53248
	s_waitcnt lgkmcnt(0)
	v_mfma_f32_32x32x16_bf16 v[32:47], v[106:109], v[110:113], v[32:47]
	v_mfma_f32_32x32x16_bf16 v[48:63], v[106:109], v[114:117], v[48:63]
	ds_read_b128 v[106:109], v89 offset:36864
	s_waitcnt vmcnt(0)
	s_waitcnt vmcnt(0) lgkmcnt(0)
	s_barrier
	v_mfma_f32_32x32x16_bf16 v[0:15], v[106:109], v[110:113], v[0:15]
	v_mfma_f32_32x32x16_bf16 v[16:31], v[106:109], v[114:117], v[16:31]
	v_lshl_add_u64 v[106:107], v[64:65], 0, s[74:75]
	global_load_lds_dwordx4 v[106:107], off
	v_lshl_add_u64 v[106:107], v[66:67], 0, s[74:75]
	s_mov_b32 m0, s59
	s_nop 0
	global_load_lds_dwordx4 v[106:107], off
	v_lshl_add_u64 v[106:107], v[68:69], 0, s[74:75]
	s_mov_b32 m0, s60
	s_nop 0
	global_load_lds_dwordx4 v[106:107], off
	v_lshl_add_u64 v[106:107], v[70:71], 0, s[74:75]
	s_mov_b32 m0, s61
	s_nop 0
	global_load_lds_dwordx4 v[106:107], off
	v_lshl_add_u64 v[106:107], v[72:73], 0, s[74:75]
	s_mov_b32 m0, s62
	s_nop 0
	global_load_lds_dwordx4 v[106:107], off
	v_lshl_add_u64 v[106:107], v[74:75], 0, s[74:75]
	s_mov_b32 m0, s63
	s_nop 0
	global_load_lds_dwordx4 v[106:107], off
	v_lshl_add_u64 v[106:107], v[76:77], 0, s[74:75]
	s_mov_b32 m0, s69
	s_nop 0
	global_load_lds_dwordx4 v[106:107], off
	v_lshl_add_u64 v[106:107], v[78:79], 0, s[74:75]
	s_mov_b32 m0, s70
	s_nop 0
	global_load_lds_dwordx4 v[106:107], off
	ds_read_b128 v[106:109], v83
	ds_read_b128 v[110:113], v85 offset:16384
	ds_read_b128 v[114:117], v85 offset:20480
	s_waitcnt lgkmcnt(0)
	v_mfma_f32_32x32x16_bf16 v[32:47], v[106:109], v[110:113], v[32:47]
	s_mov_b32 m0, s71
	v_mfma_f32_32x32x16_bf16 v[48:63], v[106:109], v[114:117], v[48:63]
	ds_read_b128 v[106:109], v83 offset:4096
	s_waitcnt lgkmcnt(0)
	v_mfma_f32_32x32x16_bf16 v[0:15], v[106:109], v[110:113], v[0:15]
	v_mfma_f32_32x32x16_bf16 v[16:31], v[106:109], v[114:117], v[16:31]
	ds_read_b128 v[106:109], v84
	ds_read_b128 v[110:113], v87 offset:16384
	ds_read_b128 v[114:117], v87 offset:20480
	s_waitcnt lgkmcnt(0)
	v_mfma_f32_32x32x16_bf16 v[32:47], v[106:109], v[110:113], v[32:47]
	v_mfma_f32_32x32x16_bf16 v[48:63], v[106:109], v[114:117], v[48:63]
	ds_read_b128 v[106:109], v84 offset:4096
	s_waitcnt lgkmcnt(0)
	v_mfma_f32_32x32x16_bf16 v[0:15], v[106:109], v[110:113], v[0:15]
	v_mfma_f32_32x32x16_bf16 v[16:31], v[106:109], v[114:117], v[16:31]
	ds_read_b128 v[106:109], v86
	ds_read_b128 v[110:113], v88 offset:16384
	ds_read_b128 v[114:117], v88 offset:20480
	s_waitcnt lgkmcnt(0)
	v_mfma_f32_32x32x16_bf16 v[32:47], v[106:109], v[110:113], v[32:47]
	v_mfma_f32_32x32x16_bf16 v[48:63], v[106:109], v[114:117], v[48:63]
	ds_read_b128 v[106:109], v86 offset:4096
	s_waitcnt lgkmcnt(0)
	v_mfma_f32_32x32x16_bf16 v[0:15], v[106:109], v[110:113], v[0:15]
	v_mfma_f32_32x32x16_bf16 v[16:31], v[106:109], v[114:117], v[16:31]
	ds_read_b128 v[106:109], v89
	ds_read_b128 v[110:113], v90 offset:16384
	ds_read_b128 v[114:117], v90 offset:20480
	s_waitcnt lgkmcnt(0)
	v_mfma_f32_32x32x16_bf16 v[32:47], v[106:109], v[110:113], v[32:47]
	v_mfma_f32_32x32x16_bf16 v[48:63], v[106:109], v[114:117], v[48:63]
	ds_read_b128 v[106:109], v89 offset:4096
	s_waitcnt vmcnt(0)
	s_waitcnt vmcnt(0) lgkmcnt(0)
	s_barrier
; #define MFMA(a, b, c) __builtin_amdgcn_mfma_f32_32x32x16_bf16(a, b, c, 0, 0, 0)
; #define ISSUE(k0, bf) do { char* A_ = lw + (bf) * BUF; \
;     _Pragma("unroll") for (int i_ = 0; i_ < 4; ++i_) { glds16(al.ptr(lrow + 32 * i_, (k0) + cg), A_ + i_ * 4096); glds16(bl.ptr(lrow + 32 * i_, (k0) + cg), A_ + ABYTES + i_ * 4096); } \
;     if (HALO) { if (wid == 0) glds16(gh + (k0), A_ + 16384); } } while (0)
; template <bool HALO, class AL, class BL>
; __device__ __forceinline__ void gemm_core(f32x16 (&acc)[2][2], f32x16& hacc, const AL& al, const BL& bl, int K, char* lds,
;                                           const u16* halo0, const u16* halo1, int brow0, int brow1) {
;     ...
;   for (int kt = 0; kt < nk; ++kt) {
;     asm volatile("s_waitcnt vmcnt(0)" ::: "memory");
;     __syncthreads();
;     if (kt + 1 < nk) ISSUE((kt + 1) * 64, (kt + 1) & 1);
;     const char* T = lds + (kt & 1) * BUF;
; #pragma unroll
;     for (int kk = 0; kk < 4; ++kk) {
;       const int c = kk * 2 + hi;
;       bf16x8 a0 = *(const bf16x8*)(T + oa + ((c ^ sa) << 4));
;       bf16x8 a1 = *(const bf16x8*)(T + oa + 4096 + ((c ^ sa) << 4));
;       bf16x8 b0 = *(const bf16x8*)(T + ob0 + ((c ^ sb0) << 4));
;       bf16x8 b1 = *(const bf16x8*)(T + ob1 + ((c ^ sb1) << 4));
;       acc[0][0] = MFMA(a0, b0, acc[0][0]); acc[0][1] = MFMA(a0, b1, acc[0][1]);
;       acc[1][0] = MFMA(a1, b0, acc[1][0]); acc[1][1] = MFMA(a1, b1, acc[1][1]);
;       if (HALO) { bf16x8 ah = *(const bf16x8*)(T + oh + ((c ^ sh) << 4)); hacc = MFMA(ah, b0, hacc); }
;     }
;   }
	v_mfma_f32_32x32x16_bf16 v[0:15], v[106:109], v[110:113], v[0:15]
	v_mfma_f32_32x32x16_bf16 v[16:31], v[106:109], v[114:117], v[16:31]
	v_lshl_add_u64 v[106:107], v[64:65], 0, s[20:21]
	global_load_lds_dwordx4 v[106:107], off
	v_lshl_add_u64 v[106:107], v[66:67], 0, s[20:21]
	s_mov_b32 m0, s72
	s_nop 0
	global_load_lds_dwordx4 v[106:107], off
	v_lshl_add_u64 v[106:107], v[68:69], 0, s[20:21]
	s_mov_b32 m0, s73
	s_nop 0
	global_load_lds_dwordx4 v[106:107], off
	v_lshl_add_u64 v[106:107], v[70:71], 0, s[20:21]
	s_mov_b32 m0, s76
	s_nop 0
	global_load_lds_dwordx4 v[106:107], off
	v_lshl_add_u64 v[106:107], v[72:73], 0, s[20:21]
	s_mov_b32 m0, s47
	s_nop 0
	global_load_lds_dwordx4 v[106:107], off
	v_lshl_add_u64 v[106:107], v[74:75], 0, s[20:21]
	s_mov_b32 m0, s49
	s_nop 0
	global_load_lds_dwordx4 v[106:107], off
	v_lshl_add_u64 v[106:107], v[76:77], 0, s[20:21]
	s_mov_b32 m0, s56
	s_nop 0
	global_load_lds_dwordx4 v[106:107], off
	v_lshl_add_u64 v[106:107], v[78:79], 0, s[20:21]
	s_mov_b32 m0, s57
	s_nop 0
	global_load_lds_dwordx4 v[106:107], off
	ds_read_b128 v[106:109], v83 offset:32768
	ds_read_b128 v[110:113], v85 offset:49152
	ds_read_b128 v[114:117], v85 offset:53248
	s_waitcnt lgkmcnt(0)
	v_mfma_f32_32x32x16_bf16 v[32:47], v[106:109], v[110:113], v[32:47]
	s_mov_b32 m0, s58
	v_mfma_f32_32x32x16_bf16 v[48:63], v[106:109], v[114:117], v[48:63]
	ds_read_b128 v[106:109], v83 offset:36864
	s_waitcnt lgkmcnt(0)
	v_mfma_f32_32x32x16_bf16 v[0:15], v[106:109], v[110:113], v[0:15]
	v_mfma_f32_32x32x16_bf16 v[16:31], v[106:109], v[114:117], v[16:31]
	ds_read_b128 v[106:109], v84 offset:32768
	ds_read_b128 v[110:113], v87 offset:49152
	ds_read_b128 v[114:117], v87 offset:53248
	s_waitcnt lgkmcnt(0)
	v_mfma_f32_32x32x16_bf16 v[32:47], v[106:109], v[110:113], v[32:47]
	v_mfma_f32_32x32x16_bf16 v[48:63], v[106:109], v[114:117], v[48:63]
	ds_read_b128 v[106:109], v84 offset:36864
	s_waitcnt lgkmcnt(0)
	v_mfma_f32_32x32x16_bf16 v[0:15], v[106:109], v[110:113], v[0:15]
	v_mfma_f32_32x32x16_bf16 v[16:31], v[106:109], v[114:117], v[16:31]
	ds_read_b128 v[106:109], v86 offset:32768
	ds_read_b128 v[110:113], v88 offset:49152
	ds_read_b128 v[114:117], v88 offset:53248
	s_waitcnt lgkmcnt(0)
	v_mfma_f32_32x32x16_bf16 v[32:47], v[106:109], v[110:113], v[32:47]
	v_mfma_f32_32x32x16_bf16 v[48:63], v[106:109], v[114:117], v[48:63]
	ds_read_b128 v[106:109], v86 offset:36864
	s_waitcnt lgkmcnt(0)
	v_mfma_f32_32x32x16_bf16 v[0:15], v[106:109], v[110:113], v[0:15]
	v_mfma_f32_32x32x16_bf16 v[16:31], v[106:109], v[114:117], v[16:31]
	ds_read_b128 v[106:109], v89 offset:32768
	ds_read_b128 v[110:113], v90 offset:49152
	ds_read_b128 v[114:117], v90 offset:53248
	s_waitcnt lgkmcnt(0)
	v_mfma_f32_32x32x16_bf16 v[32:47], v[106:109], v[110:113], v[32:47]
	v_mfma_f32_32x32x16_bf16 v[48:63], v[106:109], v[114:117], v[48:63]
	ds_read_b128 v[106:109], v89 offset:36864
	s_waitcnt vmcnt(0)
	s_waitcnt vmcnt(0) lgkmcnt(0)
	s_barrier
	v_mfma_f32_32x32x16_bf16 v[0:15], v[106:109], v[110:113], v[0:15]
	v_mfma_f32_32x32x16_bf16 v[16:31], v[106:109], v[114:117], v[16:31]
	v_lshl_add_u64 v[106:107], v[64:65], 0, s[86:87]
	global_load_lds_dwordx4 v[106:107], off
	v_lshl_add_u64 v[106:107], v[66:67], 0, s[86:87]
	s_mov_b32 m0, s59
	s_nop 0
	global_load_lds_dwordx4 v[106:107], off
	v_lshl_add_u64 v[106:107], v[68:69], 0, s[86:87]
	s_mov_b32 m0, s60
	s_nop 0
	global_load_lds_dwordx4 v[106:107], off
	v_lshl_add_u64 v[106:107], v[70:71], 0, s[86:87]
	s_mov_b32 m0, s61
	s_nop 0
	global_load_lds_dwordx4 v[106:107], off
	v_lshl_add_u64 v[106:107], v[72:73], 0, s[86:87]
	s_mov_b32 m0, s62
	s_nop 0
	global_load_lds_dwordx4 v[106:107], off
	v_lshl_add_u64 v[106:107], v[74:75], 0, s[86:87]
	s_mov_b32 m0, s63
	s_nop 0
	global_load_lds_dwordx4 v[106:107], off
	v_lshl_add_u64 v[106:107], v[76:77], 0, s[86:87]
	s_mov_b32 m0, s69
	s_nop 0
	global_load_lds_dwordx4 v[106:107], off
	v_lshl_add_u64 v[106:107], v[78:79], 0, s[86:87]
	s_mov_b32 m0, s70
	s_nop 0
	global_load_lds_dwordx4 v[106:107], off
	ds_read_b128 v[106:109], v83
	ds_read_b128 v[110:113], v85 offset:16384
	ds_read_b128 v[114:117], v85 offset:20480
	s_waitcnt lgkmcnt(0)
	v_mfma_f32_32x32x16_bf16 v[32:47], v[106:109], v[110:113], v[32:47]
	s_mov_b32 m0, s71
	v_readfirstlane_b32 s71, v99
	v_mfma_f32_32x32x16_bf16 v[48:63], v[106:109], v[114:117], v[48:63]
	ds_read_b128 v[106:109], v83 offset:4096
	s_waitcnt lgkmcnt(0)
	v_mfma_f32_32x32x16_bf16 v[0:15], v[106:109], v[110:113], v[0:15]
	v_mfma_f32_32x32x16_bf16 v[16:31], v[106:109], v[114:117], v[16:31]
	ds_read_b128 v[106:109], v84
	ds_read_b128 v[110:113], v87 offset:16384
	ds_read_b128 v[114:117], v87 offset:20480
	s_waitcnt lgkmcnt(0)
	v_mfma_f32_32x32x16_bf16 v[32:47], v[106:109], v[110:113], v[32:47]
	v_mfma_f32_32x32x16_bf16 v[48:63], v[106:109], v[114:117], v[48:63]
	ds_read_b128 v[106:109], v84 offset:4096
	s_waitcnt lgkmcnt(0)
	v_mfma_f32_32x32x16_bf16 v[0:15], v[106:109], v[110:113], v[0:15]
	v_mfma_f32_32x32x16_bf16 v[16:31], v[106:109], v[114:117], v[16:31]
	ds_read_b128 v[106:109], v86
	ds_read_b128 v[110:113], v88 offset:16384
	ds_read_b128 v[114:117], v88 offset:20480
	s_waitcnt lgkmcnt(0)
	v_mfma_f32_32x32x16_bf16 v[32:47], v[106:109], v[110:113], v[32:47]
	v_mfma_f32_32x32x16_bf16 v[48:63], v[106:109], v[114:117], v[48:63]
	ds_read_b128 v[106:109], v86 offset:4096
	s_waitcnt lgkmcnt(0)
	v_mfma_f32_32x32x16_bf16 v[0:15], v[106:109], v[110:113], v[0:15]
	v_mfma_f32_32x32x16_bf16 v[16:31], v[106:109], v[114:117], v[16:31]
	ds_read_b128 v[106:109], v89
	ds_read_b128 v[110:113], v90 offset:16384
	ds_read_b128 v[114:117], v90 offset:20480
	s_waitcnt lgkmcnt(0)
	v_mfma_f32_32x32x16_bf16 v[32:47], v[106:109], v[110:113], v[32:47]
	v_mfma_f32_32x32x16_bf16 v[48:63], v[106:109], v[114:117], v[48:63]
	ds_read_b128 v[106:109], v89 offset:4096
	s_waitcnt vmcnt(0)
	s_waitcnt vmcnt(0) lgkmcnt(0)
	s_barrier
; #define MFMA(a, b, c) __builtin_amdgcn_mfma_f32_32x32x16_bf16(a, b, c, 0, 0, 0)
; #define ISSUE(k0, bf) do { char* A_ = lw + (bf) * BUF; \
;     _Pragma("unroll") for (int i_ = 0; i_ < 4; ++i_) { glds16(al.ptr(lrow + 32 * i_, (k0) + cg), A_ + i_ * 4096); glds16(bl.ptr(lrow + 32 * i_, (k0) + cg), A_ + ABYTES + i_ * 4096); } \
;     if (HALO) { if (wid == 0) glds16(gh + (k0), A_ + 16384); } } while (0)
; template <bool HALO, class AL, class BL>
; __device__ __forceinline__ void gemm_core(f32x16 (&acc)[2][2], f32x16& hacc, const AL& al, const BL& bl, int K, char* lds,
;                                           const u16* halo0, const u16* halo1, int brow0, int brow1) {
;     ...
;   for (int kt = 0; kt < nk; ++kt) {
;     asm volatile("s_waitcnt vmcnt(0)" ::: "memory");
;     __syncthreads();
;     if (kt + 1 < nk) ISSUE((kt + 1) * 64, (kt + 1) & 1);
;     const char* T = lds + (kt & 1) * BUF;
; #pragma unroll
;     for (int kk = 0; kk < 4; ++kk) {
;       const int c = kk * 2 + hi;
;       bf16x8 a0 = *(const bf16x8*)(T + oa + ((c ^ sa) << 4));
;       bf16x8 a1 = *(const bf16x8*)(T + oa + 4096 + ((c ^ sa) << 4));
;       bf16x8 b0 = *(const bf16x8*)(T + ob0 + ((c ^ sb0) << 4));
;       bf16x8 b1 = *(const bf16x8*)(T + ob1 + ((c ^ sb1) << 4));
;       acc[0][0] = MFMA(a0, b0, acc[0][0]); acc[0][1] = MFMA(a0, b1, acc[0][1]);
;       acc[1][0] = MFMA(a1, b0, acc[1][0]); acc[1][1] = MFMA(a1, b1, acc[1][1]);
;       if (HALO) { bf16x8 ah = *(const bf16x8*)(T + oh + ((c ^ sh) << 4)); hacc = MFMA(ah, b0, hacc); }
;     }
;   }
	v_mfma_f32_32x32x16_bf16 v[0:15], v[106:109], v[110:113], v[0:15]
	v_mfma_f32_32x32x16_bf16 v[16:31], v[106:109], v[114:117], v[16:31]
	v_lshl_add_u64 v[106:107], v[64:65], 0, s[30:31]
	global_load_lds_dwordx4 v[106:107], off
	v_lshl_add_u64 v[106:107], v[66:67], 0, s[30:31]
	s_mov_b32 m0, s72
	v_readfirstlane_b32 s72, v100
	global_load_lds_dwordx4 v[106:107], off
	v_lshl_add_u64 v[106:107], v[68:69], 0, s[30:31]
	s_mov_b32 m0, s73
	s_nop 0
	global_load_lds_dwordx4 v[106:107], off
	v_lshl_add_u64 v[106:107], v[70:71], 0, s[30:31]
	s_mov_b32 m0, s76
	s_nop 0
	global_load_lds_dwordx4 v[106:107], off
	v_lshl_add_u64 v[106:107], v[72:73], 0, s[30:31]
	s_mov_b32 m0, s47
	s_nop 0
	global_load_lds_dwordx4 v[106:107], off
	v_lshl_add_u64 v[106:107], v[74:75], 0, s[30:31]
	s_mov_b32 m0, s49
	s_nop 0
	global_load_lds_dwordx4 v[106:107], off
	v_lshl_add_u64 v[106:107], v[76:77], 0, s[30:31]
	s_mov_b32 m0, s56
	s_nop 0
	global_load_lds_dwordx4 v[106:107], off
	v_lshl_add_u64 v[106:107], v[78:79], 0, s[30:31]
	s_mov_b32 m0, s57
	s_nop 0
	global_load_lds_dwordx4 v[106:107], off
	ds_read_b128 v[106:109], v83 offset:32768
	ds_read_b128 v[110:113], v85 offset:49152
	ds_read_b128 v[114:117], v85 offset:53248
	s_waitcnt lgkmcnt(0)
	v_mfma_f32_32x32x16_bf16 v[32:47], v[106:109], v[110:113], v[32:47]
	s_mov_b32 m0, s58
	v_readfirstlane_b32 s58, v101
	v_mfma_f32_32x32x16_bf16 v[48:63], v[106:109], v[114:117], v[48:63]
	ds_read_b128 v[106:109], v83 offset:36864
	s_waitcnt lgkmcnt(0)
	v_mfma_f32_32x32x16_bf16 v[0:15], v[106:109], v[110:113], v[0:15]
	v_mfma_f32_32x32x16_bf16 v[16:31], v[106:109], v[114:117], v[16:31]
	ds_read_b128 v[106:109], v84 offset:32768
	ds_read_b128 v[110:113], v87 offset:49152
	ds_read_b128 v[114:117], v87 offset:53248
	s_waitcnt lgkmcnt(0)
	v_mfma_f32_32x32x16_bf16 v[32:47], v[106:109], v[110:113], v[32:47]
	v_mfma_f32_32x32x16_bf16 v[48:63], v[106:109], v[114:117], v[48:63]
	ds_read_b128 v[106:109], v84 offset:36864
	s_waitcnt lgkmcnt(0)
	v_mfma_f32_32x32x16_bf16 v[0:15], v[106:109], v[110:113], v[0:15]
	v_mfma_f32_32x32x16_bf16 v[16:31], v[106:109], v[114:117], v[16:31]
	ds_read_b128 v[106:109], v86 offset:32768
	ds_read_b128 v[110:113], v88 offset:49152
	ds_read_b128 v[114:117], v88 offset:53248
	s_waitcnt lgkmcnt(0)
	v_mfma_f32_32x32x16_bf16 v[32:47], v[106:109], v[110:113], v[32:47]
	v_mfma_f32_32x32x16_bf16 v[48:63], v[106:109], v[114:117], v[48:63]
	ds_read_b128 v[106:109], v86 offset:36864
	s_waitcnt lgkmcnt(0)
	v_mfma_f32_32x32x16_bf16 v[0:15], v[106:109], v[110:113], v[0:15]
	v_mfma_f32_32x32x16_bf16 v[16:31], v[106:109], v[114:117], v[16:31]
	ds_read_b128 v[106:109], v89 offset:32768
	ds_read_b128 v[110:113], v90 offset:49152
	ds_read_b128 v[114:117], v90 offset:53248
	s_waitcnt lgkmcnt(0)
	v_mfma_f32_32x32x16_bf16 v[32:47], v[106:109], v[110:113], v[32:47]
	v_mfma_f32_32x32x16_bf16 v[48:63], v[106:109], v[114:117], v[48:63]
	ds_read_b128 v[106:109], v89 offset:36864
	s_waitcnt vmcnt(0)
	s_waitcnt vmcnt(0) lgkmcnt(0)
	s_barrier
	v_mfma_f32_32x32x16_bf16 v[0:15], v[106:109], v[110:113], v[0:15]
	v_mfma_f32_32x32x16_bf16 v[16:31], v[106:109], v[114:117], v[16:31]
	v_lshl_add_u64 v[106:107], v[64:65], 0, s[4:5]
	global_load_lds_dwordx4 v[106:107], off
	v_lshl_add_u64 v[106:107], v[66:67], 0, s[4:5]
	s_mov_b32 m0, s59
	v_readfirstlane_b32 s59, v102
	global_load_lds_dwordx4 v[106:107], off
	v_lshl_add_u64 v[106:107], v[68:69], 0, s[4:5]
	s_mov_b32 m0, s60
	v_readfirstlane_b32 s60, v103
	global_load_lds_dwordx4 v[106:107], off
	v_lshl_add_u64 v[106:107], v[70:71], 0, s[4:5]
	s_mov_b32 m0, s61
	v_readfirstlane_b32 s61, v104
	global_load_lds_dwordx4 v[106:107], off
	v_lshl_add_u64 v[106:107], v[72:73], 0, s[4:5]
	s_mov_b32 m0, s62
	v_lshl_add_u64 v[102:103], v[70:71], 0, s[66:67]
	global_load_lds_dwordx4 v[106:107], off
	v_lshl_add_u64 v[106:107], v[74:75], 0, s[4:5]
	s_mov_b32 m0, s63
	v_readfirstlane_b32 s62, v95
	global_load_lds_dwordx4 v[106:107], off
	v_lshl_add_u64 v[106:107], v[76:77], 0, s[4:5]
	s_mov_b32 m0, s69
	v_readfirstlane_b32 s63, v96
	global_load_lds_dwordx4 v[106:107], off
	v_lshl_add_u64 v[106:107], v[78:79], 0, s[4:5]
	s_mov_b32 m0, s70
	v_readfirstlane_b32 s69, v97
	global_load_lds_dwordx4 v[106:107], off
	ds_read_b128 v[106:109], v83
	ds_read_b128 v[110:113], v85 offset:16384
	ds_read_b128 v[114:117], v85 offset:20480
	s_waitcnt lgkmcnt(0)
	v_mfma_f32_32x32x16_bf16 v[32:47], v[106:109], v[110:113], v[32:47]
	s_mov_b32 m0, s58
	v_readfirstlane_b32 s70, v98
	v_mfma_f32_32x32x16_bf16 v[48:63], v[106:109], v[114:117], v[48:63]
	ds_read_b128 v[106:109], v83 offset:4096
	s_waitcnt lgkmcnt(0)
	v_mfma_f32_32x32x16_bf16 v[0:15], v[106:109], v[110:113], v[0:15]
	v_mfma_f32_32x32x16_bf16 v[16:31], v[106:109], v[114:117], v[16:31]
	ds_read_b128 v[106:109], v84
	ds_read_b128 v[110:113], v87 offset:16384
	ds_read_b128 v[114:117], v87 offset:20480
	s_waitcnt lgkmcnt(0)
	v_mfma_f32_32x32x16_bf16 v[32:47], v[106:109], v[110:113], v[32:47]
	v_mfma_f32_32x32x16_bf16 v[48:63], v[106:109], v[114:117], v[48:63]
	ds_read_b128 v[106:109], v84 offset:4096
	s_waitcnt lgkmcnt(0)
	v_mfma_f32_32x32x16_bf16 v[0:15], v[106:109], v[110:113], v[0:15]
	v_mfma_f32_32x32x16_bf16 v[16:31], v[106:109], v[114:117], v[16:31]
	ds_read_b128 v[106:109], v86
	ds_read_b128 v[110:113], v88 offset:16384
	ds_read_b128 v[114:117], v88 offset:20480
	s_waitcnt lgkmcnt(0)
	v_mfma_f32_32x32x16_bf16 v[32:47], v[106:109], v[110:113], v[32:47]
	v_mfma_f32_32x32x16_bf16 v[48:63], v[106:109], v[114:117], v[48:63]
	ds_read_b128 v[106:109], v86 offset:4096
	s_waitcnt lgkmcnt(0)
	v_mfma_f32_32x32x16_bf16 v[0:15], v[106:109], v[110:113], v[0:15]
	v_mfma_f32_32x32x16_bf16 v[16:31], v[106:109], v[114:117], v[16:31]
	ds_read_b128 v[106:109], v89
	ds_read_b128 v[110:113], v90 offset:16384
	ds_read_b128 v[114:117], v90 offset:20480
	s_waitcnt lgkmcnt(0)
	v_mfma_f32_32x32x16_bf16 v[32:47], v[106:109], v[110:113], v[32:47]
	v_mfma_f32_32x32x16_bf16 v[48:63], v[106:109], v[114:117], v[48:63]
	ds_read_b128 v[106:109], v89 offset:4096
	s_waitcnt vmcnt(0)
	s_waitcnt vmcnt(0) lgkmcnt(0)
	s_barrier
; #define MFMA(a, b, c) __builtin_amdgcn_mfma_f32_32x32x16_bf16(a, b, c, 0, 0, 0)
; #define ISSUE(k0, bf) do { char* A_ = lw + (bf) * BUF; \
;     _Pragma("unroll") for (int i_ = 0; i_ < 4; ++i_) { glds16(al.ptr(lrow + 32 * i_, (k0) + cg), A_ + i_ * 4096); glds16(bl.ptr(lrow + 32 * i_, (k0) + cg), A_ + ABYTES + i_ * 4096); } \
;     if (HALO) { if (wid == 0) glds16(gh + (k0), A_ + 16384); } } while (0)
; template <bool HALO, class AL, class BL>
; __device__ __forceinline__ void gemm_core(f32x16 (&acc)[2][2], f32x16& hacc, const AL& al, const BL& bl, int K, char* lds,
;                                           const u16* halo0, const u16* halo1, int brow0, int brow1) {
;     ...
;   for (int kt = 0; kt < nk; ++kt) {
;     asm volatile("s_waitcnt vmcnt(0)" ::: "memory");
;     __syncthreads();
;     if (kt + 1 < nk) ISSUE((kt + 1) * 64, (kt + 1) & 1);
;     const char* T = lds + (kt & 1) * BUF;
; #pragma unroll
;     for (int kk = 0; kk < 4; ++kk) {
;       const int c = kk * 2 + hi;
;       bf16x8 a0 = *(const bf16x8*)(T + oa + ((c ^ sa) << 4));
;       bf16x8 a1 = *(const bf16x8*)(T + oa + 4096 + ((c ^ sa) << 4));
;       bf16x8 b0 = *(const bf16x8*)(T + ob0 + ((c ^ sb0) << 4));
;       bf16x8 b1 = *(const bf16x8*)(T + ob1 + ((c ^ sb1) << 4));
;       acc[0][0] = MFMA(a0, b0, acc[0][0]); acc[0][1] = MFMA(a0, b1, acc[0][1]);
;       acc[1][0] = MFMA(a1, b0, acc[1][0]); acc[1][1] = MFMA(a1, b1, acc[1][1]);
;       if (HALO) { bf16x8 ah = *(const bf16x8*)(T + oh + ((c ^ sh) << 4)); hacc = MFMA(ah, b0, hacc); }
;     }
;   }
	v_mfma_f32_32x32x16_bf16 v[0:15], v[106:109], v[110:113], v[0:15]
	v_mfma_f32_32x32x16_bf16 v[16:31], v[106:109], v[114:117], v[16:31]
	v_lshl_add_u64 v[106:107], v[64:65], 0, s[66:67]
	global_load_lds_dwordx4 v[106:107], off
	v_lshl_add_u64 v[106:107], v[66:67], 0, s[66:67]
	s_mov_b32 m0, s59
	s_nop 0
	global_load_lds_dwordx4 v[106:107], off
	v_lshl_add_u64 v[106:107], v[68:69], 0, s[66:67]
	s_mov_b32 m0, s60
	s_nop 0
	global_load_lds_dwordx4 v[106:107], off
	s_mov_b32 m0, s61
	s_nop 0
	global_load_lds_dwordx4 v[102:103], off
	v_lshl_add_u64 v[102:103], v[72:73], 0, s[66:67]
	s_mov_b32 m0, s47
	s_nop 0
	global_load_lds_dwordx4 v[102:103], off
	v_lshl_add_u64 v[102:103], v[74:75], 0, s[66:67]
	s_mov_b32 m0, s49
	s_nop 0
	global_load_lds_dwordx4 v[102:103], off
	v_lshl_add_u64 v[102:103], v[76:77], 0, s[66:67]
	s_mov_b32 m0, s56
	v_readfirstlane_b32 s56, v94
	global_load_lds_dwordx4 v[102:103], off
	v_lshl_add_u64 v[102:103], v[78:79], 0, s[66:67]
	s_mov_b32 m0, s57
	v_readfirstlane_b32 s57, v93
	global_load_lds_dwordx4 v[102:103], off
	ds_read_b128 v[102:105], v83 offset:32768
	ds_read_b128 v[106:109], v85 offset:49152
	ds_read_b128 v[110:113], v85 offset:53248
	s_waitcnt lgkmcnt(0)
	v_mfma_f32_32x32x16_bf16 v[32:47], v[102:105], v[106:109], v[32:47]
	s_mov_b32 m0, s56
	v_lshl_add_u64 v[94:95], v[70:71], 0, s[26:27]
	v_mfma_f32_32x32x16_bf16 v[48:63], v[102:105], v[110:113], v[48:63]
	ds_read_b128 v[102:105], v83 offset:36864
	s_waitcnt lgkmcnt(0)
	v_mfma_f32_32x32x16_bf16 v[0:15], v[102:105], v[106:109], v[0:15]
	v_mfma_f32_32x32x16_bf16 v[16:31], v[102:105], v[110:113], v[16:31]
	ds_read_b128 v[102:105], v84 offset:32768
	ds_read_b128 v[106:109], v87 offset:49152
	ds_read_b128 v[110:113], v87 offset:53248
	s_waitcnt lgkmcnt(0)
	v_mfma_f32_32x32x16_bf16 v[32:47], v[102:105], v[106:109], v[32:47]
	v_mfma_f32_32x32x16_bf16 v[48:63], v[102:105], v[110:113], v[48:63]
	ds_read_b128 v[102:105], v84 offset:36864
	s_waitcnt lgkmcnt(0)
	v_mfma_f32_32x32x16_bf16 v[0:15], v[102:105], v[106:109], v[0:15]
	v_mfma_f32_32x32x16_bf16 v[16:31], v[102:105], v[110:113], v[16:31]
	ds_read_b128 v[102:105], v86 offset:32768
	ds_read_b128 v[106:109], v88 offset:49152
	ds_read_b128 v[110:113], v88 offset:53248
	s_waitcnt lgkmcnt(0)
	v_mfma_f32_32x32x16_bf16 v[32:47], v[102:105], v[106:109], v[32:47]
	v_mfma_f32_32x32x16_bf16 v[48:63], v[102:105], v[110:113], v[48:63]
	ds_read_b128 v[102:105], v86 offset:36864
	s_waitcnt lgkmcnt(0)
	v_mfma_f32_32x32x16_bf16 v[0:15], v[102:105], v[106:109], v[0:15]
	v_mfma_f32_32x32x16_bf16 v[16:31], v[102:105], v[110:113], v[16:31]
	ds_read_b128 v[102:105], v89 offset:32768
	ds_read_b128 v[106:109], v90 offset:49152
	ds_read_b128 v[110:113], v90 offset:53248
	s_waitcnt lgkmcnt(0)
	v_mfma_f32_32x32x16_bf16 v[32:47], v[102:105], v[106:109], v[32:47]
	v_mfma_f32_32x32x16_bf16 v[48:63], v[102:105], v[110:113], v[48:63]
	ds_read_b128 v[102:105], v89 offset:36864
	s_waitcnt vmcnt(0)
	s_waitcnt vmcnt(0) lgkmcnt(0)
	s_barrier
	v_mfma_f32_32x32x16_bf16 v[0:15], v[102:105], v[106:109], v[0:15]
	v_mfma_f32_32x32x16_bf16 v[16:31], v[102:105], v[110:113], v[16:31]
	v_lshl_add_u64 v[102:103], v[64:65], 0, s[26:27]
	global_load_lds_dwordx4 v[102:103], off
	v_lshl_add_u64 v[102:103], v[66:67], 0, s[26:27]
	s_mov_b32 m0, s57
	s_nop 0
	global_load_lds_dwordx4 v[102:103], off
	v_lshl_add_u64 v[102:103], v[68:69], 0, s[26:27]
	s_mov_b32 m0, s62
	s_nop 0
	global_load_lds_dwordx4 v[102:103], off
	s_mov_b32 m0, s63
	s_nop 0
	global_load_lds_dwordx4 v[94:95], off
	v_lshl_add_u64 v[94:95], v[72:73], 0, s[26:27]
	s_mov_b32 m0, s69
	s_nop 0
	global_load_lds_dwordx4 v[94:95], off
	v_lshl_add_u64 v[94:95], v[74:75], 0, s[26:27]
	s_mov_b32 m0, s70
	s_nop 0
	global_load_lds_dwordx4 v[94:95], off
	v_lshl_add_u64 v[94:95], v[76:77], 0, s[26:27]
	s_mov_b32 m0, s71
	s_nop 0
	global_load_lds_dwordx4 v[94:95], off
	v_lshl_add_u64 v[94:95], v[78:79], 0, s[26:27]
	s_mov_b32 m0, s72
	s_nop 0
	global_load_lds_dwordx4 v[94:95], off
	ds_read_b128 v[94:97], v83
	ds_read_b128 v[98:101], v85 offset:16384
	ds_read_b128 v[102:105], v85 offset:20480
	s_waitcnt lgkmcnt(0)
	v_mfma_f32_32x32x16_bf16 v[32:47], v[94:97], v[98:101], v[32:47]
	s_mov_b32 m0, s58
	v_mfma_f32_32x32x16_bf16 v[48:63], v[94:97], v[102:105], v[48:63]
	ds_read_b128 v[94:97], v83 offset:4096
	s_waitcnt lgkmcnt(0)
	v_mfma_f32_32x32x16_bf16 v[0:15], v[94:97], v[98:101], v[0:15]
	v_mfma_f32_32x32x16_bf16 v[16:31], v[94:97], v[102:105], v[16:31]
	ds_read_b128 v[94:97], v84
	ds_read_b128 v[98:101], v87 offset:16384
	ds_read_b128 v[102:105], v87 offset:20480
	s_waitcnt lgkmcnt(0)
	v_mfma_f32_32x32x16_bf16 v[32:47], v[94:97], v[98:101], v[32:47]
	v_mfma_f32_32x32x16_bf16 v[48:63], v[94:97], v[102:105], v[48:63]
	ds_read_b128 v[94:97], v84 offset:4096
	s_waitcnt lgkmcnt(0)
	v_mfma_f32_32x32x16_bf16 v[0:15], v[94:97], v[98:101], v[0:15]
	v_mfma_f32_32x32x16_bf16 v[16:31], v[94:97], v[102:105], v[16:31]
	ds_read_b128 v[94:97], v86
	ds_read_b128 v[98:101], v88 offset:16384
	ds_read_b128 v[102:105], v88 offset:20480
	s_waitcnt lgkmcnt(0)
	v_mfma_f32_32x32x16_bf16 v[32:47], v[94:97], v[98:101], v[32:47]
	v_mfma_f32_32x32x16_bf16 v[48:63], v[94:97], v[102:105], v[48:63]
	ds_read_b128 v[94:97], v86 offset:4096
	s_waitcnt lgkmcnt(0)
	v_mfma_f32_32x32x16_bf16 v[0:15], v[94:97], v[98:101], v[0:15]
	v_mfma_f32_32x32x16_bf16 v[16:31], v[94:97], v[102:105], v[16:31]
	ds_read_b128 v[94:97], v89
	ds_read_b128 v[98:101], v90 offset:16384
	ds_read_b128 v[102:105], v90 offset:20480
	s_waitcnt lgkmcnt(0)
	v_mfma_f32_32x32x16_bf16 v[32:47], v[94:97], v[98:101], v[32:47]
	v_mfma_f32_32x32x16_bf16 v[48:63], v[94:97], v[102:105], v[48:63]
	ds_read_b128 v[94:97], v89 offset:4096
	s_waitcnt vmcnt(0)
	s_waitcnt vmcnt(0) lgkmcnt(0)
	s_barrier
; #define MFMA(a, b, c) __builtin_amdgcn_mfma_f32_32x32x16_bf16(a, b, c, 0, 0, 0)
; #define ISSUE(k0, bf) do { char* A_ = lw + (bf) * BUF; \
;     _Pragma("unroll") for (int i_ = 0; i_ < 4; ++i_) { glds16(al.ptr(lrow + 32 * i_, (k0) + cg), A_ + i_ * 4096); glds16(bl.ptr(lrow + 32 * i_, (k0) + cg), A_ + ABYTES + i_ * 4096); } \
;     if (HALO) { if (wid == 0) glds16(gh + (k0), A_ + 16384); } } while (0)
; template <bool HALO, class AL, class BL>
; __device__ __forceinline__ void gemm_core(f32x16 (&acc)[2][2], f32x16& hacc, const AL& al, const BL& bl, int K, char* lds,
;                                           const u16* halo0, const u16* halo1, int brow0, int brow1) {
;     ...
;   for (int kt = 0; kt < nk; ++kt) {
;     asm volatile("s_waitcnt vmcnt(0)" ::: "memory");
;     __syncthreads();
;     if (kt + 1 < nk) ISSUE((kt + 1) * 64, (kt + 1) & 1);
;     const char* T = lds + (kt & 1) * BUF;
; #pragma unroll
;     for (int kk = 0; kk < 4; ++kk) {
;       const int c = kk * 2 + hi;
;       bf16x8 a0 = *(const bf16x8*)(T + oa + ((c ^ sa) << 4));
;       bf16x8 a1 = *(const bf16x8*)(T + oa + 4096 + ((c ^ sa) << 4));
;       bf16x8 b0 = *(const bf16x8*)(T + ob0 + ((c ^ sb0) << 4));
;       bf16x8 b1 = *(const bf16x8*)(T + ob1 + ((c ^ sb1) << 4));
;       acc[0][0] = MFMA(a0, b0, acc[0][0]); acc[0][1] = MFMA(a0, b1, acc[0][1]);
;       acc[1][0] = MFMA(a1, b0, acc[1][0]); acc[1][1] = MFMA(a1, b1, acc[1][1]);
;       if (HALO) { bf16x8 ah = *(const bf16x8*)(T + oh + ((c ^ sh) << 4)); hacc = MFMA(ah, b0, hacc); }
;     }
;   }
	v_mfma_f32_32x32x16_bf16 v[0:15], v[94:97], v[98:101], v[0:15]
	v_mfma_f32_32x32x16_bf16 v[16:31], v[94:97], v[102:105], v[16:31]
	v_lshl_add_u64 v[94:95], v[64:65], 0, s[88:89]
	global_load_lds_dwordx4 v[94:95], off
	v_lshl_add_u64 v[94:95], v[66:67], 0, s[88:89]
	s_mov_b32 m0, s59
	s_nop 0
	global_load_lds_dwordx4 v[94:95], off
	v_lshl_add_u64 v[94:95], v[68:69], 0, s[88:89]
	s_mov_b32 m0, s60
	s_nop 0
	global_load_lds_dwordx4 v[94:95], off
	v_lshl_add_u64 v[94:95], v[70:71], 0, s[88:89]
	s_mov_b32 m0, s61
	s_nop 0
	global_load_lds_dwordx4 v[94:95], off
	v_lshl_add_u64 v[94:95], v[72:73], 0, s[88:89]
	s_mov_b32 m0, s47
	s_nop 0
	global_load_lds_dwordx4 v[94:95], off
	v_lshl_add_u64 v[94:95], v[74:75], 0, s[88:89]
	s_mov_b32 m0, s49
	s_nop 0
	global_load_lds_dwordx4 v[94:95], off
	v_lshl_add_u64 v[94:95], v[76:77], 0, s[88:89]
	s_mov_b32 m0, s64
	s_nop 0
	global_load_lds_dwordx4 v[94:95], off
	v_lshl_add_u64 v[94:95], v[78:79], 0, s[88:89]
	s_mov_b32 m0, s65
	s_nop 0
	global_load_lds_dwordx4 v[94:95], off
	ds_read_b128 v[92:95], v83 offset:32768
	ds_read_b128 v[96:99], v85 offset:49152
	ds_read_b128 v[100:103], v85 offset:53248
	s_waitcnt lgkmcnt(0)
	v_mfma_f32_32x32x16_bf16 v[32:47], v[92:95], v[96:99], v[32:47]
	s_mov_b32 m0, s56
	v_mfma_f32_32x32x16_bf16 v[48:63], v[92:95], v[100:103], v[48:63]
	ds_read_b128 v[92:95], v83 offset:36864
	s_waitcnt lgkmcnt(0)
	v_mfma_f32_32x32x16_bf16 v[0:15], v[92:95], v[96:99], v[0:15]
	v_mfma_f32_32x32x16_bf16 v[16:31], v[92:95], v[100:103], v[16:31]
	ds_read_b128 v[92:95], v84 offset:32768
	ds_read_b128 v[96:99], v87 offset:49152
	ds_read_b128 v[100:103], v87 offset:53248
	s_waitcnt lgkmcnt(0)
	v_mfma_f32_32x32x16_bf16 v[32:47], v[92:95], v[96:99], v[32:47]
	v_mfma_f32_32x32x16_bf16 v[48:63], v[92:95], v[100:103], v[48:63]
	ds_read_b128 v[92:95], v84 offset:36864
	s_waitcnt lgkmcnt(0)
	v_mfma_f32_32x32x16_bf16 v[0:15], v[92:95], v[96:99], v[0:15]
	v_mfma_f32_32x32x16_bf16 v[16:31], v[92:95], v[100:103], v[16:31]
	ds_read_b128 v[92:95], v86 offset:32768
	ds_read_b128 v[96:99], v88 offset:49152
	ds_read_b128 v[100:103], v88 offset:53248
	s_waitcnt lgkmcnt(0)
	v_mfma_f32_32x32x16_bf16 v[32:47], v[92:95], v[96:99], v[32:47]
	v_mfma_f32_32x32x16_bf16 v[48:63], v[92:95], v[100:103], v[48:63]
	ds_read_b128 v[92:95], v86 offset:36864
	s_waitcnt lgkmcnt(0)
	v_mfma_f32_32x32x16_bf16 v[0:15], v[92:95], v[96:99], v[0:15]
	v_mfma_f32_32x32x16_bf16 v[16:31], v[92:95], v[100:103], v[16:31]
	ds_read_b128 v[92:95], v89 offset:32768
	ds_read_b128 v[96:99], v90 offset:49152
	ds_read_b128 v[100:103], v90 offset:53248
	s_waitcnt lgkmcnt(0)
	v_mfma_f32_32x32x16_bf16 v[32:47], v[92:95], v[96:99], v[32:47]
	v_mfma_f32_32x32x16_bf16 v[48:63], v[92:95], v[100:103], v[48:63]
	ds_read_b128 v[92:95], v89 offset:36864
	s_waitcnt vmcnt(0)
	s_waitcnt vmcnt(0) lgkmcnt(0)
	s_barrier
	v_mfma_f32_32x32x16_bf16 v[0:15], v[92:95], v[96:99], v[0:15]
	v_mfma_f32_32x32x16_bf16 v[16:31], v[92:95], v[100:103], v[16:31]
	v_lshl_add_u64 v[92:93], v[64:65], 0, s[22:23]
	global_load_lds_dwordx4 v[92:93], off
	v_lshl_add_u64 v[92:93], v[66:67], 0, s[22:23]
	s_mov_b32 m0, s57
	s_nop 0
	global_load_lds_dwordx4 v[92:93], off
	v_lshl_add_u64 v[92:93], v[68:69], 0, s[22:23]
	s_mov_b32 m0, s62
	s_nop 0
	global_load_lds_dwordx4 v[92:93], off
	v_lshl_add_u64 v[92:93], v[70:71], 0, s[22:23]
	s_mov_b32 m0, s63
	s_nop 0
	global_load_lds_dwordx4 v[92:93], off
	v_lshl_add_u64 v[92:93], v[72:73], 0, s[22:23]
	s_mov_b32 m0, s69
	s_nop 0
	global_load_lds_dwordx4 v[92:93], off
	v_lshl_add_u64 v[92:93], v[74:75], 0, s[22:23]
	s_mov_b32 m0, s70
	s_nop 0
	global_load_lds_dwordx4 v[92:93], off
	v_lshl_add_u64 v[92:93], v[76:77], 0, s[22:23]
	s_mov_b32 m0, s71
	s_nop 0
	global_load_lds_dwordx4 v[92:93], off
	v_lshl_add_u64 v[92:93], v[78:79], 0, s[22:23]
	s_mov_b32 m0, s72
	s_nop 0
	global_load_lds_dwordx4 v[92:93], off
	ds_read_b128 v[92:95], v83
	ds_read_b128 v[96:99], v85 offset:16384
	ds_read_b128 v[100:103], v85 offset:20480
	s_waitcnt lgkmcnt(0)
	v_mfma_f32_32x32x16_bf16 v[32:47], v[92:95], v[96:99], v[32:47]
	s_mov_b32 m0, s58
	v_mfma_f32_32x32x16_bf16 v[48:63], v[92:95], v[100:103], v[48:63]
	ds_read_b128 v[92:95], v83 offset:4096
	s_waitcnt lgkmcnt(0)
	v_mfma_f32_32x32x16_bf16 v[0:15], v[92:95], v[96:99], v[0:15]
	v_mfma_f32_32x32x16_bf16 v[16:31], v[92:95], v[100:103], v[16:31]
	ds_read_b128 v[92:95], v84
	ds_read_b128 v[96:99], v87 offset:16384
	ds_read_b128 v[100:103], v87 offset:20480
	s_waitcnt lgkmcnt(0)
	v_mfma_f32_32x32x16_bf16 v[32:47], v[92:95], v[96:99], v[32:47]
	v_mfma_f32_32x32x16_bf16 v[48:63], v[92:95], v[100:103], v[48:63]
	ds_read_b128 v[92:95], v84 offset:4096
	s_waitcnt lgkmcnt(0)
	v_mfma_f32_32x32x16_bf16 v[0:15], v[92:95], v[96:99], v[0:15]
	v_mfma_f32_32x32x16_bf16 v[16:31], v[92:95], v[100:103], v[16:31]
	ds_read_b128 v[92:95], v86
	ds_read_b128 v[96:99], v88 offset:16384
	ds_read_b128 v[100:103], v88 offset:20480
	s_waitcnt lgkmcnt(0)
	v_mfma_f32_32x32x16_bf16 v[32:47], v[92:95], v[96:99], v[32:47]
	v_mfma_f32_32x32x16_bf16 v[48:63], v[92:95], v[100:103], v[48:63]
	ds_read_b128 v[92:95], v86 offset:4096
	s_waitcnt lgkmcnt(0)
	v_mfma_f32_32x32x16_bf16 v[0:15], v[92:95], v[96:99], v[0:15]
	v_mfma_f32_32x32x16_bf16 v[16:31], v[92:95], v[100:103], v[16:31]
	ds_read_b128 v[92:95], v89
	ds_read_b128 v[96:99], v90 offset:16384
	ds_read_b128 v[100:103], v90 offset:20480
	s_waitcnt lgkmcnt(0)
	v_mfma_f32_32x32x16_bf16 v[32:47], v[92:95], v[96:99], v[32:47]
	v_mfma_f32_32x32x16_bf16 v[48:63], v[92:95], v[100:103], v[48:63]
	ds_read_b128 v[92:95], v89 offset:4096
	s_waitcnt vmcnt(0)
	s_waitcnt vmcnt(0) lgkmcnt(0)
	s_barrier
; #define MFMA(a, b, c) __builtin_amdgcn_mfma_f32_32x32x16_bf16(a, b, c, 0, 0, 0)
; #define ISSUE(k0, bf) do { char* A_ = lw + (bf) * BUF; \
;     _Pragma("unroll") for (int i_ = 0; i_ < 4; ++i_) { glds16(al.ptr(lrow + 32 * i_, (k0) + cg), A_ + i_ * 4096); glds16(bl.ptr(lrow + 32 * i_, (k0) + cg), A_ + ABYTES + i_ * 4096); } \
;     if (HALO) { if (wid == 0) glds16(gh + (k0), A_ + 16384); } } while (0)
; template <bool HALO, class AL, class BL>
; __device__ __forceinline__ void gemm_core(f32x16 (&acc)[2][2], f32x16& hacc, const AL& al, const BL& bl, int K, char* lds,
;                                           const u16* halo0, const u16* halo1, int brow0, int brow1) {
;     ...
;   for (int kt = 0; kt < nk; ++kt) {
;     asm volatile("s_waitcnt vmcnt(0)" ::: "memory");
;     __syncthreads();
;     if (kt + 1 < nk) ISSUE((kt + 1) * 64, (kt + 1) & 1);
;     const char* T = lds + (kt & 1) * BUF;
; #pragma unroll
;     for (int kk = 0; kk < 4; ++kk) {
;       const int c = kk * 2 + hi;
;       bf16x8 a0 = *(const bf16x8*)(T + oa + ((c ^ sa) << 4));
;       bf16x8 a1 = *(const bf16x8*)(T + oa + 4096 + ((c ^ sa) << 4));
;       bf16x8 b0 = *(const bf16x8*)(T + ob0 + ((c ^ sb0) << 4));
;       bf16x8 b1 = *(const bf16x8*)(T + ob1 + ((c ^ sb1) << 4));
;       acc[0][0] = MFMA(a0, b0, acc[0][0]); acc[0][1] = MFMA(a0, b1, acc[0][1]);
;       acc[1][0] = MFMA(a1, b0, acc[1][0]); acc[1][1] = MFMA(a1, b1, acc[1][1]);
;       if (HALO) { bf16x8 ah = *(const bf16x8*)(T + oh + ((c ^ sh) << 4)); hacc = MFMA(ah, b0, hacc); }
;     }
;   }
	v_mfma_f32_32x32x16_bf16 v[0:15], v[92:95], v[96:99], v[0:15]
	v_mfma_f32_32x32x16_bf16 v[16:31], v[92:95], v[100:103], v[16:31]
	v_lshl_add_u64 v[92:93], v[64:65], 0, s[90:91]
	global_load_lds_dwordx4 v[92:93], off
	v_lshl_add_u64 v[92:93], v[66:67], 0, s[90:91]
	s_mov_b32 m0, s59
	s_nop 0
	global_load_lds_dwordx4 v[92:93], off
	v_lshl_add_u64 v[92:93], v[68:69], 0, s[90:91]
	s_mov_b32 m0, s60
	s_nop 0
	global_load_lds_dwordx4 v[92:93], off
	v_lshl_add_u64 v[92:93], v[70:71], 0, s[90:91]
	s_mov_b32 m0, s61
	s_nop 0
	global_load_lds_dwordx4 v[92:93], off
	v_lshl_add_u64 v[92:93], v[72:73], 0, s[90:91]
	s_mov_b32 m0, s47
	s_nop 0
	global_load_lds_dwordx4 v[92:93], off
	v_lshl_add_u64 v[92:93], v[74:75], 0, s[90:91]
	s_mov_b32 m0, s49
	s_nop 0
	global_load_lds_dwordx4 v[92:93], off
	v_lshl_add_u64 v[92:93], v[76:77], 0, s[90:91]
	s_mov_b32 m0, s64
	s_nop 0
	global_load_lds_dwordx4 v[92:93], off
	v_lshl_add_u64 v[92:93], v[78:79], 0, s[90:91]
	s_mov_b32 m0, s65
	s_nop 0
	global_load_lds_dwordx4 v[92:93], off
	ds_read_b128 v[92:95], v83 offset:32768
	ds_read_b128 v[96:99], v85 offset:49152
	ds_read_b128 v[100:103], v85 offset:53248
	s_waitcnt lgkmcnt(0)
	v_mfma_f32_32x32x16_bf16 v[32:47], v[92:95], v[96:99], v[32:47]
	s_mov_b32 m0, s56
	v_mfma_f32_32x32x16_bf16 v[48:63], v[92:95], v[100:103], v[48:63]
	ds_read_b128 v[92:95], v83 offset:36864
	s_waitcnt lgkmcnt(0)
	v_mfma_f32_32x32x16_bf16 v[0:15], v[92:95], v[96:99], v[0:15]
	v_mfma_f32_32x32x16_bf16 v[16:31], v[92:95], v[100:103], v[16:31]
	ds_read_b128 v[92:95], v84 offset:32768
	ds_read_b128 v[96:99], v87 offset:49152
	ds_read_b128 v[100:103], v87 offset:53248
	s_waitcnt lgkmcnt(0)
	v_mfma_f32_32x32x16_bf16 v[32:47], v[92:95], v[96:99], v[32:47]
	v_mfma_f32_32x32x16_bf16 v[48:63], v[92:95], v[100:103], v[48:63]
	ds_read_b128 v[92:95], v84 offset:36864
	s_waitcnt lgkmcnt(0)
	v_mfma_f32_32x32x16_bf16 v[0:15], v[92:95], v[96:99], v[0:15]
	v_mfma_f32_32x32x16_bf16 v[16:31], v[92:95], v[100:103], v[16:31]
	ds_read_b128 v[92:95], v86 offset:32768
	ds_read_b128 v[96:99], v88 offset:49152
	ds_read_b128 v[100:103], v88 offset:53248
	s_waitcnt lgkmcnt(0)
	v_mfma_f32_32x32x16_bf16 v[32:47], v[92:95], v[96:99], v[32:47]
	v_mfma_f32_32x32x16_bf16 v[48:63], v[92:95], v[100:103], v[48:63]
	ds_read_b128 v[92:95], v86 offset:36864
	s_waitcnt lgkmcnt(0)
	v_mfma_f32_32x32x16_bf16 v[0:15], v[92:95], v[96:99], v[0:15]
	v_mfma_f32_32x32x16_bf16 v[16:31], v[92:95], v[100:103], v[16:31]
	ds_read_b128 v[92:95], v89 offset:32768
	ds_read_b128 v[96:99], v90 offset:49152
	ds_read_b128 v[100:103], v90 offset:53248
	s_waitcnt lgkmcnt(0)
	v_mfma_f32_32x32x16_bf16 v[32:47], v[92:95], v[96:99], v[32:47]
	v_mfma_f32_32x32x16_bf16 v[48:63], v[92:95], v[100:103], v[48:63]
	ds_read_b128 v[92:95], v89 offset:36864
	s_waitcnt vmcnt(0)
	s_waitcnt vmcnt(0) lgkmcnt(0)
	s_barrier
	v_mfma_f32_32x32x16_bf16 v[0:15], v[92:95], v[96:99], v[0:15]
	v_mfma_f32_32x32x16_bf16 v[16:31], v[92:95], v[100:103], v[16:31]
	v_lshl_add_u64 v[92:93], v[64:65], 0, s[0:1]
	global_load_lds_dwordx4 v[92:93], off
	v_lshl_add_u64 v[92:93], v[66:67], 0, s[0:1]
	s_mov_b32 m0, s57
	s_nop 0
	global_load_lds_dwordx4 v[92:93], off
	v_lshl_add_u64 v[92:93], v[68:69], 0, s[0:1]
	s_mov_b32 m0, s62
	s_nop 0
	global_load_lds_dwordx4 v[92:93], off
	v_lshl_add_u64 v[92:93], v[70:71], 0, s[0:1]
	s_mov_b32 m0, s63
	s_nop 0
	global_load_lds_dwordx4 v[92:93], off
	v_lshl_add_u64 v[92:93], v[72:73], 0, s[0:1]
	s_mov_b32 m0, s69
	s_nop 0
	global_load_lds_dwordx4 v[92:93], off
	v_lshl_add_u64 v[92:93], v[74:75], 0, s[0:1]
	s_mov_b32 m0, s70
	s_nop 0
	global_load_lds_dwordx4 v[92:93], off
	v_lshl_add_u64 v[92:93], v[76:77], 0, s[0:1]
	s_mov_b32 m0, s71
	s_nop 0
	global_load_lds_dwordx4 v[92:93], off
	v_lshl_add_u64 v[92:93], v[78:79], 0, s[0:1]
	s_mov_b32 m0, s72
	s_nop 0
	global_load_lds_dwordx4 v[92:93], off
	ds_read_b128 v[92:95], v83
	ds_read_b128 v[96:99], v85 offset:16384
	ds_read_b128 v[100:103], v85 offset:20480
	s_waitcnt lgkmcnt(0)
	v_mfma_f32_32x32x16_bf16 v[32:47], v[92:95], v[96:99], v[32:47]
	s_mov_b32 m0, s58
	v_mfma_f32_32x32x16_bf16 v[48:63], v[92:95], v[100:103], v[48:63]
	ds_read_b128 v[92:95], v83 offset:4096
	s_waitcnt lgkmcnt(0)
	v_mfma_f32_32x32x16_bf16 v[0:15], v[92:95], v[96:99], v[0:15]
	v_mfma_f32_32x32x16_bf16 v[16:31], v[92:95], v[100:103], v[16:31]
	ds_read_b128 v[92:95], v84
	ds_read_b128 v[96:99], v87 offset:16384
	ds_read_b128 v[100:103], v87 offset:20480
	s_waitcnt lgkmcnt(0)
	v_mfma_f32_32x32x16_bf16 v[32:47], v[92:95], v[96:99], v[32:47]
	v_mfma_f32_32x32x16_bf16 v[48:63], v[92:95], v[100:103], v[48:63]
	ds_read_b128 v[92:95], v84 offset:4096
	s_waitcnt lgkmcnt(0)
	v_mfma_f32_32x32x16_bf16 v[0:15], v[92:95], v[96:99], v[0:15]
	v_mfma_f32_32x32x16_bf16 v[16:31], v[92:95], v[100:103], v[16:31]
	ds_read_b128 v[92:95], v86
	ds_read_b128 v[96:99], v88 offset:16384
	ds_read_b128 v[100:103], v88 offset:20480
	s_waitcnt lgkmcnt(0)
	v_mfma_f32_32x32x16_bf16 v[32:47], v[92:95], v[96:99], v[32:47]
	v_mfma_f32_32x32x16_bf16 v[48:63], v[92:95], v[100:103], v[48:63]
	ds_read_b128 v[92:95], v86 offset:4096
	s_waitcnt lgkmcnt(0)
	v_mfma_f32_32x32x16_bf16 v[0:15], v[92:95], v[96:99], v[0:15]
	v_mfma_f32_32x32x16_bf16 v[16:31], v[92:95], v[100:103], v[16:31]
	ds_read_b128 v[92:95], v89
	ds_read_b128 v[96:99], v90 offset:16384
	ds_read_b128 v[100:103], v90 offset:20480
	s_waitcnt lgkmcnt(0)
	v_mfma_f32_32x32x16_bf16 v[32:47], v[92:95], v[96:99], v[32:47]
	v_mfma_f32_32x32x16_bf16 v[48:63], v[92:95], v[100:103], v[48:63]
	ds_read_b128 v[92:95], v89 offset:4096
	s_waitcnt vmcnt(0)
	s_waitcnt vmcnt(0) lgkmcnt(0)
	s_barrier
; #define MFMA(a, b, c) __builtin_amdgcn_mfma_f32_32x32x16_bf16(a, b, c, 0, 0, 0)
; #define ISSUE(k0, bf) do { char* A_ = lw + (bf) * BUF; \
;     _Pragma("unroll") for (int i_ = 0; i_ < 4; ++i_) { glds16(al.ptr(lrow + 32 * i_, (k0) + cg), A_ + i_ * 4096); glds16(bl.ptr(lrow + 32 * i_, (k0) + cg), A_ + ABYTES + i_ * 4096); } \
;     if (HALO) { if (wid == 0) glds16(gh + (k0), A_ + 16384); } } while (0)
; template <bool HALO, class AL, class BL>
; __device__ __forceinline__ void gemm_core(f32x16 (&acc)[2][2], f32x16& hacc, const AL& al, const BL& bl, int K, char* lds,
;                                           const u16* halo0, const u16* halo1, int brow0, int brow1) {
;     ...
;   for (int kt = 0; kt < nk; ++kt) {
;     asm volatile("s_waitcnt vmcnt(0)" ::: "memory");
;     __syncthreads();
;     if (kt + 1 < nk) ISSUE((kt + 1) * 64, (kt + 1) & 1);
;     const char* T = lds + (kt & 1) * BUF;
; #pragma unroll
;     for (int kk = 0; kk < 4; ++kk) {
;       const int c = kk * 2 + hi;
;       bf16x8 a0 = *(const bf16x8*)(T + oa + ((c ^ sa) << 4));
;       bf16x8 a1 = *(const bf16x8*)(T + oa + 4096 + ((c ^ sa) << 4));
;       bf16x8 b0 = *(const bf16x8*)(T + ob0 + ((c ^ sb0) << 4));
;       bf16x8 b1 = *(const bf16x8*)(T + ob1 + ((c ^ sb1) << 4));
;       acc[0][0] = MFMA(a0, b0, acc[0][0]); acc[0][1] = MFMA(a0, b1, acc[0][1]);
;       acc[1][0] = MFMA(a1, b0, acc[1][0]); acc[1][1] = MFMA(a1, b1, acc[1][1]);
;       if (HALO) { bf16x8 ah = *(const bf16x8*)(T + oh + ((c ^ sh) << 4)); hacc = MFMA(ah, b0, hacc); }
;     }
;   }
; __device__ __forceinline__ void phase_z(const P& p, int layer, char* lds) {
;     ...
;     const int span = tn * 2 + wc, colb = span * 64;
;     const bool rope = (span < 16) || (span >= 24 && span < 32);
	v_mfma_f32_32x32x16_bf16 v[0:15], v[92:95], v[96:99], v[0:15]
	v_mfma_f32_32x32x16_bf16 v[16:31], v[92:95], v[100:103], v[16:31]
	v_lshl_add_u64 v[92:93], v[64:65], 0, s[34:35]
	global_load_lds_dwordx4 v[92:93], off
	v_lshl_add_u64 v[92:93], v[66:67], 0, s[34:35]
	s_mov_b32 m0, s59
	v_lshl_add_u64 v[64:65], v[64:65], 0, s[38:39]
	global_load_lds_dwordx4 v[92:93], off
	v_lshl_add_u64 v[92:93], v[68:69], 0, s[34:35]
	s_mov_b32 m0, s60
	s_nop 0
	global_load_lds_dwordx4 v[92:93], off
	v_lshl_add_u64 v[92:93], v[70:71], 0, s[34:35]
	s_mov_b32 m0, s61
	s_nop 0
	global_load_lds_dwordx4 v[92:93], off
	v_lshl_add_u64 v[92:93], v[72:73], 0, s[34:35]
	s_mov_b32 m0, s47
	s_and_b32 s47, s46, 0x7ffffffc
	global_load_lds_dwordx4 v[92:93], off
	v_lshl_add_u64 v[92:93], v[74:75], 0, s[34:35]
	s_mov_b32 m0, s49
	s_cmp_lg_u32 s47, 12
	global_load_lds_dwordx4 v[92:93], off
	v_lshl_add_u64 v[92:93], v[76:77], 0, s[34:35]
	s_mov_b32 m0, s64
	s_nop 0
	global_load_lds_dwordx4 v[92:93], off
	v_lshl_add_u64 v[92:93], v[78:79], 0, s[34:35]
	s_mov_b32 m0, s65
	s_nop 0
	global_load_lds_dwordx4 v[92:93], off
	ds_read_b128 v[92:95], v83 offset:32768
	ds_read_b128 v[96:99], v85 offset:49152
	ds_read_b128 v[100:103], v85 offset:53248
	s_waitcnt lgkmcnt(0)
	v_mfma_f32_32x32x16_bf16 v[32:47], v[92:95], v[96:99], v[32:47]
	s_mov_b32 m0, s56
	v_mfma_f32_32x32x16_bf16 v[48:63], v[92:95], v[100:103], v[48:63]
	ds_read_b128 v[92:95], v83 offset:36864
	s_waitcnt lgkmcnt(0)
	v_mfma_f32_32x32x16_bf16 v[0:15], v[92:95], v[96:99], v[0:15]
	v_mfma_f32_32x32x16_bf16 v[16:31], v[92:95], v[100:103], v[16:31]
	ds_read_b128 v[92:95], v84 offset:32768
	ds_read_b128 v[96:99], v87 offset:49152
	ds_read_b128 v[100:103], v87 offset:53248
	s_waitcnt lgkmcnt(0)
	v_mfma_f32_32x32x16_bf16 v[32:47], v[92:95], v[96:99], v[32:47]
	v_mfma_f32_32x32x16_bf16 v[48:63], v[92:95], v[100:103], v[48:63]
	ds_read_b128 v[92:95], v84 offset:36864
	s_waitcnt lgkmcnt(0)
	v_mfma_f32_32x32x16_bf16 v[0:15], v[92:95], v[96:99], v[0:15]
	v_mfma_f32_32x32x16_bf16 v[16:31], v[92:95], v[100:103], v[16:31]
	ds_read_b128 v[92:95], v86 offset:32768
	ds_read_b128 v[96:99], v88 offset:49152
	ds_read_b128 v[100:103], v88 offset:53248
	s_waitcnt lgkmcnt(0)
	v_mfma_f32_32x32x16_bf16 v[32:47], v[92:95], v[96:99], v[32:47]
	v_mfma_f32_32x32x16_bf16 v[48:63], v[92:95], v[100:103], v[48:63]
	ds_read_b128 v[92:95], v86 offset:36864
	s_waitcnt lgkmcnt(0)
	v_mfma_f32_32x32x16_bf16 v[0:15], v[92:95], v[96:99], v[0:15]
	v_mfma_f32_32x32x16_bf16 v[16:31], v[92:95], v[100:103], v[16:31]
	ds_read_b128 v[92:95], v89 offset:32768
	ds_read_b128 v[96:99], v90 offset:49152
	ds_read_b128 v[100:103], v90 offset:53248
	s_waitcnt lgkmcnt(0)
	v_mfma_f32_32x32x16_bf16 v[32:47], v[92:95], v[96:99], v[32:47]
	v_mfma_f32_32x32x16_bf16 v[48:63], v[92:95], v[100:103], v[48:63]
	ds_read_b128 v[92:95], v89 offset:36864
	s_waitcnt vmcnt(0)
	s_waitcnt vmcnt(0) lgkmcnt(0)
	s_barrier
	global_load_lds_dwordx4 v[64:65], off
	v_lshl_add_u64 v[64:65], v[66:67], 0, s[38:39]
	s_mov_b32 m0, s57
	v_mfma_f32_32x32x16_bf16 v[0:15], v[92:95], v[96:99], v[0:15]
	global_load_lds_dwordx4 v[64:65], off
	v_lshl_add_u64 v[64:65], v[68:69], 0, s[38:39]
	s_mov_b32 m0, s62
	s_cselect_b64 s[56:57], -1, 0
	global_load_lds_dwordx4 v[64:65], off
	v_lshl_add_u64 v[64:65], v[70:71], 0, s[38:39]
	s_mov_b32 m0, s63
	v_mfma_f32_32x32x16_bf16 v[16:31], v[92:95], v[100:103], v[16:31]
	global_load_lds_dwordx4 v[64:65], off
	v_lshl_add_u64 v[64:65], v[72:73], 0, s[38:39]
	s_mov_b32 m0, s69
	s_nop 0
	global_load_lds_dwordx4 v[64:65], off
	v_lshl_add_u64 v[64:65], v[74:75], 0, s[38:39]
	s_mov_b32 m0, s70
	s_nop 0
	global_load_lds_dwordx4 v[64:65], off
	v_lshl_add_u64 v[64:65], v[76:77], 0, s[38:39]
	s_mov_b32 m0, s71
	s_nop 0
	global_load_lds_dwordx4 v[64:65], off
	v_lshl_add_u64 v[64:65], v[78:79], 0, s[38:39]
	s_mov_b32 m0, s72
	s_nop 0
	global_load_lds_dwordx4 v[64:65], off
	ds_read_b128 v[64:67], v83
	ds_read_b128 v[68:71], v85 offset:16384
	ds_read_b128 v[72:75], v85 offset:20480
	s_waitcnt lgkmcnt(0)
	v_mfma_f32_32x32x16_bf16 v[32:47], v[64:67], v[68:71], v[32:47]
	v_mfma_f32_32x32x16_bf16 v[48:63], v[64:67], v[72:75], v[48:63]
	ds_read_b128 v[64:67], v83 offset:4096
	s_waitcnt lgkmcnt(0)
	v_mfma_f32_32x32x16_bf16 v[0:15], v[64:67], v[68:71], v[0:15]
	v_mfma_f32_32x32x16_bf16 v[16:31], v[64:67], v[72:75], v[16:31]
	ds_read_b128 v[64:67], v84
	ds_read_b128 v[68:71], v87 offset:16384
	ds_read_b128 v[72:75], v87 offset:20480
	s_waitcnt lgkmcnt(0)
	v_mfma_f32_32x32x16_bf16 v[32:47], v[64:67], v[68:71], v[32:47]
	v_mfma_f32_32x32x16_bf16 v[48:63], v[64:67], v[72:75], v[48:63]
	ds_read_b128 v[64:67], v84 offset:4096
	s_waitcnt lgkmcnt(0)
	v_mfma_f32_32x32x16_bf16 v[0:15], v[64:67], v[68:71], v[0:15]
	v_mfma_f32_32x32x16_bf16 v[16:31], v[64:67], v[72:75], v[16:31]
	ds_read_b128 v[64:67], v86
	ds_read_b128 v[68:71], v88 offset:16384
	ds_read_b128 v[72:75], v88 offset:20480
	s_waitcnt lgkmcnt(0)
	v_mfma_f32_32x32x16_bf16 v[32:47], v[64:67], v[68:71], v[32:47]
	v_mfma_f32_32x32x16_bf16 v[48:63], v[64:67], v[72:75], v[48:63]
	ds_read_b128 v[64:67], v86 offset:4096
	s_waitcnt lgkmcnt(0)
	v_mfma_f32_32x32x16_bf16 v[0:15], v[64:67], v[68:71], v[0:15]
	v_mfma_f32_32x32x16_bf16 v[16:31], v[64:67], v[72:75], v[16:31]
	ds_read_b128 v[64:67], v89
	ds_read_b128 v[68:71], v90 offset:16384
	ds_read_b128 v[72:75], v90 offset:20480
	s_waitcnt lgkmcnt(0)
	v_mfma_f32_32x32x16_bf16 v[32:47], v[64:67], v[68:71], v[32:47]
	v_mfma_f32_32x32x16_bf16 v[48:63], v[64:67], v[72:75], v[48:63]
	ds_read_b128 v[64:67], v89 offset:4096
	s_waitcnt vmcnt(0)
	s_waitcnt vmcnt(0) lgkmcnt(0)
	s_barrier
; #define SBAR() __builtin_amdgcn_sched_barrier(0)
; template <bool HALO, class AL, class BL>
; __device__ __forceinline__ void gemm_core(f32x16 (&acc)[2][2], f32x16& hacc, const AL& al, const BL& bl, int K, char* lds,
;                                           const u16* halo0, const u16* halo1, int brow0, int brow1) {
;     ...
;     for (int kk = 0; kk < 4; ++kk) {
;       const int c = kk * 2 + hi;
;       bf16x8 a0 = *(const bf16x8*)(T + oa + ((c ^ sa) << 4));
;       bf16x8 a1 = *(const bf16x8*)(T + oa + 4096 + ((c ^ sa) << 4));
;       bf16x8 b0 = *(const bf16x8*)(T + ob0 + ((c ^ sb0) << 4));
;       bf16x8 b1 = *(const bf16x8*)(T + ob1 + ((c ^ sb1) << 4));
;       acc[0][0] = MFMA(a0, b0, acc[0][0]); acc[0][1] = MFMA(a0, b1, acc[0][1]);
;       acc[1][0] = MFMA(a1, b0, acc[1][0]); acc[1][1] = MFMA(a1, b1, acc[1][1]);
;       if (HALO) { bf16x8 ah = *(const bf16x8*)(T + oh + ((c ^ sh) << 4)); hacc = MFMA(ah, b0, hacc); }
;     }
; __device__ __forceinline__ void phase_z(const P& p, int layer, char* lds) {
;     ...
;     const int span = tn * 2 + wc, colb = span * 64;
;     const bool rope = (span < 16) || (span >= 24 && span < 32);
;     const float sc = (span < 8 || (span >= 28 && span < 32)) ? 0.125f : 1.f;
;     const unsigned rb = (unsigned)(tm * 128 + wr * 64 + 4 * hi + opq());
;     if (rope) {
;       float cc[2][16], ss[2][16];
; #pragma unroll
;       for (int mi = 0; mi < 2; ++mi)
; #pragma unroll
;         for (int r = 0; r < 16; ++r) { const unsigned row = rb + mi * 32 + (r & 3) + 8 * (r >> 2); cc[mi][r] = ct[row * 32 + r32]; ss[mi][r] = st[row * 32 + r32]; }
; #pragma unroll
;       for (int mi = 0; mi < 2; ++mi) {
; #pragma unroll
;         for (int r = 0; r < 16; ++r) {
;           const unsigned row = rb + mi * 32 + (r & 3) + 8 * (r >> 2);
;           const float x1 = acc[mi][0][r], x2 = acc[mi][1][r];
;           const unsigned w = cvtpk((x1 * cc[mi][r] - x2 * ss[mi][r]) * sc, (x2 * cc[mi][r] + x1 * ss[mi][r]) * sc);
;           z[row * ZC + colb + r32] = (u16)w; z[row * ZC + colb + 32 + r32] = (u16)(w >> 16);
;         }
;         SBAR();
;       }
;     } else {
; #pragma unroll
;       for (int mi = 0; mi < 2; ++mi) {
; #pragma unroll
;         for (int r = 0; r < 16; ++r) {
;           const unsigned row = rb + mi * 32 + (r & 3) + 8 * (r >> 2);
;           const unsigned w = cvtpk(acc[mi][0][r] * sc, acc[mi][1][r] * sc);
	v_mfma_f32_32x32x16_bf16 v[0:15], v[64:67], v[68:71], v[0:15]
	v_mfma_f32_32x32x16_bf16 v[16:31], v[64:67], v[72:75], v[16:31]
	ds_read_b128 v[64:67], v83 offset:32768
	ds_read_b128 v[68:71], v85 offset:49152
	ds_read_b128 v[72:75], v85 offset:53248
	s_waitcnt lgkmcnt(1)
	v_mfma_f32_32x32x16_bf16 v[32:47], v[64:67], v[68:71], v[32:47]
	s_waitcnt lgkmcnt(0)
	v_mfma_f32_32x32x16_bf16 v[48:63], v[64:67], v[72:75], v[48:63]
	ds_read_b128 v[64:67], v83 offset:36864
	v_lshl_or_b32 v83, s46, 1, v80
	v_cmp_lt_i32_e32 vcc, 15, v83
	s_and_b64 s[56:57], vcc, s[56:57]
	s_and_b32 s46, s46, 0x7ffffffe
	s_cmp_eq_u32 s46, 14
	v_cmp_gt_i32_e32 vcc, 8, v83
	s_waitcnt lgkmcnt(0)
	v_mfma_f32_32x32x16_bf16 v[0:15], v[64:67], v[68:71], v[0:15]
	s_cselect_b64 s[46:47], -1, 0
	s_or_b64 vcc, vcc, s[46:47]
	s_lshl_b32 s46, s48, 7
	v_mfma_f32_32x32x16_bf16 v[16:31], v[64:67], v[72:75], v[16:31]
	ds_read_b128 v[64:67], v84 offset:32768
	ds_read_b128 v[68:71], v87 offset:49152
	ds_read_b128 v[72:75], v87 offset:53248
	s_waitcnt lgkmcnt(1)
	v_mfma_f32_32x32x16_bf16 v[32:47], v[64:67], v[68:71], v[32:47]
	s_waitcnt lgkmcnt(0)
	v_mfma_f32_32x32x16_bf16 v[48:63], v[64:67], v[72:75], v[48:63]
	ds_read_b128 v[64:67], v84 offset:36864
	v_lshlrev_b32_e32 v84, 6, v83
	s_waitcnt lgkmcnt(0)
	v_mfma_f32_32x32x16_bf16 v[0:15], v[64:67], v[68:71], v[0:15]
	v_mfma_f32_32x32x16_bf16 v[16:31], v[64:67], v[72:75], v[16:31]
	ds_read_b128 v[64:67], v86 offset:32768
	ds_read_b128 v[68:71], v88 offset:49152
	ds_read_b128 v[72:75], v88 offset:53248
	s_waitcnt lgkmcnt(1)
	v_mfma_f32_32x32x16_bf16 v[32:47], v[64:67], v[68:71], v[32:47]
	s_waitcnt lgkmcnt(0)
	v_mfma_f32_32x32x16_bf16 v[48:63], v[64:67], v[72:75], v[48:63]
	ds_read_b128 v[64:67], v86 offset:36864
	s_waitcnt lgkmcnt(0)
	v_mfma_f32_32x32x16_bf16 v[0:15], v[64:67], v[68:71], v[0:15]
	v_mfma_f32_32x32x16_bf16 v[16:31], v[64:67], v[72:75], v[16:31]
	ds_read_b128 v[64:67], v89 offset:32768
	ds_read_b128 v[68:71], v90 offset:49152
	ds_read_b128 v[72:75], v90 offset:53248
	ds_read_b128 v[76:79], v89 offset:36864
	s_waitcnt lgkmcnt(2)
	v_mfma_f32_32x32x16_bf16 v[32:47], v[64:67], v[68:71], v[32:47]
	s_waitcnt lgkmcnt(1)
	v_mfma_f32_32x32x16_bf16 v[48:63], v[64:67], v[72:75], v[48:63]
	v_mov_b32_e32 v64, 0x3e000000
	v_cndmask_b32_e32 v66, 1.0, v64, vcc
	v_mov_b32_e32 v64, v201
	s_nop 0
	v_add3_u32 v65, v82, s46, v64
	v_or_b32_e32 v64, v84, v81
	s_waitcnt lgkmcnt(0)
	v_mfma_f32_32x32x16_bf16 v[0:15], v[76:79], v[68:71], v[0:15]
	v_mfma_f32_32x32x16_bf16 v[16:31], v[76:79], v[72:75], v[16:31]
	s_and_saveexec_b64 s[46:47], s[56:57]
	s_xor_b64 s[46:47], exec, s[46:47]
	s_cbranch_execz .LBB0_347
	v_mad_u64_u32 v[64:65], s[48:49], v65, s11, v[64:65]
	v_mov_b32_e32 v65, v201
	v_mul_f32_e32 v32, v66, v32
	v_lshl_add_u64 v[68:69], v[64:65], 1, s[40:41]
	v_or_b32_e32 v200, 32, v64
	v_mul_f32_e32 v48, v66, v48
	v_cvt_pk_bf16_f32 v32, v32, v48
	global_store_short v[68:69], v32, off
	v_lshl_add_u64 v[68:69], v[200:201], 1, s[40:41]
	global_store_short_d16_hi v[68:69], v32, off
	v_mul_f32_e32 v32, v66, v33
	v_mul_f32_e32 v33, v66, v49
	v_add_u32_e32 v200, 0xb00, v64
	v_cvt_pk_bf16_f32 v48, v32, v33
	v_lshl_add_u64 v[32:33], v[200:201], 1, s[40:41]
	v_add_u32_e32 v200, 0xb20, v64
	global_store_short v[32:33], v48, off
	v_lshl_add_u64 v[32:33], v[200:201], 1, s[40:41]
	global_store_short_d16_hi v[32:33], v48, off
	v_mul_f32_e32 v32, v66, v34
	v_mul_f32_e32 v33, v66, v50
	v_add_u32_e32 v200, 0x1600, v64
	v_cvt_pk_bf16_f32 v34, v32, v33
	v_lshl_add_u64 v[32:33], v[200:201], 1, s[40:41]
	v_add_u32_e32 v200, 0x1620, v64
	global_store_short v[32:33], v34, off
	v_lshl_add_u64 v[32:33], v[200:201], 1, s[40:41]
	global_store_short_d16_hi v[32:33], v34, off
	v_mul_f32_e32 v32, v66, v35
	v_mul_f32_e32 v33, v66, v51
	v_add_u32_e32 v200, 0x2100, v64
	v_cvt_pk_bf16_f32 v34, v32, v33
	v_lshl_add_u64 v[32:33], v[200:201], 1, s[40:41]
	v_add_u32_e32 v200, 0x2120, v64
	global_store_short v[32:33], v34, off
	v_lshl_add_u64 v[32:33], v[200:201], 1, s[40:41]
	global_store_short_d16_hi v[32:33], v34, off
	v_mul_f32_e32 v32, v66, v36
	v_mul_f32_e32 v33, v66, v52
	v_add_u32_e32 v200, 0x5800, v64
	v_cvt_pk_bf16_f32 v34, v32, v33
	v_lshl_add_u64 v[32:33], v[200:201], 1, s[40:41]
	v_add_u32_e32 v200, 0x5820, v64
	global_store_short v[32:33], v34, off
	v_lshl_add_u64 v[32:33], v[200:201], 1, s[40:41]
	global_store_short_d16_hi v[32:33], v34, off
	v_mul_f32_e32 v32, v66, v37
	v_mul_f32_e32 v33, v66, v53
	v_add_u32_e32 v200, 0x6300, v64
	v_cvt_pk_bf16_f32 v34, v32, v33
	v_lshl_add_u64 v[32:33], v[200:201], 1, s[40:41]
	v_add_u32_e32 v200, 0x6320, v64
	global_store_short v[32:33], v34, off
	v_lshl_add_u64 v[32:33], v[200:201], 1, s[40:41]
	global_store_short_d16_hi v[32:33], v34, off
	v_mul_f32_e32 v32, v66, v38
	v_mul_f32_e32 v33, v66, v54
	v_add_u32_e32 v200, 0x6e00, v64
	v_cvt_pk_bf16_f32 v34, v32, v33
	v_lshl_add_u64 v[32:33], v[200:201], 1, s[40:41]
	v_add_u32_e32 v200, 0x6e20, v64
	global_store_short v[32:33], v34, off
	v_lshl_add_u64 v[32:33], v[200:201], 1, s[40:41]
	global_store_short_d16_hi v[32:33], v34, off
	v_mul_f32_e32 v32, v66, v39
	v_mul_f32_e32 v33, v66, v55
	v_add_u32_e32 v200, 0x7900, v64
	v_cvt_pk_bf16_f32 v34, v32, v33
	v_lshl_add_u64 v[32:33], v[200:201], 1, s[40:41]
	v_add_u32_e32 v200, 0x7920, v64
	global_store_short v[32:33], v34, off
	v_lshl_add_u64 v[32:33], v[200:201], 1, s[40:41]
	global_store_short_d16_hi v[32:33], v34, off
	v_mul_f32_e32 v32, v66, v40
	v_mul_f32_e32 v33, v66, v56
	v_add_u32_e32 v200, 0xb000, v64
	v_cvt_pk_bf16_f32 v34, v32, v33
	v_lshl_add_u64 v[32:33], v[200:201], 1, s[40:41]
	v_add_u32_e32 v200, 0xb020, v64
; #define SBAR() __builtin_amdgcn_sched_barrier(0)
; __device__ __forceinline__ void phase_z(const P& p, int layer, char* lds) {
;     ...
; #pragma unroll
;       for (int mi = 0; mi < 2; ++mi) {
; #pragma unroll
;         for (int r = 0; r < 16; ++r) {
;           const unsigned row = rb + mi * 32 + (r & 3) + 8 * (r >> 2);
;           const unsigned w = cvtpk(acc[mi][0][r] * sc, acc[mi][1][r] * sc);
;           z[row * ZC + colb + r32] = (u16)w; z[row * ZC + colb + 32 + r32] = (u16)(w >> 16);
;         }
;         SBAR();
;       }
	global_store_short v[32:33], v34, off
	v_lshl_add_u64 v[32:33], v[200:201], 1, s[40:41]
	global_store_short_d16_hi v[32:33], v34, off
	v_mul_f32_e32 v32, v66, v41
	v_mul_f32_e32 v33, v66, v57
	v_add_u32_e32 v200, 0xbb00, v64
	v_cvt_pk_bf16_f32 v34, v32, v33
	v_lshl_add_u64 v[32:33], v[200:201], 1, s[40:41]
	v_add_u32_e32 v200, 0xbb20, v64
	global_store_short v[32:33], v34, off
	v_lshl_add_u64 v[32:33], v[200:201], 1, s[40:41]
	global_store_short_d16_hi v[32:33], v34, off
	v_mul_f32_e32 v32, v66, v42
	v_mul_f32_e32 v33, v66, v58
	v_add_u32_e32 v200, 0xc600, v64
	v_cvt_pk_bf16_f32 v34, v32, v33
	v_lshl_add_u64 v[32:33], v[200:201], 1, s[40:41]
	v_add_u32_e32 v200, 0xc620, v64
	global_store_short v[32:33], v34, off
	v_lshl_add_u64 v[32:33], v[200:201], 1, s[40:41]
	global_store_short_d16_hi v[32:33], v34, off
	v_mul_f32_e32 v32, v66, v43
	v_mul_f32_e32 v33, v66, v59
	v_add_u32_e32 v200, 0xd100, v64
	v_cvt_pk_bf16_f32 v34, v32, v33
	v_lshl_add_u64 v[32:33], v[200:201], 1, s[40:41]
	v_add_u32_e32 v200, 0xd120, v64
	global_store_short v[32:33], v34, off
	v_lshl_add_u64 v[32:33], v[200:201], 1, s[40:41]
	global_store_short_d16_hi v[32:33], v34, off
	v_mul_f32_e32 v32, v66, v44
	v_mul_f32_e32 v33, v66, v60
	v_add_u32_e32 v200, 0x10800, v64
	v_cvt_pk_bf16_f32 v34, v32, v33
	v_lshl_add_u64 v[32:33], v[200:201], 1, s[40:41]
	v_add_u32_e32 v200, 0x10820, v64
	global_store_short v[32:33], v34, off
	v_lshl_add_u64 v[32:33], v[200:201], 1, s[40:41]
	global_store_short_d16_hi v[32:33], v34, off
	v_mul_f32_e32 v32, v66, v45
	v_mul_f32_e32 v33, v66, v61
	v_add_u32_e32 v200, 0x11300, v64
	v_cvt_pk_bf16_f32 v34, v32, v33
	v_lshl_add_u64 v[32:33], v[200:201], 1, s[40:41]
	v_add_u32_e32 v200, 0x11320, v64
	global_store_short v[32:33], v34, off
	v_lshl_add_u64 v[32:33], v[200:201], 1, s[40:41]
	global_store_short_d16_hi v[32:33], v34, off
	v_mul_f32_e32 v32, v66, v46
	v_mul_f32_e32 v33, v66, v62
	v_add_u32_e32 v200, 0x11e00, v64
	v_cvt_pk_bf16_f32 v34, v32, v33
	v_lshl_add_u64 v[32:33], v[200:201], 1, s[40:41]
	v_add_u32_e32 v200, 0x11e20, v64
	global_store_short v[32:33], v34, off
	v_lshl_add_u64 v[32:33], v[200:201], 1, s[40:41]
	global_store_short_d16_hi v[32:33], v34, off
	v_mul_f32_e32 v32, v66, v47
	v_mul_f32_e32 v33, v66, v63
	v_add_u32_e32 v200, 0x12900, v64
	v_cvt_pk_bf16_f32 v34, v32, v33
	v_lshl_add_u64 v[32:33], v[200:201], 1, s[40:41]
	v_add_u32_e32 v200, 0x12920, v64
	global_store_short v[32:33], v34, off
	v_lshl_add_u64 v[32:33], v[200:201], 1, s[40:41]
	global_store_short_d16_hi v[32:33], v34, off
	v_add_u32_e32 v200, 0x16000, v64
	v_mul_f32_e32 v0, v66, v0
	v_lshl_add_u64 v[32:33], v[200:201], 1, s[40:41]
	v_add_u32_e32 v200, 0x16020, v64
	v_mul_f32_e32 v16, v66, v16
	v_cvt_pk_bf16_f32 v0, v0, v16
	global_store_short v[32:33], v0, off
	v_lshl_add_u64 v[32:33], v[200:201], 1, s[40:41]
	global_store_short_d16_hi v[32:33], v0, off
	v_mul_f32_e32 v0, v66, v1
	v_mul_f32_e32 v1, v66, v17
	v_add_u32_e32 v200, 0x16b00, v64
	v_cvt_pk_bf16_f32 v16, v0, v1
	v_lshl_add_u64 v[0:1], v[200:201], 1, s[40:41]
	v_add_u32_e32 v200, 0x16b20, v64
	global_store_short v[0:1], v16, off
	v_lshl_add_u64 v[0:1], v[200:201], 1, s[40:41]
	global_store_short_d16_hi v[0:1], v16, off
	v_mul_f32_e32 v0, v66, v2
	v_mul_f32_e32 v1, v66, v18
	v_add_u32_e32 v200, 0x17600, v64
	v_cvt_pk_bf16_f32 v2, v0, v1
	v_lshl_add_u64 v[0:1], v[200:201], 1, s[40:41]
	v_add_u32_e32 v200, 0x17620, v64
	global_store_short v[0:1], v2, off
	v_lshl_add_u64 v[0:1], v[200:201], 1, s[40:41]
	global_store_short_d16_hi v[0:1], v2, off
	v_mul_f32_e32 v0, v66, v3
	v_mul_f32_e32 v1, v66, v19
	v_add_u32_e32 v200, 0x18100, v64
	v_cvt_pk_bf16_f32 v2, v0, v1
	v_lshl_add_u64 v[0:1], v[200:201], 1, s[40:41]
	v_add_u32_e32 v200, 0x18120, v64
	global_store_short v[0:1], v2, off
	v_lshl_add_u64 v[0:1], v[200:201], 1, s[40:41]
	global_store_short_d16_hi v[0:1], v2, off
	v_mul_f32_e32 v0, v66, v4
; #define SBAR() __builtin_amdgcn_sched_barrier(0)
; __device__ __forceinline__ void phase_z(const P& p, int layer, char* lds) {
;     ...
; #pragma unroll
;       for (int mi = 0; mi < 2; ++mi) {
; #pragma unroll
;         for (int r = 0; r < 16; ++r) {
;           const unsigned row = rb + mi * 32 + (r & 3) + 8 * (r >> 2);
;           const unsigned w = cvtpk(acc[mi][0][r] * sc, acc[mi][1][r] * sc);
;           z[row * ZC + colb + r32] = (u16)w; z[row * ZC + colb + 32 + r32] = (u16)(w >> 16);
;         }
;         SBAR();
;       }
	v_mul_f32_e32 v1, v66, v20
	v_add_u32_e32 v200, 0x1b800, v64
	v_cvt_pk_bf16_f32 v2, v0, v1
	v_lshl_add_u64 v[0:1], v[200:201], 1, s[40:41]
	v_add_u32_e32 v200, 0x1b820, v64
	global_store_short v[0:1], v2, off
	v_lshl_add_u64 v[0:1], v[200:201], 1, s[40:41]
	global_store_short_d16_hi v[0:1], v2, off
	v_mul_f32_e32 v0, v66, v5
	v_mul_f32_e32 v1, v66, v21
	v_add_u32_e32 v200, 0x1c300, v64
	v_cvt_pk_bf16_f32 v2, v0, v1
	v_lshl_add_u64 v[0:1], v[200:201], 1, s[40:41]
	v_add_u32_e32 v200, 0x1c320, v64
	global_store_short v[0:1], v2, off
	v_lshl_add_u64 v[0:1], v[200:201], 1, s[40:41]
	global_store_short_d16_hi v[0:1], v2, off
	v_mul_f32_e32 v0, v66, v6
	v_mul_f32_e32 v1, v66, v22
	v_add_u32_e32 v200, 0x1ce00, v64
	v_cvt_pk_bf16_f32 v2, v0, v1
	v_lshl_add_u64 v[0:1], v[200:201], 1, s[40:41]
	v_add_u32_e32 v200, 0x1ce20, v64
	global_store_short v[0:1], v2, off
	v_lshl_add_u64 v[0:1], v[200:201], 1, s[40:41]
	global_store_short_d16_hi v[0:1], v2, off
	v_mul_f32_e32 v0, v66, v7
	v_mul_f32_e32 v1, v66, v23
	v_add_u32_e32 v200, 0x1d900, v64
	v_cvt_pk_bf16_f32 v2, v0, v1
	v_lshl_add_u64 v[0:1], v[200:201], 1, s[40:41]
	v_add_u32_e32 v200, 0x1d920, v64
	global_store_short v[0:1], v2, off
	v_lshl_add_u64 v[0:1], v[200:201], 1, s[40:41]
	global_store_short_d16_hi v[0:1], v2, off
	v_mul_f32_e32 v0, v66, v8
	v_mul_f32_e32 v1, v66, v24
	v_add_u32_e32 v200, 0x21000, v64
	v_cvt_pk_bf16_f32 v2, v0, v1
	v_lshl_add_u64 v[0:1], v[200:201], 1, s[40:41]
	v_add_u32_e32 v200, 0x21020, v64
	global_store_short v[0:1], v2, off
	v_lshl_add_u64 v[0:1], v[200:201], 1, s[40:41]
	global_store_short_d16_hi v[0:1], v2, off
	v_mul_f32_e32 v0, v66, v9
	v_mul_f32_e32 v1, v66, v25
	v_add_u32_e32 v200, 0x21b00, v64
	v_cvt_pk_bf16_f32 v2, v0, v1
	v_lshl_add_u64 v[0:1], v[200:201], 1, s[40:41]
	v_add_u32_e32 v200, 0x21b20, v64
	global_store_short v[0:1], v2, off
	v_lshl_add_u64 v[0:1], v[200:201], 1, s[40:41]
	global_store_short_d16_hi v[0:1], v2, off
	v_mul_f32_e32 v0, v66, v10
	v_mul_f32_e32 v1, v66, v26
	v_add_u32_e32 v200, 0x22600, v64
	v_cvt_pk_bf16_f32 v2, v0, v1
	v_lshl_add_u64 v[0:1], v[200:201], 1, s[40:41]
	v_add_u32_e32 v200, 0x22620, v64
	global_store_short v[0:1], v2, off
	v_lshl_add_u64 v[0:1], v[200:201], 1, s[40:41]
	global_store_short_d16_hi v[0:1], v2, off
	v_mul_f32_e32 v0, v66, v11
	v_mul_f32_e32 v1, v66, v27
	v_add_u32_e32 v200, 0x23100, v64
	v_cvt_pk_bf16_f32 v2, v0, v1
	v_lshl_add_u64 v[0:1], v[200:201], 1, s[40:41]
	v_add_u32_e32 v200, 0x23120, v64
	global_store_short v[0:1], v2, off
	v_lshl_add_u64 v[0:1], v[200:201], 1, s[40:41]
	global_store_short_d16_hi v[0:1], v2, off
	v_mul_f32_e32 v0, v66, v12
	v_mul_f32_e32 v1, v66, v28
	v_add_u32_e32 v200, 0x26800, v64
	v_cvt_pk_bf16_f32 v2, v0, v1
	v_lshl_add_u64 v[0:1], v[200:201], 1, s[40:41]
	v_add_u32_e32 v200, 0x26820, v64
	global_store_short v[0:1], v2, off
	v_lshl_add_u64 v[0:1], v[200:201], 1, s[40:41]
	global_store_short_d16_hi v[0:1], v2, off
	v_mul_f32_e32 v0, v66, v13
	v_mul_f32_e32 v1, v66, v29
	v_add_u32_e32 v200, 0x27300, v64
	v_cvt_pk_bf16_f32 v2, v0, v1
	v_lshl_add_u64 v[0:1], v[200:201], 1, s[40:41]
	v_add_u32_e32 v200, 0x27320, v64
	global_store_short v[0:1], v2, off
	v_lshl_add_u64 v[0:1], v[200:201], 1, s[40:41]
	global_store_short_d16_hi v[0:1], v2, off
	v_mul_f32_e32 v0, v66, v14
	v_mul_f32_e32 v1, v66, v30
	v_add_u32_e32 v200, 0x27e00, v64
	v_cvt_pk_bf16_f32 v2, v0, v1
	v_lshl_add_u64 v[0:1], v[200:201], 1, s[40:41]
	v_add_u32_e32 v200, 0x27e20, v64
	global_store_short v[0:1], v2, off
	v_lshl_add_u64 v[0:1], v[200:201], 1, s[40:41]
	global_store_short_d16_hi v[0:1], v2, off
	v_mul_f32_e32 v0, v66, v15
	v_mul_f32_e32 v1, v66, v31
	v_add_u32_e32 v200, 0x28900, v64
	v_cvt_pk_bf16_f32 v2, v0, v1
	v_lshl_add_u64 v[0:1], v[200:201], 1, s[40:41]
	v_add_u32_e32 v200, 0x28920, v64
	global_store_short v[0:1], v2, off
	v_lshl_add_u64 v[0:1], v[200:201], 1, s[40:41]
	global_store_short_d16_hi v[0:1], v2, off
